# v041 + de-serialised waits in P0 (norm_w preload, transpose unroll) and RG-LRU (conv-load and parameter-load hoists)
# baseline (speedup 1.0000x reference)
.LBB0_24:
	v_lshl_add_u64 v[52:53], v[36:37], 0, s[6:7]
	v_lshl_add_u64 v[54:55], v[34:35], 0, s[6:7]
	v_lshl_add_u64 v[56:57], v[32:33], 0, s[6:7]
	v_lshl_add_u64 v[58:59], v[30:31], 0, s[6:7]
	v_lshl_add_u64 v[60:61], v[28:29], 0, s[6:7]
	v_lshl_add_u64 v[62:63], v[26:27], 0, s[6:7]
	v_lshl_add_u64 v[64:65], v[24:25], 0, s[6:7]
	v_lshl_add_u64 v[66:67], v[22:23], 0, s[6:7]
	global_load_dword v68, v[52:53], off nt
	global_load_dword v69, v[54:55], off nt
	global_load_dword v70, v[56:57], off nt
	global_load_dword v71, v[58:59], off nt
	global_load_dword v72, v[60:61], off nt
	global_load_dword v73, v[62:63], off nt
	global_load_dword v74, v[64:65], off nt
	global_load_dword v75, v[66:67], off nt
	s_add_u32 s6, s6, 0x2000
	s_addc_u32 s7, s7, 0
	v_lshl_add_u64 v[52:53], v[36:37], 0, s[6:7]
	v_lshl_add_u64 v[54:55], v[34:35], 0, s[6:7]
	v_lshl_add_u64 v[56:57], v[32:33], 0, s[6:7]
	v_lshl_add_u64 v[58:59], v[30:31], 0, s[6:7]
	v_lshl_add_u64 v[60:61], v[28:29], 0, s[6:7]
	v_lshl_add_u64 v[62:63], v[26:27], 0, s[6:7]
	v_lshl_add_u64 v[64:65], v[24:25], 0, s[6:7]
	v_lshl_add_u64 v[66:67], v[22:23], 0, s[6:7]
	global_load_dword v76, v[52:53], off nt
	global_load_dword v77, v[54:55], off nt
	global_load_dword v78, v[56:57], off nt
	global_load_dword v79, v[58:59], off nt
	global_load_dword v80, v[60:61], off nt
	global_load_dword v81, v[62:63], off nt
	global_load_dword v82, v[64:65], off nt
	global_load_dword v83, v[66:67], off nt
	s_add_u32 s6, s6, 0x2000
	s_addc_u32 s7, s7, 0
	v_lshl_add_u64 v[52:53], v[36:37], 0, s[6:7]
	v_lshl_add_u64 v[54:55], v[34:35], 0, s[6:7]
	v_lshl_add_u64 v[56:57], v[32:33], 0, s[6:7]
	v_lshl_add_u64 v[58:59], v[30:31], 0, s[6:7]
	v_lshl_add_u64 v[60:61], v[28:29], 0, s[6:7]
	v_lshl_add_u64 v[62:63], v[26:27], 0, s[6:7]
	v_lshl_add_u64 v[64:65], v[24:25], 0, s[6:7]
	v_lshl_add_u64 v[66:67], v[22:23], 0, s[6:7]
	global_load_dword v84, v[52:53], off nt
	global_load_dword v85, v[54:55], off nt
	global_load_dword v86, v[56:57], off nt
	global_load_dword v87, v[58:59], off nt
	global_load_dword v88, v[60:61], off nt
	global_load_dword v89, v[62:63], off nt
	global_load_dword v90, v[64:65], off nt
	global_load_dword v91, v[66:67], off nt
	s_add_u32 s6, s6, 0x2000
	s_addc_u32 s7, s7, 0
	v_lshl_add_u64 v[52:53], v[36:37], 0, s[6:7]
	v_lshl_add_u64 v[54:55], v[34:35], 0, s[6:7]
	v_lshl_add_u64 v[56:57], v[32:33], 0, s[6:7]
	v_lshl_add_u64 v[58:59], v[30:31], 0, s[6:7]
	v_lshl_add_u64 v[60:61], v[28:29], 0, s[6:7]
	v_lshl_add_u64 v[62:63], v[26:27], 0, s[6:7]
	v_lshl_add_u64 v[64:65], v[24:25], 0, s[6:7]
	v_lshl_add_u64 v[66:67], v[22:23], 0, s[6:7]
	global_load_dword v92, v[52:53], off nt
	global_load_dword v93, v[54:55], off nt
	global_load_dword v94, v[56:57], off nt
	global_load_dword v95, v[58:59], off nt
	global_load_dword v96, v[60:61], off nt
	global_load_dword v97, v[62:63], off nt
	global_load_dword v98, v[64:65], off nt
	global_load_dword v99, v[66:67], off nt
	s_add_u32 s6, s6, 0x2000
	s_addc_u32 s7, s7, 0
	v_add_u32_e32 v59, 0x400, v0
	s_waitcnt vmcnt(30)
	ds_write2_b32 v0, v68, v69 offset1:66
	s_waitcnt vmcnt(28)
	ds_write2_b32 v0, v70, v71 offset0:132 offset1:198
	s_waitcnt vmcnt(26)
	ds_write2_b32 v59, v72, v73 offset0:8 offset1:74
	s_waitcnt vmcnt(24)
	ds_write2_b32 v59, v74, v75 offset0:140 offset1:206
	v_add_u32_e32 v0, 0x840, v0
	v_add_u32_e32 v59, 0x400, v0
	s_waitcnt vmcnt(22)
	ds_write2_b32 v0, v76, v77 offset1:66
	s_waitcnt vmcnt(20)
	ds_write2_b32 v0, v78, v79 offset0:132 offset1:198
	s_waitcnt vmcnt(18)
	ds_write2_b32 v59, v80, v81 offset0:8 offset1:74
	s_waitcnt vmcnt(16)
	ds_write2_b32 v59, v82, v83 offset0:140 offset1:206
	v_add_u32_e32 v0, 0x840, v0
	v_add_u32_e32 v59, 0x400, v0
	s_waitcnt vmcnt(14)
	ds_write2_b32 v0, v84, v85 offset1:66
	s_waitcnt vmcnt(12)
	ds_write2_b32 v0, v86, v87 offset0:132 offset1:198
	s_waitcnt vmcnt(10)
	ds_write2_b32 v59, v88, v89 offset0:8 offset1:74
	s_waitcnt vmcnt(8)
	ds_write2_b32 v59, v90, v91 offset0:140 offset1:206
	v_add_u32_e32 v0, 0x840, v0
	v_add_u32_e32 v59, 0x400, v0
	s_waitcnt vmcnt(6)
	ds_write2_b32 v0, v92, v93 offset1:66
	s_waitcnt vmcnt(4)
	ds_write2_b32 v0, v94, v95 offset0:132 offset1:198
	s_waitcnt vmcnt(2)
	ds_write2_b32 v59, v96, v97 offset0:8 offset1:74
	s_waitcnt vmcnt(0)
	ds_write2_b32 v59, v98, v99 offset0:140 offset1:206
	v_add_u32_e32 v0, 0x840, v0
	s_cmpk_lg_u32 s6, 0x8000
	s_and_b32 s0, s0, 0xffffff80
	s_lshl_b32 s6, s21, 13
	s_and_b32 s8, s6, 0xf0000
	s_lshl_b64 s[6:7], s[0:1], 8
	s_add_u32 s0, s14, s8
	s_addc_u32 s8, s15, 0
	s_add_u32 s0, s0, s6
	s_addc_u32 s7, s8, s7
	s_lshl_b32 s6, s21, 5
	s_waitcnt lgkmcnt(0)
	s_and_b32 s6, s6, 0x80
	ds_read2_b32 v[22:23], v40 offset1:33
	s_add_u32 s6, s0, s6
	s_waitcnt lgkmcnt(0)
	v_cvt_pk_bf16_f32 v22, v22, v23
	ds_read2_b32 v[24:25], v40 offset0:66 offset1:99
	v_mov_b32_e32 v21, v1
	s_addc_u32 s7, s7, 0
	s_waitcnt lgkmcnt(0)
	v_cvt_pk_bf16_f32 v23, v24, v25
	ds_read2_b32 v[24:25], v40 offset0:132 offset1:165
	v_lshl_add_u64 v[28:29], s[6:7], 0, v[20:21]
	s_waitcnt lgkmcnt(0)
	v_cvt_pk_bf16_f32 v24, v24, v25
	ds_read2_b32 v[26:27], v40 offset0:198 offset1:231
	s_waitcnt lgkmcnt(0)
	v_cvt_pk_bf16_f32 v25, v26, v27
	v_lshl_add_u64 v[30:31], v[28:29], 0, v[6:7]
	ds_read2_b32 v[26:27], v40 offset0:8 offset1:41
	global_store_dwordx4 v[30:31], v[22:25], off
	v_lshl_add_u64 v[30:31], v[28:29], 0, v[8:9]
	s_mov_b64 s[6:7], 0
	s_waitcnt lgkmcnt(0)
	v_cvt_pk_bf16_f32 v22, v26, v27
	ds_read2_b32 v[24:25], v40 offset0:74 offset1:107
	s_waitcnt lgkmcnt(0)
	v_cvt_pk_bf16_f32 v23, v24, v25
	ds_read2_b32 v[24:25], v40 offset0:140 offset1:173
	s_waitcnt lgkmcnt(0)
	v_cvt_pk_bf16_f32 v24, v24, v25
	ds_read2_b32 v[26:27], v40 offset0:206 offset1:239
	s_waitcnt lgkmcnt(0)
	v_cvt_pk_bf16_f32 v25, v26, v27
	ds_read2_b32 v[26:27], v40 offset0:16 offset1:49
	global_store_dwordx4 v[30:31], v[22:25], off
	v_lshl_add_u64 v[30:31], v[28:29], 0, v[10:11]
	s_waitcnt lgkmcnt(0)
	v_cvt_pk_bf16_f32 v22, v26, v27
	ds_read2_b32 v[24:25], v40 offset0:82 offset1:115
	s_waitcnt lgkmcnt(0)
	v_cvt_pk_bf16_f32 v23, v24, v25
	ds_read2_b32 v[24:25], v40 offset0:148 offset1:181
	s_waitcnt lgkmcnt(0)
	v_cvt_pk_bf16_f32 v24, v24, v25
	ds_read2_b32 v[26:27], v40 offset0:214 offset1:247
	s_waitcnt lgkmcnt(0)
	v_cvt_pk_bf16_f32 v25, v26, v27
	ds_read2_b32 v[26:27], v40 offset0:24 offset1:57
	global_store_dwordx4 v[30:31], v[22:25], off
	s_waitcnt lgkmcnt(0)
	s_nop 0
	v_cvt_pk_bf16_f32 v22, v26, v27
	ds_read2_b32 v[24:25], v40 offset0:90 offset1:123
	s_waitcnt lgkmcnt(0)
	v_cvt_pk_bf16_f32 v23, v24, v25
	ds_read2_b32 v[24:25], v40 offset0:156 offset1:189
	s_waitcnt lgkmcnt(0)
	v_cvt_pk_bf16_f32 v24, v24, v25
	ds_read2_b32 v[26:27], v40 offset0:222 offset1:255
	s_waitcnt lgkmcnt(0)
	v_cvt_pk_bf16_f32 v25, v26, v27
	v_lshl_add_u64 v[26:27], v[28:29], 0, v[12:13]
	global_store_dwordx4 v[26:27], v[22:25], off
	s_waitcnt lgkmcnt(0)

.LBB0_28:
	v_lshl_add_u64 v[52:53], v[36:37], 0, s[6:7]
	v_lshl_add_u64 v[54:55], v[34:35], 0, s[6:7]
	v_lshl_add_u64 v[56:57], v[32:33], 0, s[6:7]
	v_lshl_add_u64 v[58:59], v[30:31], 0, s[6:7]
	v_lshl_add_u64 v[60:61], v[28:29], 0, s[6:7]
	v_lshl_add_u64 v[62:63], v[26:27], 0, s[6:7]
	v_lshl_add_u64 v[64:65], v[24:25], 0, s[6:7]
	v_lshl_add_u64 v[66:67], v[22:23], 0, s[6:7]
	global_load_dword v68, v[52:53], off nt
	global_load_dword v69, v[54:55], off nt
	global_load_dword v70, v[56:57], off nt
	global_load_dword v71, v[58:59], off nt
	global_load_dword v72, v[60:61], off nt
	global_load_dword v73, v[62:63], off nt
	global_load_dword v74, v[64:65], off nt
	global_load_dword v75, v[66:67], off nt
	s_add_u32 s6, s6, 0x20000
	s_addc_u32 s7, s7, 0
	v_lshl_add_u64 v[52:53], v[36:37], 0, s[6:7]
	v_lshl_add_u64 v[54:55], v[34:35], 0, s[6:7]
	v_lshl_add_u64 v[56:57], v[32:33], 0, s[6:7]
	v_lshl_add_u64 v[58:59], v[30:31], 0, s[6:7]
	v_lshl_add_u64 v[60:61], v[28:29], 0, s[6:7]
	v_lshl_add_u64 v[62:63], v[26:27], 0, s[6:7]
	v_lshl_add_u64 v[64:65], v[24:25], 0, s[6:7]
	v_lshl_add_u64 v[66:67], v[22:23], 0, s[6:7]
	global_load_dword v76, v[52:53], off nt
	global_load_dword v77, v[54:55], off nt
	global_load_dword v78, v[56:57], off nt
	global_load_dword v79, v[58:59], off nt
	global_load_dword v80, v[60:61], off nt
	global_load_dword v81, v[62:63], off nt
	global_load_dword v82, v[64:65], off nt
	global_load_dword v83, v[66:67], off nt
	s_add_u32 s6, s6, 0x20000
	s_addc_u32 s7, s7, 0
	v_lshl_add_u64 v[52:53], v[36:37], 0, s[6:7]
	v_lshl_add_u64 v[54:55], v[34:35], 0, s[6:7]
	v_lshl_add_u64 v[56:57], v[32:33], 0, s[6:7]
	v_lshl_add_u64 v[58:59], v[30:31], 0, s[6:7]
	v_lshl_add_u64 v[60:61], v[28:29], 0, s[6:7]
	v_lshl_add_u64 v[62:63], v[26:27], 0, s[6:7]
	v_lshl_add_u64 v[64:65], v[24:25], 0, s[6:7]
	v_lshl_add_u64 v[66:67], v[22:23], 0, s[6:7]
	global_load_dword v84, v[52:53], off nt
	global_load_dword v85, v[54:55], off nt
	global_load_dword v86, v[56:57], off nt
	global_load_dword v87, v[58:59], off nt
	global_load_dword v88, v[60:61], off nt
	global_load_dword v89, v[62:63], off nt
	global_load_dword v90, v[64:65], off nt
	global_load_dword v91, v[66:67], off nt
	s_add_u32 s6, s6, 0x20000
	s_addc_u32 s7, s7, 0
	v_lshl_add_u64 v[52:53], v[36:37], 0, s[6:7]
	v_lshl_add_u64 v[54:55], v[34:35], 0, s[6:7]
	v_lshl_add_u64 v[56:57], v[32:33], 0, s[6:7]
	v_lshl_add_u64 v[58:59], v[30:31], 0, s[6:7]
	v_lshl_add_u64 v[60:61], v[28:29], 0, s[6:7]
	v_lshl_add_u64 v[62:63], v[26:27], 0, s[6:7]
	v_lshl_add_u64 v[64:65], v[24:25], 0, s[6:7]
	v_lshl_add_u64 v[66:67], v[22:23], 0, s[6:7]
	global_load_dword v92, v[52:53], off nt
	global_load_dword v93, v[54:55], off nt
	global_load_dword v94, v[56:57], off nt
	global_load_dword v95, v[58:59], off nt
	global_load_dword v96, v[60:61], off nt
	global_load_dword v97, v[62:63], off nt
	global_load_dword v98, v[64:65], off nt
	global_load_dword v99, v[66:67], off nt
	s_add_u32 s6, s6, 0x20000
	s_addc_u32 s7, s7, 0
	v_add_u32_e32 v59, 0x400, v0
	s_waitcnt vmcnt(30)
	ds_write2_b32 v0, v68, v69 offset1:66
	s_waitcnt vmcnt(28)
	ds_write2_b32 v0, v70, v71 offset0:132 offset1:198
	s_waitcnt vmcnt(26)
	ds_write2_b32 v59, v72, v73 offset0:8 offset1:74
	s_waitcnt vmcnt(24)
	ds_write2_b32 v59, v74, v75 offset0:140 offset1:206
	v_add_u32_e32 v0, 0x840, v0
	v_add_u32_e32 v59, 0x400, v0
	s_waitcnt vmcnt(22)
	ds_write2_b32 v0, v76, v77 offset1:66
	s_waitcnt vmcnt(20)
	ds_write2_b32 v0, v78, v79 offset0:132 offset1:198
	s_waitcnt vmcnt(18)
	ds_write2_b32 v59, v80, v81 offset0:8 offset1:74
	s_waitcnt vmcnt(16)
	ds_write2_b32 v59, v82, v83 offset0:140 offset1:206
	v_add_u32_e32 v0, 0x840, v0
	v_add_u32_e32 v59, 0x400, v0
	s_waitcnt vmcnt(14)
	ds_write2_b32 v0, v84, v85 offset1:66
	s_waitcnt vmcnt(12)
	ds_write2_b32 v0, v86, v87 offset0:132 offset1:198
	s_waitcnt vmcnt(10)
	ds_write2_b32 v59, v88, v89 offset0:8 offset1:74
	s_waitcnt vmcnt(8)
	ds_write2_b32 v59, v90, v91 offset0:140 offset1:206
	v_add_u32_e32 v0, 0x840, v0
	v_add_u32_e32 v59, 0x400, v0
	s_waitcnt vmcnt(6)
	ds_write2_b32 v0, v92, v93 offset1:66
	s_waitcnt vmcnt(4)
	ds_write2_b32 v0, v94, v95 offset0:132 offset1:198
	s_waitcnt vmcnt(2)
	ds_write2_b32 v59, v96, v97 offset0:8 offset1:74
	s_waitcnt vmcnt(0)
	ds_write2_b32 v59, v98, v99 offset0:140 offset1:206
	v_add_u32_e32 v0, 0x840, v0
	s_cmp_lg_u32 s6, 0x80000
	s_waitcnt lgkmcnt(0)
	s_add_i32 s0, s21, 0xee00
	s_lshl_b32 s6, s21, 5
	ds_read2_b32 v[22:23], v40 offset1:33
	s_and_b32 s0, s0, 0xffc0
	s_and_b32 s6, s6, 0x7e0
	s_waitcnt lgkmcnt(0)
	v_cvt_pk_bf16_f32 v22, v22, v23
	ds_read2_b32 v[24:25], v40 offset0:66 offset1:99
	s_lshl_b32 s0, s0, 1
	v_or_b32_e32 v0, s6, v39
	s_waitcnt lgkmcnt(0)
	v_cvt_pk_bf16_f32 v23, v24, v25
	ds_read2_b32 v[24:25], v40 offset0:132 offset1:165
	v_lshl_add_u64 v[28:29], v[2:3], 0, s[0:1]
	v_lshlrev_b32_e32 v0, 12, v0
	s_waitcnt lgkmcnt(0)
	v_cvt_pk_bf16_f32 v24, v24, v25
	ds_read2_b32 v[26:27], v40 offset0:198 offset1:231
	s_waitcnt lgkmcnt(0)
	v_cvt_pk_bf16_f32 v25, v26, v27
	v_lshl_add_u64 v[30:31], v[28:29], 0, v[0:1]
	ds_read2_b32 v[26:27], v40 offset0:8 offset1:41
	global_store_dwordx4 v[30:31], v[22:25], off
	v_or_b32_e32 v0, s6, v41
	v_lshlrev_b32_e32 v0, 12, v0
	s_waitcnt lgkmcnt(0)
	v_cvt_pk_bf16_f32 v22, v26, v27
	ds_read2_b32 v[24:25], v40 offset0:74 offset1:107
	s_waitcnt lgkmcnt(0)
	v_cvt_pk_bf16_f32 v23, v24, v25
	ds_read2_b32 v[24:25], v40 offset0:140 offset1:173
	s_waitcnt lgkmcnt(0)
	v_cvt_pk_bf16_f32 v24, v24, v25
	ds_read2_b32 v[26:27], v40 offset0:206 offset1:239
	s_waitcnt lgkmcnt(0)
	v_cvt_pk_bf16_f32 v25, v26, v27
	v_lshl_add_u64 v[30:31], v[28:29], 0, v[0:1]
	ds_read2_b32 v[26:27], v40 offset0:16 offset1:49
	global_store_dwordx4 v[30:31], v[22:25], off
	v_or_b32_e32 v0, s6, v42
	v_lshlrev_b32_e32 v0, 12, v0
	s_waitcnt lgkmcnt(0)
	v_cvt_pk_bf16_f32 v22, v26, v27
	ds_read2_b32 v[24:25], v40 offset0:82 offset1:115
	s_waitcnt lgkmcnt(0)
	v_cvt_pk_bf16_f32 v23, v24, v25
	ds_read2_b32 v[24:25], v40 offset0:148 offset1:181
	s_waitcnt lgkmcnt(0)
	v_cvt_pk_bf16_f32 v24, v24, v25
	ds_read2_b32 v[26:27], v40 offset0:214 offset1:247
	s_waitcnt lgkmcnt(0)
	v_cvt_pk_bf16_f32 v25, v26, v27
	v_lshl_add_u64 v[30:31], v[28:29], 0, v[0:1]
	ds_read2_b32 v[26:27], v40 offset0:24 offset1:57
	global_store_dwordx4 v[30:31], v[22:25], off
	v_or_b32_e32 v0, s6, v43
	v_lshlrev_b32_e32 v0, 12, v0
	s_waitcnt lgkmcnt(0)
	v_cvt_pk_bf16_f32 v22, v26, v27
	ds_read2_b32 v[24:25], v40 offset0:90 offset1:123
	s_waitcnt lgkmcnt(0)
	v_cvt_pk_bf16_f32 v23, v24, v25
	ds_read2_b32 v[24:25], v40 offset0:156 offset1:189
	s_waitcnt lgkmcnt(0)
	v_cvt_pk_bf16_f32 v24, v24, v25
	ds_read2_b32 v[26:27], v40 offset0:222 offset1:255
	s_waitcnt lgkmcnt(0)
	v_cvt_pk_bf16_f32 v25, v26, v27
	v_lshl_add_u64 v[26:27], v[28:29], 0, v[0:1]
	global_store_dwordx4 v[26:27], v[22:25], off
	s_waitcnt lgkmcnt(0)

.LBB0_33:
	v_lshl_add_u64 v[52:53], v[36:37], 0, s[12:13]
	v_lshl_add_u64 v[54:55], v[34:35], 0, s[12:13]
	v_lshl_add_u64 v[56:57], v[32:33], 0, s[12:13]
	v_lshl_add_u64 v[58:59], v[30:31], 0, s[12:13]
	v_lshl_add_u64 v[60:61], v[28:29], 0, s[12:13]
	v_lshl_add_u64 v[62:63], v[26:27], 0, s[12:13]
	v_lshl_add_u64 v[64:65], v[24:25], 0, s[12:13]
	v_lshl_add_u64 v[66:67], v[22:23], 0, s[12:13]
	global_load_dword v68, v[52:53], off nt
	global_load_dword v69, v[54:55], off nt
	global_load_dword v70, v[56:57], off nt
	global_load_dword v71, v[58:59], off nt
	global_load_dword v72, v[60:61], off nt
	global_load_dword v73, v[62:63], off nt
	global_load_dword v74, v[64:65], off nt
	global_load_dword v75, v[66:67], off nt
	s_add_u32 s12, s12, 0x48000
	s_addc_u32 s13, s13, 0
	v_lshl_add_u64 v[52:53], v[36:37], 0, s[12:13]
	v_lshl_add_u64 v[54:55], v[34:35], 0, s[12:13]
	v_lshl_add_u64 v[56:57], v[32:33], 0, s[12:13]
	v_lshl_add_u64 v[58:59], v[30:31], 0, s[12:13]
	v_lshl_add_u64 v[60:61], v[28:29], 0, s[12:13]
	v_lshl_add_u64 v[62:63], v[26:27], 0, s[12:13]
	v_lshl_add_u64 v[64:65], v[24:25], 0, s[12:13]
	v_lshl_add_u64 v[66:67], v[22:23], 0, s[12:13]
	global_load_dword v76, v[52:53], off nt
	global_load_dword v77, v[54:55], off nt
	global_load_dword v78, v[56:57], off nt
	global_load_dword v79, v[58:59], off nt
	global_load_dword v80, v[60:61], off nt
	global_load_dword v81, v[62:63], off nt
	global_load_dword v82, v[64:65], off nt
	global_load_dword v83, v[66:67], off nt
	s_add_u32 s12, s12, 0x48000
	s_addc_u32 s13, s13, 0
	v_lshl_add_u64 v[52:53], v[36:37], 0, s[12:13]
	v_lshl_add_u64 v[54:55], v[34:35], 0, s[12:13]
	v_lshl_add_u64 v[56:57], v[32:33], 0, s[12:13]
	v_lshl_add_u64 v[58:59], v[30:31], 0, s[12:13]
	v_lshl_add_u64 v[60:61], v[28:29], 0, s[12:13]
	v_lshl_add_u64 v[62:63], v[26:27], 0, s[12:13]
	v_lshl_add_u64 v[64:65], v[24:25], 0, s[12:13]
	v_lshl_add_u64 v[66:67], v[22:23], 0, s[12:13]
	global_load_dword v84, v[52:53], off nt
	global_load_dword v85, v[54:55], off nt
	global_load_dword v86, v[56:57], off nt
	global_load_dword v87, v[58:59], off nt
	global_load_dword v88, v[60:61], off nt
	global_load_dword v89, v[62:63], off nt
	global_load_dword v90, v[64:65], off nt
	global_load_dword v91, v[66:67], off nt
	s_add_u32 s12, s12, 0x48000
	s_addc_u32 s13, s13, 0
	v_lshl_add_u64 v[52:53], v[36:37], 0, s[12:13]
	v_lshl_add_u64 v[54:55], v[34:35], 0, s[12:13]
	v_lshl_add_u64 v[56:57], v[32:33], 0, s[12:13]
	v_lshl_add_u64 v[58:59], v[30:31], 0, s[12:13]
	v_lshl_add_u64 v[60:61], v[28:29], 0, s[12:13]
	v_lshl_add_u64 v[62:63], v[26:27], 0, s[12:13]
	v_lshl_add_u64 v[64:65], v[24:25], 0, s[12:13]
	v_lshl_add_u64 v[66:67], v[22:23], 0, s[12:13]
	global_load_dword v92, v[52:53], off nt
	global_load_dword v93, v[54:55], off nt
	global_load_dword v94, v[56:57], off nt
	global_load_dword v95, v[58:59], off nt
	global_load_dword v96, v[60:61], off nt
	global_load_dword v97, v[62:63], off nt
	global_load_dword v98, v[64:65], off nt
	global_load_dword v99, v[66:67], off nt
	s_add_u32 s12, s12, 0x48000
	s_addc_u32 s13, s13, 0
	v_add_u32_e32 v59, 0x400, v0
	s_waitcnt vmcnt(30)
	ds_write2_b32 v0, v68, v69 offset1:66
	s_waitcnt vmcnt(28)
	ds_write2_b32 v0, v70, v71 offset0:132 offset1:198
	s_waitcnt vmcnt(26)
	ds_write2_b32 v59, v72, v73 offset0:8 offset1:74
	s_waitcnt vmcnt(24)
	ds_write2_b32 v59, v74, v75 offset0:140 offset1:206
	v_add_u32_e32 v0, 0x840, v0
	v_add_u32_e32 v59, 0x400, v0
	s_waitcnt vmcnt(22)
	ds_write2_b32 v0, v76, v77 offset1:66
	s_waitcnt vmcnt(20)
	ds_write2_b32 v0, v78, v79 offset0:132 offset1:198
	s_waitcnt vmcnt(18)
	ds_write2_b32 v59, v80, v81 offset0:8 offset1:74
	s_waitcnt vmcnt(16)
	ds_write2_b32 v59, v82, v83 offset0:140 offset1:206
	v_add_u32_e32 v0, 0x840, v0
	v_add_u32_e32 v59, 0x400, v0
	s_waitcnt vmcnt(14)
	ds_write2_b32 v0, v84, v85 offset1:66
	s_waitcnt vmcnt(12)
	ds_write2_b32 v0, v86, v87 offset0:132 offset1:198
	s_waitcnt vmcnt(10)
	ds_write2_b32 v59, v88, v89 offset0:8 offset1:74
	s_waitcnt vmcnt(8)
	ds_write2_b32 v59, v90, v91 offset0:140 offset1:206
	v_add_u32_e32 v0, 0x840, v0
	v_add_u32_e32 v59, 0x400, v0
	s_waitcnt vmcnt(6)
	ds_write2_b32 v0, v92, v93 offset1:66
	s_waitcnt vmcnt(4)
	ds_write2_b32 v0, v94, v95 offset0:132 offset1:198
	s_waitcnt vmcnt(2)
	ds_write2_b32 v59, v96, v97 offset0:8 offset1:74
	s_waitcnt vmcnt(0)
	ds_write2_b32 v59, v98, v99 offset0:140 offset1:206
	v_add_u32_e32 v0, 0x840, v0
	s_cmp_lg_u32 s12, 0x120000
	s_waitcnt lgkmcnt(0)
	v_or_b32_e32 v28, s6, v39
	ds_read2_b32 v[22:23], v40 offset1:33
	s_ashr_i32 s9, s8, 31
	v_ashrrev_i32_e32 v29, 31, v28
	s_waitcnt lgkmcnt(0)
	v_cvt_pk_bf16_f32 v22, v22, v23
	ds_read2_b32 v[24:25], v40 offset0:66 offset1:99
	v_lshl_add_u64 v[30:31], s[8:9], 1, v[4:5]
	v_lshlrev_b64 v[28:29], 12, v[28:29]
	s_waitcnt lgkmcnt(0)
	v_cvt_pk_bf16_f32 v23, v24, v25
	ds_read2_b32 v[24:25], v40 offset0:132 offset1:165
	v_lshl_add_u64 v[28:29], v[30:31], 0, v[28:29]
	s_waitcnt lgkmcnt(0)
	v_cvt_pk_bf16_f32 v24, v24, v25
	ds_read2_b32 v[26:27], v40 offset0:198 offset1:231
	s_waitcnt lgkmcnt(0)
	v_cvt_pk_bf16_f32 v25, v26, v27
	global_store_dwordx4 v[28:29], v[22:25], off
	v_or_b32_e32 v28, s6, v41
	v_ashrrev_i32_e32 v29, 31, v28
	ds_read2_b32 v[26:27], v40 offset0:8 offset1:41
	s_waitcnt lgkmcnt(0)
	v_cvt_pk_bf16_f32 v22, v26, v27
	ds_read2_b32 v[24:25], v40 offset0:74 offset1:107
	v_lshlrev_b64 v[28:29], 12, v[28:29]
	s_waitcnt lgkmcnt(0)
	v_cvt_pk_bf16_f32 v23, v24, v25
	ds_read2_b32 v[24:25], v40 offset0:140 offset1:173
	v_lshl_add_u64 v[28:29], v[30:31], 0, v[28:29]
	s_waitcnt lgkmcnt(0)
	v_cvt_pk_bf16_f32 v24, v24, v25
	ds_read2_b32 v[26:27], v40 offset0:206 offset1:239
	s_waitcnt lgkmcnt(0)
	v_cvt_pk_bf16_f32 v25, v26, v27
	global_store_dwordx4 v[28:29], v[22:25], off
	v_or_b32_e32 v28, s6, v42
	ds_read2_b32 v[26:27], v40 offset0:16 offset1:49
	s_waitcnt lgkmcnt(0)
	v_cvt_pk_bf16_f32 v22, v26, v27
	ds_read2_b32 v[24:25], v40 offset0:82 offset1:115
	v_ashrrev_i32_e32 v29, 31, v28
	s_waitcnt lgkmcnt(0)
	v_cvt_pk_bf16_f32 v23, v24, v25
	ds_read2_b32 v[24:25], v40 offset0:148 offset1:181
	v_lshlrev_b64 v[28:29], 12, v[28:29]
	s_waitcnt lgkmcnt(0)
	v_cvt_pk_bf16_f32 v24, v24, v25
	ds_read2_b32 v[26:27], v40 offset0:214 offset1:247
	s_waitcnt lgkmcnt(0)
	v_cvt_pk_bf16_f32 v25, v26, v27
	v_lshl_add_u64 v[28:29], v[30:31], 0, v[28:29]
	ds_read2_b32 v[26:27], v40 offset0:24 offset1:57
	global_store_dwordx4 v[28:29], v[22:25], off
	v_or_b32_e32 v28, s6, v43
	v_ashrrev_i32_e32 v29, 31, v28
	s_waitcnt lgkmcnt(0)
	v_cvt_pk_bf16_f32 v22, v26, v27
	ds_read2_b32 v[24:25], v40 offset0:90 offset1:123
	s_waitcnt lgkmcnt(0)
	v_cvt_pk_bf16_f32 v23, v24, v25
	ds_read2_b32 v[24:25], v40 offset0:156 offset1:189
	s_waitcnt lgkmcnt(0)
	v_cvt_pk_bf16_f32 v24, v24, v25
	ds_read2_b32 v[26:27], v40 offset0:222 offset1:255
	v_lshlrev_b64 v[28:29], 12, v[28:29]
	s_waitcnt lgkmcnt(0)
	v_cvt_pk_bf16_f32 v25, v26, v27
	v_lshl_add_u64 v[26:27], v[30:31], 0, v[28:29]
	global_store_dwordx4 v[26:27], v[22:25], off
	s_waitcnt lgkmcnt(0)
	s_branch .LBB0_20

.LBB0_41:
	s_or_b64 exec, exec, s[6:7]
	s_cmpk_gt_i32 s56, 0x3fff
	s_cbranch_scc1 .LBB0_44
	v_mbcnt_lo_u32_b32 v2, -1, 0
	v_mbcnt_hi_u32_b32 v2, -1, v2
	v_and_b32_e32 v3, 64, v2
	v_add_u32_e32 v3, 64, v3
	v_xor_b32_e32 v4, 1, v2
	v_cmp_lt_i32_e32 vcc, v4, v3
	v_lshlrev_b32_e32 v0, 4, v176
	v_mov_b32_e32 v1, 0
	v_cndmask_b32_e32 v4, v2, v4, vcc
	v_lshlrev_b32_e32 v38, 2, v4
	v_xor_b32_e32 v4, 2, v2
	v_cmp_lt_i32_e32 vcc, v4, v3
	s_waitcnt lgkmcnt(0)
	v_lshl_add_u64 v[24:25], s[18:19], 0, v[0:1]
	s_mov_b64 s[6:7], 0x1400
	v_cndmask_b32_e32 v4, v2, v4, vcc
	v_lshlrev_b32_e32 v39, 2, v4
	v_xor_b32_e32 v4, 4, v2
	v_cmp_lt_i32_e32 vcc, v4, v3
	v_lshl_add_u64 v[28:29], v[24:25], 0, s[6:7]
	s_mov_b64 s[6:7], 0x1800
	v_cndmask_b32_e32 v4, v2, v4, vcc
	v_lshlrev_b32_e32 v40, 2, v4
	v_xor_b32_e32 v4, 8, v2
	v_cmp_lt_i32_e32 vcc, v4, v3
	v_lshl_add_u64 v[30:31], v[24:25], 0, s[6:7]
	s_mov_b64 s[6:7], 0x1c00
	v_cndmask_b32_e32 v4, v2, v4, vcc
	v_lshlrev_b32_e32 v41, 2, v4
	v_xor_b32_e32 v4, 16, v2
	v_cmp_lt_i32_e32 vcc, v4, v3
	s_ashr_i32 s57, s56, 31
	v_lshl_add_u64 v[32:33], v[24:25], 0, s[6:7]
	v_cndmask_b32_e32 v4, v2, v4, vcc
	v_lshlrev_b32_e32 v42, 2, v4
	v_xor_b32_e32 v4, 32, v2
	s_lshl_b64 s[6:7], s[56:57], 13
	v_cmp_lt_i32_e32 vcc, v4, v3
	s_add_u32 s6, s16, s6
	s_addc_u32 s7, s17, s7
	v_cndmask_b32_e32 v2, v2, v4, vcc
	v_lshlrev_b32_e32 v43, 2, v2
	s_mov_b64 s[0:1], 0x1000
	v_lshl_add_u64 v[2:3], s[6:7], 0, v[0:1]
	s_ashr_i32 s59, s58, 31
	v_lshl_add_u64 v[26:27], v[24:25], 0, s[0:1]
	v_lshl_add_u64 v[34:35], v[2:3], 0, s[0:1]
	s_lshl_b64 s[0:1], s[58:59], 13
	s_lshl_b64 s[6:7], s[56:57], 12
	s_add_u32 s6, s52, s6
	v_lshlrev_b32_e32 v0, 3, v176
	s_addc_u32 s7, s53, s7
	v_lshl_add_u64 v[0:1], s[6:7], 0, v[0:1]
	s_mov_b64 s[6:7], 0x2000000
	v_lshl_add_u64 v[36:37], v[0:1], 0, s[6:7]
	s_lshl_b64 s[6:7], s[58:59], 12
	v_mov_b32_e32 v44, 0x358637bd
	s_mov_b32 s8, 0x800000
	s_mov_b32 s9, s56
	global_load_dwordx4 v[90:93], v[24:25], off
	global_load_dwordx4 v[94:97], v[24:25], off offset:1024
	global_load_dwordx4 v[98:101], v[24:25], off offset:2048
	global_load_dwordx4 v[102:105], v[24:25], off offset:3072
	global_load_dwordx4 v[106:109], v[26:27], off
	global_load_dwordx4 v[110:113], v[28:29], off
	global_load_dwordx4 v[114:117], v[30:31], off
	global_load_dwordx4 v[118:121], v[32:33], off
.LBB0_43:
	global_load_dwordx4 v[46:49], v[34:35], off offset:-4096 nt
	global_load_dwordx4 v[12:15], v[34:35], off offset:-3072 nt
	global_load_dwordx4 v[16:19], v[34:35], off offset:-2048 nt
	global_load_dwordx4 v[8:11], v[34:35], off offset:1024 nt
	global_load_dwordx4 v[20:23], v[34:35], off nt
	global_load_dwordx4 v[50:53], v[34:35], off offset:-1024 nt
	global_load_dwordx4 v[0:3], v[34:35], off offset:3072 nt
	global_load_dwordx4 v[4:7], v[34:35], off offset:2048 nt
	s_add_i32 s9, s9, s58
	v_lshl_add_u64 v[34:35], v[34:35], 0, s[0:1]
	s_cmpk_lt_i32 s9, 0x4000
	s_waitcnt vmcnt(7)
	v_mov_b32_e32 v60, v47
	s_waitcnt vmcnt(6)
	v_mov_b32_e32 v61, v13
	s_waitcnt vmcnt(5)
	v_pk_mul_f32 v[62:63], v[18:19], v[18:19]
	v_pk_mul_f32 v[64:65], v[16:17], v[16:17]
	s_waitcnt vmcnt(4)
	v_pk_mul_f32 v[66:67], v[10:11], v[10:11]
	v_pk_mul_f32 v[68:69], v[8:9], v[8:9]
	v_mov_b32_e32 v72, v49
	v_mov_b32_e32 v73, v15
	v_mov_b32_e32 v58, v46
	v_mov_b32_e32 v59, v12
	v_mov_b32_e32 v70, v48
	v_mov_b32_e32 v71, v14
	v_pk_mov_b32 v[82:83], v[64:65], v[62:63] op_sel:[1,0]
	v_mov_b32_e32 v65, v63
	v_pk_mov_b32 v[62:63], v[68:69], v[66:67] op_sel:[1,0]
	v_mov_b32_e32 v69, v67
	v_pk_mul_f32 v[60:61], v[60:61], v[60:61]
	v_pk_mul_f32 v[66:67], v[72:73], v[72:73]
	v_pk_fma_f32 v[58:59], v[58:59], v[58:59], v[60:61]
	v_pk_fma_f32 v[60:61], v[70:71], v[70:71], v[66:67]
	s_waitcnt vmcnt(2)
	v_mul_f32_e32 v74, v51, v51
	v_mul_f32_e32 v76, v53, v53
	v_pk_add_f32 v[64:65], v[82:83], v[64:65]
	v_pk_add_f32 v[58:59], v[58:59], v[60:61]
	v_mul_f32_e32 v45, v22, v22
	v_mul_f32_e32 v81, v23, v23
	v_mul_f32_e32 v86, v21, v21
	v_mul_f32_e32 v88, v20, v20
	v_pk_fma_f32 v[72:73], v[50:51], v[50:51], v[74:75] op_sel_hi:[1,1,0]
	v_pk_fma_f32 v[74:75], v[52:53], v[52:53], v[76:77] op_sel_hi:[1,1,0]
	v_pk_add_f32 v[64:65], v[64:65], v[64:65] op_sel:[0,1] op_sel_hi:[1,0]
	v_pk_add_f32 v[58:59], v[58:59], v[58:59] op_sel:[0,1] op_sel_hi:[1,0]
	v_mov_b32_e32 v73, v45
	v_mov_b32_e32 v75, v81
	v_mov_b32_e32 v65, v86
	v_mov_b32_e32 v59, v88
	v_pk_add_f32 v[60:61], v[72:73], v[74:75]
	v_pk_add_f32 v[58:59], v[58:59], v[64:65]
	s_waitcnt vmcnt(0)
	v_mul_f32_e32 v78, v5, v5
	v_mul_f32_e32 v80, v7, v7
	v_pk_add_f32 v[62:63], v[62:63], v[68:69]
	v_pk_add_f32 v[58:59], v[58:59], v[60:61]
	v_mul_f32_e32 v84, v2, v2
	v_mul_f32_e32 v85, v3, v3
	v_mul_f32_e32 v87, v1, v1
	v_mul_f32_e32 v89, v0, v0
	v_pk_fma_f32 v[76:77], v[4:5], v[4:5], v[78:79] op_sel_hi:[1,1,0]
	v_pk_fma_f32 v[78:79], v[6:7], v[6:7], v[80:81] op_sel_hi:[1,1,0]
	v_pk_add_f32 v[62:63], v[62:63], v[62:63] op_sel:[0,1] op_sel_hi:[1,0]
	v_pk_add_f32 v[58:59], v[58:59], v[58:59] op_sel:[0,1] op_sel_hi:[1,0]
	v_mov_b32_e32 v77, v84
	v_mov_b32_e32 v79, v85
	v_mov_b32_e32 v63, v87
	v_mov_b32_e32 v59, v89
	v_pk_add_f32 v[66:67], v[76:77], v[78:79]
	v_pk_add_f32 v[58:59], v[58:59], v[62:63]
	s_nop 0
	v_pk_add_f32 v[58:59], v[58:59], v[66:67]
	s_nop 0
	v_add_f32_e32 v45, v58, v59
	ds_bpermute_b32 v58, v38, v45
	s_waitcnt lgkmcnt(0)
	v_add_f32_e32 v45, v45, v58
	ds_bpermute_b32 v58, v39, v45
	s_waitcnt lgkmcnt(0)
	v_add_f32_e32 v45, v45, v58
	ds_bpermute_b32 v58, v40, v45
	s_waitcnt lgkmcnt(0)
	v_add_f32_e32 v45, v45, v58
	ds_bpermute_b32 v58, v41, v45
	s_waitcnt lgkmcnt(0)
	v_add_f32_e32 v45, v45, v58
	ds_bpermute_b32 v58, v42, v45
	s_waitcnt lgkmcnt(0)
	v_add_f32_e32 v45, v45, v58
	ds_bpermute_b32 v58, v43, v45
	s_waitcnt lgkmcnt(0)
	v_add_f32_e32 v45, v45, v58
	v_fmamk_f32 v45, v45, 0x3a000000, v44
	v_mul_f32_e32 v58, 0x4b800000, v45
	v_cmp_gt_f32_e32 vcc, s8, v45
	s_nop 1
	v_cndmask_b32_e32 v45, v45, v58, vcc
	v_rsq_f32_e32 v45, v45
	s_nop 0
	v_mul_f32_e32 v58, 0x45800000, v45
	v_cndmask_b32_e32 v45, v45, v58, vcc
	v_mul_f32_e32 v46, v46, v45
	v_mul_f32_e32 v47, v47, v45
	v_mul_f32_e32 v48, v48, v45
	v_mul_f32_e32 v49, v49, v45
	v_mul_f32_e32 v46, v90, v46
	v_mul_f32_e32 v47, v91, v47
	v_mul_f32_e32 v48, v92, v48
	v_mul_f32_e32 v49, v93, v49
	v_cvt_pk_bf16_f32 v46, v46, v47
	v_cvt_pk_bf16_f32 v47, v48, v49
	global_store_dwordx2 v[36:37], v[46:47], off
	v_mul_f32_e32 v12, v12, v45
	v_mul_f32_e32 v13, v13, v45
	v_mul_f32_e32 v14, v14, v45
	v_mul_f32_e32 v15, v15, v45
	v_mul_f32_e32 v16, v16, v45
	v_mul_f32_e32 v17, v17, v45
	v_mul_f32_e32 v18, v18, v45
	v_mul_f32_e32 v19, v19, v45
	v_mul_f32_e32 v8, v8, v45
	v_mul_f32_e32 v9, v9, v45
	v_mul_f32_e32 v10, v10, v45
	v_mul_f32_e32 v11, v11, v45
	v_mul_f32_e32 v4, v4, v45
	v_mul_f32_e32 v5, v5, v45
	v_mul_f32_e32 v6, v6, v45
	v_mul_f32_e32 v7, v7, v45
	v_mul_f32_e32 v0, v0, v45
	v_mul_f32_e32 v1, v1, v45
	v_mul_f32_e32 v2, v2, v45
	v_mul_f32_e32 v3, v3, v45
	v_mul_f32_e32 v12, v94, v12
	v_mul_f32_e32 v13, v95, v13
	v_mul_f32_e32 v14, v96, v14
	v_mul_f32_e32 v15, v97, v15
	v_cvt_pk_bf16_f32 v12, v12, v13
	v_cvt_pk_bf16_f32 v13, v14, v15
	global_store_dwordx2 v[36:37], v[12:13], off offset:512
	v_mul_f32_e32 v12, v98, v16
	v_mul_f32_e32 v13, v99, v17
	v_mul_f32_e32 v14, v100, v18
	v_mul_f32_e32 v15, v101, v19
	v_cvt_pk_bf16_f32 v12, v12, v13
	v_cvt_pk_bf16_f32 v13, v14, v15
	global_store_dwordx2 v[36:37], v[12:13], off offset:1024
	v_mul_f32_e32 v16, v50, v45
	v_mul_f32_e32 v17, v51, v45
	v_mul_f32_e32 v18, v52, v45
	v_mul_f32_e32 v19, v53, v45
	v_mul_f32_e32 v12, v16, v102
	v_mul_f32_e32 v13, v17, v103
	v_mul_f32_e32 v14, v18, v104
	v_mul_f32_e32 v15, v19, v105
	v_cvt_pk_bf16_f32 v12, v12, v13
	v_cvt_pk_bf16_f32 v13, v14, v15
	global_store_dwordx2 v[36:37], v[12:13], off offset:1536
	v_mul_f32_e32 v16, v20, v45
	v_mul_f32_e32 v17, v21, v45
	v_mul_f32_e32 v18, v22, v45
	v_mul_f32_e32 v19, v23, v45
	v_mul_f32_e32 v12, v16, v106
	v_mul_f32_e32 v13, v17, v107
	v_mul_f32_e32 v14, v18, v108
	v_mul_f32_e32 v15, v19, v109
	v_cvt_pk_bf16_f32 v12, v12, v13
	v_cvt_pk_bf16_f32 v13, v14, v15
	global_store_dwordx2 v[36:37], v[12:13], off offset:2048
	v_mul_f32_e32 v8, v8, v110
	v_mul_f32_e32 v9, v9, v111
	v_mul_f32_e32 v10, v10, v112
	v_mul_f32_e32 v11, v11, v113
	v_cvt_pk_bf16_f32 v8, v8, v9
	v_cvt_pk_bf16_f32 v9, v10, v11
	global_store_dwordx2 v[36:37], v[8:9], off offset:2560
	v_mul_f32_e32 v4, v4, v114
	v_mul_f32_e32 v5, v5, v115
	v_mul_f32_e32 v6, v6, v116
	v_mul_f32_e32 v7, v7, v117
	v_cvt_pk_bf16_f32 v4, v4, v5
	v_cvt_pk_bf16_f32 v5, v6, v7
	global_store_dwordx2 v[36:37], v[4:5], off offset:3072
	v_mul_f32_e32 v0, v0, v118
	v_mul_f32_e32 v1, v1, v119
	v_mul_f32_e32 v2, v2, v120
	v_mul_f32_e32 v3, v3, v121
	v_cvt_pk_bf16_f32 v0, v0, v1
	v_cvt_pk_bf16_f32 v1, v2, v3
	global_store_dwordx2 v[36:37], v[0:1], off offset:3584
	v_lshl_add_u64 v[36:37], v[36:37], 0, s[6:7]
	s_cbranch_scc1 .LBB0_43

.LBB0_264:
	s_and_b32 s65, s96, 63
	s_ashr_i32 s64, s20, 6
	s_lshl_b32 s4, s65, 8
	s_lshl_b32 s5, s64, 5
	v_and_b32_e32 v93, 31, v90
	s_add_i32 s12, s5, s4
	v_or_b32_e32 v9, s12, v93
	v_add_u32_e32 v0, -2, v9
	v_cmp_gt_u32_e32 vcc, s84, v0
	v_bfe_u32 v92, v90, 5, 1
	s_lshl_b32 s20, s73, 1
	v_cndmask_b32_e32 v2, v9, v0, vcc
	v_mov_b64_e32 v[0:1], s[52:53]
	v_mad_i64_i32 v[2:3], s[4:5], v2, s85, v[0:1]
	v_lshl_add_u64 v[2:3], v[2:3], 0, s[20:21]
	v_lshlrev_b32_e32 v88, 4, v92
	v_lshl_add_u64 v[4:5], v[2:3], 0, v[88:89]
	v_add_co_u32_e64 v2, s[4:5], s86, v4
	s_waitcnt lgkmcnt(0)
	s_nop 0
	v_addc_co_u32_e64 v3, s[4:5], 0, v5, s[4:5]
	s_barrier
	global_load_dwordx4 v[10:13], v[2:3], off offset:1024
	global_load_dwordx4 v[178:181], v[2:3], off offset:1056
	global_load_dwordx4 v[194:197], v[2:3], off offset:1088
	global_load_dwordx4 v[210:213], v[2:3], off offset:1120
	global_load_dwordx4 v[226:229], v[2:3], off offset:1152
	global_load_dwordx4 v[242:245], v[2:3], off offset:1184
	v_add_u32_e32 v2, -1, v9
	v_cmp_gt_u32_e64 s[4:5], s84, v2
	v_add_u32_e32 v18, 1, v9
	s_cmpk_lt_u32 s12, 0x4000
	v_cndmask_b32_e64 v2, v9, v2, s[4:5]
	v_mad_i64_i32 v[2:3], s[6:7], v2, s85, v[0:1]
	v_lshl_add_u64 v[2:3], v[2:3], 0, s[20:21]
	v_lshl_add_u64 v[2:3], v[2:3], 0, v[88:89]
	v_add_co_u32_e64 v6, s[6:7], s86, v2
	v_lshlrev_b32_e32 v91, 8, v93
	s_nop 0
	v_addc_co_u32_e64 v7, s[6:7], 0, v3, s[6:7]
	global_load_dwordx4 v[14:17], v[6:7], off offset:1024
	global_load_dwordx4 v[182:185], v[6:7], off offset:1056
	global_load_dwordx4 v[198:201], v[6:7], off offset:1088
	global_load_dwordx4 v[214:217], v[6:7], off offset:1120
	global_load_dwordx4 v[230:233], v[6:7], off offset:1152
	global_load_dwordx4 v[246:249], v[6:7], off offset:1184
	v_mad_i64_i32 v[6:7], s[6:7], v9, s85, v[0:1]
	v_cmp_gt_u32_e64 s[6:7], s84, v18
	v_lshl_add_u64 v[6:7], v[6:7], 0, s[20:21]
	v_lshl_add_u64 v[52:53], v[6:7], 0, v[88:89]
	v_cndmask_b32_e64 v9, v9, v18, s[6:7]
	v_mad_i64_i32 v[0:1], s[8:9], v9, s85, v[0:1]
	v_add_co_u32_e64 v6, s[8:9], s86, v52
	v_lshl_add_u64 v[0:1], v[0:1], 0, s[20:21]
	s_nop 0
	v_addc_co_u32_e64 v7, s[8:9], 0, v53, s[8:9]
	global_load_dwordx4 v[18:21], v[6:7], off offset:1024
	global_load_dwordx4 v[186:189], v[6:7], off offset:1056
	global_load_dwordx4 v[202:205], v[6:7], off offset:1088
	global_load_dwordx4 v[218:221], v[6:7], off offset:1120
	global_load_dwordx4 v[234:237], v[6:7], off offset:1152
	global_load_dwordx4 v[252:255], v[6:7], off offset:1184
	v_lshl_add_u64 v[6:7], v[0:1], 0, v[88:89]
	v_add_co_u32_e64 v0, s[8:9], s86, v6
	v_lshl_add_u32 v9, v92, 5, 16
	s_nop 0
	v_addc_co_u32_e64 v1, s[8:9], 0, v7, s[8:9]
	global_load_dwordx4 v[22:25], v[0:1], off offset:1024
	global_load_dwordx4 v[190:193], v[0:1], off offset:1056
	global_load_dwordx4 v[206:209], v[0:1], off offset:1088
	global_load_dwordx4 v[222:225], v[0:1], off offset:1120
	global_load_dwordx4 v[238:241], v[0:1], off offset:1152
	global_load_dwordx4 v[168:171], v[0:1], off offset:1184
	ds_read_b128 v[26:29], v9 offset:8192
	s_waitcnt vmcnt(26)
	ds_read_b128 v[30:33], v9 offset:8704
	ds_read_b128 v[34:37], v9 offset:10240
	ds_read_b128 v[38:41], v9 offset:10256
	ds_read_b128 v[42:45], v9 offset:8208
	ds_read_b128 v[46:49], v9 offset:8720
	s_waitcnt lgkmcnt(4)
	v_mov_b32_e32 v51, v30
	v_mov_b32_e32 v30, v27
	v_mov_b32_e32 v27, v32
	v_mov_b32_e32 v50, v26
	v_lshl_add_u64 v[0:1], v[4:5], 0, s[38:39]
	v_mov_b32_e32 v26, v28
	s_cselect_b64 s[8:9], -1, 0
	v_lshl_add_u64 v[6:7], v[6:7], 0, s[38:39]
	v_or_b32_e32 v138, s73, v93
	v_and_b32_e32 v8, 0x70, v8
	v_add_u32_e32 v94, 16, v91
	s_waitcnt vmcnt(23)
	v_cndmask_b32_e32 v32, 0, v11, vcc
	v_cndmask_b32_e32 v10, 0, v10, vcc
	v_lshlrev_b32_e32 v4, 16, v10
	v_and_b32_e32 v10, 0xffff0000, v10
	v_cndmask_b32_e32 v54, 0, v12, vcc
	v_lshlrev_b32_e32 v12, 16, v32
	v_cndmask_b32_e32 v28, 0, v13, vcc
	s_waitcnt vmcnt(17)
	v_cndmask_b32_e64 v11, 0, v14, s[4:5]
	v_lshlrev_b32_e32 v5, 16, v11
	v_pk_mul_f32 v[4:5], v[50:51], v[4:5]
	v_cndmask_b32_e64 v15, 0, v15, s[4:5]
	v_and_b32_e32 v11, 0xffff0000, v11
	s_waitcnt lgkmcnt(3)
	v_add_f32_e32 v4, v34, v4
	v_pk_mul_f32 v[10:11], v[30:31], v[10:11]
	v_add_f32_e32 v30, v4, v5
	v_and_b32_e32 v5, 0xffff0000, v15
	v_and_b32_e32 v4, 0xffff0000, v32
	v_mov_b32_e32 v32, v29
	v_pk_mul_f32 v[4:5], v[32:33], v[4:5]
	v_cndmask_b32_e64 v16, 0, v16, s[4:5]
	v_add_f32_e32 v10, v35, v10
	v_add_f32_e32 v4, v37, v4
	v_add_f32_e32 v31, v10, v11
	v_add_f32_e32 v29, v4, v5
	v_lshlrev_b32_e32 v5, 16, v16
	v_lshlrev_b32_e32 v4, 16, v54
	s_waitcnt lgkmcnt(1)
	v_mov_b32_e32 v10, v42
	s_waitcnt lgkmcnt(0)
	v_mov_b32_e32 v11, v46
	v_pk_mul_f32 v[4:5], v[10:11], v[4:5]
	v_mov_b32_e32 v46, v43
	v_add_f32_e32 v4, v38, v4
	v_add_f32_e32 v32, v4, v5
	v_and_b32_e32 v5, 0xffff0000, v16
	v_and_b32_e32 v4, 0xffff0000, v54
	v_pk_mul_f32 v[4:5], v[46:47], v[4:5]
	v_cndmask_b32_e64 v17, 0, v17, s[4:5]
	v_add_f32_e32 v4, v39, v4
	v_add_f32_e32 v33, v4, v5
	v_lshlrev_b32_e32 v5, 16, v17
	v_lshlrev_b32_e32 v4, 16, v28
	v_mov_b32_e32 v10, v44
	v_mov_b32_e32 v11, v48
	v_pk_mul_f32 v[4:5], v[10:11], v[4:5]
	v_lshlrev_b32_e32 v13, 16, v15
	v_add_f32_e32 v4, v40, v4
	v_pk_mul_f32 v[12:13], v[26:27], v[12:13]
	v_add_f32_e32 v35, v4, v5
	v_and_b32_e32 v5, 0xffff0000, v17
	v_and_b32_e32 v4, 0xffff0000, v28
	v_mov_b32_e32 v48, v45
	v_add_f32_e32 v12, v36, v12
	v_pk_mul_f32 v[4:5], v[48:49], v[4:5]
	v_add_f32_e32 v34, v12, v13
	v_add_f32_e32 v4, v41, v4
	s_waitcnt vmcnt(11)
	v_cndmask_b32_e64 v36, 0, v21, s[8:9]
	v_cndmask_b32_e64 v37, 0, v20, s[8:9]
	v_cndmask_b32_e64 v38, 0, v19, s[8:9]
	v_cndmask_b32_e64 v39, 0, v18, s[8:9]
	ds_read_b128 v[10:13], v9 offset:9216
	ds_read_b128 v[14:17], v9 offset:9232
	s_waitcnt vmcnt(5)
	v_cndmask_b32_e64 v40, 0, v25, s[6:7]
	v_cndmask_b32_e64 v41, 0, v24, s[6:7]
	v_cndmask_b32_e64 v42, 0, v23, s[6:7]
	v_cndmask_b32_e64 v43, 0, v22, s[6:7]
	ds_read_b128 v[18:21], v9 offset:9728
	ds_read_b128 v[22:25], v9 offset:9744
	v_add_f32_e32 v28, v4, v5
	v_lshlrev_b32_e32 v5, 16, v43
	v_lshlrev_b32_e32 v4, 16, v39
	s_waitcnt lgkmcnt(3)
	v_mov_b32_e32 v26, v10
	s_waitcnt lgkmcnt(1)
	v_mov_b32_e32 v27, v18
	v_pk_mul_f32 v[4:5], v[26:27], v[4:5]
	v_mov_b32_e32 v18, v11
	v_add_f32_e32 v4, v30, v4
	v_add_f32_e32 v26, v4, v5
	v_and_b32_e32 v5, 0xffff0000, v43
	v_and_b32_e32 v4, 0xffff0000, v39
	v_pk_mul_f32 v[4:5], v[18:19], v[4:5]
	v_mov_b32_e32 v10, v12
	v_add_f32_e32 v4, v31, v4
	v_add_f32_e32 v18, v4, v5
	v_lshlrev_b32_e32 v5, 16, v42
	v_lshlrev_b32_e32 v4, 16, v38
	v_mov_b32_e32 v11, v20
	v_pk_mul_f32 v[4:5], v[10:11], v[4:5]
	v_mov_b32_e32 v20, v13
	v_add_f32_e32 v4, v34, v4
	v_add_f32_e32 v12, v4, v5
	v_and_b32_e32 v5, 0xffff0000, v42
	v_and_b32_e32 v4, 0xffff0000, v38
	v_pk_mul_f32 v[4:5], v[20:21], v[4:5]
	v_mov_b32_e32 v10, v14
	v_add_f32_e32 v4, v29, v4
	v_add_f32_e32 v13, v4, v5
	v_lshlrev_b32_e32 v5, 16, v41
	v_lshlrev_b32_e32 v4, 16, v37
	s_waitcnt lgkmcnt(0)
	v_mov_b32_e32 v11, v22
	v_pk_mul_f32 v[4:5], v[10:11], v[4:5]
	v_mov_b32_e32 v22, v15
	v_add_f32_e32 v4, v32, v4
	v_add_f32_e32 v14, v4, v5
	v_and_b32_e32 v5, 0xffff0000, v41
	v_and_b32_e32 v4, 0xffff0000, v37
	v_pk_mul_f32 v[4:5], v[22:23], v[4:5]
	v_mov_b32_e32 v10, v16
	v_add_f32_e32 v4, v33, v4
	v_add_f32_e32 v15, v4, v5
	v_lshlrev_b32_e32 v5, 16, v40
	v_lshlrev_b32_e32 v4, 16, v36
	v_mov_b32_e32 v11, v24
	v_pk_mul_f32 v[4:5], v[10:11], v[4:5]
	v_mov_b32_e32 v24, v17
	v_add_f32_e32 v4, v35, v4
	v_add_f32_e32 v10, v4, v5
	v_and_b32_e32 v5, 0xffff0000, v40
	v_and_b32_e32 v4, 0xffff0000, v36
	v_pk_mul_f32 v[4:5], v[24:25], v[4:5]
	v_cvt_pk_bf16_f32 v48, v26, v18
	v_cvt_pk_bf16_f32 v49, v12, v13
	v_cvt_pk_bf16_f32 v50, v14, v15
	s_nop 0
	v_add_f32_e32 v4, v28, v4
	v_add_f32_e32 v4, v4, v5
	v_cvt_pk_bf16_f32 v51, v10, v4
	v_lshl_add_u64 v[4:5], v[2:3], 0, s[38:39]
	v_lshl_add_u64 v[2:3], v[52:53], 0, s[38:39]
	ds_read_b128 v[26:29], v9 offset:10304
	ds_read_b128 v[30:33], v9 offset:10320
	s_waitcnt vmcnt(4)
	v_cndmask_b32_e32 v46, 0, v181, vcc
	v_cndmask_b32_e32 v47, 0, v180, vcc
	v_cndmask_b32_e32 v52, 0, v179, vcc
	v_cndmask_b32_e32 v53, 0, v178, vcc
	ds_read_b128 v[10:13], v9 offset:8256
	ds_read_b128 v[34:37], v9 offset:8272
	s_waitcnt vmcnt(4)
	v_cndmask_b32_e64 v54, 0, v185, s[4:5]
	v_cndmask_b32_e64 v55, 0, v184, s[4:5]
	v_cndmask_b32_e64 v56, 0, v183, s[4:5]
	v_cndmask_b32_e64 v57, 0, v182, s[4:5]
	ds_read_b128 v[14:17], v9 offset:8768
	ds_read_b128 v[38:41], v9 offset:8784
	v_lshlrev_b32_e32 v43, 16, v57
	v_lshlrev_b32_e32 v42, 16, v53
	s_waitcnt lgkmcnt(3)
	v_mov_b32_e32 v44, v10
	s_waitcnt lgkmcnt(1)
	v_mov_b32_e32 v45, v14
	v_pk_mul_f32 v[42:43], v[44:45], v[42:43]
	v_mov_b32_e32 v14, v11
	v_add_f32_e32 v10, v26, v42
	v_add_f32_e32 v44, v10, v43
	v_and_b32_e32 v43, 0xffff0000, v57
	v_and_b32_e32 v42, 0xffff0000, v53
	v_pk_mul_f32 v[10:11], v[14:15], v[42:43]
	v_mov_b32_e32 v14, v12
	v_add_f32_e32 v10, v27, v10
	v_add_f32_e32 v42, v10, v11
	v_lshlrev_b32_e32 v11, 16, v56
	v_lshlrev_b32_e32 v10, 16, v52
	v_mov_b32_e32 v15, v16
	v_pk_mul_f32 v[10:11], v[14:15], v[10:11]
	v_mov_b32_e32 v16, v13
	v_add_f32_e32 v10, v28, v10
	v_add_f32_e32 v43, v10, v11
	v_and_b32_e32 v11, 0xffff0000, v56
	v_and_b32_e32 v10, 0xffff0000, v52
	v_pk_mul_f32 v[10:11], v[16:17], v[10:11]
	v_mov_b32_e32 v12, v34
	v_add_f32_e32 v10, v29, v10
	v_add_f32_e32 v45, v10, v11
	v_lshlrev_b32_e32 v11, 16, v55
	v_lshlrev_b32_e32 v10, 16, v47
	s_waitcnt lgkmcnt(0)
	v_mov_b32_e32 v13, v38
	v_pk_mul_f32 v[10:11], v[12:13], v[10:11]
	v_mov_b32_e32 v38, v35
	v_add_f32_e32 v10, v30, v10
	v_add_f32_e32 v30, v10, v11
	v_and_b32_e32 v11, 0xffff0000, v55
	v_and_b32_e32 v10, 0xffff0000, v47
	v_pk_mul_f32 v[10:11], v[38:39], v[10:11]
	v_mov_b32_e32 v12, v36
	v_add_f32_e32 v10, v31, v10
	v_add_f32_e32 v31, v10, v11
	v_lshlrev_b32_e32 v11, 16, v54
	v_lshlrev_b32_e32 v10, 16, v46
	v_mov_b32_e32 v13, v40
	v_pk_mul_f32 v[10:11], v[12:13], v[10:11]
	v_mov_b32_e32 v40, v37
	v_add_f32_e32 v10, v32, v10
	v_add_f32_e32 v32, v10, v11
	v_and_b32_e32 v11, 0xffff0000, v54
	v_and_b32_e32 v10, 0xffff0000, v46
	v_pk_mul_f32 v[10:11], v[40:41], v[10:11]
	s_waitcnt vmcnt(4)
	v_cndmask_b32_e64 v34, 0, v189, s[8:9]
	v_add_f32_e32 v10, v33, v10
	v_add_f32_e32 v33, v10, v11
	v_cndmask_b32_e64 v35, 0, v188, s[8:9]
	v_cndmask_b32_e64 v36, 0, v187, s[8:9]
	v_cndmask_b32_e64 v37, 0, v186, s[8:9]
	ds_read_b128 v[10:13], v9 offset:9280
	ds_read_b128 v[14:17], v9 offset:9296
	v_cndmask_b32_e64 v38, 0, v193, s[6:7]
	v_cndmask_b32_e64 v39, 0, v192, s[6:7]
	v_cndmask_b32_e64 v40, 0, v191, s[6:7]
	v_cndmask_b32_e64 v41, 0, v190, s[6:7]
	ds_read_b128 v[18:21], v9 offset:9792
	ds_read_b128 v[22:25], v9 offset:9808
	v_lshlrev_b32_e32 v27, 16, v41
	v_lshlrev_b32_e32 v26, 16, v37
	s_waitcnt lgkmcnt(3)
	v_mov_b32_e32 v28, v10
	s_waitcnt lgkmcnt(1)
	v_mov_b32_e32 v29, v18
	v_pk_mul_f32 v[26:27], v[28:29], v[26:27]
	v_mov_b32_e32 v18, v11
	v_add_f32_e32 v10, v44, v26
	v_add_f32_e32 v28, v10, v27
	v_and_b32_e32 v27, 0xffff0000, v41
	v_and_b32_e32 v26, 0xffff0000, v37
	v_pk_mul_f32 v[10:11], v[18:19], v[26:27]
	v_mov_b32_e32 v18, v12
	v_add_f32_e32 v10, v42, v10
	v_add_f32_e32 v26, v10, v11
	v_lshlrev_b32_e32 v11, 16, v40
	v_lshlrev_b32_e32 v10, 16, v36
	v_mov_b32_e32 v19, v20
	v_pk_mul_f32 v[10:11], v[18:19], v[10:11]
	v_mov_b32_e32 v20, v13
	v_add_f32_e32 v10, v43, v10
	v_add_f32_e32 v18, v10, v11
	v_and_b32_e32 v11, 0xffff0000, v40
	v_and_b32_e32 v10, 0xffff0000, v36
	v_pk_mul_f32 v[10:11], v[20:21], v[10:11]
	v_mov_b32_e32 v12, v14
	v_add_f32_e32 v10, v45, v10
	v_add_f32_e32 v19, v10, v11
	v_lshlrev_b32_e32 v11, 16, v39
	v_lshlrev_b32_e32 v10, 16, v35
	s_waitcnt lgkmcnt(0)
	v_mov_b32_e32 v13, v22
	v_pk_mul_f32 v[10:11], v[12:13], v[10:11]
	v_mov_b32_e32 v22, v15
	v_add_f32_e32 v10, v30, v10
	v_add_f32_e32 v14, v10, v11
	v_and_b32_e32 v11, 0xffff0000, v39
	v_and_b32_e32 v10, 0xffff0000, v35
	v_pk_mul_f32 v[10:11], v[22:23], v[10:11]
	v_mov_b32_e32 v12, v16
	v_add_f32_e32 v10, v31, v10
	v_add_f32_e32 v15, v10, v11
	v_lshlrev_b32_e32 v11, 16, v38
	v_lshlrev_b32_e32 v10, 16, v34
	v_mov_b32_e32 v13, v24
	v_pk_mul_f32 v[10:11], v[12:13], v[10:11]
	v_mov_b32_e32 v24, v17
	v_add_f32_e32 v10, v32, v10
	v_add_f32_e32 v12, v10, v11
	v_and_b32_e32 v11, 0xffff0000, v38
	v_and_b32_e32 v10, 0xffff0000, v34
	v_pk_mul_f32 v[10:11], v[24:25], v[10:11]
	v_cvt_pk_bf16_f32 v52, v28, v26
	v_cvt_pk_bf16_f32 v53, v18, v19
	v_cvt_pk_bf16_f32 v54, v14, v15
	s_nop 0
	v_add_f32_e32 v10, v33, v10
	v_add_f32_e32 v10, v10, v11
	v_cvt_pk_bf16_f32 v55, v12, v10
	global_load_dwordx4 v[178:181], v[0:1], off offset:192
	global_load_dwordx4 v[182:185], v[4:5], off offset:192
	global_load_dwordx4 v[186:189], v[2:3], off offset:192
	global_load_dwordx4 v[190:193], v[6:7], off offset:192
	ds_read_b128 v[26:29], v9 offset:10368
	ds_read_b128 v[30:33], v9 offset:10384
	s_waitcnt vmcnt(7)
	v_cndmask_b32_e32 v46, 0, v197, vcc
	v_cndmask_b32_e32 v47, 0, v196, vcc
	v_cndmask_b32_e32 v56, 0, v195, vcc
	v_cndmask_b32_e32 v57, 0, v194, vcc
	ds_read_b128 v[10:13], v9 offset:8320
	ds_read_b128 v[34:37], v9 offset:8336
	s_waitcnt vmcnt(7)
	v_cndmask_b32_e64 v58, 0, v201, s[4:5]
	v_cndmask_b32_e64 v59, 0, v200, s[4:5]
	v_cndmask_b32_e64 v60, 0, v199, s[4:5]
	v_cndmask_b32_e64 v61, 0, v198, s[4:5]
	ds_read_b128 v[14:17], v9 offset:8832
	ds_read_b128 v[38:41], v9 offset:8848
	v_lshlrev_b32_e32 v43, 16, v61
	v_lshlrev_b32_e32 v42, 16, v57
	s_waitcnt lgkmcnt(3)
	v_mov_b32_e32 v44, v10
	s_waitcnt lgkmcnt(1)
	v_mov_b32_e32 v45, v14
	v_pk_mul_f32 v[42:43], v[44:45], v[42:43]
	v_mov_b32_e32 v14, v11
	v_add_f32_e32 v10, v26, v42
	v_add_f32_e32 v44, v10, v43
	v_and_b32_e32 v43, 0xffff0000, v61
	v_and_b32_e32 v42, 0xffff0000, v57
	v_pk_mul_f32 v[10:11], v[14:15], v[42:43]
	v_mov_b32_e32 v14, v12
	v_add_f32_e32 v10, v27, v10
	v_add_f32_e32 v42, v10, v11
	v_lshlrev_b32_e32 v11, 16, v60
	v_lshlrev_b32_e32 v10, 16, v56
	v_mov_b32_e32 v15, v16
	v_pk_mul_f32 v[10:11], v[14:15], v[10:11]
	v_mov_b32_e32 v16, v13
	v_add_f32_e32 v10, v28, v10
	v_add_f32_e32 v43, v10, v11
	v_and_b32_e32 v11, 0xffff0000, v60
	v_and_b32_e32 v10, 0xffff0000, v56
	v_pk_mul_f32 v[10:11], v[16:17], v[10:11]
	v_mov_b32_e32 v12, v34
	v_add_f32_e32 v10, v29, v10
	v_add_f32_e32 v45, v10, v11
	v_lshlrev_b32_e32 v11, 16, v59
	v_lshlrev_b32_e32 v10, 16, v47
	s_waitcnt lgkmcnt(0)
	v_mov_b32_e32 v13, v38
	v_pk_mul_f32 v[10:11], v[12:13], v[10:11]
	v_mov_b32_e32 v38, v35
	v_add_f32_e32 v10, v30, v10
	v_add_f32_e32 v30, v10, v11
	v_and_b32_e32 v11, 0xffff0000, v59
	v_and_b32_e32 v10, 0xffff0000, v47
	v_pk_mul_f32 v[10:11], v[38:39], v[10:11]
	v_mov_b32_e32 v12, v36
	v_add_f32_e32 v10, v31, v10
	v_add_f32_e32 v31, v10, v11
	v_lshlrev_b32_e32 v11, 16, v58
	v_lshlrev_b32_e32 v10, 16, v46
	v_mov_b32_e32 v13, v40
	v_pk_mul_f32 v[10:11], v[12:13], v[10:11]
	v_mov_b32_e32 v40, v37
	v_add_f32_e32 v10, v32, v10
	v_add_f32_e32 v32, v10, v11
	v_and_b32_e32 v11, 0xffff0000, v58
	v_and_b32_e32 v10, 0xffff0000, v46
	v_pk_mul_f32 v[10:11], v[40:41], v[10:11]
	s_waitcnt vmcnt(7)
	v_cndmask_b32_e64 v34, 0, v205, s[8:9]
	v_add_f32_e32 v10, v33, v10
	v_add_f32_e32 v33, v10, v11
	v_cndmask_b32_e64 v35, 0, v204, s[8:9]
	v_cndmask_b32_e64 v36, 0, v203, s[8:9]
	v_cndmask_b32_e64 v37, 0, v202, s[8:9]
	ds_read_b128 v[10:13], v9 offset:9344
	ds_read_b128 v[14:17], v9 offset:9360
	s_waitcnt vmcnt(7)
	v_cndmask_b32_e64 v38, 0, v209, s[6:7]
	v_cndmask_b32_e64 v39, 0, v208, s[6:7]
	v_cndmask_b32_e64 v40, 0, v207, s[6:7]
	v_cndmask_b32_e64 v41, 0, v206, s[6:7]
	ds_read_b128 v[18:21], v9 offset:9856
	ds_read_b128 v[22:25], v9 offset:9872
	v_lshlrev_b32_e32 v27, 16, v41
	v_lshlrev_b32_e32 v26, 16, v37
	s_waitcnt lgkmcnt(3)
	v_mov_b32_e32 v28, v10
	s_waitcnt lgkmcnt(1)
	v_mov_b32_e32 v29, v18
	v_pk_mul_f32 v[26:27], v[28:29], v[26:27]
	v_mov_b32_e32 v18, v11
	v_add_f32_e32 v10, v44, v26
	v_add_f32_e32 v28, v10, v27
	v_and_b32_e32 v27, 0xffff0000, v41
	v_and_b32_e32 v26, 0xffff0000, v37
	v_pk_mul_f32 v[10:11], v[18:19], v[26:27]
	v_mov_b32_e32 v18, v12
	v_add_f32_e32 v10, v42, v10
	v_add_f32_e32 v26, v10, v11
	v_lshlrev_b32_e32 v11, 16, v40
	v_lshlrev_b32_e32 v10, 16, v36
	v_mov_b32_e32 v19, v20
	v_pk_mul_f32 v[10:11], v[18:19], v[10:11]
	v_mov_b32_e32 v20, v13
	v_add_f32_e32 v10, v43, v10
	v_add_f32_e32 v18, v10, v11
	v_and_b32_e32 v11, 0xffff0000, v40
	v_and_b32_e32 v10, 0xffff0000, v36
	v_pk_mul_f32 v[10:11], v[20:21], v[10:11]
	v_mov_b32_e32 v12, v14
	v_add_f32_e32 v10, v45, v10
	v_add_f32_e32 v19, v10, v11
	v_lshlrev_b32_e32 v11, 16, v39
	v_lshlrev_b32_e32 v10, 16, v35
	s_waitcnt lgkmcnt(0)
	v_mov_b32_e32 v13, v22
	v_pk_mul_f32 v[10:11], v[12:13], v[10:11]
	v_mov_b32_e32 v22, v15
	v_add_f32_e32 v10, v30, v10
	v_add_f32_e32 v14, v10, v11
	v_and_b32_e32 v11, 0xffff0000, v39
	v_and_b32_e32 v10, 0xffff0000, v35
	v_pk_mul_f32 v[10:11], v[22:23], v[10:11]
	v_mov_b32_e32 v12, v16
	v_add_f32_e32 v10, v31, v10
	v_add_f32_e32 v15, v10, v11
	v_lshlrev_b32_e32 v11, 16, v38
	v_lshlrev_b32_e32 v10, 16, v34
	v_mov_b32_e32 v13, v24
	v_pk_mul_f32 v[10:11], v[12:13], v[10:11]
	v_mov_b32_e32 v24, v17
	v_add_f32_e32 v10, v32, v10
	v_add_f32_e32 v12, v10, v11
	v_and_b32_e32 v11, 0xffff0000, v38
	v_and_b32_e32 v10, 0xffff0000, v34
	v_pk_mul_f32 v[10:11], v[24:25], v[10:11]
	v_cvt_pk_bf16_f32 v56, v28, v26
	v_cvt_pk_bf16_f32 v57, v18, v19
	v_cvt_pk_bf16_f32 v58, v14, v15
	s_nop 0
	v_add_f32_e32 v10, v33, v10
	v_add_f32_e32 v10, v10, v11
	v_cvt_pk_bf16_f32 v59, v12, v10
	global_load_dwordx4 v[194:197], v[0:1], off offset:224
	global_load_dwordx4 v[198:201], v[4:5], off offset:224
	global_load_dwordx4 v[202:205], v[2:3], off offset:224
	global_load_dwordx4 v[206:209], v[6:7], off offset:224
	ds_read_b128 v[26:29], v9 offset:10432
	ds_read_b128 v[30:33], v9 offset:10448
	s_waitcnt vmcnt(10)
	v_cndmask_b32_e32 v46, 0, v213, vcc
	v_cndmask_b32_e32 v47, 0, v212, vcc
	v_cndmask_b32_e32 v60, 0, v211, vcc
	v_cndmask_b32_e32 v61, 0, v210, vcc
	ds_read_b128 v[10:13], v9 offset:8384
	ds_read_b128 v[34:37], v9 offset:8400
	s_waitcnt vmcnt(10)
	v_cndmask_b32_e64 v62, 0, v217, s[4:5]
	v_cndmask_b32_e64 v63, 0, v216, s[4:5]
	v_cndmask_b32_e64 v64, 0, v215, s[4:5]
	v_cndmask_b32_e64 v65, 0, v214, s[4:5]
	ds_read_b128 v[14:17], v9 offset:8896
	ds_read_b128 v[38:41], v9 offset:8912
	v_lshlrev_b32_e32 v43, 16, v65
	v_lshlrev_b32_e32 v42, 16, v61
	s_waitcnt lgkmcnt(3)
	v_mov_b32_e32 v44, v10
	s_waitcnt lgkmcnt(1)
	v_mov_b32_e32 v45, v14
	v_pk_mul_f32 v[42:43], v[44:45], v[42:43]
	v_mov_b32_e32 v14, v11
	v_add_f32_e32 v10, v26, v42
	v_add_f32_e32 v44, v10, v43
	v_and_b32_e32 v43, 0xffff0000, v65
	v_and_b32_e32 v42, 0xffff0000, v61
	v_pk_mul_f32 v[10:11], v[14:15], v[42:43]
	v_mov_b32_e32 v14, v12
	v_add_f32_e32 v10, v27, v10
	v_add_f32_e32 v42, v10, v11
	v_lshlrev_b32_e32 v11, 16, v64
	v_lshlrev_b32_e32 v10, 16, v60
	v_mov_b32_e32 v15, v16
	v_pk_mul_f32 v[10:11], v[14:15], v[10:11]
	v_mov_b32_e32 v16, v13
	v_add_f32_e32 v10, v28, v10
	v_add_f32_e32 v43, v10, v11
	v_and_b32_e32 v11, 0xffff0000, v64
	v_and_b32_e32 v10, 0xffff0000, v60
	v_pk_mul_f32 v[10:11], v[16:17], v[10:11]
	v_mov_b32_e32 v12, v34
	v_add_f32_e32 v10, v29, v10
	v_add_f32_e32 v45, v10, v11
	v_lshlrev_b32_e32 v11, 16, v63
	v_lshlrev_b32_e32 v10, 16, v47
	s_waitcnt lgkmcnt(0)
	v_mov_b32_e32 v13, v38
	v_pk_mul_f32 v[10:11], v[12:13], v[10:11]
	v_mov_b32_e32 v38, v35
	v_add_f32_e32 v10, v30, v10
	v_add_f32_e32 v30, v10, v11
	v_and_b32_e32 v11, 0xffff0000, v63
	v_and_b32_e32 v10, 0xffff0000, v47
	v_pk_mul_f32 v[10:11], v[38:39], v[10:11]
	v_mov_b32_e32 v12, v36
	v_add_f32_e32 v10, v31, v10
	v_add_f32_e32 v31, v10, v11
	v_lshlrev_b32_e32 v11, 16, v62
	v_lshlrev_b32_e32 v10, 16, v46
	v_mov_b32_e32 v13, v40
	v_pk_mul_f32 v[10:11], v[12:13], v[10:11]
	v_mov_b32_e32 v40, v37
	v_add_f32_e32 v10, v32, v10
	v_add_f32_e32 v32, v10, v11
	v_and_b32_e32 v11, 0xffff0000, v62
	v_and_b32_e32 v10, 0xffff0000, v46
	v_pk_mul_f32 v[10:11], v[40:41], v[10:11]
	s_waitcnt vmcnt(10)
	v_cndmask_b32_e64 v34, 0, v221, s[8:9]
	v_add_f32_e32 v10, v33, v10
	v_add_f32_e32 v33, v10, v11
	v_cndmask_b32_e64 v35, 0, v220, s[8:9]
	v_cndmask_b32_e64 v36, 0, v219, s[8:9]
	v_cndmask_b32_e64 v37, 0, v218, s[8:9]
	ds_read_b128 v[10:13], v9 offset:9408
	ds_read_b128 v[14:17], v9 offset:9424
	s_waitcnt vmcnt(10)
	v_cndmask_b32_e64 v38, 0, v225, s[6:7]
	v_cndmask_b32_e64 v39, 0, v224, s[6:7]
	v_cndmask_b32_e64 v40, 0, v223, s[6:7]
	v_cndmask_b32_e64 v41, 0, v222, s[6:7]
	ds_read_b128 v[18:21], v9 offset:9920
	ds_read_b128 v[22:25], v9 offset:9936
	v_lshlrev_b32_e32 v27, 16, v41
	v_lshlrev_b32_e32 v26, 16, v37
	s_waitcnt lgkmcnt(3)
	v_mov_b32_e32 v28, v10
	s_waitcnt lgkmcnt(1)
	v_mov_b32_e32 v29, v18
	v_pk_mul_f32 v[26:27], v[28:29], v[26:27]
	v_mov_b32_e32 v18, v11
	v_add_f32_e32 v10, v44, v26
	v_add_f32_e32 v28, v10, v27
	v_and_b32_e32 v27, 0xffff0000, v41
	v_and_b32_e32 v26, 0xffff0000, v37
	v_pk_mul_f32 v[10:11], v[18:19], v[26:27]
	v_mov_b32_e32 v18, v12
	v_add_f32_e32 v10, v42, v10
	v_add_f32_e32 v26, v10, v11
	v_lshlrev_b32_e32 v11, 16, v40
	v_lshlrev_b32_e32 v10, 16, v36
	v_mov_b32_e32 v19, v20
	v_pk_mul_f32 v[10:11], v[18:19], v[10:11]
	v_mov_b32_e32 v20, v13
	v_add_f32_e32 v10, v43, v10
	v_add_f32_e32 v18, v10, v11
	v_and_b32_e32 v11, 0xffff0000, v40
	v_and_b32_e32 v10, 0xffff0000, v36
	v_pk_mul_f32 v[10:11], v[20:21], v[10:11]
	v_mov_b32_e32 v12, v14
	v_add_f32_e32 v10, v45, v10
	v_add_f32_e32 v19, v10, v11
	v_lshlrev_b32_e32 v11, 16, v39
	v_lshlrev_b32_e32 v10, 16, v35
	s_waitcnt lgkmcnt(0)
	v_mov_b32_e32 v13, v22
	v_pk_mul_f32 v[10:11], v[12:13], v[10:11]
	v_mov_b32_e32 v22, v15
	v_add_f32_e32 v10, v30, v10
	v_add_f32_e32 v14, v10, v11
	v_and_b32_e32 v11, 0xffff0000, v39
	v_and_b32_e32 v10, 0xffff0000, v35
	v_pk_mul_f32 v[10:11], v[22:23], v[10:11]
	v_mov_b32_e32 v12, v16
	v_add_f32_e32 v10, v31, v10
	v_add_f32_e32 v15, v10, v11
	v_lshlrev_b32_e32 v11, 16, v38
	v_lshlrev_b32_e32 v10, 16, v34
	v_mov_b32_e32 v13, v24
	v_pk_mul_f32 v[10:11], v[12:13], v[10:11]
	v_mov_b32_e32 v24, v17
	v_add_f32_e32 v10, v32, v10
	v_add_f32_e32 v12, v10, v11
	v_and_b32_e32 v11, 0xffff0000, v38
	v_and_b32_e32 v10, 0xffff0000, v34
	v_pk_mul_f32 v[10:11], v[24:25], v[10:11]
	v_cvt_pk_bf16_f32 v60, v28, v26
	v_cvt_pk_bf16_f32 v61, v18, v19
	v_cvt_pk_bf16_f32 v62, v14, v15
	s_nop 0
	v_add_f32_e32 v10, v33, v10
	v_add_f32_e32 v10, v10, v11
	v_cvt_pk_bf16_f32 v63, v12, v10
	ds_read_b128 v[26:29], v9 offset:10496
	ds_read_b128 v[30:33], v9 offset:10512
	s_waitcnt vmcnt(9)
	v_cndmask_b32_e32 v46, 0, v229, vcc
	v_cndmask_b32_e32 v47, 0, v228, vcc
	v_cndmask_b32_e32 v64, 0, v227, vcc
	v_cndmask_b32_e32 v65, 0, v226, vcc
	ds_read_b128 v[10:13], v9 offset:8448
	ds_read_b128 v[34:37], v9 offset:8464
	s_waitcnt vmcnt(9)
	v_cndmask_b32_e64 v66, 0, v233, s[4:5]
	v_cndmask_b32_e64 v67, 0, v232, s[4:5]
	v_cndmask_b32_e64 v68, 0, v231, s[4:5]
	v_cndmask_b32_e64 v69, 0, v230, s[4:5]
	ds_read_b128 v[14:17], v9 offset:8960
	ds_read_b128 v[38:41], v9 offset:8976
	v_lshlrev_b32_e32 v43, 16, v69
	v_lshlrev_b32_e32 v42, 16, v65
	s_waitcnt lgkmcnt(3)
	v_mov_b32_e32 v44, v10
	s_waitcnt lgkmcnt(1)
	v_mov_b32_e32 v45, v14
	v_pk_mul_f32 v[42:43], v[44:45], v[42:43]
	v_mov_b32_e32 v14, v11
	v_add_f32_e32 v10, v26, v42
	v_add_f32_e32 v44, v10, v43
	v_and_b32_e32 v43, 0xffff0000, v69
	v_and_b32_e32 v42, 0xffff0000, v65
	v_pk_mul_f32 v[10:11], v[14:15], v[42:43]
	v_mov_b32_e32 v14, v12
	v_add_f32_e32 v10, v27, v10
	v_add_f32_e32 v42, v10, v11
	v_lshlrev_b32_e32 v11, 16, v68
	v_lshlrev_b32_e32 v10, 16, v64
	v_mov_b32_e32 v15, v16
	v_pk_mul_f32 v[10:11], v[14:15], v[10:11]
	v_mov_b32_e32 v16, v13
	v_add_f32_e32 v10, v28, v10
	v_add_f32_e32 v43, v10, v11
	v_and_b32_e32 v11, 0xffff0000, v68
	v_and_b32_e32 v10, 0xffff0000, v64
	v_pk_mul_f32 v[10:11], v[16:17], v[10:11]
	v_mov_b32_e32 v12, v34
	v_add_f32_e32 v10, v29, v10
	v_add_f32_e32 v45, v10, v11
	v_lshlrev_b32_e32 v11, 16, v67
	v_lshlrev_b32_e32 v10, 16, v47
	s_waitcnt lgkmcnt(0)
	v_mov_b32_e32 v13, v38
	v_pk_mul_f32 v[10:11], v[12:13], v[10:11]
	v_mov_b32_e32 v38, v35
	v_add_f32_e32 v10, v30, v10
	v_add_f32_e32 v30, v10, v11
	v_and_b32_e32 v11, 0xffff0000, v67
	v_and_b32_e32 v10, 0xffff0000, v47
	v_pk_mul_f32 v[10:11], v[38:39], v[10:11]
	v_mov_b32_e32 v12, v36
	v_add_f32_e32 v10, v31, v10
	v_add_f32_e32 v31, v10, v11
	v_lshlrev_b32_e32 v11, 16, v66
	v_lshlrev_b32_e32 v10, 16, v46
	v_mov_b32_e32 v13, v40
	v_pk_mul_f32 v[10:11], v[12:13], v[10:11]
	v_mov_b32_e32 v40, v37
	v_add_f32_e32 v10, v32, v10
	v_add_f32_e32 v32, v10, v11
	v_and_b32_e32 v11, 0xffff0000, v66
	v_and_b32_e32 v10, 0xffff0000, v46
	v_pk_mul_f32 v[10:11], v[40:41], v[10:11]
	s_waitcnt vmcnt(9)
	v_cndmask_b32_e64 v34, 0, v237, s[8:9]
	v_add_f32_e32 v10, v33, v10
	v_add_f32_e32 v33, v10, v11
	v_cndmask_b32_e64 v35, 0, v236, s[8:9]
	v_cndmask_b32_e64 v36, 0, v235, s[8:9]
	v_cndmask_b32_e64 v37, 0, v234, s[8:9]
	ds_read_b128 v[10:13], v9 offset:9472
	ds_read_b128 v[14:17], v9 offset:9488
	s_waitcnt vmcnt(9)
	v_cndmask_b32_e64 v38, 0, v241, s[6:7]
	v_cndmask_b32_e64 v39, 0, v240, s[6:7]
	v_cndmask_b32_e64 v40, 0, v239, s[6:7]
	v_cndmask_b32_e64 v41, 0, v238, s[6:7]
	ds_read_b128 v[18:21], v9 offset:9984
	ds_read_b128 v[22:25], v9 offset:10000
	v_lshlrev_b32_e32 v27, 16, v41
	v_lshlrev_b32_e32 v26, 16, v37
	s_waitcnt lgkmcnt(3)
	v_mov_b32_e32 v28, v10
	s_waitcnt lgkmcnt(1)
	v_mov_b32_e32 v29, v18
	v_pk_mul_f32 v[26:27], v[28:29], v[26:27]
	v_mov_b32_e32 v18, v11
	v_add_f32_e32 v10, v44, v26
	v_add_f32_e32 v28, v10, v27
	v_and_b32_e32 v27, 0xffff0000, v41
	v_and_b32_e32 v26, 0xffff0000, v37
	v_pk_mul_f32 v[10:11], v[18:19], v[26:27]
	v_mov_b32_e32 v18, v12
	v_add_f32_e32 v10, v42, v10
	v_add_f32_e32 v26, v10, v11
	v_lshlrev_b32_e32 v11, 16, v40
	v_lshlrev_b32_e32 v10, 16, v36
	v_mov_b32_e32 v19, v20
	v_pk_mul_f32 v[10:11], v[18:19], v[10:11]
	v_mov_b32_e32 v20, v13
	v_add_f32_e32 v10, v43, v10
	v_add_f32_e32 v18, v10, v11
	v_and_b32_e32 v11, 0xffff0000, v40
	v_and_b32_e32 v10, 0xffff0000, v36
	v_pk_mul_f32 v[10:11], v[20:21], v[10:11]
	v_mov_b32_e32 v12, v14
	v_add_f32_e32 v10, v45, v10
	v_add_f32_e32 v19, v10, v11
	v_lshlrev_b32_e32 v11, 16, v39
	v_lshlrev_b32_e32 v10, 16, v35
	s_waitcnt lgkmcnt(0)
	v_mov_b32_e32 v13, v22
	v_pk_mul_f32 v[10:11], v[12:13], v[10:11]
	v_mov_b32_e32 v22, v15
	v_add_f32_e32 v10, v30, v10
	v_add_f32_e32 v14, v10, v11
	v_and_b32_e32 v11, 0xffff0000, v39
	v_and_b32_e32 v10, 0xffff0000, v35
	v_pk_mul_f32 v[10:11], v[22:23], v[10:11]
	v_mov_b32_e32 v12, v16
	v_add_f32_e32 v10, v31, v10
	v_add_f32_e32 v15, v10, v11
	v_lshlrev_b32_e32 v11, 16, v38
	v_lshlrev_b32_e32 v10, 16, v34
	v_mov_b32_e32 v13, v24
	v_pk_mul_f32 v[10:11], v[12:13], v[10:11]
	v_mov_b32_e32 v24, v17
	v_add_f32_e32 v10, v32, v10
	v_add_f32_e32 v12, v10, v11
	v_and_b32_e32 v11, 0xffff0000, v38
	v_and_b32_e32 v10, 0xffff0000, v34
	v_pk_mul_f32 v[10:11], v[24:25], v[10:11]
	v_cvt_pk_bf16_f32 v64, v28, v26
	v_cvt_pk_bf16_f32 v65, v18, v19
	v_cvt_pk_bf16_f32 v66, v14, v15
	s_nop 0
	v_add_f32_e32 v10, v33, v10
	v_add_f32_e32 v10, v10, v11
	v_cvt_pk_bf16_f32 v67, v12, v10
	ds_read_b128 v[26:29], v9 offset:10560
	ds_read_b128 v[30:33], v9 offset:10576
	s_waitcnt vmcnt(8)
	v_cndmask_b32_e32 v46, 0, v245, vcc
	v_cndmask_b32_e32 v47, 0, v244, vcc
	v_cndmask_b32_e32 v68, 0, v243, vcc
	v_cndmask_b32_e32 v69, 0, v242, vcc
	ds_read_b128 v[10:13], v9 offset:8512
	ds_read_b128 v[34:37], v9 offset:8528
	s_waitcnt vmcnt(8)
	v_cndmask_b32_e64 v70, 0, v249, s[4:5]
	v_cndmask_b32_e64 v71, 0, v248, s[4:5]
	v_cndmask_b32_e64 v72, 0, v247, s[4:5]
	v_cndmask_b32_e64 v73, 0, v246, s[4:5]
	ds_read_b128 v[14:17], v9 offset:9024
	ds_read_b128 v[38:41], v9 offset:9040
	v_lshlrev_b32_e32 v43, 16, v73
	v_lshlrev_b32_e32 v42, 16, v69
	s_waitcnt lgkmcnt(3)
	v_mov_b32_e32 v44, v10
	s_waitcnt lgkmcnt(1)
	v_mov_b32_e32 v45, v14
	v_pk_mul_f32 v[42:43], v[44:45], v[42:43]
	v_mov_b32_e32 v14, v11
	v_add_f32_e32 v10, v26, v42
	v_add_f32_e32 v44, v10, v43
	v_and_b32_e32 v43, 0xffff0000, v73
	v_and_b32_e32 v42, 0xffff0000, v69
	v_pk_mul_f32 v[10:11], v[14:15], v[42:43]
	v_mov_b32_e32 v14, v12
	v_add_f32_e32 v10, v27, v10
	v_add_f32_e32 v42, v10, v11
	v_lshlrev_b32_e32 v11, 16, v72
	v_lshlrev_b32_e32 v10, 16, v68
	v_mov_b32_e32 v15, v16
	v_pk_mul_f32 v[10:11], v[14:15], v[10:11]
	v_mov_b32_e32 v16, v13
	v_add_f32_e32 v10, v28, v10
	v_add_f32_e32 v43, v10, v11
	v_and_b32_e32 v11, 0xffff0000, v72
	v_and_b32_e32 v10, 0xffff0000, v68
	v_pk_mul_f32 v[10:11], v[16:17], v[10:11]
	v_mov_b32_e32 v12, v34
	v_add_f32_e32 v10, v29, v10
	v_add_f32_e32 v45, v10, v11
	v_lshlrev_b32_e32 v11, 16, v71
	v_lshlrev_b32_e32 v10, 16, v47
	s_waitcnt lgkmcnt(0)
	v_mov_b32_e32 v13, v38
	v_pk_mul_f32 v[10:11], v[12:13], v[10:11]
	v_mov_b32_e32 v38, v35
	v_add_f32_e32 v10, v30, v10
	v_add_f32_e32 v30, v10, v11
	v_and_b32_e32 v11, 0xffff0000, v71
	v_and_b32_e32 v10, 0xffff0000, v47
	v_pk_mul_f32 v[10:11], v[38:39], v[10:11]
	v_mov_b32_e32 v12, v36
	v_add_f32_e32 v10, v31, v10
	v_add_f32_e32 v31, v10, v11
	v_lshlrev_b32_e32 v11, 16, v70
	v_lshlrev_b32_e32 v10, 16, v46
	v_mov_b32_e32 v13, v40
	v_pk_mul_f32 v[10:11], v[12:13], v[10:11]
	v_mov_b32_e32 v40, v37
	v_add_f32_e32 v10, v32, v10
	v_add_f32_e32 v32, v10, v11
	v_and_b32_e32 v11, 0xffff0000, v70
	v_and_b32_e32 v10, 0xffff0000, v46
	v_pk_mul_f32 v[10:11], v[40:41], v[10:11]
	s_waitcnt vmcnt(8)
	v_cndmask_b32_e64 v34, 0, v255, s[8:9]
	v_add_f32_e32 v10, v33, v10
	v_add_f32_e32 v33, v10, v11
	v_cndmask_b32_e64 v35, 0, v254, s[8:9]
	v_cndmask_b32_e64 v36, 0, v253, s[8:9]
	v_cndmask_b32_e64 v37, 0, v252, s[8:9]
	ds_read_b128 v[10:13], v9 offset:9536
	ds_read_b128 v[14:17], v9 offset:9552
	s_waitcnt vmcnt(8)
	v_cndmask_b32_e64 v38, 0, v171, s[6:7]
	v_cndmask_b32_e64 v39, 0, v170, s[6:7]
	v_cndmask_b32_e64 v40, 0, v169, s[6:7]
	v_cndmask_b32_e64 v41, 0, v168, s[6:7]
	ds_read_b128 v[18:21], v9 offset:10048
	ds_read_b128 v[22:25], v9 offset:10064
	v_lshlrev_b32_e32 v27, 16, v41
	v_lshlrev_b32_e32 v26, 16, v37
	s_waitcnt lgkmcnt(3)
	v_mov_b32_e32 v28, v10
	s_waitcnt lgkmcnt(1)
	v_mov_b32_e32 v29, v18
	v_pk_mul_f32 v[26:27], v[28:29], v[26:27]
	v_mov_b32_e32 v18, v11
	v_add_f32_e32 v10, v44, v26
	v_add_f32_e32 v28, v10, v27
	v_and_b32_e32 v27, 0xffff0000, v41
	v_and_b32_e32 v26, 0xffff0000, v37
	v_pk_mul_f32 v[10:11], v[18:19], v[26:27]
	v_mov_b32_e32 v18, v12
	v_add_f32_e32 v10, v42, v10
	v_add_f32_e32 v26, v10, v11
	v_lshlrev_b32_e32 v11, 16, v40
	v_lshlrev_b32_e32 v10, 16, v36
	v_mov_b32_e32 v19, v20
	v_pk_mul_f32 v[10:11], v[18:19], v[10:11]
	v_mov_b32_e32 v20, v13
	v_add_f32_e32 v10, v43, v10
	v_add_f32_e32 v18, v10, v11
	v_and_b32_e32 v11, 0xffff0000, v40
	v_and_b32_e32 v10, 0xffff0000, v36
	v_pk_mul_f32 v[10:11], v[20:21], v[10:11]
	v_mov_b32_e32 v12, v14
	v_add_f32_e32 v10, v45, v10
	v_add_f32_e32 v19, v10, v11
	v_lshlrev_b32_e32 v11, 16, v39
	v_lshlrev_b32_e32 v10, 16, v35
	s_waitcnt lgkmcnt(0)
	v_mov_b32_e32 v13, v22
	v_pk_mul_f32 v[10:11], v[12:13], v[10:11]
	v_mov_b32_e32 v22, v15
	v_add_f32_e32 v10, v30, v10
	v_add_f32_e32 v14, v10, v11
	v_and_b32_e32 v11, 0xffff0000, v39
	v_and_b32_e32 v10, 0xffff0000, v35
	v_pk_mul_f32 v[10:11], v[22:23], v[10:11]
	v_mov_b32_e32 v12, v16
	v_add_f32_e32 v10, v31, v10
	v_add_f32_e32 v15, v10, v11
	v_lshlrev_b32_e32 v11, 16, v38
	v_lshlrev_b32_e32 v10, 16, v34
	v_mov_b32_e32 v13, v24
	v_pk_mul_f32 v[10:11], v[12:13], v[10:11]
	v_mov_b32_e32 v24, v17
	v_add_f32_e32 v10, v32, v10
	v_add_f32_e32 v12, v10, v11
	v_and_b32_e32 v11, 0xffff0000, v38
	v_and_b32_e32 v10, 0xffff0000, v34
	v_pk_mul_f32 v[10:11], v[24:25], v[10:11]
	v_cvt_pk_bf16_f32 v68, v28, v26
	v_cvt_pk_bf16_f32 v69, v18, v19
	v_cvt_pk_bf16_f32 v70, v14, v15
	s_nop 0
	v_add_f32_e32 v10, v33, v10
	v_add_f32_e32 v10, v10, v11
	v_cvt_pk_bf16_f32 v71, v12, v10
	ds_read_b128 v[26:29], v9 offset:10624
	ds_read_b128 v[30:33], v9 offset:10640
	s_waitcnt vmcnt(4)
	v_cndmask_b32_e32 v46, 0, v181, vcc
	v_cndmask_b32_e32 v47, 0, v180, vcc
	v_cndmask_b32_e32 v72, 0, v179, vcc
	v_cndmask_b32_e32 v73, 0, v178, vcc
	ds_read_b128 v[10:13], v9 offset:8576
	ds_read_b128 v[34:37], v9 offset:8592
	s_waitcnt vmcnt(4)
	v_cndmask_b32_e64 v74, 0, v185, s[4:5]
	v_cndmask_b32_e64 v75, 0, v184, s[4:5]
	v_cndmask_b32_e64 v76, 0, v183, s[4:5]
	v_cndmask_b32_e64 v77, 0, v182, s[4:5]
	ds_read_b128 v[14:17], v9 offset:9088
	ds_read_b128 v[38:41], v9 offset:9104
	v_lshlrev_b32_e32 v43, 16, v77
	v_lshlrev_b32_e32 v42, 16, v73
	s_waitcnt lgkmcnt(3)
	v_mov_b32_e32 v44, v10
	s_waitcnt lgkmcnt(1)
	v_mov_b32_e32 v45, v14
	v_pk_mul_f32 v[42:43], v[44:45], v[42:43]
	v_mov_b32_e32 v14, v11
	v_add_f32_e32 v10, v26, v42
	v_add_f32_e32 v44, v10, v43
	v_and_b32_e32 v43, 0xffff0000, v77
	v_and_b32_e32 v42, 0xffff0000, v73
	v_pk_mul_f32 v[10:11], v[14:15], v[42:43]
	v_mov_b32_e32 v14, v12
	v_add_f32_e32 v10, v27, v10
	v_add_f32_e32 v42, v10, v11
	v_lshlrev_b32_e32 v11, 16, v76
	v_lshlrev_b32_e32 v10, 16, v72
	v_mov_b32_e32 v15, v16
	v_pk_mul_f32 v[10:11], v[14:15], v[10:11]
	v_mov_b32_e32 v16, v13
	v_add_f32_e32 v10, v28, v10
	v_add_f32_e32 v43, v10, v11
	v_and_b32_e32 v11, 0xffff0000, v76
	v_and_b32_e32 v10, 0xffff0000, v72
	v_pk_mul_f32 v[10:11], v[16:17], v[10:11]
	v_mov_b32_e32 v12, v34
	v_add_f32_e32 v10, v29, v10
	v_add_f32_e32 v45, v10, v11
	v_lshlrev_b32_e32 v11, 16, v75
	v_lshlrev_b32_e32 v10, 16, v47
	s_waitcnt lgkmcnt(0)
	v_mov_b32_e32 v13, v38
	v_pk_mul_f32 v[10:11], v[12:13], v[10:11]
	v_mov_b32_e32 v38, v35
	v_add_f32_e32 v10, v30, v10
	v_add_f32_e32 v30, v10, v11
	v_and_b32_e32 v11, 0xffff0000, v75
	v_and_b32_e32 v10, 0xffff0000, v47
	v_pk_mul_f32 v[10:11], v[38:39], v[10:11]
	v_mov_b32_e32 v12, v36
	v_add_f32_e32 v10, v31, v10
	v_add_f32_e32 v31, v10, v11
	v_lshlrev_b32_e32 v11, 16, v74
	v_lshlrev_b32_e32 v10, 16, v46
	v_mov_b32_e32 v13, v40
	v_pk_mul_f32 v[10:11], v[12:13], v[10:11]
	v_mov_b32_e32 v40, v37
	v_add_f32_e32 v10, v32, v10
	v_add_f32_e32 v32, v10, v11
	v_and_b32_e32 v11, 0xffff0000, v74
	v_and_b32_e32 v10, 0xffff0000, v46
	v_pk_mul_f32 v[10:11], v[40:41], v[10:11]
	s_waitcnt vmcnt(4)
	v_cndmask_b32_e64 v34, 0, v189, s[8:9]
	v_add_f32_e32 v10, v33, v10
	v_add_f32_e32 v33, v10, v11
	v_cndmask_b32_e64 v35, 0, v188, s[8:9]
	v_cndmask_b32_e64 v36, 0, v187, s[8:9]
	v_cndmask_b32_e64 v37, 0, v186, s[8:9]
	ds_read_b128 v[10:13], v9 offset:9600
	ds_read_b128 v[14:17], v9 offset:9616
	s_waitcnt vmcnt(4)
	v_cndmask_b32_e64 v38, 0, v193, s[6:7]
	v_cndmask_b32_e64 v39, 0, v192, s[6:7]
	v_cndmask_b32_e64 v40, 0, v191, s[6:7]
	v_cndmask_b32_e64 v41, 0, v190, s[6:7]
	ds_read_b128 v[18:21], v9 offset:10112
	ds_read_b128 v[22:25], v9 offset:10128
	v_lshlrev_b32_e32 v27, 16, v41
	v_lshlrev_b32_e32 v26, 16, v37
	s_waitcnt lgkmcnt(3)
	v_mov_b32_e32 v28, v10
	s_waitcnt lgkmcnt(1)
	v_mov_b32_e32 v29, v18
	v_pk_mul_f32 v[26:27], v[28:29], v[26:27]
	v_mov_b32_e32 v18, v11
	v_add_f32_e32 v10, v44, v26
	v_add_f32_e32 v28, v10, v27
	v_and_b32_e32 v27, 0xffff0000, v41
	v_and_b32_e32 v26, 0xffff0000, v37
	v_pk_mul_f32 v[10:11], v[18:19], v[26:27]
	v_mov_b32_e32 v18, v12
	v_add_f32_e32 v10, v42, v10
	v_add_f32_e32 v26, v10, v11
	v_lshlrev_b32_e32 v11, 16, v40
	v_lshlrev_b32_e32 v10, 16, v36
	v_mov_b32_e32 v19, v20
	v_pk_mul_f32 v[10:11], v[18:19], v[10:11]
	v_mov_b32_e32 v20, v13
	v_add_f32_e32 v10, v43, v10
	v_add_f32_e32 v18, v10, v11
	v_and_b32_e32 v11, 0xffff0000, v40
	v_and_b32_e32 v10, 0xffff0000, v36
	v_pk_mul_f32 v[10:11], v[20:21], v[10:11]
	v_mov_b32_e32 v12, v14
	v_add_f32_e32 v10, v45, v10
	v_add_f32_e32 v19, v10, v11
	v_lshlrev_b32_e32 v11, 16, v39
	v_lshlrev_b32_e32 v10, 16, v35
	s_waitcnt lgkmcnt(0)
	v_mov_b32_e32 v13, v22
	v_pk_mul_f32 v[10:11], v[12:13], v[10:11]
	v_mov_b32_e32 v22, v15
	v_add_f32_e32 v10, v30, v10
	v_add_f32_e32 v14, v10, v11
	v_and_b32_e32 v11, 0xffff0000, v39
	v_and_b32_e32 v10, 0xffff0000, v35
	v_pk_mul_f32 v[10:11], v[22:23], v[10:11]
	v_mov_b32_e32 v12, v16
	v_add_f32_e32 v10, v31, v10
	v_add_f32_e32 v15, v10, v11
	v_lshlrev_b32_e32 v11, 16, v38
	v_lshlrev_b32_e32 v10, 16, v34
	v_mov_b32_e32 v13, v24
	v_pk_mul_f32 v[10:11], v[12:13], v[10:11]
	v_mov_b32_e32 v24, v17
	v_add_f32_e32 v10, v32, v10
	v_add_f32_e32 v12, v10, v11
	v_and_b32_e32 v11, 0xffff0000, v38
	v_and_b32_e32 v10, 0xffff0000, v34
	v_pk_mul_f32 v[10:11], v[24:25], v[10:11]
	v_cvt_pk_bf16_f32 v72, v28, v26
	v_cvt_pk_bf16_f32 v73, v18, v19
	v_cvt_pk_bf16_f32 v74, v14, v15
	v_lshlrev_b32_e32 v38, 3, v92
	v_add_f32_e32 v10, v33, v10
	v_add_f32_e32 v10, v10, v11
	v_cvt_pk_bf16_f32 v75, v12, v10
	s_nop 0
	s_nop 0
	ds_read_b128 v[18:21], v9 offset:10688
	ds_read_b128 v[22:25], v9 offset:10704
	v_or_b32_e32 v39, 16, v38
	s_waitcnt vmcnt(0)
	v_cndmask_b32_e32 v40, 0, v197, vcc
	v_cndmask_b32_e32 v41, 0, v196, vcc
	v_cndmask_b32_e32 v42, 0, v195, vcc
	v_cndmask_b32_e32 v43, 0, v194, vcc
	ds_read_b128 v[10:13], v9 offset:8640
	ds_read_b128 v[26:29], v9 offset:8656
	s_waitcnt vmcnt(0)
	v_cndmask_b32_e64 v44, 0, v201, s[4:5]
	v_cndmask_b32_e64 v45, 0, v200, s[4:5]
	v_cndmask_b32_e64 v46, 0, v199, s[4:5]
	v_cndmask_b32_e64 v47, 0, v198, s[4:5]
	ds_read_b128 v[14:17], v9 offset:9152
	ds_read_b128 v[30:33], v9 offset:9168
	v_lshlrev_b32_e32 v35, 16, v47
	v_lshlrev_b32_e32 v34, 16, v43
	s_waitcnt lgkmcnt(3)
	v_mov_b32_e32 v36, v10
	s_waitcnt lgkmcnt(1)
	v_mov_b32_e32 v37, v14
	v_pk_mul_f32 v[34:35], v[36:37], v[34:35]
	v_mov_b32_e32 v14, v11
	v_add_f32_e32 v10, v18, v34
	v_add_f32_e32 v36, v10, v35
	v_and_b32_e32 v35, 0xffff0000, v47
	v_and_b32_e32 v34, 0xffff0000, v43
	v_pk_mul_f32 v[10:11], v[14:15], v[34:35]
	v_mov_b32_e32 v14, v12
	v_add_f32_e32 v10, v19, v10
	v_add_f32_e32 v34, v10, v11
	v_lshlrev_b32_e32 v11, 16, v46
	v_lshlrev_b32_e32 v10, 16, v42
	v_mov_b32_e32 v15, v16
	v_pk_mul_f32 v[10:11], v[14:15], v[10:11]
	v_mov_b32_e32 v16, v13
	v_add_f32_e32 v10, v20, v10
	v_add_f32_e32 v35, v10, v11
	v_and_b32_e32 v11, 0xffff0000, v46
	v_and_b32_e32 v10, 0xffff0000, v42
	v_pk_mul_f32 v[10:11], v[16:17], v[10:11]
	v_mov_b32_e32 v12, v26
	v_add_f32_e32 v10, v21, v10
	v_add_f32_e32 v37, v10, v11
	v_lshlrev_b32_e32 v11, 16, v45
	v_lshlrev_b32_e32 v10, 16, v41
	s_waitcnt lgkmcnt(0)
	v_mov_b32_e32 v13, v30
	v_pk_mul_f32 v[10:11], v[12:13], v[10:11]
	v_mov_b32_e32 v30, v27
	v_add_f32_e32 v10, v22, v10
	v_add_f32_e32 v22, v10, v11
	v_and_b32_e32 v11, 0xffff0000, v45
	v_and_b32_e32 v10, 0xffff0000, v41
	v_pk_mul_f32 v[10:11], v[30:31], v[10:11]
	v_mov_b32_e32 v12, v28
	v_add_f32_e32 v10, v23, v10
	v_add_f32_e32 v23, v10, v11
	v_lshlrev_b32_e32 v11, 16, v44
	v_lshlrev_b32_e32 v10, 16, v40
	v_mov_b32_e32 v13, v32
	v_pk_mul_f32 v[10:11], v[12:13], v[10:11]
	v_mov_b32_e32 v32, v29
	v_add_f32_e32 v10, v24, v10
	v_add_f32_e32 v24, v10, v11
	v_and_b32_e32 v11, 0xffff0000, v44
	v_and_b32_e32 v10, 0xffff0000, v40
	v_pk_mul_f32 v[10:11], v[32:33], v[10:11]
	s_waitcnt vmcnt(0)
	v_cndmask_b32_e64 v26, 0, v205, s[8:9]
	v_add_f32_e32 v10, v25, v10
	v_add_f32_e32 v25, v10, v11
	v_cndmask_b32_e64 v27, 0, v204, s[8:9]
	v_cndmask_b32_e64 v28, 0, v203, s[8:9]
	v_cndmask_b32_e64 v29, 0, v202, s[8:9]
	ds_read_b128 v[0:3], v9 offset:9664
	ds_read_b128 v[10:13], v9 offset:9680
	s_waitcnt vmcnt(0)
	v_cndmask_b32_e64 v30, 0, v209, s[6:7]
	v_cndmask_b32_e64 v31, 0, v208, s[6:7]
	v_cndmask_b32_e64 v32, 0, v207, s[6:7]
	v_cndmask_b32_e64 v33, 0, v206, s[6:7]
	ds_read_b128 v[4:7], v9 offset:10176
	ds_read_b128 v[14:17], v9 offset:10192
	v_lshlrev_b32_e32 v19, 16, v33
	v_lshlrev_b32_e32 v18, 16, v29
	s_waitcnt lgkmcnt(3)
	v_mov_b32_e32 v20, v0
	s_waitcnt lgkmcnt(1)
	v_mov_b32_e32 v21, v4
	v_pk_mul_f32 v[18:19], v[20:21], v[18:19]
	v_mov_b32_e32 v4, v1
	v_add_f32_e32 v0, v36, v18
	v_add_f32_e32 v9, v0, v19
	v_and_b32_e32 v19, 0xffff0000, v33
	v_and_b32_e32 v18, 0xffff0000, v29
	v_pk_mul_f32 v[0:1], v[4:5], v[18:19]
	v_mov_b32_e32 v4, v2
	v_add_f32_e32 v0, v34, v0
	v_add_f32_e32 v18, v0, v1
	v_lshlrev_b32_e32 v1, 16, v32
	v_lshlrev_b32_e32 v0, 16, v28
	v_mov_b32_e32 v5, v6
	v_pk_mul_f32 v[0:1], v[4:5], v[0:1]
	v_mov_b32_e32 v6, v3
	v_add_f32_e32 v0, v35, v0
	v_add_f32_e32 v4, v0, v1
	v_and_b32_e32 v1, 0xffff0000, v32
	v_and_b32_e32 v0, 0xffff0000, v28
	v_pk_mul_f32 v[0:1], v[6:7], v[0:1]
	v_mov_b32_e32 v2, v10
	v_add_f32_e32 v0, v37, v0
	v_add_f32_e32 v5, v0, v1
	v_lshlrev_b32_e32 v1, 16, v31
	v_lshlrev_b32_e32 v0, 16, v27
	s_waitcnt lgkmcnt(0)
	v_mov_b32_e32 v3, v14
	v_pk_mul_f32 v[0:1], v[2:3], v[0:1]
	v_mov_b32_e32 v14, v11
	v_add_f32_e32 v0, v22, v0
	v_add_f32_e32 v6, v0, v1
	v_and_b32_e32 v1, 0xffff0000, v31
	v_and_b32_e32 v0, 0xffff0000, v27
	v_pk_mul_f32 v[0:1], v[14:15], v[0:1]
	v_mov_b32_e32 v2, v12
	v_add_f32_e32 v0, v23, v0
	v_add_f32_e32 v7, v0, v1
	v_lshlrev_b32_e32 v1, 16, v30
	v_lshlrev_b32_e32 v0, 16, v26
	v_mov_b32_e32 v3, v16
	v_pk_mul_f32 v[0:1], v[2:3], v[0:1]
	v_mov_b32_e32 v16, v13
	v_add_f32_e32 v0, v24, v0
	v_add_f32_e32 v2, v0, v1
	v_and_b32_e32 v1, 0xffff0000, v30
	v_and_b32_e32 v0, 0xffff0000, v26
	v_pk_mul_f32 v[0:1], v[16:17], v[0:1]
	v_cvt_pk_bf16_f32 v76, v9, v18
	v_cvt_pk_bf16_f32 v77, v4, v5
	v_cvt_pk_bf16_f32 v78, v6, v7
	v_cmp_eq_u32_e32 vcc, v38, v93
	v_add_f32_e32 v0, v25, v0
	v_add_f32_e32 v0, v0, v1
	v_cvt_pk_bf16_f32 v79, v2, v0
	v_or_b32_e32 v2, 1, v38
	v_cndmask_b32_e32 v0, 0, v128, vcc
	v_or_b32_e32 v1, 2, v38
	v_cmp_eq_u32_e32 vcc, v2, v93
	v_or_b32_e32 v4, 3, v38
	v_or_b32_e32 v3, 4, v38
	v_cndmask_b32_e32 v2, 0, v128, vcc
	v_cmp_eq_u32_e32 vcc, v1, v93
	v_or_b32_e32 v5, 6, v38
	v_or_b32_e32 v6, 5, v38
	v_cndmask_b32_e32 v1, 0, v128, vcc
	v_cmp_eq_u32_e32 vcc, v4, v93
	v_or_b32_e32 v7, 7, v38
	v_or_b32_e32 v11, 17, v38
	v_cndmask_b32_e32 v4, 0, v128, vcc
	v_cmp_eq_u32_e32 vcc, v3, v93
	v_or_b32_e32 v10, 18, v38
	v_or_b32_e32 v13, 19, v38
	v_cndmask_b32_e32 v3, 0, v128, vcc
	v_cmp_eq_u32_e32 vcc, v5, v93
	v_or_b32_e32 v12, 20, v38
	v_or_b32_e32 v14, 22, v38
	v_cndmask_b32_e32 v5, 0, v128, vcc
	v_cmp_eq_u32_e32 vcc, v6, v93
	v_or_b32_e32 v15, 21, v38
	v_or_b32_e32 v16, 23, v38
	v_cndmask_b32_e32 v6, 0, v128, vcc
	v_cmp_eq_u32_e32 vcc, v7, v93
	v_and_b32_e32 v18, 64, v126
	v_xor_b32_e32 v17, 32, v126
	v_cndmask_b32_e32 v7, 0, v128, vcc
	v_cmp_eq_u32_e32 vcc, v39, v93
	v_add_u32_e32 v18, 64, v18
	s_lshl_b32 s6, s64, 8
	v_cndmask_b32_e32 v9, 0, v128, vcc
	v_cmp_eq_u32_e32 vcc, v11, v93
	s_add_i32 s6, s6, 16
	v_cmp_eq_u32_e64 s[4:5], 0, v92
	v_cndmask_b32_e32 v11, 0, v128, vcc
	v_cmp_eq_u32_e32 vcc, v10, v93
	v_lshl_add_u32 v136, v93, 3, s6
	v_perm_b32 v82, v6, v3, s87
	v_cndmask_b32_e32 v10, 0, v128, vcc
	v_cmp_eq_u32_e32 vcc, v13, v93
	v_perm_b32 v81, v4, v1, s87
	v_perm_b32 v83, v7, v5, s87
	v_cndmask_b32_e32 v13, 0, v128, vcc
	v_cmp_eq_u32_e32 vcc, v12, v93
	v_perm_b32 v80, v2, v0, s87
	v_perm_b32 v85, v13, v10, s87
	v_cndmask_b32_e32 v12, 0, v128, vcc
	v_cmp_eq_u32_e32 vcc, v14, v93
	v_perm_b32 v84, v11, v9, s87
	s_nop 0
	v_cndmask_b32_e32 v14, 0, v128, vcc
	v_cmp_eq_u32_e32 vcc, v15, v93
	s_nop 1
	v_cndmask_b32_e32 v15, 0, v128, vcc
	v_cmp_eq_u32_e32 vcc, v16, v93
	v_perm_b32 v86, v15, v12, s87
	s_nop 0
	v_cndmask_b32_e32 v16, 0, v128, vcc
	v_cmp_lt_i32_e32 vcc, v17, v18
	v_perm_b32 v87, v16, v14, s87
	s_nop 0
	v_cndmask_b32_e32 v17, v126, v17, vcc
	v_lshlrev_b32_e32 v137, 2, v17
	v_lshl_or_b32 v175, v138, 2, v129
	global_load_dword v172, v175, s[42:43]
	global_load_dword v173, v175, s[36:37]
	global_load_dword v174, v175, s[40:41]
	s_setprio 1
	v_xad_u32 v145, v88, v8, v94
	ds_read_b128 v[0:3], v145 offset:16384
	ds_read_b128 v[4:7], v145 offset:49152
	s_waitcnt lgkmcnt(1)
	v_mfma_f32_32x32x16_bf16 v[32:47], v[48:51], v[0:3], 0
	v_or_b32_e32 v0, 32, v88
	v_xad_u32 v147, v0, v8, v94
	s_waitcnt lgkmcnt(0)
	v_mfma_f32_32x32x16_bf16 v[16:31], v[48:51], v[4:7], 0
	ds_read_b128 v[0:3], v147 offset:16384
	ds_read_b128 v[4:7], v147 offset:49152
	s_waitcnt lgkmcnt(1)
	v_mfma_f32_32x32x16_bf16 v[32:47], v[52:55], v[0:3], v[32:47]
	v_or_b32_e32 v0, 64, v88
	v_xad_u32 v142, v0, v8, v94
	s_waitcnt lgkmcnt(0)
	v_mfma_f32_32x32x16_bf16 v[16:31], v[52:55], v[4:7], v[16:31]
	ds_read_b128 v[0:3], v142 offset:16384
	ds_read_b128 v[4:7], v142 offset:49152
	s_waitcnt lgkmcnt(1)
	v_mfma_f32_32x32x16_bf16 v[32:47], v[56:59], v[0:3], v[32:47]
	v_or_b32_e32 v0, 0x60, v88
	v_xad_u32 v146, v0, v8, v94
	s_waitcnt lgkmcnt(0)
	v_mfma_f32_32x32x16_bf16 v[16:31], v[56:59], v[4:7], v[16:31]
	ds_read_b128 v[0:3], v146 offset:16384
	ds_read_b128 v[4:7], v146 offset:49152
	s_waitcnt lgkmcnt(1)
	v_mfma_f32_32x32x16_bf16 v[32:47], v[60:63], v[0:3], v[32:47]
	v_or_b32_e32 v0, 0x80, v88
	v_xad_u32 v141, v0, v8, v94
	s_waitcnt lgkmcnt(0)
	v_mfma_f32_32x32x16_bf16 v[16:31], v[60:63], v[4:7], v[16:31]
	ds_read_b128 v[0:3], v141 offset:16384
	ds_read_b128 v[4:7], v141 offset:49152
	s_waitcnt lgkmcnt(1)
	v_mfma_f32_32x32x16_bf16 v[32:47], v[64:67], v[0:3], v[32:47]
	v_or_b32_e32 v0, 0xa0, v88
	v_xad_u32 v144, v0, v8, v94
	s_waitcnt lgkmcnt(0)
	v_mfma_f32_32x32x16_bf16 v[16:31], v[64:67], v[4:7], v[16:31]
	ds_read_b128 v[0:3], v144 offset:16384
	ds_read_b128 v[4:7], v144 offset:49152
	s_waitcnt lgkmcnt(1)
	v_mfma_f32_32x32x16_bf16 v[32:47], v[68:71], v[0:3], v[32:47]
	v_or_b32_e32 v0, 0xc0, v88
	v_xad_u32 v139, v0, v8, v94
	s_waitcnt lgkmcnt(0)
	v_mfma_f32_32x32x16_bf16 v[16:31], v[68:71], v[4:7], v[16:31]
	ds_read_b128 v[0:3], v139 offset:16384
	ds_read_b128 v[4:7], v139 offset:49152
	s_waitcnt lgkmcnt(1)
	v_mfma_f32_32x32x16_bf16 v[32:47], v[72:75], v[0:3], v[32:47]
	v_or_b32_e32 v0, 0xe0, v88
	v_xad_u32 v143, v0, v8, v94
	s_waitcnt lgkmcnt(0)
	v_mfma_f32_32x32x16_bf16 v[16:31], v[72:75], v[4:7], v[16:31]
	ds_read_b128 v[0:3], v143 offset:16384
	ds_read_b128 v[4:7], v143 offset:49152
	s_waitcnt lgkmcnt(1)
	v_mfma_f32_32x32x16_bf16 v[32:47], v[76:79], v[0:3], v[32:47]
	s_waitcnt lgkmcnt(0)
	v_mfma_f32_32x32x16_bf16 v[16:31], v[76:79], v[4:7], v[16:31]
	v_mfma_f32_32x32x16_bf16 v[0:15], v[48:51], v[80:83], 0
	v_mfma_f32_32x32x16_bf16 v[0:15], v[52:55], v[84:87], v[0:15]
	s_setprio 0
	v_lshl_or_b32 v88, v138, 2, v129
	s_waitcnt vmcnt(0)
	v_mov_b32_e32 v95, v172
	v_mov_b32_e32 v94, v173
	v_mov_b32_e32 v88, v174
	v_mul_f32_e32 v95, 0xbfb8aa3b, v95
	v_add_f32_e32 v32, v32, v94
	v_add_f32_e32 v16, v16, v88
	v_exp_f32_e32 v95, v95
	v_mul_f32_e32 v32, 0xbfb8aa3b, v32
	v_mul_f32_e32 v16, 0xbfb8aa3b, v16
	v_exp_f32_e32 v32, v32
	v_exp_f32_e32 v96, v16
	v_add_f32_e32 v17, v17, v88
	v_mul_f32_e32 v17, 0xbfb8aa3b, v17
	v_add_f32_e32 v98, 1.0, v95
	v_exp_f32_e32 v97, v17
	v_add_f32_e32 v99, -1.0, v98
	v_frexp_mant_f32_e32 v100, v98
	v_cvt_f64_f32_e32 v[16:17], v98
	v_add_f32_e32 v32, 1.0, v32
	v_add_f32_e32 v96, 1.0, v96
	v_sub_f32_e32 v101, v99, v98
	v_frexp_exp_i32_f64_e32 v16, v[16:17]
	v_cmp_gt_f32_e32 vcc, s88, v100
	v_sub_f32_e32 v99, v95, v99
	v_rcp_f32_e32 v17, v32
	v_rcp_f32_e32 v32, v96
	v_add_f32_e32 v96, 1.0, v101
	v_subbrev_co_u32_e32 v16, vcc, 0, v16, vcc
	v_add_f32_e32 v96, v99, v96
	v_sub_u32_e32 v99, 0, v16
	v_cvt_f32_i32_e32 v16, v16
	v_ldexp_f32 v98, v98, v99
	v_ldexp_f32 v96, v96, v99
	v_add_f32_e32 v99, -1.0, v98
	v_add_f32_e32 v100, 1.0, v98
	v_add_f32_e32 v101, 1.0, v99
	v_add_f32_e32 v102, -1.0, v100
	v_sub_f32_e32 v101, v98, v101
	v_sub_f32_e32 v98, v98, v102
	v_mul_f32_e32 v102, 0x3f317218, v16
	v_add_f32_e32 v101, v96, v101
	v_add_f32_e32 v96, v96, v98
	v_fma_f32 v98, v16, s89, -v102
	v_add_f32_e32 v103, v99, v101
	v_add_f32_e32 v104, v100, v96
	v_fmac_f32_e32 v98, 0xb102e308, v16
	v_sub_f32_e32 v16, v103, v99
	v_sub_f32_e32 v99, v104, v100
	v_rcp_f32_e32 v100, v104
	v_add_f32_e32 v105, v102, v98
	v_sub_f32_e32 v96, v96, v99
	v_sub_f32_e32 v99, v105, v102
	v_sub_f32_e32 v98, v98, v99
	v_mul_f32_e32 v99, v103, v100
	v_sub_f32_e32 v16, v101, v16
	v_mul_f32_e32 v101, v104, v99
	v_fma_f32 v102, v99, v104, -v101
	v_fmac_f32_e32 v102, v99, v96
	v_add_f32_e32 v106, v101, v102
	v_sub_f32_e32 v107, v103, v106
	v_sub_f32_e32 v101, v106, v101
	v_sub_f32_e32 v103, v103, v107
	v_sub_f32_e32 v101, v101, v102
	v_sub_f32_e32 v102, v103, v106
	v_add_f32_e32 v16, v16, v102
	v_add_f32_e32 v16, v101, v16
	v_add_f32_e32 v101, v107, v16
	v_mul_f32_e32 v102, v100, v101
	v_sub_f32_e32 v103, v107, v101
	v_mul_f32_e32 v106, v104, v102
	v_add_f32_e32 v16, v16, v103
	v_add_f32_e32 v103, v99, v102
	v_fma_f32 v104, v102, v104, -v106
	v_sub_f32_e32 v99, v103, v99
	v_fmac_f32_e32 v104, v102, v96
	v_sub_f32_e32 v96, v102, v99
	v_add_f32_e32 v99, v106, v104
	v_sub_f32_e32 v102, v99, v106
	v_sub_f32_e32 v106, v101, v99
	v_sub_f32_e32 v101, v101, v106
	v_sub_f32_e32 v99, v101, v99
	v_sub_f32_e32 v102, v102, v104
	v_add_f32_e32 v16, v16, v99
	v_add_f32_e32 v16, v102, v16
	v_add_f32_e32 v16, v106, v16
	v_mul_f32_e32 v16, v100, v16
	v_add_f32_e32 v16, v96, v16
	v_add_f32_e32 v96, v103, v16
	v_mul_f32_e32 v99, v96, v96
	v_fmamk_f32 v102, v99, 0x3e9b6dac, v127
	v_sub_f32_e32 v100, v96, v103
	v_ldexp_f32 v101, v96, 1
	v_mul_f32_e32 v96, v96, v99
	v_fmaak_f32 v99, v99, v102, 0x3f2aaada
	v_mul_f32_e32 v96, v96, v99
	v_add_f32_e32 v99, v101, v96
	v_sub_f32_e32 v16, v16, v100
	v_sub_f32_e32 v100, v99, v101
	v_ldexp_f32 v16, v16, 1
	v_sub_f32_e32 v96, v96, v100
	v_add_f32_e32 v16, v16, v96
	v_add_f32_e32 v96, v99, v16
	v_sub_f32_e32 v99, v96, v99
	v_add_f32_e32 v100, v105, v96
	v_sub_f32_e32 v16, v16, v99
	v_sub_f32_e32 v99, v100, v105
	v_sub_f32_e32 v101, v100, v99
	v_sub_f32_e32 v96, v96, v99
	v_add_f32_e32 v99, v98, v16
	v_sub_f32_e32 v101, v105, v101
	v_sub_f32_e32 v102, v99, v98
	v_add_f32_e32 v96, v96, v101
	v_sub_f32_e32 v101, v99, v102
	v_sub_f32_e32 v16, v16, v102
	v_sub_f32_e32 v98, v98, v101
	v_add_f32_e32 v96, v99, v96
	v_add_f32_e32 v16, v16, v98
	v_add_f32_e32 v98, v100, v96
	v_add_f32_e32 v33, v33, v94
	v_add_f32_e32 v34, v34, v94
	v_sub_f32_e32 v99, v98, v100
	v_mul_f32_e32 v33, 0xbfb8aa3b, v33
	v_mul_f32_e32 v34, 0xbfb8aa3b, v34
	v_sub_f32_e32 v96, v96, v99
	v_exp_f32_e32 v33, v33
	v_exp_f32_e32 v34, v34
	v_add_f32_e32 v16, v16, v96
	v_add_f32_e32 v16, v98, v16
	v_cmp_neq_f32_e32 vcc, s90, v95
	v_add_f32_e32 v33, 1.0, v33
	v_add_f32_e32 v34, 1.0, v34
	v_cndmask_b32_e32 v16, v130, v16, vcc
	v_cmp_ngt_f32_e32 vcc, -1.0, v95
	v_rcp_f32_e32 v33, v33
	v_rcp_f32_e32 v34, v34
	v_cndmask_b32_e32 v16, v131, v16, vcc
	v_cmp_neq_f32_e32 vcc, -1.0, v95
	v_add_f32_e32 v18, v18, v88
	v_mul_f32_e32 v18, 0xbfb8aa3b, v18
	v_cndmask_b32_e32 v16, v132, v16, vcc
	v_cmp_lt_f32_e64 vcc, |v95|, s91
	v_add_f32_e32 v19, v19, v88
	v_exp_f32_e32 v18, v18
	v_cndmask_b32_e32 v16, v16, v95, vcc
	v_mul_f32_e32 v95, 0xc1000000, v16
	v_mul_f32_e32 v16, v17, v95
	v_mul_f32_e32 v16, 0x3fb8aa3b, v16
	v_mul_f32_e32 v17, v33, v95
	v_exp_f32_e32 v33, v16
	v_mul_f32_e32 v16, v34, v95
	v_mul_f32_e32 v16, 0x3fb8aa3b, v16
	v_exp_f32_e32 v98, v16
	v_add_f32_e32 v16, v35, v94
	v_mul_f32_e32 v16, 0xbfb8aa3b, v16
	v_exp_f32_e32 v16, v16
	v_mul_f32_e32 v17, 0x3fb8aa3b, v17
	v_mul_f32_e32 v19, 0xbfb8aa3b, v19
	v_exp_f32_e32 v96, v17
	v_add_f32_e32 v16, 1.0, v16
	v_rcp_f32_e32 v16, v16
	v_exp_f32_e32 v19, v19
	v_add_f32_e32 v97, 1.0, v97
	v_add_f32_e32 v18, 1.0, v18
	v_mul_f32_e32 v16, v16, v95
	v_mul_f32_e32 v16, 0x3fb8aa3b, v16
	v_exp_f32_e32 v16, v16
	v_fma_f32 v35, -v98, v98, 1.0
	v_rcp_f32_e32 v17, v97
	v_fma_f32 v34, -v33, v33, 1.0
	v_fma_f32 v97, -v96, v96, 1.0
	v_rcp_f32_e32 v18, v18
	v_sqrt_f32_e32 v35, v35
	v_add_f32_e32 v19, 1.0, v19
	v_fma_f32 v99, -v16, v16, 1.0
	v_sqrt_f32_e32 v34, v34
	v_sqrt_f32_e32 v97, v97
	v_rcp_f32_e32 v19, v19
	v_sqrt_f32_e32 v99, v99
	v_mul_f32_e32 v35, v18, v35
	v_add_f32_e32 v18, v36, v94
	v_mul_f32_e32 v32, v32, v34
	v_mul_f32_e32 v34, v17, v97
	v_mul_f32_e32 v17, v19, v99
	v_mul_f32_e32 v18, 0xbfb8aa3b, v18
	v_add_f32_e32 v19, v20, v88
	v_exp_f32_e32 v18, v18
	v_mul_f32_e32 v19, 0xbfb8aa3b, v19
	v_exp_f32_e32 v19, v19
	v_mul_f32_e32 v3, v3, v17
	v_add_f32_e32 v17, 1.0, v18
	v_rcp_f32_e32 v17, v17
	v_add_f32_e32 v18, 1.0, v19
	v_add_f32_e32 v19, v37, v94
	v_mul_f32_e32 v19, 0xbfb8aa3b, v19
	v_exp_f32_e32 v19, v19
	v_mul_f32_e32 v17, v17, v95
	v_mul_f32_e32 v17, 0x3fb8aa3b, v17
	v_exp_f32_e32 v36, v17
	v_add_f32_e32 v17, 1.0, v19
	v_rcp_f32_e32 v17, v17
	v_add_f32_e32 v19, v21, v88
	v_mul_f32_e32 v19, 0xbfb8aa3b, v19
	v_exp_f32_e32 v19, v19
	v_mul_f32_e32 v17, v17, v95
	v_mul_f32_e32 v17, 0x3fb8aa3b, v17
	v_exp_f32_e32 v37, v17
	v_add_f32_e32 v17, v38, v94
	v_mul_f32_e32 v17, 0xbfb8aa3b, v17
	v_exp_f32_e32 v17, v17
	v_add_f32_e32 v23, v23, v88
	v_add_f32_e32 v19, 1.0, v19
	v_fma_f32 v21, -v37, v37, 1.0
	v_add_f32_e32 v17, 1.0, v17
	v_rcp_f32_e32 v17, v17
	v_mul_f32_e32 v23, 0xbfb8aa3b, v23
	v_rcp_f32_e32 v19, v19
	v_sqrt_f32_e32 v21, v21
	v_mul_f32_e32 v17, v17, v95
	v_mul_f32_e32 v17, 0x3fb8aa3b, v17
	v_exp_f32_e32 v38, v17
	v_add_f32_e32 v17, v39, v94
	v_mul_f32_e32 v17, 0xbfb8aa3b, v17
	v_exp_f32_e32 v17, v17
	v_exp_f32_e32 v23, v23
	v_fma_f32 v20, -v36, v36, 1.0
	v_mul_f32_e32 v100, v19, v21
	v_add_f32_e32 v17, 1.0, v17
	v_rcp_f32_e32 v17, v17
	v_add_f32_e32 v23, 1.0, v23
	v_add_f32_e32 v19, v40, v94
	v_rcp_f32_e32 v18, v18
	v_mul_f32_e32 v17, v17, v95
	v_mul_f32_e32 v17, 0x3fb8aa3b, v17
	v_exp_f32_e32 v17, v17
	v_sqrt_f32_e32 v20, v20
	v_rcp_f32_e32 v23, v23
	v_mul_f32_e32 v19, 0xbfb8aa3b, v19
	v_fma_f32 v97, -v17, v17, 1.0
	v_sqrt_f32_e32 v97, v97
	v_add_f32_e32 v21, v24, v88
	v_add_f32_e32 v22, v22, v88
	v_exp_f32_e32 v19, v19
	v_mul_f32_e32 v21, 0xbfb8aa3b, v21
	v_mul_f32_e32 v22, 0xbfb8aa3b, v22
	v_exp_f32_e32 v21, v21
	v_exp_f32_e32 v22, v22
	v_mul_f32_e32 v99, v18, v20
	v_mul_f32_e32 v18, v23, v97
	v_mul_f32_e32 v7, v7, v18
	v_add_f32_e32 v18, 1.0, v19
	v_rcp_f32_e32 v18, v18
	v_add_f32_e32 v19, 1.0, v21
	v_add_f32_e32 v21, v41, v94
	v_add_f32_e32 v22, 1.0, v22
	v_fma_f32 v39, -v38, v38, 1.0
	v_mul_f32_e32 v21, 0xbfb8aa3b, v21
	v_rcp_f32_e32 v22, v22
	v_sqrt_f32_e32 v39, v39
	v_exp_f32_e32 v21, v21
	v_mul_f32_e32 v18, v18, v95
	v_mul_f32_e32 v18, 0x3fb8aa3b, v18
	v_mul_f32_e32 v20, v22, v39
	v_exp_f32_e32 v39, v18
	v_add_f32_e32 v18, 1.0, v21
	v_rcp_f32_e32 v18, v18
	v_add_f32_e32 v21, v25, v88
	v_mul_f32_e32 v21, 0xbfb8aa3b, v21
	v_exp_f32_e32 v21, v21
	v_mul_f32_e32 v18, v18, v95
	v_mul_f32_e32 v18, 0x3fb8aa3b, v18
	v_exp_f32_e32 v40, v18
	v_add_f32_e32 v18, v42, v94
	v_mul_f32_e32 v18, 0xbfb8aa3b, v18
	v_exp_f32_e32 v18, v18
	v_add_f32_e32 v24, v26, v88
	v_add_f32_e32 v26, v27, v88
	v_add_f32_e32 v21, 1.0, v21
	v_add_f32_e32 v18, 1.0, v18
	v_rcp_f32_e32 v18, v18
	v_fma_f32 v23, -v40, v40, 1.0
	v_mul_f32_e32 v26, 0xbfb8aa3b, v26
	v_fma_f32 v22, -v39, v39, 1.0
	v_mul_f32_e32 v18, v18, v95
	v_mul_f32_e32 v18, 0x3fb8aa3b, v18
	v_exp_f32_e32 v41, v18
	v_add_f32_e32 v18, v43, v94
	v_mul_f32_e32 v18, 0xbfb8aa3b, v18
	v_exp_f32_e32 v18, v18
	v_rcp_f32_e32 v21, v21
	v_sqrt_f32_e32 v23, v23
	v_exp_f32_e32 v26, v26
	v_add_f32_e32 v18, 1.0, v18
	v_rcp_f32_e32 v18, v18
	v_rcp_f32_e32 v19, v19
	v_sqrt_f32_e32 v22, v22
	v_add_f32_e32 v26, 1.0, v26
	v_mul_f32_e32 v18, v18, v95
	v_mul_f32_e32 v18, 0x3fb8aa3b, v18
	v_exp_f32_e32 v18, v18
	v_mul_f32_e32 v43, v21, v23
	v_add_f32_e32 v21, v44, v94
	v_rcp_f32_e32 v26, v26
	v_fma_f32 v27, -v18, v18, 1.0
	v_sqrt_f32_e32 v27, v27
	v_mul_f32_e32 v42, v19, v22
	v_mul_f32_e32 v21, 0xbfb8aa3b, v21
	v_add_f32_e32 v22, v28, v88
	v_exp_f32_e32 v21, v21
	v_mul_f32_e32 v22, 0xbfb8aa3b, v22
	v_exp_f32_e32 v22, v22
	v_mul_f32_e32 v19, v26, v27
	v_mul_f32_e32 v11, v11, v19
	v_add_f32_e32 v19, 1.0, v21
	v_rcp_f32_e32 v19, v19
	v_add_f32_e32 v21, 1.0, v22
	v_add_f32_e32 v22, v45, v94
	v_mul_f32_e32 v22, 0xbfb8aa3b, v22
	v_exp_f32_e32 v22, v22
	v_mul_f32_e32 v19, v19, v95
	v_mul_f32_e32 v19, 0x3fb8aa3b, v19
	v_exp_f32_e32 v44, v19
	v_add_f32_e32 v19, 1.0, v22
	v_rcp_f32_e32 v19, v19
	v_mul_f32_e32 v24, 0xbfb8aa3b, v24
	v_exp_f32_e32 v24, v24
	v_fma_f32 v25, -v41, v41, 1.0
	v_mul_f32_e32 v19, v19, v95
	v_mul_f32_e32 v19, 0x3fb8aa3b, v19
	v_exp_f32_e32 v45, v19
	v_add_f32_e32 v19, v46, v94
	v_mul_f32_e32 v19, 0xbfb8aa3b, v19
	v_exp_f32_e32 v19, v19
	v_add_f32_e32 v24, 1.0, v24
	v_rcp_f32_e32 v24, v24
	v_sqrt_f32_e32 v25, v25
	v_add_f32_e32 v19, 1.0, v19
	v_rcp_f32_e32 v19, v19
	v_add_f32_e32 v22, v29, v88
	v_mul_f32_e32 v97, v24, v25
	v_fma_f32 v24, -v45, v45, 1.0
	v_mul_f32_e32 v19, v19, v95
	v_mul_f32_e32 v19, 0x3fb8aa3b, v19
	v_exp_f32_e32 v46, v19
	v_add_f32_e32 v19, v47, v94
	v_mul_f32_e32 v19, 0xbfb8aa3b, v19
	v_exp_f32_e32 v19, v19
	v_sqrt_f32_e32 v25, v24
	v_add_f32_e32 v24, v30, v88
	v_mul_f32_e32 v24, 0xbfb8aa3b, v24
	v_exp_f32_e32 v24, v24
	v_add_f32_e32 v19, 1.0, v19
	v_rcp_f32_e32 v19, v19
	v_fma_f32 v27, -v46, v46, 1.0
	v_add_f32_e32 v24, 1.0, v24
	v_rcp_f32_e32 v26, v24
	v_add_f32_e32 v24, v31, v88
	v_mul_f32_e32 v19, v19, v95
	v_mul_f32_e32 v24, 0xbfb8aa3b, v24
	v_mul_f32_e32 v19, 0x3fb8aa3b, v19
	v_exp_f32_e32 v28, v24
	v_exp_f32_e32 v24, v19
	v_mul_f32_e32 v22, 0xbfb8aa3b, v22
	v_sqrt_f32_e32 v19, v27
	v_add_f32_e32 v27, 1.0, v28
	v_fma_f32 v28, -v24, v24, 1.0
	v_exp_f32_e32 v22, v22
	v_rcp_f32_e32 v27, v27
	v_sqrt_f32_e32 v28, v28
	v_fma_f32 v23, -v44, v44, 1.0
	v_rcp_f32_e32 v21, v21
	v_sqrt_f32_e32 v23, v23
	v_add_f32_e32 v22, 1.0, v22
	v_mul_f32_e32 v94, v26, v19
	v_mul_f32_e32 v19, v27, v28
	v_fmac_f32_e32 v7, 0, v17
	v_rcp_f32_e32 v22, v22
	v_mul_f32_e32 v15, v15, v19
	v_mul_f32_e32 v19, v38, v7
	v_fmac_f32_e32 v3, 0, v16
	v_fmac_f32_e32 v19, v6, v20
	v_mul_f32_e32 v47, v21, v23
	v_mul_f32_e32 v21, v98, v3
	v_mul_f32_e32 v20, v37, v19
	v_fmac_f32_e32 v15, 0, v24
	v_fmac_f32_e32 v21, v2, v35
	v_fmac_f32_e32 v20, v5, v100
	v_mul_f32_e32 v2, v46, v15
	v_mul_f32_e32 v88, v22, v25
	v_mul_f32_e32 v22, v36, v20
	v_fmac_f32_e32 v2, v14, v94
	v_fmac_f32_e32 v22, v4, v99
	v_mul_f32_e32 v4, v45, v2
	v_mul_f32_e32 v23, v96, v21
	v_fmac_f32_e32 v4, v13, v88
	v_fmac_f32_e32 v23, v1, v34
	v_fmac_f32_e32 v11, 0, v18
	v_mul_f32_e32 v14, v24, v46
	v_mul_f32_e32 v6, v44, v4
	v_mul_f32_e32 v25, v33, v23
	v_mul_f32_e32 v5, v41, v11
	v_mul_f32_e32 v13, v45, v14
	v_fmac_f32_e32 v6, v12, v47
	v_fmac_f32_e32 v25, v0, v32
	v_fmac_f32_e32 v5, v10, v97
	v_mul_f32_e32 v12, v44, v13
	ds_bpermute_b32 v0, v137, v6
	v_mul_f32_e32 v10, v40, v5
	ds_bpermute_b32 v35, v137, v12
	v_mul_f32_e32 v28, v18, v41
	v_fmac_f32_e32 v10, v9, v43
	v_mul_f32_e32 v26, v16, v98
	v_mul_f32_e32 v27, v17, v38
	v_mul_f32_e32 v31, v40, v28
	v_mul_f32_e32 v9, v39, v10
	v_mul_f32_e32 v29, v96, v26
	v_mul_f32_e32 v30, v37, v27
	v_fmac_f32_e32 v9, v8, v42
	v_mul_f32_e32 v34, v39, v31
	v_mul_f32_e32 v32, v33, v29
	v_mul_f32_e32 v33, v36, v30
	s_waitcnt lgkmcnt(1)
	v_cndmask_b32_e64 v36, v0, v6, s[4:5]
	v_cndmask_b32_e64 v37, v6, v0, s[4:5]
	ds_bpermute_b32 v0, v137, v34
	ds_bpermute_b32 v40, v137, v9
	s_waitcnt lgkmcnt(2)
	v_cndmask_b32_e64 v8, v12, v35, s[4:5]
	v_fmac_f32_e32 v37, 0, v8
	ds_bpermute_b32 v8, v137, v33
	v_cndmask_b32_e64 v1, v35, v12, s[4:5]
	v_mul_f32_e32 v38, v12, v35
	v_fmac_f32_e32 v36, v1, v37
	s_waitcnt lgkmcnt(2)
	v_cndmask_b32_e64 v1, v0, v34, s[4:5]
	s_waitcnt lgkmcnt(1)
	v_cndmask_b32_e64 v39, v40, v9, s[4:5]
	v_cndmask_b32_e64 v0, v34, v0, s[4:5]
	v_cndmask_b32_e64 v40, v9, v40, s[4:5]
	ds_bpermute_b32 v44, v137, v22
	v_mul_f32_e32 v41, v38, v0
	v_fmac_f32_e32 v40, v0, v36
	v_mul_f32_e32 v42, v1, v41
	v_fmac_f32_e32 v39, v1, v40
	s_waitcnt lgkmcnt(1)
	v_cndmask_b32_e64 v0, v8, v33, s[4:5]
	v_cndmask_b32_e64 v1, v33, v8, s[4:5]
	ds_bpermute_b32 v8, v137, v32
	ds_bpermute_b32 v47, v137, v25
	s_waitcnt lgkmcnt(2)
	v_cndmask_b32_e64 v43, v44, v22, s[4:5]
	v_cndmask_b32_e64 v44, v22, v44, s[4:5]
	v_mul_f32_e32 v45, v1, v42
	v_fmac_f32_e32 v44, v1, v39
	v_mul_f32_e32 v46, v0, v45
	v_fmac_f32_e32 v43, v0, v44
	s_waitcnt lgkmcnt(1)
	v_cndmask_b32_e64 v0, v32, v8, s[4:5]
	s_waitcnt lgkmcnt(0)
	v_cndmask_b32_e64 v47, v25, v47, s[4:5]
	v_mul_f32_e32 v88, v0, v46
	v_fmac_f32_e32 v47, v0, v43
	s_and_saveexec_b64 s[6:7], s[4:5]
	v_mul_f32_e32 v0, v32, v88
	v_fma_f32 v1, v32, v47, v25
	ds_write_b64 v136, v[0:1]
	s_or_b64 exec, exec, s[6:7]
	s_cmp_lt_i32 s64, 7
	s_cselect_b64 s[14:15], -1, 0
	s_cmp_gt_i32 s64, 6
	v_mul_i32_i24_e32 v140, 0xffffff08, v93
	s_waitcnt lgkmcnt(0)
	s_barrier
	s_cbranch_scc1 .LBB0_269
	v_add3_u32 v94, v140, v91, s92
	v_mov_b32_e32 v8, 1.0
	v_mov_b32_e32 v1, 0
	s_mov_b32 s6, 7

.LBB0_270:
	v_cndmask_b32_e64 v0, 1.0, v35, s[4:5]
	v_cndmask_b32_e64 v35, 0, v37, s[4:5]
	v_cndmask_b32_e64 v37, v38, v41, s[4:5]
	v_cndmask_b32_e64 v36, v36, v40, s[4:5]
	v_cndmask_b32_e64 v40, v46, v88, s[4:5]
	v_cndmask_b32_e64 v41, v43, v47, s[4:5]
	s_ashr_i32 s13, s12, 31
	v_lshlrev_b32_e32 v88, 2, v93
	v_fmac_f32_e32 v25, v32, v41
	v_mul_f32_e32 v32, v32, v40
	v_fmac_f32_e32 v9, v34, v36
	v_mul_f32_e32 v34, v34, v37
	v_fmac_f32_e32 v10, v31, v36
	v_mul_f32_e32 v31, v31, v37
	v_fmac_f32_e32 v5, v28, v36
	v_mul_f32_e32 v28, v28, v37
	v_fmac_f32_e32 v11, v18, v36
	v_mul_f32_e32 v18, v18, v37
	v_fmac_f32_e32 v6, v12, v35
	v_mul_f32_e32 v36, v0, v12
	v_fmac_f32_e32 v4, v13, v35
	v_mul_f32_e32 v37, v0, v13
	v_lshl_add_u64 v[12:13], s[24:25], 0, v[88:89]
	s_lshl_b64 s[6:7], s[12:13], 12
	v_lshl_add_u64 v[94:95], v[12:13], 0, s[6:7]
	v_mul_f32_e32 v13, v32, v8
	v_fmac_f32_e32 v23, v29, v41
	v_mul_f32_e32 v29, v29, v40
	v_fmac_f32_e32 v21, v26, v41
	v_mul_f32_e32 v26, v26, v40
	v_fmac_f32_e32 v3, v16, v41
	v_mul_f32_e32 v40, v16, v40
	v_lshlrev_b32_e32 v12, 14, v92
	v_fmac_f32_e32 v25, v32, v1
	v_cvt_pk_bf16_f32 v16, v25, v13
	v_mov_b32_e32 v13, v89
	v_cndmask_b32_e64 v38, v42, v45, s[4:5]
	v_cndmask_b32_e64 v39, v39, v44, s[4:5]
	v_lshl_add_u64 v[96:97], v[94:95], 0, v[12:13]
	v_mul_f32_e32 v13, v29, v8
	v_or_b32_e32 v88, 0x1000, v12
	v_fmac_f32_e32 v22, v33, v39
	v_mul_f32_e32 v33, v33, v38
	v_fmac_f32_e32 v20, v30, v39
	v_mul_f32_e32 v30, v30, v38
	v_fmac_f32_e32 v19, v27, v39
	v_mul_f32_e32 v27, v27, v38
	v_fmac_f32_e32 v7, v17, v39
	v_mul_f32_e32 v38, v17, v38
	v_lshl_or_b32 v175, v138, 2, v133
	global_load_dword v172, v175, s[42:43]
	global_load_dword v173, v175, s[36:37]
	global_load_dword v174, v175, s[40:41]
	global_store_dword v[96:97], v16, off nt
	v_fmac_f32_e32 v23, v29, v1
	v_cvt_pk_bf16_f32 v13, v23, v13
	v_lshl_add_u64 v[16:17], v[94:95], 0, v[88:89]
	global_store_dword v[16:17], v13, off nt
	v_mul_f32_e32 v13, v26, v8
	v_or_b32_e32 v98, 0x2000, v12
	v_mov_b32_e32 v99, v89
	v_fmac_f32_e32 v21, v26, v1
	v_cvt_pk_bf16_f32 v13, v21, v13
	v_lshl_add_u64 v[16:17], v[94:95], 0, v[98:99]
	v_fmac_f32_e32 v3, v40, v1
	v_or_b32_e32 v100, 0x3000, v12
	v_mov_b32_e32 v101, v89
	global_store_dword v[16:17], v13, off nt
	v_mul_f32_e32 v13, v40, v8
	v_cvt_pk_bf16_f32 v3, v3, v13
	v_lshl_add_u64 v[16:17], v[94:95], 0, v[100:101]
	global_store_dword v[16:17], v3, off nt
	v_mul_f32_e32 v3, v33, v8
	v_or_b32_e32 v102, 0x8000, v12
	v_mov_b32_e32 v103, v89
	v_fmac_f32_e32 v22, v33, v1
	v_cvt_pk_bf16_f32 v3, v22, v3
	v_lshl_add_u64 v[16:17], v[94:95], 0, v[102:103]
	global_store_dword v[16:17], v3, off nt
	v_mul_f32_e32 v3, v30, v8
	v_or_b32_e32 v104, 0x9000, v12
	v_mov_b32_e32 v105, v89
	v_fmac_f32_e32 v20, v30, v1
	v_cvt_pk_bf16_f32 v3, v20, v3
	v_lshl_add_u64 v[16:17], v[94:95], 0, v[104:105]
	global_store_dword v[16:17], v3, off nt
	v_mul_f32_e32 v3, v27, v8
	v_or_b32_e32 v106, 0xa000, v12
	v_mov_b32_e32 v107, v89
	v_fmac_f32_e32 v19, v27, v1
	v_cvt_pk_bf16_f32 v3, v19, v3
	v_lshl_add_u64 v[16:17], v[94:95], 0, v[106:107]
	global_store_dword v[16:17], v3, off nt
	v_mul_f32_e32 v3, v38, v8
	v_or_b32_e32 v108, 0xb000, v12
	v_mov_b32_e32 v109, v89
	v_fmac_f32_e32 v7, v38, v1
	v_cvt_pk_bf16_f32 v3, v7, v3
	v_lshl_add_u64 v[16:17], v[94:95], 0, v[108:109]
	global_store_dword v[16:17], v3, off nt
	v_mul_f32_e32 v3, v34, v8
	v_or_b32_e32 v110, 0x10000, v12
	v_mov_b32_e32 v111, v89
	v_fmac_f32_e32 v9, v34, v1
	v_cvt_pk_bf16_f32 v3, v9, v3
	v_lshl_add_u64 v[16:17], v[94:95], 0, v[110:111]
	global_store_dword v[16:17], v3, off nt
	v_mul_f32_e32 v3, v31, v8
	v_or_b32_e32 v112, 0x11000, v12
	v_mov_b32_e32 v113, v89
	v_fmac_f32_e32 v10, v31, v1
	v_cvt_pk_bf16_f32 v3, v10, v3
	v_lshl_add_u64 v[16:17], v[94:95], 0, v[112:113]
	global_store_dword v[16:17], v3, off nt
	v_mul_f32_e32 v3, v28, v8
	v_or_b32_e32 v114, 0x12000, v12
	v_mov_b32_e32 v115, v89
	v_fmac_f32_e32 v5, v28, v1
	v_cvt_pk_bf16_f32 v3, v5, v3
	v_lshl_add_u64 v[16:17], v[94:95], 0, v[114:115]
	global_store_dword v[16:17], v3, off nt
	v_fmac_f32_e32 v11, v18, v1
	v_mul_f32_e32 v3, v18, v8
	v_or_b32_e32 v116, 0x13000, v12
	v_mov_b32_e32 v117, v89
	v_cvt_pk_bf16_f32 v3, v11, v3
	v_lshl_add_u64 v[10:11], v[94:95], 0, v[116:117]
	global_store_dword v[10:11], v3, off nt
	v_fmac_f32_e32 v6, v36, v1
	v_mul_f32_e32 v3, v36, v8
	v_or_b32_e32 v118, 0x18000, v12
	v_mov_b32_e32 v119, v89
	v_cvt_pk_bf16_f32 v3, v6, v3
	v_lshl_add_u64 v[6:7], v[94:95], 0, v[118:119]
	global_store_dword v[6:7], v3, off nt
	v_fmac_f32_e32 v4, v37, v1
	v_mul_f32_e32 v3, v37, v8
	v_or_b32_e32 v120, 0x19000, v12
	v_mov_b32_e32 v121, v89
	v_fmac_f32_e32 v2, v14, v35
	v_mul_f32_e32 v14, v0, v14
	v_cvt_pk_bf16_f32 v3, v4, v3
	v_lshl_add_u64 v[4:5], v[94:95], 0, v[120:121]
	v_fmac_f32_e32 v15, v24, v35
	v_mul_f32_e32 v0, v0, v24
	s_lshl_b32 s8, s65, 11
	global_store_dword v[4:5], v3, off nt
	v_fmac_f32_e32 v2, v14, v1
	v_mul_f32_e32 v3, v14, v8
	v_or_b32_e32 v122, 0x1a000, v12
	v_mov_b32_e32 v123, v89
	s_or_b32 s8, s8, s76
	v_cvt_pk_bf16_f32 v4, v2, v3
	v_lshl_add_u64 v[2:3], v[94:95], 0, v[122:123]
	v_fmac_f32_e32 v15, v0, v1
	v_mul_f32_e32 v0, v0, v8
	v_or_b32_e32 v124, 0x1b000, v12
	v_mov_b32_e32 v125, v89
	v_cmp_gt_i32_e64 s[6:7], 32, v90
	v_add_u32_e32 v92, s8, v90
	global_store_dword v[2:3], v4, off nt
	v_cvt_pk_bf16_f32 v2, v15, v0
	v_lshl_add_u64 v[0:1], v[94:95], 0, v[124:125]
	v_lshl_add_u32 v90, v90, 3, 16
	global_store_dword v[0:1], v2, off nt
	s_and_saveexec_b64 s[8:9], s[6:7]
	s_cbranch_execz .LBB0_272
	ds_read2_b64 v[0:3], v90 offset0:192 offset1:224
	ds_read2_b64 v[4:7], v90 offset0:128 offset1:160
	ds_read2_b64 v[8:11], v90 offset0:64 offset1:96
	ds_read2_b64 v[12:15], v90 offset1:32
	v_ashrrev_i32_e32 v93, 31, v92
	s_waitcnt lgkmcnt(3)
	v_fma_f32 v16, 0, v2, v3
	v_pk_mul_f32 v[2:3], v[2:3], v[0:1]
	v_fma_f32 v0, v0, v16, v1
	s_waitcnt lgkmcnt(2)
	v_fma_f32 v0, v6, v0, v7
	v_fma_f32 v0, v4, v0, v5
	s_waitcnt lgkmcnt(1)
	v_fma_f32 v1, v10, v0, v11
	v_mov_b32_e32 v0, v2
	v_mov_b32_e32 v16, v6
	v_mov_b32_e32 v17, v8
	v_pk_mul_f32 v[2:3], v[2:3], v[6:7]
	v_pk_fma_f32 v[0:1], v[0:1], v[16:17], v[8:9]
	v_pk_mul_f32 v[2:3], v[2:3], v[4:5]
	s_waitcnt lgkmcnt(0)
	v_mov_b32_e32 v11, v14
	v_mov_b32_e32 v3, v1
	v_pk_mul_f32 v[0:1], v[2:3], v[10:11]
	v_pk_fma_f32 v[2:3], v[2:3], v[10:11], v[14:15]
	v_pk_mul_f32 v[0:1], v[0:1], v[8:9]
	v_mov_b32_e32 v4, v14
	v_mov_b32_e32 v2, v0
	v_mov_b32_e32 v5, v12
	v_pk_mul_f32 v[0:1], v[0:1], v[14:15]
	v_pk_fma_f32 v[2:3], v[2:3], v[4:5], v[12:13]
	v_pk_mul_f32 v[0:1], v[0:1], v[12:13]
	s_nop 0
	v_mov_b32_e32 v1, v3
	v_lshl_add_u64 v[2:3], v[92:93], 3, s[30:31]
	global_store_dwordx2 v[2:3], v[0:1], off
.LBB0_272:
	s_or_b64 exec, exec, s[8:9]
	s_setprio 1
	ds_read_b128 v[0:3], v145 offset:24576
	ds_read_b128 v[4:7], v145 offset:57344
	s_waitcnt lgkmcnt(1)
	v_mfma_f32_32x32x16_bf16 v[32:47], v[48:51], v[0:3], 0
	s_waitcnt lgkmcnt(0)
	v_mfma_f32_32x32x16_bf16 v[16:31], v[48:51], v[4:7], 0
	ds_read_b128 v[0:3], v147 offset:24576
	ds_read_b128 v[4:7], v147 offset:57344
	s_waitcnt lgkmcnt(1)
	v_mfma_f32_32x32x16_bf16 v[32:47], v[52:55], v[0:3], v[32:47]
	s_waitcnt lgkmcnt(0)
	v_mfma_f32_32x32x16_bf16 v[16:31], v[52:55], v[4:7], v[16:31]
	ds_read_b128 v[0:3], v142 offset:24576
	ds_read_b128 v[4:7], v142 offset:57344
	s_waitcnt lgkmcnt(1)
	v_mfma_f32_32x32x16_bf16 v[32:47], v[56:59], v[0:3], v[32:47]
	s_waitcnt lgkmcnt(0)
	v_mfma_f32_32x32x16_bf16 v[16:31], v[56:59], v[4:7], v[16:31]
	ds_read_b128 v[0:3], v146 offset:24576
	ds_read_b128 v[4:7], v146 offset:57344
	s_waitcnt lgkmcnt(1)
	v_mfma_f32_32x32x16_bf16 v[32:47], v[60:63], v[0:3], v[32:47]
	s_waitcnt lgkmcnt(0)
	v_mfma_f32_32x32x16_bf16 v[16:31], v[60:63], v[4:7], v[16:31]
	ds_read_b128 v[0:3], v141 offset:24576
	ds_read_b128 v[4:7], v141 offset:57344
	s_waitcnt lgkmcnt(1)
	v_mfma_f32_32x32x16_bf16 v[32:47], v[64:67], v[0:3], v[32:47]
	s_waitcnt lgkmcnt(0)
	v_mfma_f32_32x32x16_bf16 v[16:31], v[64:67], v[4:7], v[16:31]
	ds_read_b128 v[0:3], v144 offset:24576
	ds_read_b128 v[4:7], v144 offset:57344
	s_waitcnt lgkmcnt(1)
	v_mfma_f32_32x32x16_bf16 v[32:47], v[68:71], v[0:3], v[32:47]
	s_waitcnt lgkmcnt(0)
	v_mfma_f32_32x32x16_bf16 v[16:31], v[68:71], v[4:7], v[16:31]
	ds_read_b128 v[0:3], v139 offset:24576
	ds_read_b128 v[4:7], v139 offset:57344
	s_waitcnt lgkmcnt(1)
	v_mfma_f32_32x32x16_bf16 v[32:47], v[72:75], v[0:3], v[32:47]
	s_waitcnt lgkmcnt(0)
	v_mfma_f32_32x32x16_bf16 v[16:31], v[72:75], v[4:7], v[16:31]
	ds_read_b128 v[0:3], v143 offset:24576
	ds_read_b128 v[4:7], v143 offset:57344
	s_waitcnt lgkmcnt(1)
	v_mfma_f32_32x32x16_bf16 v[32:47], v[76:79], v[0:3], v[32:47]
	s_waitcnt lgkmcnt(0)
	v_mfma_f32_32x32x16_bf16 v[16:31], v[76:79], v[4:7], v[16:31]
	v_mfma_f32_32x32x16_bf16 v[0:15], v[56:59], v[80:83], 0
	v_mfma_f32_32x32x16_bf16 v[0:15], v[60:63], v[84:87], v[0:15]
	s_setprio 0
	v_lshl_or_b32 v93, v138, 2, v133
	s_waitcnt vmcnt(16)
	v_mov_b32_e32 v149, v172
	v_mov_b32_e32 v148, v173
	v_mov_b32_e32 v93, v174
	v_mul_f32_e32 v149, 0xbfb8aa3b, v149
	v_add_f32_e32 v32, v32, v148
	v_add_f32_e32 v16, v16, v93
	v_exp_f32_e32 v149, v149
	v_mul_f32_e32 v32, 0xbfb8aa3b, v32
	v_mul_f32_e32 v16, 0xbfb8aa3b, v16
	v_exp_f32_e32 v32, v32
	v_exp_f32_e32 v150, v16
	v_add_f32_e32 v17, v17, v93
	v_mul_f32_e32 v17, 0xbfb8aa3b, v17
	v_add_f32_e32 v152, 1.0, v149
	v_exp_f32_e32 v151, v17
	v_add_f32_e32 v153, -1.0, v152
	v_frexp_mant_f32_e32 v154, v152
	v_cvt_f64_f32_e32 v[16:17], v152
	v_add_f32_e32 v32, 1.0, v32
	v_add_f32_e32 v150, 1.0, v150
	v_sub_f32_e32 v155, v153, v152
	v_frexp_exp_i32_f64_e32 v16, v[16:17]
	v_cmp_gt_f32_e32 vcc, s88, v154
	v_sub_f32_e32 v153, v149, v153
	v_rcp_f32_e32 v17, v32
	v_rcp_f32_e32 v32, v150
	v_add_f32_e32 v150, 1.0, v155
	v_subbrev_co_u32_e32 v16, vcc, 0, v16, vcc
	v_add_f32_e32 v150, v153, v150
	v_sub_u32_e32 v153, 0, v16
	v_cvt_f32_i32_e32 v16, v16
	v_ldexp_f32 v152, v152, v153
	v_ldexp_f32 v150, v150, v153
	v_add_f32_e32 v153, -1.0, v152
	v_add_f32_e32 v154, 1.0, v152
	v_add_f32_e32 v155, 1.0, v153
	v_add_f32_e32 v156, -1.0, v154
	v_sub_f32_e32 v155, v152, v155
	v_sub_f32_e32 v152, v152, v156
	v_mul_f32_e32 v156, 0x3f317218, v16
	v_add_f32_e32 v155, v150, v155
	v_add_f32_e32 v150, v150, v152
	v_fma_f32 v152, v16, s89, -v156
	v_add_f32_e32 v157, v153, v155
	v_add_f32_e32 v158, v154, v150
	v_fmac_f32_e32 v152, 0xb102e308, v16
	v_sub_f32_e32 v16, v157, v153
	v_sub_f32_e32 v153, v158, v154
	v_rcp_f32_e32 v154, v158
	v_add_f32_e32 v159, v156, v152
	v_sub_f32_e32 v150, v150, v153
	v_sub_f32_e32 v153, v159, v156
	v_sub_f32_e32 v152, v152, v153
	v_mul_f32_e32 v153, v157, v154
	v_sub_f32_e32 v16, v155, v16
	v_mul_f32_e32 v155, v158, v153
	v_fma_f32 v156, v153, v158, -v155
	v_fmac_f32_e32 v156, v153, v150
	v_add_f32_e32 v160, v155, v156
	v_sub_f32_e32 v161, v157, v160
	v_sub_f32_e32 v155, v160, v155
	v_sub_f32_e32 v157, v157, v161
	v_sub_f32_e32 v155, v155, v156
	v_sub_f32_e32 v156, v157, v160
	v_add_f32_e32 v16, v16, v156
	v_add_f32_e32 v16, v155, v16
	v_add_f32_e32 v155, v161, v16
	v_mul_f32_e32 v156, v154, v155
	v_sub_f32_e32 v157, v161, v155
	v_mul_f32_e32 v160, v158, v156
	v_add_f32_e32 v16, v16, v157
	v_add_f32_e32 v157, v153, v156
	v_fma_f32 v158, v156, v158, -v160
	v_sub_f32_e32 v153, v157, v153
	v_fmac_f32_e32 v158, v156, v150
	v_sub_f32_e32 v150, v156, v153
	v_add_f32_e32 v153, v160, v158
	v_sub_f32_e32 v156, v153, v160
	v_sub_f32_e32 v160, v155, v153
	v_sub_f32_e32 v155, v155, v160
	v_sub_f32_e32 v153, v155, v153
	v_sub_f32_e32 v156, v156, v158
	v_add_f32_e32 v16, v16, v153
	v_add_f32_e32 v16, v156, v16
	v_add_f32_e32 v16, v160, v16
	v_mul_f32_e32 v16, v154, v16
	v_add_f32_e32 v16, v150, v16
	v_add_f32_e32 v150, v157, v16
	v_mul_f32_e32 v153, v150, v150
	v_fmamk_f32 v156, v153, 0x3e9b6dac, v127
	v_sub_f32_e32 v154, v150, v157
	v_ldexp_f32 v155, v150, 1
	v_mul_f32_e32 v150, v150, v153
	v_fmaak_f32 v153, v153, v156, 0x3f2aaada
	v_mul_f32_e32 v150, v150, v153
	v_add_f32_e32 v153, v155, v150
	v_sub_f32_e32 v16, v16, v154
	v_sub_f32_e32 v154, v153, v155
	v_ldexp_f32 v16, v16, 1
	v_sub_f32_e32 v150, v150, v154
	v_add_f32_e32 v16, v16, v150
	v_add_f32_e32 v150, v153, v16
	v_sub_f32_e32 v153, v150, v153
	v_add_f32_e32 v154, v159, v150
	v_sub_f32_e32 v16, v16, v153
	v_sub_f32_e32 v153, v154, v159
	v_sub_f32_e32 v155, v154, v153
	v_sub_f32_e32 v150, v150, v153
	v_add_f32_e32 v153, v152, v16
	v_sub_f32_e32 v155, v159, v155
	v_sub_f32_e32 v156, v153, v152
	v_add_f32_e32 v150, v150, v155
	v_sub_f32_e32 v155, v153, v156
	v_sub_f32_e32 v16, v16, v156
	v_sub_f32_e32 v152, v152, v155
	v_add_f32_e32 v150, v153, v150
	v_add_f32_e32 v16, v16, v152
	v_add_f32_e32 v152, v154, v150
	v_add_f32_e32 v33, v33, v148
	v_add_f32_e32 v34, v34, v148
	v_sub_f32_e32 v153, v152, v154
	v_mul_f32_e32 v33, 0xbfb8aa3b, v33
	v_mul_f32_e32 v34, 0xbfb8aa3b, v34
	v_sub_f32_e32 v150, v150, v153
	v_exp_f32_e32 v33, v33
	v_exp_f32_e32 v34, v34
	v_add_f32_e32 v16, v16, v150
	v_add_f32_e32 v16, v152, v16
	v_cmp_neq_f32_e32 vcc, s90, v149
	v_add_f32_e32 v33, 1.0, v33
	v_add_f32_e32 v34, 1.0, v34
	v_cndmask_b32_e32 v16, v130, v16, vcc
	v_cmp_ngt_f32_e32 vcc, -1.0, v149
	v_rcp_f32_e32 v33, v33
	v_rcp_f32_e32 v34, v34
	v_cndmask_b32_e32 v16, v131, v16, vcc
	v_cmp_neq_f32_e32 vcc, -1.0, v149
	v_add_f32_e32 v18, v18, v93
	v_mul_f32_e32 v18, 0xbfb8aa3b, v18
	v_cndmask_b32_e32 v16, v132, v16, vcc
	v_cmp_lt_f32_e64 vcc, |v149|, s91
	v_add_f32_e32 v19, v19, v93
	v_exp_f32_e32 v18, v18
	v_cndmask_b32_e32 v16, v16, v149, vcc
	v_mul_f32_e32 v149, 0xc1000000, v16
	v_mul_f32_e32 v16, v17, v149
	v_mul_f32_e32 v16, 0x3fb8aa3b, v16
	v_mul_f32_e32 v17, v33, v149
	v_exp_f32_e32 v33, v16
	v_mul_f32_e32 v16, v34, v149
	v_mul_f32_e32 v16, 0x3fb8aa3b, v16
	v_exp_f32_e32 v152, v16
	v_add_f32_e32 v16, v35, v148
	v_mul_f32_e32 v16, 0xbfb8aa3b, v16
	v_exp_f32_e32 v16, v16
	v_mul_f32_e32 v17, 0x3fb8aa3b, v17
	v_mul_f32_e32 v19, 0xbfb8aa3b, v19
	v_exp_f32_e32 v150, v17
	v_add_f32_e32 v16, 1.0, v16
	v_rcp_f32_e32 v16, v16
	v_exp_f32_e32 v19, v19
	v_add_f32_e32 v151, 1.0, v151
	v_add_f32_e32 v18, 1.0, v18
	v_mul_f32_e32 v16, v16, v149
	v_mul_f32_e32 v16, 0x3fb8aa3b, v16
	v_exp_f32_e32 v16, v16
	v_fma_f32 v35, -v152, v152, 1.0
	v_rcp_f32_e32 v17, v151
	v_fma_f32 v34, -v33, v33, 1.0
	v_fma_f32 v151, -v150, v150, 1.0
	v_rcp_f32_e32 v18, v18
	v_sqrt_f32_e32 v35, v35
	v_add_f32_e32 v19, 1.0, v19
	v_fma_f32 v153, -v16, v16, 1.0
	v_sqrt_f32_e32 v34, v34
	v_sqrt_f32_e32 v151, v151
	v_rcp_f32_e32 v19, v19
	v_sqrt_f32_e32 v153, v153
	v_mul_f32_e32 v35, v18, v35
	v_add_f32_e32 v18, v36, v148
	v_mul_f32_e32 v32, v32, v34
	v_mul_f32_e32 v34, v17, v151
	v_mul_f32_e32 v17, v19, v153
	v_mul_f32_e32 v18, 0xbfb8aa3b, v18
	v_add_f32_e32 v19, v20, v93
	v_exp_f32_e32 v18, v18
	v_mul_f32_e32 v19, 0xbfb8aa3b, v19
	v_exp_f32_e32 v19, v19
	v_mul_f32_e32 v3, v3, v17
	v_add_f32_e32 v17, 1.0, v18
	v_rcp_f32_e32 v17, v17
	v_add_f32_e32 v18, 1.0, v19
	v_add_f32_e32 v19, v37, v148
	v_mul_f32_e32 v19, 0xbfb8aa3b, v19
	v_exp_f32_e32 v19, v19
	v_mul_f32_e32 v17, v17, v149
	v_mul_f32_e32 v17, 0x3fb8aa3b, v17
	v_exp_f32_e32 v36, v17
	v_add_f32_e32 v17, 1.0, v19
	v_rcp_f32_e32 v17, v17
	v_add_f32_e32 v19, v21, v93
	v_mul_f32_e32 v19, 0xbfb8aa3b, v19
	v_exp_f32_e32 v19, v19
	v_mul_f32_e32 v17, v17, v149
	v_mul_f32_e32 v17, 0x3fb8aa3b, v17
	v_exp_f32_e32 v37, v17
	v_add_f32_e32 v17, v38, v148
	v_mul_f32_e32 v17, 0xbfb8aa3b, v17
	v_exp_f32_e32 v17, v17
	v_add_f32_e32 v23, v23, v93
	v_add_f32_e32 v19, 1.0, v19
	v_fma_f32 v21, -v37, v37, 1.0
	v_add_f32_e32 v17, 1.0, v17
	v_rcp_f32_e32 v17, v17
	v_mul_f32_e32 v23, 0xbfb8aa3b, v23
	v_fma_f32 v20, -v36, v36, 1.0
	v_rcp_f32_e32 v19, v19
	v_mul_f32_e32 v17, v17, v149
	v_mul_f32_e32 v17, 0x3fb8aa3b, v17
	v_exp_f32_e32 v38, v17
	v_add_f32_e32 v17, v39, v148
	v_mul_f32_e32 v17, 0xbfb8aa3b, v17
	v_exp_f32_e32 v17, v17
	v_sqrt_f32_e32 v21, v21
	v_exp_f32_e32 v23, v23
	v_rcp_f32_e32 v18, v18
	v_add_f32_e32 v17, 1.0, v17
	v_rcp_f32_e32 v17, v17
	v_sqrt_f32_e32 v20, v20
	v_add_f32_e32 v23, 1.0, v23
	v_mul_f32_e32 v154, v19, v21
	v_mul_f32_e32 v17, v17, v149
	v_mul_f32_e32 v17, 0x3fb8aa3b, v17
	v_exp_f32_e32 v17, v17
	v_add_f32_e32 v19, v40, v148
	v_rcp_f32_e32 v23, v23
	v_mul_f32_e32 v153, v18, v20
	v_fma_f32 v151, -v17, v17, 1.0
	v_sqrt_f32_e32 v151, v151
	v_mul_f32_e32 v19, 0xbfb8aa3b, v19
	v_add_f32_e32 v20, v24, v93
	v_add_f32_e32 v22, v22, v93
	v_exp_f32_e32 v19, v19
	v_mul_f32_e32 v20, 0xbfb8aa3b, v20
	v_mul_f32_e32 v22, 0xbfb8aa3b, v22
	v_exp_f32_e32 v20, v20
	v_exp_f32_e32 v22, v22
	v_mul_f32_e32 v18, v23, v151
	v_mul_f32_e32 v7, v7, v18
	v_add_f32_e32 v18, 1.0, v19
	v_rcp_f32_e32 v18, v18
	v_add_f32_e32 v19, 1.0, v20
	v_add_f32_e32 v20, v41, v148
	v_add_f32_e32 v22, 1.0, v22
	v_fma_f32 v39, -v38, v38, 1.0
	v_mul_f32_e32 v20, 0xbfb8aa3b, v20
	v_rcp_f32_e32 v22, v22
	v_sqrt_f32_e32 v39, v39
	v_exp_f32_e32 v20, v20
	v_mul_f32_e32 v18, v18, v149
	v_mul_f32_e32 v18, 0x3fb8aa3b, v18
	v_mul_f32_e32 v21, v22, v39
	v_exp_f32_e32 v39, v18
	v_add_f32_e32 v18, 1.0, v20
	v_rcp_f32_e32 v18, v18
	v_add_f32_e32 v20, v25, v93
	v_mul_f32_e32 v20, 0xbfb8aa3b, v20
	v_exp_f32_e32 v20, v20
	v_mul_f32_e32 v18, v18, v149
	v_mul_f32_e32 v18, 0x3fb8aa3b, v18
	v_exp_f32_e32 v40, v18
	v_add_f32_e32 v18, v42, v148
	v_mul_f32_e32 v18, 0xbfb8aa3b, v18
	v_exp_f32_e32 v18, v18
	v_add_f32_e32 v24, v26, v93
	v_add_f32_e32 v26, v27, v93
	v_add_f32_e32 v20, 1.0, v20
	v_add_f32_e32 v18, 1.0, v18
	v_rcp_f32_e32 v18, v18
	v_fma_f32 v23, -v40, v40, 1.0
	v_mul_f32_e32 v26, 0xbfb8aa3b, v26
	v_fma_f32 v22, -v39, v39, 1.0
	v_mul_f32_e32 v18, v18, v149
	v_mul_f32_e32 v18, 0x3fb8aa3b, v18
	v_exp_f32_e32 v41, v18
	v_add_f32_e32 v18, v43, v148
	v_mul_f32_e32 v18, 0xbfb8aa3b, v18
	v_exp_f32_e32 v18, v18
	v_rcp_f32_e32 v20, v20
	v_sqrt_f32_e32 v23, v23
	v_exp_f32_e32 v26, v26
	v_add_f32_e32 v18, 1.0, v18
	v_rcp_f32_e32 v18, v18
	v_rcp_f32_e32 v19, v19
	v_sqrt_f32_e32 v22, v22
	v_add_f32_e32 v26, 1.0, v26
	v_mul_f32_e32 v18, v18, v149
	v_mul_f32_e32 v18, 0x3fb8aa3b, v18
	v_exp_f32_e32 v18, v18
	v_mul_f32_e32 v43, v20, v23
	v_add_f32_e32 v20, v44, v148
	v_rcp_f32_e32 v26, v26
	v_fma_f32 v27, -v18, v18, 1.0
	v_sqrt_f32_e32 v27, v27
	v_mul_f32_e32 v42, v19, v22
	v_mul_f32_e32 v20, 0xbfb8aa3b, v20
	v_add_f32_e32 v22, v28, v93
	v_exp_f32_e32 v20, v20
	v_mul_f32_e32 v22, 0xbfb8aa3b, v22
	v_exp_f32_e32 v22, v22
	v_mul_f32_e32 v19, v26, v27
	v_mul_f32_e32 v11, v11, v19
	v_add_f32_e32 v19, 1.0, v20
	v_rcp_f32_e32 v19, v19
	v_add_f32_e32 v20, 1.0, v22
	v_add_f32_e32 v22, v45, v148
	v_mul_f32_e32 v22, 0xbfb8aa3b, v22
	v_exp_f32_e32 v22, v22
	v_mul_f32_e32 v19, v19, v149
	v_mul_f32_e32 v19, 0x3fb8aa3b, v19
	v_exp_f32_e32 v44, v19
	v_add_f32_e32 v19, 1.0, v22
	v_rcp_f32_e32 v19, v19
	v_mul_f32_e32 v24, 0xbfb8aa3b, v24
	v_exp_f32_e32 v24, v24
	v_add_f32_e32 v22, v29, v93
	v_mul_f32_e32 v19, v19, v149
	v_mul_f32_e32 v19, 0x3fb8aa3b, v19
	v_exp_f32_e32 v45, v19
	v_add_f32_e32 v19, v46, v148
	v_mul_f32_e32 v19, 0xbfb8aa3b, v19
	v_exp_f32_e32 v19, v19
	v_mul_f32_e32 v22, 0xbfb8aa3b, v22
	v_add_f32_e32 v24, 1.0, v24
	v_fma_f32 v25, -v41, v41, 1.0
	v_add_f32_e32 v19, 1.0, v19
	v_rcp_f32_e32 v19, v19
	v_exp_f32_e32 v22, v22
	v_rcp_f32_e32 v24, v24
	v_sqrt_f32_e32 v25, v25
	v_mul_f32_e32 v19, v19, v149
	v_mul_f32_e32 v19, 0x3fb8aa3b, v19
	v_exp_f32_e32 v46, v19
	v_add_f32_e32 v19, v47, v148
	v_mul_f32_e32 v19, 0xbfb8aa3b, v19
	v_add_f32_e32 v22, 1.0, v22
	v_exp_f32_e32 v19, v19
	v_mul_f32_e32 v151, v24, v25
	v_rcp_f32_e32 v24, v22
	v_fma_f32 v22, -v45, v45, 1.0
	v_sqrt_f32_e32 v25, v22
	v_add_f32_e32 v22, v30, v93
	v_mul_f32_e32 v22, 0xbfb8aa3b, v22
	v_exp_f32_e32 v22, v22
	v_add_f32_e32 v19, 1.0, v19
	v_rcp_f32_e32 v19, v19
	v_fma_f32 v27, -v46, v46, 1.0
	v_add_f32_e32 v22, 1.0, v22
	v_rcp_f32_e32 v26, v22
	v_add_f32_e32 v22, v31, v93
	v_mul_f32_e32 v19, v19, v149
	v_mul_f32_e32 v22, 0xbfb8aa3b, v22
	v_mul_f32_e32 v19, 0x3fb8aa3b, v19
	v_exp_f32_e32 v28, v22
	v_exp_f32_e32 v22, v19
	v_sqrt_f32_e32 v19, v27
	v_fma_f32 v23, -v44, v44, 1.0
	v_add_f32_e32 v27, 1.0, v28
	v_fma_f32 v28, -v22, v22, 1.0
	v_rcp_f32_e32 v27, v27
	v_sqrt_f32_e32 v28, v28
	v_rcp_f32_e32 v20, v20
	v_sqrt_f32_e32 v23, v23
	v_mul_f32_e32 v148, v26, v19
	v_mul_f32_e32 v19, v27, v28
	v_fmac_f32_e32 v7, 0, v17
	v_mul_f32_e32 v15, v15, v19
	v_mul_f32_e32 v19, v38, v7
	v_fmac_f32_e32 v19, v6, v21
	v_fmac_f32_e32 v3, 0, v16
	v_mul_f32_e32 v21, v37, v19
	v_mul_f32_e32 v47, v20, v23
	v_mul_f32_e32 v20, v152, v3
	v_fmac_f32_e32 v21, v5, v154
	v_fmac_f32_e32 v15, 0, v22
	v_mul_f32_e32 v93, v24, v25
	v_fmac_f32_e32 v20, v2, v35
	v_mul_f32_e32 v24, v36, v21
	v_fmac_f32_e32 v11, 0, v18
	v_mul_f32_e32 v2, v46, v15
	v_fmac_f32_e32 v24, v4, v153
	v_mul_f32_e32 v4, v41, v11
	v_fmac_f32_e32 v2, v14, v148
	v_fmac_f32_e32 v4, v10, v151
	v_mul_f32_e32 v5, v45, v2
	v_mul_f32_e32 v23, v150, v20
	v_mul_f32_e32 v6, v40, v4
	v_fmac_f32_e32 v5, v13, v93
	v_fmac_f32_e32 v23, v1, v34
	v_fmac_f32_e32 v6, v9, v43
	v_mul_f32_e32 v14, v22, v46
	v_mul_f32_e32 v9, v44, v5
	v_mul_f32_e32 v25, v33, v23
	v_mul_f32_e32 v13, v45, v14
	v_fmac_f32_e32 v9, v12, v47
	v_fmac_f32_e32 v25, v0, v32
	v_mul_f32_e32 v12, v44, v13
	ds_bpermute_b32 v0, v137, v9
	ds_bpermute_b32 v35, v137, v12
	v_mul_f32_e32 v28, v18, v41
	v_mul_f32_e32 v26, v16, v152
	v_mul_f32_e32 v27, v17, v38
	v_mul_f32_e32 v31, v40, v28
	v_mul_f32_e32 v10, v39, v6
	v_mul_f32_e32 v29, v150, v26
	v_mul_f32_e32 v30, v37, v27
	v_fmac_f32_e32 v10, v8, v42
	v_mul_f32_e32 v34, v39, v31
	v_mul_f32_e32 v32, v33, v29
	v_mul_f32_e32 v33, v36, v30
	s_waitcnt lgkmcnt(1)
	v_cndmask_b32_e64 v36, v0, v9, s[4:5]
	v_cndmask_b32_e64 v37, v9, v0, s[4:5]
	ds_bpermute_b32 v0, v137, v34
	ds_bpermute_b32 v40, v137, v10
	s_waitcnt lgkmcnt(2)
	v_cndmask_b32_e64 v8, v12, v35, s[4:5]
	v_fmac_f32_e32 v37, 0, v8
	ds_bpermute_b32 v8, v137, v33
	v_cndmask_b32_e64 v1, v35, v12, s[4:5]
	v_mul_f32_e32 v38, v12, v35
	v_fmac_f32_e32 v36, v1, v37
	s_waitcnt lgkmcnt(2)
	v_cndmask_b32_e64 v1, v0, v34, s[4:5]
	s_waitcnt lgkmcnt(1)
	v_cndmask_b32_e64 v39, v40, v10, s[4:5]
	v_cndmask_b32_e64 v0, v34, v0, s[4:5]
	v_cndmask_b32_e64 v40, v10, v40, s[4:5]
	ds_bpermute_b32 v44, v137, v24
	v_mul_f32_e32 v41, v38, v0
	v_fmac_f32_e32 v40, v0, v36
	v_mul_f32_e32 v42, v1, v41
	v_fmac_f32_e32 v39, v1, v40
	s_waitcnt lgkmcnt(1)
	v_cndmask_b32_e64 v0, v8, v33, s[4:5]
	v_cndmask_b32_e64 v1, v33, v8, s[4:5]
	ds_bpermute_b32 v8, v137, v32
	ds_bpermute_b32 v47, v137, v25
	s_waitcnt lgkmcnt(2)
	v_cndmask_b32_e64 v43, v44, v24, s[4:5]
	v_cndmask_b32_e64 v44, v24, v44, s[4:5]
	v_mul_f32_e32 v45, v1, v42
	v_fmac_f32_e32 v44, v1, v39
	v_mul_f32_e32 v46, v0, v45
	v_fmac_f32_e32 v43, v0, v44
	s_waitcnt lgkmcnt(1)
	v_cndmask_b32_e64 v0, v32, v8, s[4:5]
	s_waitcnt lgkmcnt(0)
	v_cndmask_b32_e64 v47, v25, v47, s[4:5]
	v_mul_f32_e32 v93, v0, v46
	v_fmac_f32_e32 v47, v0, v43
	s_and_saveexec_b64 s[8:9], s[4:5]
	v_mul_f32_e32 v0, v32, v93
	v_fma_f32 v1, v32, v47, v25
	ds_write_b64 v136, v[0:1] offset:2048
	s_or_b64 exec, exec, s[8:9]
	v_cndmask_b32_e64 v0, 0, 1, s[14:15]
	v_cmp_ne_u32_e64 s[8:9], 1, v0
	s_andn2_b64 vcc, exec, s[14:15]
	s_waitcnt lgkmcnt(0)
	s_barrier
	s_cbranch_vccnz .LBB0_277
	v_add3_u32 v148, v140, v91, s93
	v_mov_b32_e32 v8, 1.0
	v_mov_b32_e32 v1, 0
	s_mov_b32 s12, 7

.LBB0_278:
	v_cndmask_b32_e64 v0, 1.0, v35, s[4:5]
	v_cndmask_b32_e64 v35, 0, v37, s[4:5]
	v_cndmask_b32_e64 v37, v38, v41, s[4:5]
	v_cndmask_b32_e64 v36, v36, v40, s[4:5]
	v_cndmask_b32_e64 v40, v46, v93, s[4:5]
	v_cndmask_b32_e64 v41, v43, v47, s[4:5]
	v_fmac_f32_e32 v25, v32, v41
	v_mul_f32_e32 v32, v32, v40
	v_fmac_f32_e32 v23, v29, v41
	v_mul_f32_e32 v29, v29, v40
	v_fmac_f32_e32 v20, v26, v41
	v_mul_f32_e32 v26, v26, v40
	v_fmac_f32_e32 v3, v16, v41
	v_mul_f32_e32 v40, v16, v40
	v_mul_f32_e32 v16, v32, v8
	v_fmac_f32_e32 v25, v32, v1
	v_cvt_pk_bf16_f32 v16, v25, v16
	v_cndmask_b32_e64 v38, v42, v45, s[4:5]
	v_cndmask_b32_e64 v39, v39, v44, s[4:5]
	v_fmac_f32_e32 v10, v34, v36
	v_mul_f32_e32 v34, v34, v37
	v_fmac_f32_e32 v6, v31, v36
	v_mul_f32_e32 v31, v31, v37
	v_fmac_f32_e32 v4, v28, v36
	v_mul_f32_e32 v28, v28, v37
	v_fmac_f32_e32 v11, v18, v36
	v_mul_f32_e32 v18, v18, v37
	v_fmac_f32_e32 v9, v12, v35
	v_mul_f32_e32 v36, v0, v12
	v_fmac_f32_e32 v5, v13, v35
	v_mul_f32_e32 v37, v0, v13
	v_lshl_add_u64 v[12:13], v[94:95], 0, s[48:49]
	v_lshl_or_b32 v175, v138, 2, v134
	global_load_dword v172, v175, s[42:43]
	global_load_dword v173, v175, s[36:37]
	global_load_dword v174, v175, s[40:41]
	global_store_dword v[96:97], v16, off offset:128 nt
	v_mul_f32_e32 v16, v29, v8
	v_fmac_f32_e32 v24, v33, v39
	v_mul_f32_e32 v33, v33, v38
	v_fmac_f32_e32 v21, v30, v39
	v_mul_f32_e32 v30, v30, v38
	v_fmac_f32_e32 v19, v27, v39
	v_mul_f32_e32 v27, v27, v38
	v_fmac_f32_e32 v7, v17, v39
	v_mul_f32_e32 v38, v17, v38
	v_fmac_f32_e32 v2, v14, v35
	v_mul_f32_e32 v14, v0, v14
	v_fmac_f32_e32 v15, v22, v35
	v_mul_f32_e32 v0, v0, v22
	v_fmac_f32_e32 v23, v29, v1
	v_cvt_pk_bf16_f32 v22, v23, v16
	v_lshl_add_u64 v[16:17], v[12:13], 0, v[88:89]
	global_store_dword v[16:17], v22, off nt
	v_fmac_f32_e32 v20, v26, v1
	v_mul_f32_e32 v16, v26, v8
	v_cvt_pk_bf16_f32 v20, v20, v16
	v_lshl_add_u64 v[16:17], v[12:13], 0, v[98:99]
	global_store_dword v[16:17], v20, off nt
	v_fmac_f32_e32 v3, v40, v1
	v_mul_f32_e32 v16, v40, v8
	v_cvt_pk_bf16_f32 v3, v3, v16
	v_lshl_add_u64 v[16:17], v[12:13], 0, v[100:101]
	global_store_dword v[16:17], v3, off nt
	v_mul_f32_e32 v3, v33, v8
	v_fmac_f32_e32 v24, v33, v1
	v_cvt_pk_bf16_f32 v3, v24, v3
	v_lshl_add_u64 v[16:17], v[12:13], 0, v[102:103]
	global_store_dword v[16:17], v3, off nt
	v_mul_f32_e32 v3, v30, v8
	v_fmac_f32_e32 v21, v30, v1
	v_cvt_pk_bf16_f32 v3, v21, v3
	v_lshl_add_u64 v[16:17], v[12:13], 0, v[104:105]
	global_store_dword v[16:17], v3, off nt
	v_mul_f32_e32 v3, v27, v8
	v_fmac_f32_e32 v19, v27, v1
	v_cvt_pk_bf16_f32 v3, v19, v3
	v_lshl_add_u64 v[16:17], v[12:13], 0, v[106:107]
	global_store_dword v[16:17], v3, off nt
	v_mul_f32_e32 v3, v38, v8
	v_fmac_f32_e32 v7, v38, v1
	v_cvt_pk_bf16_f32 v3, v7, v3
	v_lshl_add_u64 v[16:17], v[12:13], 0, v[108:109]
	global_store_dword v[16:17], v3, off nt
	v_mul_f32_e32 v3, v34, v8
	v_fmac_f32_e32 v10, v34, v1
	v_cvt_pk_bf16_f32 v3, v10, v3
	v_lshl_add_u64 v[16:17], v[12:13], 0, v[110:111]
	global_store_dword v[16:17], v3, off nt
	v_fmac_f32_e32 v6, v31, v1
	v_mul_f32_e32 v3, v31, v8
	v_cvt_pk_bf16_f32 v3, v6, v3
	v_lshl_add_u64 v[6:7], v[12:13], 0, v[112:113]
	global_store_dword v[6:7], v3, off nt
	v_mul_f32_e32 v3, v28, v8
	v_fmac_f32_e32 v4, v28, v1
	v_cvt_pk_bf16_f32 v3, v4, v3
	v_lshl_add_u64 v[6:7], v[12:13], 0, v[114:115]
	global_store_dword v[6:7], v3, off nt
	v_mul_f32_e32 v3, v18, v8
	v_fmac_f32_e32 v11, v18, v1
	v_cvt_pk_bf16_f32 v3, v11, v3
	v_lshl_add_u64 v[6:7], v[12:13], 0, v[116:117]
	global_store_dword v[6:7], v3, off nt
	v_mul_f32_e32 v3, v36, v8
	v_fmac_f32_e32 v9, v36, v1
	v_cvt_pk_bf16_f32 v3, v9, v3
	v_lshl_add_u64 v[6:7], v[12:13], 0, v[118:119]
	global_store_dword v[6:7], v3, off nt
	v_fmac_f32_e32 v5, v37, v1
	v_mul_f32_e32 v3, v37, v8
	v_cvt_pk_bf16_f32 v3, v5, v3
	v_lshl_add_u64 v[4:5], v[12:13], 0, v[120:121]
	global_store_dword v[4:5], v3, off nt
	v_fmac_f32_e32 v2, v14, v1
	v_mul_f32_e32 v3, v14, v8
	v_cvt_pk_bf16_f32 v4, v2, v3
	v_lshl_add_u64 v[2:3], v[12:13], 0, v[122:123]
	v_fmac_f32_e32 v15, v0, v1
	v_mul_f32_e32 v0, v0, v8
	global_store_dword v[2:3], v4, off nt
	v_cvt_pk_bf16_f32 v2, v15, v0
	v_lshl_add_u64 v[0:1], v[12:13], 0, v[124:125]
	global_store_dword v[0:1], v2, off nt
	s_and_saveexec_b64 s[12:13], s[6:7]
	s_cbranch_execz .LBB0_280
	v_add_u32_e32 v12, 0x800, v90
	ds_read2_b64 v[0:3], v12 offset0:192 offset1:224
	ds_read2_b64 v[4:7], v12 offset0:128 offset1:160
	ds_read2_b64 v[8:11], v12 offset0:64 offset1:96
	ds_read2_b64 v[12:15], v12 offset1:32
	s_waitcnt lgkmcnt(3)
	v_fma_f32 v16, 0, v2, v3
	v_pk_mul_f32 v[2:3], v[2:3], v[0:1]
	v_fma_f32 v0, v0, v16, v1
	s_waitcnt lgkmcnt(2)
	v_fma_f32 v0, v6, v0, v7
	v_fma_f32 v0, v4, v0, v5
	s_waitcnt lgkmcnt(1)
	v_fma_f32 v1, v10, v0, v11
	v_mov_b32_e32 v0, v2
	v_mov_b32_e32 v16, v6
	v_mov_b32_e32 v17, v8
	v_pk_mul_f32 v[2:3], v[2:3], v[6:7]
	v_pk_fma_f32 v[0:1], v[0:1], v[16:17], v[8:9]
	v_pk_mul_f32 v[2:3], v[2:3], v[4:5]
	s_waitcnt lgkmcnt(0)
	v_mov_b32_e32 v11, v14
	v_mov_b32_e32 v3, v1
	v_pk_mul_f32 v[0:1], v[2:3], v[10:11]
	v_pk_fma_f32 v[2:3], v[2:3], v[10:11], v[14:15]
	v_pk_mul_f32 v[0:1], v[0:1], v[8:9]
	v_mov_b32_e32 v4, v14
	v_mov_b32_e32 v2, v0
	v_mov_b32_e32 v5, v12
	v_pk_mul_f32 v[0:1], v[0:1], v[14:15]
	v_pk_fma_f32 v[2:3], v[2:3], v[4:5], v[12:13]
	v_pk_mul_f32 v[0:1], v[0:1], v[12:13]
	v_add_u32_e32 v2, 32, v92
	v_mov_b32_e32 v1, v3
	v_ashrrev_i32_e32 v3, 31, v2
	v_lshl_add_u64 v[2:3], v[2:3], 3, s[30:31]
	global_store_dwordx2 v[2:3], v[0:1], off
.LBB0_280:
	s_or_b64 exec, exec, s[12:13]
	s_setprio 1
	ds_read_b128 v[0:3], v145 offset:32768
	ds_read_b128 v[4:7], v147 offset:32768
	v_add_u32_e32 v8, 0x8000, v147
	s_waitcnt lgkmcnt(1)
	v_mfma_f32_32x32x16_bf16 v[32:47], v[48:51], v[0:3], 0
	v_add_u32_e32 v0, 0x8000, v145
	ds_read_b128 v[0:3], v0 offset:32768
	ds_read_b128 v[8:11], v8 offset:32768
	s_waitcnt lgkmcnt(1)
	v_mfma_f32_32x32x16_bf16 v[16:31], v[48:51], v[0:3], 0
	v_mfma_f32_32x32x16_bf16 v[32:47], v[52:55], v[4:7], v[32:47]
	ds_read_b128 v[0:3], v142 offset:32768
	ds_read_b128 v[4:7], v146 offset:32768
	s_waitcnt lgkmcnt(2)
	v_mfma_f32_32x32x16_bf16 v[16:31], v[52:55], v[8:11], v[16:31]
	v_add_u32_e32 v8, 0x8000, v146
	ds_read_b128 v[8:11], v8 offset:32768
	s_waitcnt lgkmcnt(2)
	v_mfma_f32_32x32x16_bf16 v[32:47], v[56:59], v[0:3], v[32:47]
	v_add_u32_e32 v0, 0x8000, v142
	ds_read_b128 v[0:3], v0 offset:32768
	s_waitcnt lgkmcnt(0)
	v_mfma_f32_32x32x16_bf16 v[16:31], v[56:59], v[0:3], v[16:31]
	v_mfma_f32_32x32x16_bf16 v[32:47], v[60:63], v[4:7], v[32:47]
	ds_read_b128 v[0:3], v141 offset:32768
	ds_read_b128 v[4:7], v144 offset:32768
	v_mfma_f32_32x32x16_bf16 v[16:31], v[60:63], v[8:11], v[16:31]
	v_add_u32_e32 v8, 0x8000, v144
	ds_read_b128 v[8:11], v8 offset:32768
	s_waitcnt lgkmcnt(2)
	v_mfma_f32_32x32x16_bf16 v[32:47], v[64:67], v[0:3], v[32:47]
	v_add_u32_e32 v0, 0x8000, v141
	ds_read_b128 v[0:3], v0 offset:32768
	s_waitcnt lgkmcnt(0)
	v_mfma_f32_32x32x16_bf16 v[16:31], v[64:67], v[0:3], v[16:31]
	v_mfma_f32_32x32x16_bf16 v[32:47], v[68:71], v[4:7], v[32:47]
	ds_read_b128 v[0:3], v139 offset:32768
	ds_read_b128 v[4:7], v143 offset:32768
	v_mfma_f32_32x32x16_bf16 v[16:31], v[68:71], v[8:11], v[16:31]
	v_add_u32_e32 v8, 0x8000, v143
	ds_read_b128 v[8:11], v8 offset:32768
	s_waitcnt lgkmcnt(2)
	v_mfma_f32_32x32x16_bf16 v[32:47], v[72:75], v[0:3], v[32:47]
	v_add_u32_e32 v0, 0x8000, v139
	ds_read_b128 v[0:3], v0 offset:32768
	s_waitcnt lgkmcnt(0)
	v_mfma_f32_32x32x16_bf16 v[16:31], v[72:75], v[0:3], v[16:31]
	v_mfma_f32_32x32x16_bf16 v[32:47], v[76:79], v[4:7], v[32:47]
	v_mfma_f32_32x32x16_bf16 v[16:31], v[76:79], v[8:11], v[16:31]
	v_mfma_f32_32x32x16_bf16 v[0:15], v[64:67], v[80:83], 0
	v_mfma_f32_32x32x16_bf16 v[0:15], v[68:71], v[84:87], v[0:15]
	s_setprio 0
	v_lshl_or_b32 v93, v138, 2, v134
	s_waitcnt vmcnt(16)
	v_mov_b32_e32 v149, v172
	v_mov_b32_e32 v148, v173
	v_mov_b32_e32 v93, v174
	v_mul_f32_e32 v149, 0xbfb8aa3b, v149
	v_add_f32_e32 v32, v32, v148
	v_add_f32_e32 v16, v16, v93
	v_exp_f32_e32 v149, v149
	v_mul_f32_e32 v32, 0xbfb8aa3b, v32
	v_mul_f32_e32 v16, 0xbfb8aa3b, v16
	v_exp_f32_e32 v32, v32
	v_exp_f32_e32 v150, v16
	v_add_f32_e32 v17, v17, v93
	v_mul_f32_e32 v17, 0xbfb8aa3b, v17
	v_add_f32_e32 v152, 1.0, v149
	v_exp_f32_e32 v151, v17
	v_add_f32_e32 v153, -1.0, v152
	v_frexp_mant_f32_e32 v154, v152
	v_cvt_f64_f32_e32 v[16:17], v152
	v_add_f32_e32 v32, 1.0, v32
	v_add_f32_e32 v150, 1.0, v150
	v_sub_f32_e32 v155, v153, v152
	v_frexp_exp_i32_f64_e32 v16, v[16:17]
	v_cmp_gt_f32_e32 vcc, s88, v154
	v_sub_f32_e32 v153, v149, v153
	v_rcp_f32_e32 v17, v32
	v_rcp_f32_e32 v32, v150
	v_add_f32_e32 v150, 1.0, v155
	v_subbrev_co_u32_e32 v16, vcc, 0, v16, vcc
	v_add_f32_e32 v150, v153, v150
	v_sub_u32_e32 v153, 0, v16
	v_cvt_f32_i32_e32 v16, v16
	v_ldexp_f32 v152, v152, v153
	v_ldexp_f32 v150, v150, v153
	v_add_f32_e32 v153, -1.0, v152
	v_add_f32_e32 v154, 1.0, v152
	v_add_f32_e32 v155, 1.0, v153
	v_add_f32_e32 v156, -1.0, v154
	v_sub_f32_e32 v155, v152, v155
	v_sub_f32_e32 v152, v152, v156
	v_mul_f32_e32 v156, 0x3f317218, v16
	v_add_f32_e32 v155, v150, v155
	v_add_f32_e32 v150, v150, v152
	v_fma_f32 v152, v16, s89, -v156
	v_add_f32_e32 v157, v153, v155
	v_add_f32_e32 v158, v154, v150
	v_fmac_f32_e32 v152, 0xb102e308, v16
	v_sub_f32_e32 v16, v157, v153
	v_sub_f32_e32 v153, v158, v154
	v_rcp_f32_e32 v154, v158
	v_add_f32_e32 v159, v156, v152
	v_sub_f32_e32 v150, v150, v153
	v_sub_f32_e32 v153, v159, v156
	v_sub_f32_e32 v152, v152, v153
	v_mul_f32_e32 v153, v157, v154
	v_sub_f32_e32 v16, v155, v16
	v_mul_f32_e32 v155, v158, v153
	v_fma_f32 v156, v153, v158, -v155
	v_fmac_f32_e32 v156, v153, v150
	v_add_f32_e32 v160, v155, v156
	v_sub_f32_e32 v161, v157, v160
	v_sub_f32_e32 v155, v160, v155
	v_sub_f32_e32 v157, v157, v161
	v_sub_f32_e32 v155, v155, v156
	v_sub_f32_e32 v156, v157, v160
	v_add_f32_e32 v16, v16, v156
	v_add_f32_e32 v16, v155, v16
	v_add_f32_e32 v155, v161, v16
	v_mul_f32_e32 v156, v154, v155
	v_sub_f32_e32 v157, v161, v155
	v_mul_f32_e32 v160, v158, v156
	v_add_f32_e32 v16, v16, v157
	v_add_f32_e32 v157, v153, v156
	v_fma_f32 v158, v156, v158, -v160
	v_sub_f32_e32 v153, v157, v153
	v_fmac_f32_e32 v158, v156, v150
	v_sub_f32_e32 v150, v156, v153
	v_add_f32_e32 v153, v160, v158
	v_sub_f32_e32 v156, v153, v160
	v_sub_f32_e32 v160, v155, v153
	v_sub_f32_e32 v155, v155, v160
	v_sub_f32_e32 v153, v155, v153
	v_sub_f32_e32 v156, v156, v158
	v_add_f32_e32 v16, v16, v153
	v_add_f32_e32 v16, v156, v16
	v_add_f32_e32 v16, v160, v16
	v_mul_f32_e32 v16, v154, v16
	v_add_f32_e32 v16, v150, v16
	v_add_f32_e32 v150, v157, v16
	v_mul_f32_e32 v153, v150, v150
	v_fmamk_f32 v156, v153, 0x3e9b6dac, v127
	v_sub_f32_e32 v154, v150, v157
	v_ldexp_f32 v155, v150, 1
	v_mul_f32_e32 v150, v150, v153
	v_fmaak_f32 v153, v153, v156, 0x3f2aaada
	v_mul_f32_e32 v150, v150, v153
	v_add_f32_e32 v153, v155, v150
	v_sub_f32_e32 v16, v16, v154
	v_sub_f32_e32 v154, v153, v155
	v_ldexp_f32 v16, v16, 1
	v_sub_f32_e32 v150, v150, v154
	v_add_f32_e32 v16, v16, v150
	v_add_f32_e32 v150, v153, v16
	v_sub_f32_e32 v153, v150, v153
	v_add_f32_e32 v154, v159, v150
	v_sub_f32_e32 v16, v16, v153
	v_sub_f32_e32 v153, v154, v159
	v_sub_f32_e32 v155, v154, v153
	v_sub_f32_e32 v150, v150, v153
	v_add_f32_e32 v153, v152, v16
	v_sub_f32_e32 v155, v159, v155
	v_sub_f32_e32 v156, v153, v152
	v_add_f32_e32 v150, v150, v155
	v_sub_f32_e32 v155, v153, v156
	v_sub_f32_e32 v16, v16, v156
	v_sub_f32_e32 v152, v152, v155
	v_add_f32_e32 v150, v153, v150
	v_add_f32_e32 v16, v16, v152
	v_add_f32_e32 v152, v154, v150
	v_add_f32_e32 v33, v33, v148
	v_add_f32_e32 v34, v34, v148
	v_sub_f32_e32 v153, v152, v154
	v_mul_f32_e32 v33, 0xbfb8aa3b, v33
	v_mul_f32_e32 v34, 0xbfb8aa3b, v34
	v_sub_f32_e32 v150, v150, v153
	v_exp_f32_e32 v33, v33
	v_exp_f32_e32 v34, v34
	v_add_f32_e32 v16, v16, v150
	v_add_f32_e32 v16, v152, v16
	v_cmp_neq_f32_e32 vcc, s90, v149
	v_add_f32_e32 v33, 1.0, v33
	v_add_f32_e32 v34, 1.0, v34
	v_cndmask_b32_e32 v16, v130, v16, vcc
	v_cmp_ngt_f32_e32 vcc, -1.0, v149
	v_rcp_f32_e32 v33, v33
	v_rcp_f32_e32 v34, v34
	v_cndmask_b32_e32 v16, v131, v16, vcc
	v_cmp_neq_f32_e32 vcc, -1.0, v149
	v_add_f32_e32 v18, v18, v93
	v_mul_f32_e32 v18, 0xbfb8aa3b, v18
	v_cndmask_b32_e32 v16, v132, v16, vcc
	v_cmp_lt_f32_e64 vcc, |v149|, s91
	v_add_f32_e32 v19, v19, v93
	v_exp_f32_e32 v18, v18
	v_cndmask_b32_e32 v16, v16, v149, vcc
	v_mul_f32_e32 v149, 0xc1000000, v16
	v_mul_f32_e32 v16, v17, v149
	v_mul_f32_e32 v16, 0x3fb8aa3b, v16
	v_mul_f32_e32 v17, v33, v149
	v_exp_f32_e32 v33, v16
	v_mul_f32_e32 v16, v34, v149
	v_mul_f32_e32 v16, 0x3fb8aa3b, v16
	v_exp_f32_e32 v152, v16
	v_add_f32_e32 v16, v35, v148
	v_mul_f32_e32 v16, 0xbfb8aa3b, v16
	v_exp_f32_e32 v16, v16
	v_mul_f32_e32 v17, 0x3fb8aa3b, v17
	v_mul_f32_e32 v19, 0xbfb8aa3b, v19
	v_exp_f32_e32 v150, v17
	v_add_f32_e32 v16, 1.0, v16
	v_rcp_f32_e32 v16, v16
	v_exp_f32_e32 v19, v19
	v_add_f32_e32 v151, 1.0, v151
	v_add_f32_e32 v18, 1.0, v18
	v_mul_f32_e32 v16, v16, v149
	v_mul_f32_e32 v16, 0x3fb8aa3b, v16
	v_exp_f32_e32 v16, v16
	v_fma_f32 v35, -v152, v152, 1.0
	v_rcp_f32_e32 v17, v151
	v_fma_f32 v34, -v33, v33, 1.0
	v_fma_f32 v151, -v150, v150, 1.0
	v_rcp_f32_e32 v18, v18
	v_sqrt_f32_e32 v35, v35
	v_add_f32_e32 v19, 1.0, v19
	v_fma_f32 v153, -v16, v16, 1.0
	v_sqrt_f32_e32 v34, v34
	v_sqrt_f32_e32 v151, v151
	v_rcp_f32_e32 v19, v19
	v_sqrt_f32_e32 v153, v153
	v_mul_f32_e32 v35, v18, v35
	v_add_f32_e32 v18, v36, v148
	v_mul_f32_e32 v32, v32, v34
	v_mul_f32_e32 v34, v17, v151
	v_mul_f32_e32 v17, v19, v153
	v_mul_f32_e32 v18, 0xbfb8aa3b, v18
	v_add_f32_e32 v19, v20, v93
	v_exp_f32_e32 v18, v18
	v_mul_f32_e32 v19, 0xbfb8aa3b, v19
	v_exp_f32_e32 v19, v19
	v_mul_f32_e32 v3, v3, v17
	v_add_f32_e32 v17, 1.0, v18
	v_rcp_f32_e32 v17, v17
	v_add_f32_e32 v18, 1.0, v19
	v_add_f32_e32 v19, v37, v148
	v_mul_f32_e32 v19, 0xbfb8aa3b, v19
	v_exp_f32_e32 v19, v19
	v_mul_f32_e32 v17, v17, v149
	v_mul_f32_e32 v17, 0x3fb8aa3b, v17
	v_exp_f32_e32 v36, v17
	v_add_f32_e32 v17, 1.0, v19
	v_rcp_f32_e32 v17, v17
	v_add_f32_e32 v19, v21, v93
	v_mul_f32_e32 v19, 0xbfb8aa3b, v19
	v_exp_f32_e32 v19, v19
	v_mul_f32_e32 v17, v17, v149
	v_mul_f32_e32 v17, 0x3fb8aa3b, v17
	v_exp_f32_e32 v37, v17
	v_add_f32_e32 v17, v38, v148
	v_mul_f32_e32 v17, 0xbfb8aa3b, v17
	v_exp_f32_e32 v17, v17
	v_add_f32_e32 v23, v23, v93
	v_add_f32_e32 v19, 1.0, v19
	v_fma_f32 v21, -v37, v37, 1.0
	v_add_f32_e32 v17, 1.0, v17
	v_rcp_f32_e32 v17, v17
	v_mul_f32_e32 v23, 0xbfb8aa3b, v23
	v_fma_f32 v20, -v36, v36, 1.0
	v_rcp_f32_e32 v19, v19
	v_mul_f32_e32 v17, v17, v149
	v_mul_f32_e32 v17, 0x3fb8aa3b, v17
	v_exp_f32_e32 v38, v17
	v_add_f32_e32 v17, v39, v148
	v_mul_f32_e32 v17, 0xbfb8aa3b, v17
	v_exp_f32_e32 v17, v17
	v_sqrt_f32_e32 v21, v21
	v_exp_f32_e32 v23, v23
	v_rcp_f32_e32 v18, v18
	v_add_f32_e32 v17, 1.0, v17
	v_rcp_f32_e32 v17, v17
	v_sqrt_f32_e32 v20, v20
	v_add_f32_e32 v23, 1.0, v23
	v_mul_f32_e32 v154, v19, v21
	v_mul_f32_e32 v17, v17, v149
	v_mul_f32_e32 v17, 0x3fb8aa3b, v17
	v_exp_f32_e32 v17, v17
	v_add_f32_e32 v19, v40, v148
	v_rcp_f32_e32 v23, v23
	v_mul_f32_e32 v153, v18, v20
	v_fma_f32 v151, -v17, v17, 1.0
	v_sqrt_f32_e32 v151, v151
	v_mul_f32_e32 v19, 0xbfb8aa3b, v19
	v_add_f32_e32 v20, v24, v93
	v_add_f32_e32 v22, v22, v93
	v_exp_f32_e32 v19, v19
	v_mul_f32_e32 v20, 0xbfb8aa3b, v20
	v_mul_f32_e32 v22, 0xbfb8aa3b, v22
	v_exp_f32_e32 v20, v20
	v_exp_f32_e32 v22, v22
	v_mul_f32_e32 v18, v23, v151
	v_mul_f32_e32 v7, v7, v18
	v_add_f32_e32 v18, 1.0, v19
	v_rcp_f32_e32 v18, v18
	v_add_f32_e32 v19, 1.0, v20
	v_add_f32_e32 v20, v41, v148
	v_add_f32_e32 v22, 1.0, v22
	v_fma_f32 v39, -v38, v38, 1.0
	v_mul_f32_e32 v20, 0xbfb8aa3b, v20
	v_rcp_f32_e32 v22, v22
	v_sqrt_f32_e32 v39, v39
	v_exp_f32_e32 v20, v20
	v_mul_f32_e32 v18, v18, v149
	v_mul_f32_e32 v18, 0x3fb8aa3b, v18
	v_mul_f32_e32 v21, v22, v39
	v_exp_f32_e32 v39, v18
	v_add_f32_e32 v18, 1.0, v20
	v_rcp_f32_e32 v18, v18
	v_add_f32_e32 v20, v25, v93
	v_mul_f32_e32 v20, 0xbfb8aa3b, v20
	v_exp_f32_e32 v20, v20
	v_mul_f32_e32 v18, v18, v149
	v_mul_f32_e32 v18, 0x3fb8aa3b, v18
	v_exp_f32_e32 v40, v18
	v_add_f32_e32 v18, v42, v148
	v_mul_f32_e32 v18, 0xbfb8aa3b, v18
	v_exp_f32_e32 v18, v18
	v_add_f32_e32 v24, v26, v93
	v_add_f32_e32 v26, v27, v93
	v_add_f32_e32 v20, 1.0, v20
	v_add_f32_e32 v18, 1.0, v18
	v_rcp_f32_e32 v18, v18
	v_fma_f32 v23, -v40, v40, 1.0
	v_mul_f32_e32 v26, 0xbfb8aa3b, v26
	v_fma_f32 v22, -v39, v39, 1.0
	v_mul_f32_e32 v18, v18, v149
	v_mul_f32_e32 v18, 0x3fb8aa3b, v18
	v_exp_f32_e32 v41, v18
	v_add_f32_e32 v18, v43, v148
	v_mul_f32_e32 v18, 0xbfb8aa3b, v18
	v_exp_f32_e32 v18, v18
	v_rcp_f32_e32 v20, v20
	v_sqrt_f32_e32 v23, v23
	v_exp_f32_e32 v26, v26
	v_add_f32_e32 v18, 1.0, v18
	v_rcp_f32_e32 v18, v18
	v_rcp_f32_e32 v19, v19
	v_sqrt_f32_e32 v22, v22
	v_add_f32_e32 v26, 1.0, v26
	v_mul_f32_e32 v18, v18, v149
	v_mul_f32_e32 v18, 0x3fb8aa3b, v18
	v_exp_f32_e32 v18, v18
	v_mul_f32_e32 v43, v20, v23
	v_add_f32_e32 v20, v44, v148
	v_rcp_f32_e32 v26, v26
	v_fma_f32 v27, -v18, v18, 1.0
	v_sqrt_f32_e32 v27, v27
	v_mul_f32_e32 v42, v19, v22
	v_mul_f32_e32 v20, 0xbfb8aa3b, v20
	v_add_f32_e32 v22, v28, v93
	v_exp_f32_e32 v20, v20
	v_mul_f32_e32 v22, 0xbfb8aa3b, v22
	v_exp_f32_e32 v22, v22
	v_mul_f32_e32 v19, v26, v27
	v_mul_f32_e32 v11, v11, v19
	v_add_f32_e32 v19, 1.0, v20
	v_rcp_f32_e32 v19, v19
	v_add_f32_e32 v20, 1.0, v22
	v_add_f32_e32 v22, v45, v148
	v_mul_f32_e32 v22, 0xbfb8aa3b, v22
	v_exp_f32_e32 v22, v22
	v_mul_f32_e32 v19, v19, v149
	v_mul_f32_e32 v19, 0x3fb8aa3b, v19
	v_exp_f32_e32 v44, v19
	v_add_f32_e32 v19, 1.0, v22
	v_rcp_f32_e32 v19, v19
	v_mul_f32_e32 v24, 0xbfb8aa3b, v24
	v_exp_f32_e32 v24, v24
	v_add_f32_e32 v22, v29, v93
	v_mul_f32_e32 v19, v19, v149
	v_mul_f32_e32 v19, 0x3fb8aa3b, v19
	v_exp_f32_e32 v45, v19
	v_add_f32_e32 v19, v46, v148
	v_mul_f32_e32 v19, 0xbfb8aa3b, v19
	v_exp_f32_e32 v19, v19
	v_mul_f32_e32 v22, 0xbfb8aa3b, v22
	v_add_f32_e32 v24, 1.0, v24
	v_fma_f32 v25, -v41, v41, 1.0
	v_add_f32_e32 v19, 1.0, v19
	v_rcp_f32_e32 v19, v19
	v_exp_f32_e32 v22, v22
	v_rcp_f32_e32 v24, v24
	v_sqrt_f32_e32 v25, v25
	v_mul_f32_e32 v19, v19, v149
	v_mul_f32_e32 v19, 0x3fb8aa3b, v19
	v_exp_f32_e32 v46, v19
	v_add_f32_e32 v19, v47, v148
	v_mul_f32_e32 v19, 0xbfb8aa3b, v19
	v_add_f32_e32 v22, 1.0, v22
	v_exp_f32_e32 v19, v19
	v_mul_f32_e32 v151, v24, v25
	v_rcp_f32_e32 v24, v22
	v_fma_f32 v22, -v45, v45, 1.0
	v_sqrt_f32_e32 v25, v22
	v_add_f32_e32 v22, v30, v93
	v_mul_f32_e32 v22, 0xbfb8aa3b, v22
	v_exp_f32_e32 v22, v22
	v_add_f32_e32 v19, 1.0, v19
	v_rcp_f32_e32 v19, v19
	v_fma_f32 v27, -v46, v46, 1.0
	v_add_f32_e32 v22, 1.0, v22
	v_rcp_f32_e32 v26, v22
	v_add_f32_e32 v22, v31, v93
	v_mul_f32_e32 v19, v19, v149
	v_mul_f32_e32 v22, 0xbfb8aa3b, v22
	v_mul_f32_e32 v19, 0x3fb8aa3b, v19
	v_exp_f32_e32 v28, v22
	v_exp_f32_e32 v22, v19
	v_sqrt_f32_e32 v19, v27
	v_fma_f32 v23, -v44, v44, 1.0
	v_add_f32_e32 v27, 1.0, v28
	v_fma_f32 v28, -v22, v22, 1.0
	v_rcp_f32_e32 v27, v27
	v_sqrt_f32_e32 v28, v28
	v_rcp_f32_e32 v20, v20
	v_sqrt_f32_e32 v23, v23
	v_mul_f32_e32 v148, v26, v19
	v_mul_f32_e32 v19, v27, v28
	v_fmac_f32_e32 v7, 0, v17
	v_mul_f32_e32 v15, v15, v19
	v_mul_f32_e32 v19, v38, v7
	v_fmac_f32_e32 v19, v6, v21
	v_fmac_f32_e32 v3, 0, v16
	v_mul_f32_e32 v21, v37, v19
	v_mul_f32_e32 v47, v20, v23
	v_mul_f32_e32 v20, v152, v3
	v_fmac_f32_e32 v21, v5, v154
	v_fmac_f32_e32 v15, 0, v22
	v_mul_f32_e32 v93, v24, v25
	v_fmac_f32_e32 v20, v2, v35
	v_mul_f32_e32 v24, v36, v21
	v_fmac_f32_e32 v11, 0, v18
	v_mul_f32_e32 v2, v46, v15
	v_fmac_f32_e32 v24, v4, v153
	v_mul_f32_e32 v4, v41, v11
	v_fmac_f32_e32 v2, v14, v148
	v_fmac_f32_e32 v4, v10, v151
	v_mul_f32_e32 v5, v45, v2
	v_mul_f32_e32 v23, v150, v20
	v_mul_f32_e32 v6, v40, v4
	v_fmac_f32_e32 v5, v13, v93
	v_fmac_f32_e32 v23, v1, v34
	v_fmac_f32_e32 v6, v9, v43
	v_mul_f32_e32 v14, v22, v46
	v_mul_f32_e32 v9, v44, v5
	v_mul_f32_e32 v25, v33, v23
	v_mul_f32_e32 v13, v45, v14
	v_fmac_f32_e32 v9, v12, v47
	v_fmac_f32_e32 v25, v0, v32
	v_mul_f32_e32 v12, v44, v13
	ds_bpermute_b32 v0, v137, v9
	ds_bpermute_b32 v35, v137, v12
	v_mul_f32_e32 v28, v18, v41
	v_mul_f32_e32 v26, v16, v152
	v_mul_f32_e32 v27, v17, v38
	v_mul_f32_e32 v31, v40, v28
	v_mul_f32_e32 v10, v39, v6
	v_mul_f32_e32 v29, v150, v26
	v_mul_f32_e32 v30, v37, v27
	v_fmac_f32_e32 v10, v8, v42
	v_mul_f32_e32 v34, v39, v31
	v_mul_f32_e32 v32, v33, v29
	v_mul_f32_e32 v33, v36, v30
	s_waitcnt lgkmcnt(1)
	v_cndmask_b32_e64 v36, v0, v9, s[4:5]
	v_cndmask_b32_e64 v37, v9, v0, s[4:5]
	ds_bpermute_b32 v0, v137, v34
	ds_bpermute_b32 v40, v137, v10
	s_waitcnt lgkmcnt(2)
	v_cndmask_b32_e64 v8, v12, v35, s[4:5]
	v_fmac_f32_e32 v37, 0, v8
	ds_bpermute_b32 v8, v137, v33
	v_cndmask_b32_e64 v1, v35, v12, s[4:5]
	v_mul_f32_e32 v38, v12, v35
	v_fmac_f32_e32 v36, v1, v37
	s_waitcnt lgkmcnt(2)
	v_cndmask_b32_e64 v1, v0, v34, s[4:5]
	s_waitcnt lgkmcnt(1)
	v_cndmask_b32_e64 v39, v40, v10, s[4:5]
	v_cndmask_b32_e64 v0, v34, v0, s[4:5]
	v_cndmask_b32_e64 v40, v10, v40, s[4:5]
	ds_bpermute_b32 v44, v137, v24
	v_mul_f32_e32 v41, v38, v0
	v_fmac_f32_e32 v40, v0, v36
	v_mul_f32_e32 v42, v1, v41
	v_fmac_f32_e32 v39, v1, v40
	s_waitcnt lgkmcnt(1)
	v_cndmask_b32_e64 v0, v8, v33, s[4:5]
	v_cndmask_b32_e64 v1, v33, v8, s[4:5]
	ds_bpermute_b32 v8, v137, v32
	ds_bpermute_b32 v47, v137, v25
	s_waitcnt lgkmcnt(2)
	v_cndmask_b32_e64 v43, v44, v24, s[4:5]
	v_cndmask_b32_e64 v44, v24, v44, s[4:5]
	v_mul_f32_e32 v45, v1, v42
	v_fmac_f32_e32 v44, v1, v39
	v_mul_f32_e32 v46, v0, v45
	v_fmac_f32_e32 v43, v0, v44
	s_waitcnt lgkmcnt(1)
	v_cndmask_b32_e64 v0, v32, v8, s[4:5]
	s_waitcnt lgkmcnt(0)
	v_cndmask_b32_e64 v47, v25, v47, s[4:5]
	v_mul_f32_e32 v93, v0, v46
	v_fmac_f32_e32 v47, v0, v43
	s_and_saveexec_b64 s[12:13], s[4:5]
	v_mul_f32_e32 v0, v32, v93
	v_fma_f32 v1, v32, v47, v25
	ds_write_b64 v136, v[0:1] offset:4096
	s_or_b64 exec, exec, s[12:13]
	s_and_b64 vcc, exec, s[8:9]
	s_waitcnt lgkmcnt(0)
	s_barrier
	s_cbranch_vccnz .LBB0_285
	v_add3_u32 v148, v140, v91, s94
	v_mov_b32_e32 v8, 1.0
	v_mov_b32_e32 v1, 0
	s_mov_b32 s12, 7

.LBB0_286:
	v_cndmask_b32_e64 v0, 1.0, v35, s[4:5]
	v_cndmask_b32_e64 v35, 0, v37, s[4:5]
	v_cndmask_b32_e64 v37, v38, v41, s[4:5]
	v_cndmask_b32_e64 v36, v36, v40, s[4:5]
	v_cndmask_b32_e64 v40, v46, v93, s[4:5]
	v_cndmask_b32_e64 v41, v43, v47, s[4:5]
	v_fmac_f32_e32 v25, v32, v41
	v_mul_f32_e32 v32, v32, v40
	v_fmac_f32_e32 v23, v29, v41
	v_mul_f32_e32 v29, v29, v40
	v_fmac_f32_e32 v20, v26, v41
	v_mul_f32_e32 v26, v26, v40
	v_fmac_f32_e32 v3, v16, v41
	v_mul_f32_e32 v40, v16, v40
	v_mul_f32_e32 v16, v32, v8
	v_fmac_f32_e32 v25, v32, v1
	v_cvt_pk_bf16_f32 v16, v25, v16
	v_cndmask_b32_e64 v38, v42, v45, s[4:5]
	v_cndmask_b32_e64 v39, v39, v44, s[4:5]
	v_fmac_f32_e32 v10, v34, v36
	v_mul_f32_e32 v34, v34, v37
	v_fmac_f32_e32 v6, v31, v36
	v_mul_f32_e32 v31, v31, v37
	v_fmac_f32_e32 v4, v28, v36
	v_mul_f32_e32 v28, v28, v37
	v_fmac_f32_e32 v11, v18, v36
	v_mul_f32_e32 v18, v18, v37
	v_fmac_f32_e32 v9, v12, v35
	v_mul_f32_e32 v36, v0, v12
	v_fmac_f32_e32 v5, v13, v35
	v_mul_f32_e32 v37, v0, v13
	v_lshl_add_u64 v[12:13], v[94:95], 0, s[60:61]
	v_lshl_or_b32 v175, v138, 2, v135
	global_load_dword v172, v175, s[42:43]
	global_load_dword v173, v175, s[36:37]
	global_load_dword v174, v175, s[40:41]
	global_store_dword v[96:97], v16, off offset:256 nt
	v_mul_f32_e32 v16, v29, v8
	v_fmac_f32_e32 v24, v33, v39
	v_mul_f32_e32 v33, v33, v38
	v_fmac_f32_e32 v21, v30, v39
	v_mul_f32_e32 v30, v30, v38
	v_fmac_f32_e32 v19, v27, v39
	v_mul_f32_e32 v27, v27, v38
	v_fmac_f32_e32 v7, v17, v39
	v_mul_f32_e32 v38, v17, v38
	v_fmac_f32_e32 v2, v14, v35
	v_mul_f32_e32 v14, v0, v14
	v_fmac_f32_e32 v15, v22, v35
	v_mul_f32_e32 v0, v0, v22
	v_fmac_f32_e32 v23, v29, v1
	v_cvt_pk_bf16_f32 v22, v23, v16
	v_lshl_add_u64 v[16:17], v[12:13], 0, v[88:89]
	global_store_dword v[16:17], v22, off nt
	v_fmac_f32_e32 v20, v26, v1
	v_mul_f32_e32 v16, v26, v8
	v_cvt_pk_bf16_f32 v20, v20, v16
	v_lshl_add_u64 v[16:17], v[12:13], 0, v[98:99]
	global_store_dword v[16:17], v20, off nt
	v_fmac_f32_e32 v3, v40, v1
	v_mul_f32_e32 v16, v40, v8
	v_cvt_pk_bf16_f32 v3, v3, v16
	v_lshl_add_u64 v[16:17], v[12:13], 0, v[100:101]
	global_store_dword v[16:17], v3, off nt
	v_mul_f32_e32 v3, v33, v8
	v_fmac_f32_e32 v24, v33, v1
	v_cvt_pk_bf16_f32 v3, v24, v3
	v_lshl_add_u64 v[16:17], v[12:13], 0, v[102:103]
	global_store_dword v[16:17], v3, off nt
	v_mul_f32_e32 v3, v30, v8
	v_fmac_f32_e32 v21, v30, v1
	v_cvt_pk_bf16_f32 v3, v21, v3
	v_lshl_add_u64 v[16:17], v[12:13], 0, v[104:105]
	global_store_dword v[16:17], v3, off nt
	v_mul_f32_e32 v3, v27, v8
	v_fmac_f32_e32 v19, v27, v1
	v_cvt_pk_bf16_f32 v3, v19, v3
	v_lshl_add_u64 v[16:17], v[12:13], 0, v[106:107]
	global_store_dword v[16:17], v3, off nt
	v_mul_f32_e32 v3, v38, v8
	v_fmac_f32_e32 v7, v38, v1
	v_cvt_pk_bf16_f32 v3, v7, v3
	v_lshl_add_u64 v[16:17], v[12:13], 0, v[108:109]
	global_store_dword v[16:17], v3, off nt
	v_mul_f32_e32 v3, v34, v8
	v_fmac_f32_e32 v10, v34, v1
	v_cvt_pk_bf16_f32 v3, v10, v3
	v_lshl_add_u64 v[16:17], v[12:13], 0, v[110:111]
	global_store_dword v[16:17], v3, off nt
	v_fmac_f32_e32 v6, v31, v1
	v_mul_f32_e32 v3, v31, v8
	v_cvt_pk_bf16_f32 v3, v6, v3
	v_lshl_add_u64 v[6:7], v[12:13], 0, v[112:113]
	global_store_dword v[6:7], v3, off nt
	v_mul_f32_e32 v3, v28, v8
	v_fmac_f32_e32 v4, v28, v1
	v_cvt_pk_bf16_f32 v3, v4, v3
	v_lshl_add_u64 v[6:7], v[12:13], 0, v[114:115]
	global_store_dword v[6:7], v3, off nt
	v_mul_f32_e32 v3, v18, v8
	v_fmac_f32_e32 v11, v18, v1
	v_cvt_pk_bf16_f32 v3, v11, v3
	v_lshl_add_u64 v[6:7], v[12:13], 0, v[116:117]
	global_store_dword v[6:7], v3, off nt
	v_mul_f32_e32 v3, v36, v8
	v_fmac_f32_e32 v9, v36, v1
	v_cvt_pk_bf16_f32 v3, v9, v3
	v_lshl_add_u64 v[6:7], v[12:13], 0, v[118:119]
	global_store_dword v[6:7], v3, off nt
	v_fmac_f32_e32 v5, v37, v1
	v_mul_f32_e32 v3, v37, v8
	v_cvt_pk_bf16_f32 v3, v5, v3
	v_lshl_add_u64 v[4:5], v[12:13], 0, v[120:121]
	global_store_dword v[4:5], v3, off nt
	v_fmac_f32_e32 v2, v14, v1
	v_mul_f32_e32 v3, v14, v8
	v_cvt_pk_bf16_f32 v4, v2, v3
	v_lshl_add_u64 v[2:3], v[12:13], 0, v[122:123]
	v_fmac_f32_e32 v15, v0, v1
	v_mul_f32_e32 v0, v0, v8
	global_store_dword v[2:3], v4, off nt
	v_cvt_pk_bf16_f32 v2, v15, v0
	v_lshl_add_u64 v[0:1], v[12:13], 0, v[124:125]
	global_store_dword v[0:1], v2, off nt
	s_and_saveexec_b64 s[12:13], s[6:7]
	s_cbranch_execz .LBB0_288
	v_add_u32_e32 v12, 0x1000, v90
	ds_read2_b64 v[0:3], v12 offset0:192 offset1:224
	ds_read2_b64 v[4:7], v12 offset0:128 offset1:160
	ds_read2_b64 v[8:11], v12 offset0:64 offset1:96
	ds_read2_b64 v[12:15], v12 offset1:32
	s_waitcnt lgkmcnt(3)
	v_fma_f32 v16, 0, v2, v3
	v_pk_mul_f32 v[2:3], v[2:3], v[0:1]
	v_fma_f32 v0, v0, v16, v1
	s_waitcnt lgkmcnt(2)
	v_fma_f32 v0, v6, v0, v7
	v_fma_f32 v0, v4, v0, v5
	s_waitcnt lgkmcnt(1)
	v_fma_f32 v1, v10, v0, v11
	v_mov_b32_e32 v0, v2
	v_mov_b32_e32 v16, v6
	v_mov_b32_e32 v17, v8
	v_pk_mul_f32 v[2:3], v[2:3], v[6:7]
	v_pk_fma_f32 v[0:1], v[0:1], v[16:17], v[8:9]
	v_pk_mul_f32 v[2:3], v[2:3], v[4:5]
	s_waitcnt lgkmcnt(0)
	v_mov_b32_e32 v11, v14
	v_mov_b32_e32 v3, v1
	v_pk_mul_f32 v[0:1], v[2:3], v[10:11]
	v_pk_fma_f32 v[2:3], v[2:3], v[10:11], v[14:15]
	v_pk_mul_f32 v[0:1], v[0:1], v[8:9]
	v_mov_b32_e32 v4, v14
	v_mov_b32_e32 v2, v0
	v_mov_b32_e32 v5, v12
	v_pk_mul_f32 v[0:1], v[0:1], v[14:15]
	v_pk_fma_f32 v[2:3], v[2:3], v[4:5], v[12:13]
	v_pk_mul_f32 v[0:1], v[0:1], v[12:13]
	v_add_u32_e32 v2, 64, v92
	v_mov_b32_e32 v1, v3
	v_ashrrev_i32_e32 v3, 31, v2
	v_lshl_add_u64 v[2:3], v[2:3], 3, s[30:31]
	global_store_dwordx2 v[2:3], v[0:1], off
.LBB0_288:
	s_or_b64 exec, exec, s[12:13]
	s_setprio 1
	ds_read_b128 v[0:3], v145 offset:40960
	ds_read_b128 v[4:7], v147 offset:40960
	v_add_u32_e32 v8, 0xa000, v147
	s_waitcnt lgkmcnt(1)
	v_mfma_f32_32x32x16_bf16 v[32:47], v[48:51], v[0:3], 0
	v_add_u32_e32 v0, 0xa000, v145
	ds_read_b128 v[0:3], v0 offset:32768
	ds_read_b128 v[8:11], v8 offset:32768
	s_waitcnt lgkmcnt(1)
	v_mfma_f32_32x32x16_bf16 v[16:31], v[48:51], v[0:3], 0
	v_mfma_f32_32x32x16_bf16 v[32:47], v[52:55], v[4:7], v[32:47]
	ds_read_b128 v[0:3], v142 offset:40960
	ds_read_b128 v[4:7], v146 offset:40960
	s_waitcnt lgkmcnt(2)
	v_mfma_f32_32x32x16_bf16 v[16:31], v[52:55], v[8:11], v[16:31]
	v_add_u32_e32 v8, 0xa000, v146
	ds_read_b128 v[8:11], v8 offset:32768
	s_waitcnt lgkmcnt(2)
	v_mfma_f32_32x32x16_bf16 v[32:47], v[56:59], v[0:3], v[32:47]
	v_add_u32_e32 v0, 0xa000, v142
	ds_read_b128 v[0:3], v0 offset:32768
	s_waitcnt lgkmcnt(0)
	v_mfma_f32_32x32x16_bf16 v[16:31], v[56:59], v[0:3], v[16:31]
	v_mfma_f32_32x32x16_bf16 v[32:47], v[60:63], v[4:7], v[32:47]
	ds_read_b128 v[0:3], v141 offset:40960
	ds_read_b128 v[4:7], v144 offset:40960
	v_mfma_f32_32x32x16_bf16 v[16:31], v[60:63], v[8:11], v[16:31]
	v_add_u32_e32 v8, 0xa000, v144
	ds_read_b128 v[8:11], v8 offset:32768
	s_waitcnt lgkmcnt(2)
	v_mfma_f32_32x32x16_bf16 v[32:47], v[64:67], v[0:3], v[32:47]
	v_add_u32_e32 v0, 0xa000, v141
	ds_read_b128 v[0:3], v0 offset:32768
	s_waitcnt lgkmcnt(0)
	v_mfma_f32_32x32x16_bf16 v[16:31], v[64:67], v[0:3], v[16:31]
	v_mfma_f32_32x32x16_bf16 v[32:47], v[68:71], v[4:7], v[32:47]
	ds_read_b128 v[0:3], v139 offset:40960
	ds_read_b128 v[4:7], v143 offset:40960
	v_mfma_f32_32x32x16_bf16 v[16:31], v[68:71], v[8:11], v[16:31]
	v_add_u32_e32 v8, 0xa000, v143
	ds_read_b128 v[8:11], v8 offset:32768
	s_waitcnt lgkmcnt(2)
	v_mfma_f32_32x32x16_bf16 v[32:47], v[72:75], v[0:3], v[32:47]
	v_add_u32_e32 v0, 0xa000, v139
	ds_read_b128 v[0:3], v0 offset:32768
	s_waitcnt lgkmcnt(0)
	v_mfma_f32_32x32x16_bf16 v[16:31], v[72:75], v[0:3], v[16:31]
	v_mfma_f32_32x32x16_bf16 v[32:47], v[76:79], v[4:7], v[32:47]
	v_mfma_f32_32x32x16_bf16 v[16:31], v[76:79], v[8:11], v[16:31]
	v_mfma_f32_32x32x16_bf16 v[0:15], v[72:75], v[80:83], 0
	v_mfma_f32_32x32x16_bf16 v[0:15], v[76:79], v[84:87], v[0:15]
	s_setprio 0
	v_lshl_or_b32 v48, v138, 2, v135
	s_waitcnt vmcnt(16)
	v_mov_b32_e32 v50, v172
	v_mov_b32_e32 v49, v173
	v_mov_b32_e32 v48, v174
	v_mul_f32_e32 v50, 0xbfb8aa3b, v50
	v_add_f32_e32 v32, v32, v49
	v_add_f32_e32 v16, v16, v48
	v_exp_f32_e32 v50, v50
	v_mul_f32_e32 v32, 0xbfb8aa3b, v32
	v_mul_f32_e32 v16, 0xbfb8aa3b, v16
	v_exp_f32_e32 v32, v32
	v_exp_f32_e32 v51, v16
	v_add_f32_e32 v17, v17, v48
	v_mul_f32_e32 v17, 0xbfb8aa3b, v17
	v_add_f32_e32 v53, 1.0, v50
	v_exp_f32_e32 v52, v17
	v_add_f32_e32 v54, -1.0, v53
	v_frexp_mant_f32_e32 v55, v53
	v_cvt_f64_f32_e32 v[16:17], v53
	v_add_f32_e32 v32, 1.0, v32
	v_add_f32_e32 v51, 1.0, v51
	v_sub_f32_e32 v56, v54, v53
	v_frexp_exp_i32_f64_e32 v16, v[16:17]
	v_cmp_gt_f32_e32 vcc, s88, v55
	v_sub_f32_e32 v54, v50, v54
	v_rcp_f32_e32 v17, v32
	v_rcp_f32_e32 v32, v51
	v_add_f32_e32 v51, 1.0, v56
	v_subbrev_co_u32_e32 v16, vcc, 0, v16, vcc
	v_add_f32_e32 v51, v54, v51
	v_sub_u32_e32 v54, 0, v16
	v_cvt_f32_i32_e32 v16, v16
	v_ldexp_f32 v53, v53, v54
	v_ldexp_f32 v51, v51, v54
	v_add_f32_e32 v54, -1.0, v53
	v_add_f32_e32 v55, 1.0, v53
	v_add_f32_e32 v56, 1.0, v54
	v_add_f32_e32 v57, -1.0, v55
	v_sub_f32_e32 v56, v53, v56
	v_sub_f32_e32 v53, v53, v57
	v_mul_f32_e32 v57, 0x3f317218, v16
	v_add_f32_e32 v56, v51, v56
	v_add_f32_e32 v51, v51, v53
	v_fma_f32 v53, v16, s89, -v57
	v_add_f32_e32 v58, v54, v56
	v_add_f32_e32 v59, v55, v51
	v_fmac_f32_e32 v53, 0xb102e308, v16
	v_sub_f32_e32 v16, v58, v54
	v_sub_f32_e32 v54, v59, v55
	v_rcp_f32_e32 v55, v59
	v_add_f32_e32 v60, v57, v53
	v_sub_f32_e32 v51, v51, v54
	v_sub_f32_e32 v54, v60, v57
	v_sub_f32_e32 v53, v53, v54
	v_mul_f32_e32 v54, v58, v55
	v_sub_f32_e32 v16, v56, v16
	v_mul_f32_e32 v56, v59, v54
	v_fma_f32 v57, v54, v59, -v56
	v_fmac_f32_e32 v57, v54, v51
	v_add_f32_e32 v61, v56, v57
	v_sub_f32_e32 v62, v58, v61
	v_sub_f32_e32 v56, v61, v56
	v_sub_f32_e32 v58, v58, v62
	v_sub_f32_e32 v56, v56, v57
	v_sub_f32_e32 v57, v58, v61
	v_add_f32_e32 v16, v16, v57
	v_add_f32_e32 v16, v56, v16
	v_add_f32_e32 v56, v62, v16
	v_mul_f32_e32 v57, v55, v56
	v_sub_f32_e32 v58, v62, v56
	v_mul_f32_e32 v61, v59, v57
	v_add_f32_e32 v16, v16, v58
	v_add_f32_e32 v58, v54, v57
	v_fma_f32 v59, v57, v59, -v61
	v_sub_f32_e32 v54, v58, v54
	v_fmac_f32_e32 v59, v57, v51
	v_sub_f32_e32 v51, v57, v54
	v_add_f32_e32 v54, v61, v59
	v_sub_f32_e32 v57, v54, v61
	v_sub_f32_e32 v61, v56, v54
	v_sub_f32_e32 v56, v56, v61
	v_sub_f32_e32 v54, v56, v54
	v_sub_f32_e32 v57, v57, v59
	v_add_f32_e32 v16, v16, v54
	v_add_f32_e32 v16, v57, v16
	v_add_f32_e32 v16, v61, v16
	v_mul_f32_e32 v16, v55, v16
	v_add_f32_e32 v16, v51, v16
	v_add_f32_e32 v51, v58, v16
	v_mul_f32_e32 v54, v51, v51
	v_fmamk_f32 v57, v54, 0x3e9b6dac, v127
	v_sub_f32_e32 v55, v51, v58
	v_ldexp_f32 v56, v51, 1
	v_mul_f32_e32 v51, v51, v54
	v_fmaak_f32 v54, v54, v57, 0x3f2aaada
	v_mul_f32_e32 v51, v51, v54
	v_add_f32_e32 v54, v56, v51
	v_sub_f32_e32 v16, v16, v55
	v_sub_f32_e32 v55, v54, v56
	v_ldexp_f32 v16, v16, 1
	v_sub_f32_e32 v51, v51, v55
	v_add_f32_e32 v16, v16, v51
	v_add_f32_e32 v51, v54, v16
	v_sub_f32_e32 v54, v51, v54
	v_add_f32_e32 v55, v60, v51
	v_sub_f32_e32 v16, v16, v54
	v_sub_f32_e32 v54, v55, v60
	v_sub_f32_e32 v56, v55, v54
	v_sub_f32_e32 v51, v51, v54
	v_add_f32_e32 v54, v53, v16
	v_sub_f32_e32 v56, v60, v56
	v_sub_f32_e32 v57, v54, v53
	v_add_f32_e32 v51, v51, v56
	v_sub_f32_e32 v56, v54, v57
	v_sub_f32_e32 v16, v16, v57
	v_sub_f32_e32 v53, v53, v56
	v_add_f32_e32 v51, v54, v51
	v_add_f32_e32 v16, v16, v53
	v_add_f32_e32 v53, v55, v51
	v_add_f32_e32 v33, v33, v49
	v_add_f32_e32 v34, v34, v49
	v_sub_f32_e32 v54, v53, v55
	v_mul_f32_e32 v33, 0xbfb8aa3b, v33
	v_mul_f32_e32 v34, 0xbfb8aa3b, v34
	v_sub_f32_e32 v51, v51, v54
	v_exp_f32_e32 v33, v33
	v_exp_f32_e32 v34, v34
	v_add_f32_e32 v16, v16, v51
	v_add_f32_e32 v16, v53, v16
	v_cmp_neq_f32_e32 vcc, s90, v50
	v_add_f32_e32 v33, 1.0, v33
	v_add_f32_e32 v34, 1.0, v34
	v_cndmask_b32_e32 v16, v130, v16, vcc
	v_cmp_ngt_f32_e32 vcc, -1.0, v50
	v_rcp_f32_e32 v33, v33
	v_rcp_f32_e32 v34, v34
	v_cndmask_b32_e32 v16, v131, v16, vcc
	v_cmp_neq_f32_e32 vcc, -1.0, v50
	v_add_f32_e32 v18, v18, v48
	v_mul_f32_e32 v18, 0xbfb8aa3b, v18
	v_cndmask_b32_e32 v16, v132, v16, vcc
	v_cmp_lt_f32_e64 vcc, |v50|, s91
	v_add_f32_e32 v19, v19, v48
	v_exp_f32_e32 v18, v18
	v_cndmask_b32_e32 v16, v16, v50, vcc
	v_mul_f32_e32 v50, 0xc1000000, v16
	v_mul_f32_e32 v16, v17, v50
	v_mul_f32_e32 v16, 0x3fb8aa3b, v16
	v_mul_f32_e32 v17, v33, v50
	v_exp_f32_e32 v33, v16
	v_mul_f32_e32 v16, v34, v50
	v_mul_f32_e32 v16, 0x3fb8aa3b, v16
	v_exp_f32_e32 v53, v16
	v_add_f32_e32 v16, v35, v49
	v_mul_f32_e32 v16, 0xbfb8aa3b, v16
	v_exp_f32_e32 v16, v16
	v_mul_f32_e32 v17, 0x3fb8aa3b, v17
	v_mul_f32_e32 v19, 0xbfb8aa3b, v19
	v_exp_f32_e32 v51, v17
	v_add_f32_e32 v16, 1.0, v16
	v_rcp_f32_e32 v16, v16
	v_exp_f32_e32 v19, v19
	v_add_f32_e32 v52, 1.0, v52
	v_add_f32_e32 v18, 1.0, v18
	v_mul_f32_e32 v16, v16, v50
	v_mul_f32_e32 v16, 0x3fb8aa3b, v16
	v_exp_f32_e32 v16, v16
	v_fma_f32 v35, -v53, v53, 1.0
	v_rcp_f32_e32 v17, v52
	v_fma_f32 v34, -v33, v33, 1.0
	v_fma_f32 v52, -v51, v51, 1.0
	v_rcp_f32_e32 v18, v18
	v_sqrt_f32_e32 v35, v35
	v_add_f32_e32 v19, 1.0, v19
	v_fma_f32 v54, -v16, v16, 1.0
	v_sqrt_f32_e32 v34, v34
	v_sqrt_f32_e32 v52, v52
	v_rcp_f32_e32 v19, v19
	v_sqrt_f32_e32 v54, v54
	v_mul_f32_e32 v35, v18, v35
	v_add_f32_e32 v18, v36, v49
	v_mul_f32_e32 v32, v32, v34
	v_mul_f32_e32 v34, v17, v52
	v_mul_f32_e32 v17, v19, v54
	v_mul_f32_e32 v18, 0xbfb8aa3b, v18
	v_add_f32_e32 v19, v20, v48
	v_exp_f32_e32 v18, v18
	v_mul_f32_e32 v19, 0xbfb8aa3b, v19
	v_exp_f32_e32 v19, v19
	v_mul_f32_e32 v3, v3, v17
	v_add_f32_e32 v17, 1.0, v18
	v_rcp_f32_e32 v17, v17
	v_add_f32_e32 v18, 1.0, v19
	v_add_f32_e32 v19, v37, v49
	v_mul_f32_e32 v19, 0xbfb8aa3b, v19
	v_exp_f32_e32 v19, v19
	v_mul_f32_e32 v17, v17, v50
	v_mul_f32_e32 v17, 0x3fb8aa3b, v17
	v_exp_f32_e32 v36, v17
	v_add_f32_e32 v17, 1.0, v19
	v_rcp_f32_e32 v17, v17
	v_add_f32_e32 v19, v21, v48
	v_mul_f32_e32 v19, 0xbfb8aa3b, v19
	v_exp_f32_e32 v19, v19
	v_mul_f32_e32 v17, v17, v50
	v_mul_f32_e32 v17, 0x3fb8aa3b, v17
	v_exp_f32_e32 v37, v17
	v_add_f32_e32 v17, v38, v49
	v_mul_f32_e32 v17, 0xbfb8aa3b, v17
	v_exp_f32_e32 v17, v17
	v_add_f32_e32 v23, v23, v48
	v_add_f32_e32 v19, 1.0, v19
	v_fma_f32 v21, -v37, v37, 1.0
	v_add_f32_e32 v17, 1.0, v17
	v_rcp_f32_e32 v17, v17
	v_mul_f32_e32 v23, 0xbfb8aa3b, v23
	v_fma_f32 v20, -v36, v36, 1.0
	v_rcp_f32_e32 v19, v19
	v_mul_f32_e32 v17, v17, v50
	v_mul_f32_e32 v17, 0x3fb8aa3b, v17
	v_exp_f32_e32 v38, v17
	v_add_f32_e32 v17, v39, v49
	v_mul_f32_e32 v17, 0xbfb8aa3b, v17
	v_exp_f32_e32 v17, v17
	v_sqrt_f32_e32 v21, v21
	v_exp_f32_e32 v23, v23
	v_rcp_f32_e32 v18, v18
	v_add_f32_e32 v17, 1.0, v17
	v_rcp_f32_e32 v17, v17
	v_sqrt_f32_e32 v20, v20
	v_add_f32_e32 v23, 1.0, v23
	v_mul_f32_e32 v55, v19, v21
	v_mul_f32_e32 v17, v17, v50
	v_mul_f32_e32 v17, 0x3fb8aa3b, v17
	v_exp_f32_e32 v17, v17
	v_add_f32_e32 v19, v40, v49
	v_rcp_f32_e32 v23, v23
	v_mul_f32_e32 v54, v18, v20
	v_fma_f32 v52, -v17, v17, 1.0
	v_sqrt_f32_e32 v52, v52
	v_mul_f32_e32 v19, 0xbfb8aa3b, v19
	v_add_f32_e32 v20, v24, v48
	v_add_f32_e32 v22, v22, v48
	v_exp_f32_e32 v19, v19
	v_mul_f32_e32 v20, 0xbfb8aa3b, v20
	v_mul_f32_e32 v22, 0xbfb8aa3b, v22
	v_exp_f32_e32 v20, v20
	v_exp_f32_e32 v22, v22
	v_mul_f32_e32 v18, v23, v52
	v_mul_f32_e32 v7, v7, v18
	v_add_f32_e32 v18, 1.0, v19
	v_rcp_f32_e32 v18, v18
	v_add_f32_e32 v19, 1.0, v20
	v_add_f32_e32 v20, v41, v49
	v_add_f32_e32 v22, 1.0, v22
	v_fma_f32 v39, -v38, v38, 1.0
	v_mul_f32_e32 v20, 0xbfb8aa3b, v20
	v_rcp_f32_e32 v22, v22
	v_sqrt_f32_e32 v39, v39
	v_exp_f32_e32 v20, v20
	v_mul_f32_e32 v18, v18, v50
	v_mul_f32_e32 v18, 0x3fb8aa3b, v18
	v_mul_f32_e32 v21, v22, v39
	v_exp_f32_e32 v39, v18
	v_add_f32_e32 v18, 1.0, v20
	v_rcp_f32_e32 v18, v18
	v_add_f32_e32 v20, v25, v48
	v_mul_f32_e32 v20, 0xbfb8aa3b, v20
	v_exp_f32_e32 v20, v20
	v_mul_f32_e32 v18, v18, v50
	v_mul_f32_e32 v18, 0x3fb8aa3b, v18
	v_exp_f32_e32 v40, v18
	v_add_f32_e32 v18, v42, v49
	v_mul_f32_e32 v18, 0xbfb8aa3b, v18
	v_exp_f32_e32 v18, v18
	v_add_f32_e32 v24, v26, v48
	v_add_f32_e32 v26, v27, v48
	v_add_f32_e32 v20, 1.0, v20
	v_add_f32_e32 v18, 1.0, v18
	v_rcp_f32_e32 v18, v18
	v_fma_f32 v23, -v40, v40, 1.0
	v_mul_f32_e32 v26, 0xbfb8aa3b, v26
	v_fma_f32 v22, -v39, v39, 1.0
	v_mul_f32_e32 v18, v18, v50
	v_mul_f32_e32 v18, 0x3fb8aa3b, v18
	v_exp_f32_e32 v41, v18
	v_add_f32_e32 v18, v43, v49
	v_mul_f32_e32 v18, 0xbfb8aa3b, v18
	v_exp_f32_e32 v18, v18
	v_rcp_f32_e32 v20, v20
	v_sqrt_f32_e32 v23, v23
	v_exp_f32_e32 v26, v26
	v_add_f32_e32 v18, 1.0, v18
	v_rcp_f32_e32 v18, v18
	v_rcp_f32_e32 v19, v19
	v_sqrt_f32_e32 v22, v22
	v_add_f32_e32 v26, 1.0, v26
	v_mul_f32_e32 v18, v18, v50
	v_mul_f32_e32 v18, 0x3fb8aa3b, v18
	v_exp_f32_e32 v18, v18
	v_mul_f32_e32 v43, v20, v23
	v_add_f32_e32 v20, v44, v49
	v_rcp_f32_e32 v26, v26
	v_fma_f32 v27, -v18, v18, 1.0
	v_sqrt_f32_e32 v27, v27
	v_mul_f32_e32 v42, v19, v22
	v_mul_f32_e32 v20, 0xbfb8aa3b, v20
	v_add_f32_e32 v22, v28, v48
	v_exp_f32_e32 v20, v20
	v_mul_f32_e32 v22, 0xbfb8aa3b, v22
	v_exp_f32_e32 v22, v22
	v_mul_f32_e32 v19, v26, v27
	v_mul_f32_e32 v11, v11, v19
	v_add_f32_e32 v19, 1.0, v20
	v_rcp_f32_e32 v19, v19
	v_add_f32_e32 v20, 1.0, v22
	v_add_f32_e32 v22, v45, v49
	v_mul_f32_e32 v22, 0xbfb8aa3b, v22
	v_exp_f32_e32 v22, v22
	v_mul_f32_e32 v19, v19, v50
	v_mul_f32_e32 v19, 0x3fb8aa3b, v19
	v_exp_f32_e32 v44, v19
	v_add_f32_e32 v19, 1.0, v22
	v_rcp_f32_e32 v19, v19
	v_mul_f32_e32 v24, 0xbfb8aa3b, v24
	v_exp_f32_e32 v24, v24
	v_add_f32_e32 v22, v29, v48
	v_mul_f32_e32 v19, v19, v50
	v_mul_f32_e32 v19, 0x3fb8aa3b, v19
	v_exp_f32_e32 v45, v19
	v_add_f32_e32 v19, v46, v49
	v_mul_f32_e32 v19, 0xbfb8aa3b, v19
	v_exp_f32_e32 v19, v19
	v_mul_f32_e32 v22, 0xbfb8aa3b, v22
	v_add_f32_e32 v24, 1.0, v24
	v_fma_f32 v25, -v41, v41, 1.0
	v_add_f32_e32 v19, 1.0, v19
	v_rcp_f32_e32 v19, v19
	v_exp_f32_e32 v22, v22
	v_rcp_f32_e32 v24, v24
	v_sqrt_f32_e32 v25, v25
	v_mul_f32_e32 v19, v19, v50
	v_mul_f32_e32 v19, 0x3fb8aa3b, v19
	v_exp_f32_e32 v46, v19
	v_add_f32_e32 v19, v47, v49
	v_mul_f32_e32 v19, 0xbfb8aa3b, v19
	v_add_f32_e32 v22, 1.0, v22
	v_exp_f32_e32 v19, v19
	v_mul_f32_e32 v52, v24, v25
	v_rcp_f32_e32 v24, v22
	v_fma_f32 v22, -v45, v45, 1.0
	v_sqrt_f32_e32 v25, v22
	v_add_f32_e32 v22, v30, v48
	v_mul_f32_e32 v22, 0xbfb8aa3b, v22
	v_exp_f32_e32 v22, v22
	v_add_f32_e32 v19, 1.0, v19
	v_rcp_f32_e32 v19, v19
	v_fma_f32 v27, -v46, v46, 1.0
	v_add_f32_e32 v22, 1.0, v22
	v_rcp_f32_e32 v26, v22
	v_add_f32_e32 v22, v31, v48
	v_mul_f32_e32 v19, v19, v50
	v_mul_f32_e32 v22, 0xbfb8aa3b, v22
	v_mul_f32_e32 v19, 0x3fb8aa3b, v19
	v_exp_f32_e32 v28, v22
	v_exp_f32_e32 v22, v19
	v_sqrt_f32_e32 v19, v27
	v_fma_f32 v23, -v44, v44, 1.0
	v_add_f32_e32 v27, 1.0, v28
	v_fma_f32 v28, -v22, v22, 1.0
	v_rcp_f32_e32 v27, v27
	v_sqrt_f32_e32 v28, v28
	v_rcp_f32_e32 v20, v20
	v_sqrt_f32_e32 v23, v23
	v_mul_f32_e32 v49, v26, v19
	v_mul_f32_e32 v19, v27, v28
	v_fmac_f32_e32 v7, 0, v17
	v_mul_f32_e32 v15, v15, v19
	v_mul_f32_e32 v19, v38, v7
	v_fmac_f32_e32 v19, v6, v21
	v_fmac_f32_e32 v3, 0, v16
	v_mul_f32_e32 v21, v37, v19
	v_mul_f32_e32 v47, v20, v23
	v_mul_f32_e32 v20, v53, v3
	v_fmac_f32_e32 v21, v5, v55
	v_fmac_f32_e32 v15, 0, v22
	v_mul_f32_e32 v48, v24, v25
	v_fmac_f32_e32 v20, v2, v35
	v_mul_f32_e32 v24, v36, v21
	v_fmac_f32_e32 v11, 0, v18
	v_mul_f32_e32 v2, v46, v15
	v_fmac_f32_e32 v24, v4, v54
	v_mul_f32_e32 v4, v41, v11
	v_fmac_f32_e32 v2, v14, v49
	v_fmac_f32_e32 v4, v10, v52
	v_mul_f32_e32 v5, v45, v2
	v_mul_f32_e32 v23, v51, v20
	v_mul_f32_e32 v6, v40, v4
	v_fmac_f32_e32 v5, v13, v48
	v_fmac_f32_e32 v23, v1, v34
	v_fmac_f32_e32 v6, v9, v43
	v_mul_f32_e32 v14, v22, v46
	v_mul_f32_e32 v9, v44, v5
	v_mul_f32_e32 v25, v33, v23
	v_mul_f32_e32 v13, v45, v14
	v_fmac_f32_e32 v9, v12, v47
	v_fmac_f32_e32 v25, v0, v32
	v_mul_f32_e32 v12, v44, v13
	ds_bpermute_b32 v0, v137, v9
	ds_bpermute_b32 v35, v137, v12
	v_mul_f32_e32 v28, v18, v41
	v_mul_f32_e32 v26, v16, v53
	v_mul_f32_e32 v27, v17, v38
	v_mul_f32_e32 v31, v40, v28
	v_mul_f32_e32 v10, v39, v6
	v_mul_f32_e32 v29, v51, v26
	v_mul_f32_e32 v30, v37, v27
	v_fmac_f32_e32 v10, v8, v42
	v_mul_f32_e32 v34, v39, v31
	v_mul_f32_e32 v32, v33, v29
	v_mul_f32_e32 v33, v36, v30
	s_waitcnt lgkmcnt(1)
	v_cndmask_b32_e64 v36, v0, v9, s[4:5]
	v_cndmask_b32_e64 v37, v9, v0, s[4:5]
	ds_bpermute_b32 v0, v137, v34
	ds_bpermute_b32 v40, v137, v10
	s_waitcnt lgkmcnt(2)
	v_cndmask_b32_e64 v8, v12, v35, s[4:5]
	v_fmac_f32_e32 v37, 0, v8
	ds_bpermute_b32 v8, v137, v33
	v_cndmask_b32_e64 v1, v35, v12, s[4:5]
	v_mul_f32_e32 v38, v12, v35
	v_fmac_f32_e32 v36, v1, v37
	s_waitcnt lgkmcnt(2)
	v_cndmask_b32_e64 v1, v0, v34, s[4:5]
	s_waitcnt lgkmcnt(1)
	v_cndmask_b32_e64 v39, v40, v10, s[4:5]
	v_cndmask_b32_e64 v0, v34, v0, s[4:5]
	v_cndmask_b32_e64 v40, v10, v40, s[4:5]
	ds_bpermute_b32 v44, v137, v24
	v_mul_f32_e32 v41, v38, v0
	v_fmac_f32_e32 v40, v0, v36
	v_mul_f32_e32 v42, v1, v41
	v_fmac_f32_e32 v39, v1, v40
	s_waitcnt lgkmcnt(1)
	v_cndmask_b32_e64 v0, v8, v33, s[4:5]
	v_cndmask_b32_e64 v1, v33, v8, s[4:5]
	ds_bpermute_b32 v8, v137, v32
	ds_bpermute_b32 v47, v137, v25
	s_waitcnt lgkmcnt(2)
	v_cndmask_b32_e64 v43, v44, v24, s[4:5]
	v_cndmask_b32_e64 v44, v24, v44, s[4:5]
	v_mul_f32_e32 v45, v1, v42
	v_fmac_f32_e32 v44, v1, v39
	v_mul_f32_e32 v46, v0, v45
	v_fmac_f32_e32 v43, v0, v44
	s_waitcnt lgkmcnt(1)
	v_cndmask_b32_e64 v0, v32, v8, s[4:5]
	s_waitcnt lgkmcnt(0)
	v_cndmask_b32_e64 v47, v25, v47, s[4:5]
	v_mul_f32_e32 v48, v0, v46
	v_fmac_f32_e32 v47, v0, v43
	s_and_saveexec_b64 s[12:13], s[4:5]
	v_mul_f32_e32 v0, v32, v48
	v_fma_f32 v1, v32, v47, v25
	ds_write_b64 v136, v[0:1] offset:6144
	s_or_b64 exec, exec, s[12:13]
	s_and_b64 vcc, exec, s[8:9]
	s_waitcnt lgkmcnt(0)
	s_barrier
	s_cbranch_vccnz .LBB0_293
	v_add3_u32 v49, v140, v91, s95
	v_mov_b32_e32 v8, 1.0
	v_mov_b32_e32 v1, 0
	s_mov_b32 s8, 7

.LBB0_320:
	s_and_b32 s63, s57, 63
	s_ashr_i32 s62, s89, 6
	s_lshl_b32 s0, s63, 8
	s_lshl_b32 s1, s62, 5
	v_and_b32_e32 v94, 31, v92
	s_add_i32 s8, s1, s0
	v_or_b32_e32 v9, s8, v94
	v_add_u32_e32 v0, -2, v9
	v_cmp_gt_u32_e32 vcc, s80, v0
	v_bfe_u32 v93, v92, 5, 1
	s_lshl_b32 s14, s70, 1
	v_cndmask_b32_e32 v2, v9, v0, vcc
	v_mov_b64_e32 v[0:1], s[52:53]
	v_mad_i64_i32 v[2:3], s[0:1], v2, s81, v[0:1]
	v_lshl_add_u64 v[2:3], v[2:3], 0, s[14:15]
	v_lshlrev_b32_e32 v88, 4, v93
	v_lshl_add_u64 v[4:5], v[2:3], 0, v[88:89]
	v_add_co_u32_e64 v2, s[0:1], s82, v4
	s_waitcnt lgkmcnt(0)
	s_nop 0
	v_addc_co_u32_e64 v3, s[0:1], 0, v5, s[0:1]
	s_barrier
	global_load_dwordx4 v[10:13], v[2:3], off offset:1024
	global_load_dwordx4 v[178:181], v[2:3], off offset:1056
	global_load_dwordx4 v[194:197], v[2:3], off offset:1088
	global_load_dwordx4 v[210:213], v[2:3], off offset:1120
	global_load_dwordx4 v[226:229], v[2:3], off offset:1152
	global_load_dwordx4 v[242:245], v[2:3], off offset:1184
	v_add_u32_e32 v2, -1, v9
	v_cmp_gt_u32_e64 s[0:1], s80, v2
	v_add_u32_e32 v18, 1, v9
	s_cmpk_lt_u32 s8, 0x4000
	v_cndmask_b32_e64 v2, v9, v2, s[0:1]
	v_mad_i64_i32 v[2:3], s[4:5], v2, s81, v[0:1]
	v_lshl_add_u64 v[2:3], v[2:3], 0, s[14:15]
	v_lshl_add_u64 v[2:3], v[2:3], 0, v[88:89]
	v_add_co_u32_e64 v6, s[4:5], s82, v2
	v_lshlrev_b32_e32 v138, 8, v94
	s_nop 0
	v_addc_co_u32_e64 v7, s[4:5], 0, v3, s[4:5]
	global_load_dwordx4 v[14:17], v[6:7], off offset:1024
	global_load_dwordx4 v[182:185], v[6:7], off offset:1056
	global_load_dwordx4 v[198:201], v[6:7], off offset:1088
	global_load_dwordx4 v[214:217], v[6:7], off offset:1120
	global_load_dwordx4 v[230:233], v[6:7], off offset:1152
	global_load_dwordx4 v[246:249], v[6:7], off offset:1184
	v_mad_i64_i32 v[6:7], s[4:5], v9, s81, v[0:1]
	v_cmp_gt_u32_e64 s[4:5], s80, v18
	v_lshl_add_u64 v[6:7], v[6:7], 0, s[14:15]
	v_lshl_add_u64 v[52:53], v[6:7], 0, v[88:89]
	v_cndmask_b32_e64 v9, v9, v18, s[4:5]
	v_mad_i64_i32 v[0:1], s[6:7], v9, s81, v[0:1]
	v_add_co_u32_e64 v6, s[6:7], s82, v52
	v_lshl_add_u64 v[0:1], v[0:1], 0, s[14:15]
	s_nop 0
	v_addc_co_u32_e64 v7, s[6:7], 0, v53, s[6:7]
	global_load_dwordx4 v[18:21], v[6:7], off offset:1024
	global_load_dwordx4 v[186:189], v[6:7], off offset:1056
	global_load_dwordx4 v[202:205], v[6:7], off offset:1088
	global_load_dwordx4 v[218:221], v[6:7], off offset:1120
	global_load_dwordx4 v[234:237], v[6:7], off offset:1152
	global_load_dwordx4 v[252:255], v[6:7], off offset:1184
	v_lshl_add_u64 v[6:7], v[0:1], 0, v[88:89]
	v_add_co_u32_e64 v0, s[6:7], s82, v6
	v_lshl_add_u32 v9, v93, 5, 16
	s_nop 0
	v_addc_co_u32_e64 v1, s[6:7], 0, v7, s[6:7]
	global_load_dwordx4 v[22:25], v[0:1], off offset:1024
	global_load_dwordx4 v[190:193], v[0:1], off offset:1056
	global_load_dwordx4 v[206:209], v[0:1], off offset:1088
	global_load_dwordx4 v[222:225], v[0:1], off offset:1120
	global_load_dwordx4 v[238:241], v[0:1], off offset:1152
	global_load_dwordx4 v[168:171], v[0:1], off offset:1184
	ds_read_b128 v[26:29], v9 offset:8192
	s_waitcnt vmcnt(26)
	ds_read_b128 v[30:33], v9 offset:8704
	ds_read_b128 v[34:37], v9 offset:10240
	ds_read_b128 v[38:41], v9 offset:10256
	ds_read_b128 v[42:45], v9 offset:8208
	ds_read_b128 v[46:49], v9 offset:8720
	s_waitcnt lgkmcnt(4)
	v_mov_b32_e32 v51, v30
	v_mov_b32_e32 v30, v27
	v_mov_b32_e32 v27, v32
	v_mov_b32_e32 v50, v26
	v_lshl_add_u64 v[0:1], v[4:5], 0, s[30:31]
	v_mov_b32_e32 v26, v28
	s_cselect_b64 s[6:7], -1, 0
	v_lshl_add_u64 v[6:7], v[6:7], 0, s[30:31]
	v_and_b32_e32 v8, 0x70, v8
	v_add_u32_e32 v95, 16, v138
	v_or_b32_e32 v91, s70, v94
	s_waitcnt vmcnt(23)
	v_cndmask_b32_e32 v32, 0, v11, vcc
	v_cndmask_b32_e32 v10, 0, v10, vcc
	v_lshlrev_b32_e32 v4, 16, v10
	v_and_b32_e32 v10, 0xffff0000, v10
	v_cndmask_b32_e32 v54, 0, v12, vcc
	v_lshlrev_b32_e32 v12, 16, v32
	v_cndmask_b32_e32 v28, 0, v13, vcc
	s_waitcnt vmcnt(17)
	v_cndmask_b32_e64 v11, 0, v14, s[0:1]
	v_lshlrev_b32_e32 v5, 16, v11
	v_pk_mul_f32 v[4:5], v[50:51], v[4:5]
	v_cndmask_b32_e64 v15, 0, v15, s[0:1]
	v_and_b32_e32 v11, 0xffff0000, v11
	s_waitcnt lgkmcnt(3)
	v_add_f32_e32 v4, v34, v4
	v_pk_mul_f32 v[10:11], v[30:31], v[10:11]
	v_add_f32_e32 v30, v4, v5
	v_and_b32_e32 v5, 0xffff0000, v15
	v_and_b32_e32 v4, 0xffff0000, v32
	v_mov_b32_e32 v32, v29
	v_pk_mul_f32 v[4:5], v[32:33], v[4:5]
	v_cndmask_b32_e64 v16, 0, v16, s[0:1]
	v_add_f32_e32 v10, v35, v10
	v_add_f32_e32 v4, v37, v4
	v_add_f32_e32 v31, v10, v11
	v_add_f32_e32 v29, v4, v5
	v_lshlrev_b32_e32 v5, 16, v16
	v_lshlrev_b32_e32 v4, 16, v54
	s_waitcnt lgkmcnt(1)
	v_mov_b32_e32 v10, v42
	s_waitcnt lgkmcnt(0)
	v_mov_b32_e32 v11, v46
	v_pk_mul_f32 v[4:5], v[10:11], v[4:5]
	v_mov_b32_e32 v46, v43
	v_add_f32_e32 v4, v38, v4
	v_add_f32_e32 v32, v4, v5
	v_and_b32_e32 v5, 0xffff0000, v16
	v_and_b32_e32 v4, 0xffff0000, v54
	v_pk_mul_f32 v[4:5], v[46:47], v[4:5]
	v_cndmask_b32_e64 v17, 0, v17, s[0:1]
	v_add_f32_e32 v4, v39, v4
	v_add_f32_e32 v33, v4, v5
	v_lshlrev_b32_e32 v5, 16, v17
	v_lshlrev_b32_e32 v4, 16, v28
	v_mov_b32_e32 v10, v44
	v_mov_b32_e32 v11, v48
	v_pk_mul_f32 v[4:5], v[10:11], v[4:5]
	v_lshlrev_b32_e32 v13, 16, v15
	v_add_f32_e32 v4, v40, v4
	v_pk_mul_f32 v[12:13], v[26:27], v[12:13]
	v_add_f32_e32 v35, v4, v5
	v_and_b32_e32 v5, 0xffff0000, v17
	v_and_b32_e32 v4, 0xffff0000, v28
	v_mov_b32_e32 v48, v45
	v_add_f32_e32 v12, v36, v12
	v_pk_mul_f32 v[4:5], v[48:49], v[4:5]
	v_add_f32_e32 v34, v12, v13
	v_add_f32_e32 v4, v41, v4
	s_waitcnt vmcnt(11)
	v_cndmask_b32_e64 v36, 0, v21, s[6:7]
	v_cndmask_b32_e64 v37, 0, v20, s[6:7]
	v_cndmask_b32_e64 v38, 0, v19, s[6:7]
	v_cndmask_b32_e64 v39, 0, v18, s[6:7]
	ds_read_b128 v[10:13], v9 offset:9216
	ds_read_b128 v[14:17], v9 offset:9232
	s_waitcnt vmcnt(5)
	v_cndmask_b32_e64 v40, 0, v25, s[4:5]
	v_cndmask_b32_e64 v41, 0, v24, s[4:5]
	v_cndmask_b32_e64 v42, 0, v23, s[4:5]
	v_cndmask_b32_e64 v43, 0, v22, s[4:5]
	ds_read_b128 v[18:21], v9 offset:9728
	ds_read_b128 v[22:25], v9 offset:9744
	v_add_f32_e32 v28, v4, v5
	v_lshlrev_b32_e32 v5, 16, v43
	v_lshlrev_b32_e32 v4, 16, v39
	s_waitcnt lgkmcnt(3)
	v_mov_b32_e32 v26, v10
	s_waitcnt lgkmcnt(1)
	v_mov_b32_e32 v27, v18
	v_pk_mul_f32 v[4:5], v[26:27], v[4:5]
	v_mov_b32_e32 v18, v11
	v_add_f32_e32 v4, v30, v4
	v_add_f32_e32 v26, v4, v5
	v_and_b32_e32 v5, 0xffff0000, v43
	v_and_b32_e32 v4, 0xffff0000, v39
	v_pk_mul_f32 v[4:5], v[18:19], v[4:5]
	v_mov_b32_e32 v10, v12
	v_add_f32_e32 v4, v31, v4
	v_add_f32_e32 v18, v4, v5
	v_lshlrev_b32_e32 v5, 16, v42
	v_lshlrev_b32_e32 v4, 16, v38
	v_mov_b32_e32 v11, v20
	v_pk_mul_f32 v[4:5], v[10:11], v[4:5]
	v_mov_b32_e32 v20, v13
	v_add_f32_e32 v4, v34, v4
	v_add_f32_e32 v12, v4, v5
	v_and_b32_e32 v5, 0xffff0000, v42
	v_and_b32_e32 v4, 0xffff0000, v38
	v_pk_mul_f32 v[4:5], v[20:21], v[4:5]
	v_mov_b32_e32 v10, v14
	v_add_f32_e32 v4, v29, v4
	v_add_f32_e32 v13, v4, v5
	v_lshlrev_b32_e32 v5, 16, v41
	v_lshlrev_b32_e32 v4, 16, v37
	s_waitcnt lgkmcnt(0)
	v_mov_b32_e32 v11, v22
	v_pk_mul_f32 v[4:5], v[10:11], v[4:5]
	v_mov_b32_e32 v22, v15
	v_add_f32_e32 v4, v32, v4
	v_add_f32_e32 v14, v4, v5
	v_and_b32_e32 v5, 0xffff0000, v41
	v_and_b32_e32 v4, 0xffff0000, v37
	v_pk_mul_f32 v[4:5], v[22:23], v[4:5]
	v_mov_b32_e32 v10, v16
	v_add_f32_e32 v4, v33, v4
	v_add_f32_e32 v15, v4, v5
	v_lshlrev_b32_e32 v5, 16, v40
	v_lshlrev_b32_e32 v4, 16, v36
	v_mov_b32_e32 v11, v24
	v_pk_mul_f32 v[4:5], v[10:11], v[4:5]
	v_mov_b32_e32 v24, v17
	v_add_f32_e32 v4, v35, v4
	v_add_f32_e32 v10, v4, v5
	v_and_b32_e32 v5, 0xffff0000, v40
	v_and_b32_e32 v4, 0xffff0000, v36
	v_pk_mul_f32 v[4:5], v[24:25], v[4:5]
	v_cvt_pk_bf16_f32 v48, v26, v18
	v_cvt_pk_bf16_f32 v49, v12, v13
	v_cvt_pk_bf16_f32 v50, v14, v15
	s_nop 0
	v_add_f32_e32 v4, v28, v4
	v_add_f32_e32 v4, v4, v5
	v_cvt_pk_bf16_f32 v51, v10, v4
	v_lshl_add_u64 v[4:5], v[2:3], 0, s[30:31]
	v_lshl_add_u64 v[2:3], v[52:53], 0, s[30:31]
	ds_read_b128 v[26:29], v9 offset:10304
	ds_read_b128 v[30:33], v9 offset:10320
	s_waitcnt vmcnt(4)
	v_cndmask_b32_e32 v46, 0, v181, vcc
	v_cndmask_b32_e32 v47, 0, v180, vcc
	v_cndmask_b32_e32 v52, 0, v179, vcc
	v_cndmask_b32_e32 v53, 0, v178, vcc
	ds_read_b128 v[10:13], v9 offset:8256
	ds_read_b128 v[34:37], v9 offset:8272
	s_waitcnt vmcnt(4)
	v_cndmask_b32_e64 v54, 0, v185, s[0:1]
	v_cndmask_b32_e64 v55, 0, v184, s[0:1]
	v_cndmask_b32_e64 v56, 0, v183, s[0:1]
	v_cndmask_b32_e64 v57, 0, v182, s[0:1]
	ds_read_b128 v[14:17], v9 offset:8768
	ds_read_b128 v[38:41], v9 offset:8784
	v_lshlrev_b32_e32 v43, 16, v57
	v_lshlrev_b32_e32 v42, 16, v53
	s_waitcnt lgkmcnt(3)
	v_mov_b32_e32 v44, v10
	s_waitcnt lgkmcnt(1)
	v_mov_b32_e32 v45, v14
	v_pk_mul_f32 v[42:43], v[44:45], v[42:43]
	v_mov_b32_e32 v14, v11
	v_add_f32_e32 v10, v26, v42
	v_add_f32_e32 v44, v10, v43
	v_and_b32_e32 v43, 0xffff0000, v57
	v_and_b32_e32 v42, 0xffff0000, v53
	v_pk_mul_f32 v[10:11], v[14:15], v[42:43]
	v_mov_b32_e32 v14, v12
	v_add_f32_e32 v10, v27, v10
	v_add_f32_e32 v42, v10, v11
	v_lshlrev_b32_e32 v11, 16, v56
	v_lshlrev_b32_e32 v10, 16, v52
	v_mov_b32_e32 v15, v16
	v_pk_mul_f32 v[10:11], v[14:15], v[10:11]
	v_mov_b32_e32 v16, v13
	v_add_f32_e32 v10, v28, v10
	v_add_f32_e32 v43, v10, v11
	v_and_b32_e32 v11, 0xffff0000, v56
	v_and_b32_e32 v10, 0xffff0000, v52
	v_pk_mul_f32 v[10:11], v[16:17], v[10:11]
	v_mov_b32_e32 v12, v34
	v_add_f32_e32 v10, v29, v10
	v_add_f32_e32 v45, v10, v11
	v_lshlrev_b32_e32 v11, 16, v55
	v_lshlrev_b32_e32 v10, 16, v47
	s_waitcnt lgkmcnt(0)
	v_mov_b32_e32 v13, v38
	v_pk_mul_f32 v[10:11], v[12:13], v[10:11]
	v_mov_b32_e32 v38, v35
	v_add_f32_e32 v10, v30, v10
	v_add_f32_e32 v30, v10, v11
	v_and_b32_e32 v11, 0xffff0000, v55
	v_and_b32_e32 v10, 0xffff0000, v47
	v_pk_mul_f32 v[10:11], v[38:39], v[10:11]
	v_mov_b32_e32 v12, v36
	v_add_f32_e32 v10, v31, v10
	v_add_f32_e32 v31, v10, v11
	v_lshlrev_b32_e32 v11, 16, v54
	v_lshlrev_b32_e32 v10, 16, v46
	v_mov_b32_e32 v13, v40
	v_pk_mul_f32 v[10:11], v[12:13], v[10:11]
	v_mov_b32_e32 v40, v37
	v_add_f32_e32 v10, v32, v10
	v_add_f32_e32 v32, v10, v11
	v_and_b32_e32 v11, 0xffff0000, v54
	v_and_b32_e32 v10, 0xffff0000, v46
	v_pk_mul_f32 v[10:11], v[40:41], v[10:11]
	s_waitcnt vmcnt(4)
	v_cndmask_b32_e64 v34, 0, v189, s[6:7]
	v_add_f32_e32 v10, v33, v10
	v_add_f32_e32 v33, v10, v11
	v_cndmask_b32_e64 v35, 0, v188, s[6:7]
	v_cndmask_b32_e64 v36, 0, v187, s[6:7]
	v_cndmask_b32_e64 v37, 0, v186, s[6:7]
	ds_read_b128 v[10:13], v9 offset:9280
	ds_read_b128 v[14:17], v9 offset:9296
	v_cndmask_b32_e64 v38, 0, v193, s[4:5]
	v_cndmask_b32_e64 v39, 0, v192, s[4:5]
	v_cndmask_b32_e64 v40, 0, v191, s[4:5]
	v_cndmask_b32_e64 v41, 0, v190, s[4:5]
	ds_read_b128 v[18:21], v9 offset:9792
	ds_read_b128 v[22:25], v9 offset:9808
	v_lshlrev_b32_e32 v27, 16, v41
	v_lshlrev_b32_e32 v26, 16, v37
	s_waitcnt lgkmcnt(3)
	v_mov_b32_e32 v28, v10
	s_waitcnt lgkmcnt(1)
	v_mov_b32_e32 v29, v18
	v_pk_mul_f32 v[26:27], v[28:29], v[26:27]
	v_mov_b32_e32 v18, v11
	v_add_f32_e32 v10, v44, v26
	v_add_f32_e32 v28, v10, v27
	v_and_b32_e32 v27, 0xffff0000, v41
	v_and_b32_e32 v26, 0xffff0000, v37
	v_pk_mul_f32 v[10:11], v[18:19], v[26:27]
	v_mov_b32_e32 v18, v12
	v_add_f32_e32 v10, v42, v10
	v_add_f32_e32 v26, v10, v11
	v_lshlrev_b32_e32 v11, 16, v40
	v_lshlrev_b32_e32 v10, 16, v36
	v_mov_b32_e32 v19, v20
	v_pk_mul_f32 v[10:11], v[18:19], v[10:11]
	v_mov_b32_e32 v20, v13
	v_add_f32_e32 v10, v43, v10
	v_add_f32_e32 v18, v10, v11
	v_and_b32_e32 v11, 0xffff0000, v40
	v_and_b32_e32 v10, 0xffff0000, v36
	v_pk_mul_f32 v[10:11], v[20:21], v[10:11]
	v_mov_b32_e32 v12, v14
	v_add_f32_e32 v10, v45, v10
	v_add_f32_e32 v19, v10, v11
	v_lshlrev_b32_e32 v11, 16, v39
	v_lshlrev_b32_e32 v10, 16, v35
	s_waitcnt lgkmcnt(0)
	v_mov_b32_e32 v13, v22
	v_pk_mul_f32 v[10:11], v[12:13], v[10:11]
	v_mov_b32_e32 v22, v15
	v_add_f32_e32 v10, v30, v10
	v_add_f32_e32 v14, v10, v11
	v_and_b32_e32 v11, 0xffff0000, v39
	v_and_b32_e32 v10, 0xffff0000, v35
	v_pk_mul_f32 v[10:11], v[22:23], v[10:11]
	v_mov_b32_e32 v12, v16
	v_add_f32_e32 v10, v31, v10
	v_add_f32_e32 v15, v10, v11
	v_lshlrev_b32_e32 v11, 16, v38
	v_lshlrev_b32_e32 v10, 16, v34
	v_mov_b32_e32 v13, v24
	v_pk_mul_f32 v[10:11], v[12:13], v[10:11]
	v_mov_b32_e32 v24, v17
	v_add_f32_e32 v10, v32, v10
	v_add_f32_e32 v12, v10, v11
	v_and_b32_e32 v11, 0xffff0000, v38
	v_and_b32_e32 v10, 0xffff0000, v34
	v_pk_mul_f32 v[10:11], v[24:25], v[10:11]
	v_cvt_pk_bf16_f32 v52, v28, v26
	v_cvt_pk_bf16_f32 v53, v18, v19
	v_cvt_pk_bf16_f32 v54, v14, v15
	s_nop 0
	v_add_f32_e32 v10, v33, v10
	v_add_f32_e32 v10, v10, v11
	v_cvt_pk_bf16_f32 v55, v12, v10
	global_load_dwordx4 v[178:181], v[0:1], off offset:192
	global_load_dwordx4 v[182:185], v[4:5], off offset:192
	global_load_dwordx4 v[186:189], v[2:3], off offset:192
	global_load_dwordx4 v[190:193], v[6:7], off offset:192
	ds_read_b128 v[26:29], v9 offset:10368
	ds_read_b128 v[30:33], v9 offset:10384
	s_waitcnt vmcnt(7)
	v_cndmask_b32_e32 v46, 0, v197, vcc
	v_cndmask_b32_e32 v47, 0, v196, vcc
	v_cndmask_b32_e32 v56, 0, v195, vcc
	v_cndmask_b32_e32 v57, 0, v194, vcc
	ds_read_b128 v[10:13], v9 offset:8320
	ds_read_b128 v[34:37], v9 offset:8336
	s_waitcnt vmcnt(7)
	v_cndmask_b32_e64 v58, 0, v201, s[0:1]
	v_cndmask_b32_e64 v59, 0, v200, s[0:1]
	v_cndmask_b32_e64 v60, 0, v199, s[0:1]
	v_cndmask_b32_e64 v61, 0, v198, s[0:1]
	ds_read_b128 v[14:17], v9 offset:8832
	ds_read_b128 v[38:41], v9 offset:8848
	v_lshlrev_b32_e32 v43, 16, v61
	v_lshlrev_b32_e32 v42, 16, v57
	s_waitcnt lgkmcnt(3)
	v_mov_b32_e32 v44, v10
	s_waitcnt lgkmcnt(1)
	v_mov_b32_e32 v45, v14
	v_pk_mul_f32 v[42:43], v[44:45], v[42:43]
	v_mov_b32_e32 v14, v11
	v_add_f32_e32 v10, v26, v42
	v_add_f32_e32 v44, v10, v43
	v_and_b32_e32 v43, 0xffff0000, v61
	v_and_b32_e32 v42, 0xffff0000, v57
	v_pk_mul_f32 v[10:11], v[14:15], v[42:43]
	v_mov_b32_e32 v14, v12
	v_add_f32_e32 v10, v27, v10
	v_add_f32_e32 v42, v10, v11
	v_lshlrev_b32_e32 v11, 16, v60
	v_lshlrev_b32_e32 v10, 16, v56
	v_mov_b32_e32 v15, v16
	v_pk_mul_f32 v[10:11], v[14:15], v[10:11]
	v_mov_b32_e32 v16, v13
	v_add_f32_e32 v10, v28, v10
	v_add_f32_e32 v43, v10, v11
	v_and_b32_e32 v11, 0xffff0000, v60
	v_and_b32_e32 v10, 0xffff0000, v56
	v_pk_mul_f32 v[10:11], v[16:17], v[10:11]
	v_mov_b32_e32 v12, v34
	v_add_f32_e32 v10, v29, v10
	v_add_f32_e32 v45, v10, v11
	v_lshlrev_b32_e32 v11, 16, v59
	v_lshlrev_b32_e32 v10, 16, v47
	s_waitcnt lgkmcnt(0)
	v_mov_b32_e32 v13, v38
	v_pk_mul_f32 v[10:11], v[12:13], v[10:11]
	v_mov_b32_e32 v38, v35
	v_add_f32_e32 v10, v30, v10
	v_add_f32_e32 v30, v10, v11
	v_and_b32_e32 v11, 0xffff0000, v59
	v_and_b32_e32 v10, 0xffff0000, v47
	v_pk_mul_f32 v[10:11], v[38:39], v[10:11]
	v_mov_b32_e32 v12, v36
	v_add_f32_e32 v10, v31, v10
	v_add_f32_e32 v31, v10, v11
	v_lshlrev_b32_e32 v11, 16, v58
	v_lshlrev_b32_e32 v10, 16, v46
	v_mov_b32_e32 v13, v40
	v_pk_mul_f32 v[10:11], v[12:13], v[10:11]
	v_mov_b32_e32 v40, v37
	v_add_f32_e32 v10, v32, v10
	v_add_f32_e32 v32, v10, v11
	v_and_b32_e32 v11, 0xffff0000, v58
	v_and_b32_e32 v10, 0xffff0000, v46
	v_pk_mul_f32 v[10:11], v[40:41], v[10:11]
	s_waitcnt vmcnt(7)
	v_cndmask_b32_e64 v34, 0, v205, s[6:7]
	v_add_f32_e32 v10, v33, v10
	v_add_f32_e32 v33, v10, v11
	v_cndmask_b32_e64 v35, 0, v204, s[6:7]
	v_cndmask_b32_e64 v36, 0, v203, s[6:7]
	v_cndmask_b32_e64 v37, 0, v202, s[6:7]
	ds_read_b128 v[10:13], v9 offset:9344
	ds_read_b128 v[14:17], v9 offset:9360
	s_waitcnt vmcnt(7)
	v_cndmask_b32_e64 v38, 0, v209, s[4:5]
	v_cndmask_b32_e64 v39, 0, v208, s[4:5]
	v_cndmask_b32_e64 v40, 0, v207, s[4:5]
	v_cndmask_b32_e64 v41, 0, v206, s[4:5]
	ds_read_b128 v[18:21], v9 offset:9856
	ds_read_b128 v[22:25], v9 offset:9872
	v_lshlrev_b32_e32 v27, 16, v41
	v_lshlrev_b32_e32 v26, 16, v37
	s_waitcnt lgkmcnt(3)
	v_mov_b32_e32 v28, v10
	s_waitcnt lgkmcnt(1)
	v_mov_b32_e32 v29, v18
	v_pk_mul_f32 v[26:27], v[28:29], v[26:27]
	v_mov_b32_e32 v18, v11
	v_add_f32_e32 v10, v44, v26
	v_add_f32_e32 v28, v10, v27
	v_and_b32_e32 v27, 0xffff0000, v41
	v_and_b32_e32 v26, 0xffff0000, v37
	v_pk_mul_f32 v[10:11], v[18:19], v[26:27]
	v_mov_b32_e32 v18, v12
	v_add_f32_e32 v10, v42, v10
	v_add_f32_e32 v26, v10, v11
	v_lshlrev_b32_e32 v11, 16, v40
	v_lshlrev_b32_e32 v10, 16, v36
	v_mov_b32_e32 v19, v20
	v_pk_mul_f32 v[10:11], v[18:19], v[10:11]
	v_mov_b32_e32 v20, v13
	v_add_f32_e32 v10, v43, v10
	v_add_f32_e32 v18, v10, v11
	v_and_b32_e32 v11, 0xffff0000, v40
	v_and_b32_e32 v10, 0xffff0000, v36
	v_pk_mul_f32 v[10:11], v[20:21], v[10:11]
	v_mov_b32_e32 v12, v14
	v_add_f32_e32 v10, v45, v10
	v_add_f32_e32 v19, v10, v11
	v_lshlrev_b32_e32 v11, 16, v39
	v_lshlrev_b32_e32 v10, 16, v35
	s_waitcnt lgkmcnt(0)
	v_mov_b32_e32 v13, v22
	v_pk_mul_f32 v[10:11], v[12:13], v[10:11]
	v_mov_b32_e32 v22, v15
	v_add_f32_e32 v10, v30, v10
	v_add_f32_e32 v14, v10, v11
	v_and_b32_e32 v11, 0xffff0000, v39
	v_and_b32_e32 v10, 0xffff0000, v35
	v_pk_mul_f32 v[10:11], v[22:23], v[10:11]
	v_mov_b32_e32 v12, v16
	v_add_f32_e32 v10, v31, v10
	v_add_f32_e32 v15, v10, v11
	v_lshlrev_b32_e32 v11, 16, v38
	v_lshlrev_b32_e32 v10, 16, v34
	v_mov_b32_e32 v13, v24
	v_pk_mul_f32 v[10:11], v[12:13], v[10:11]
	v_mov_b32_e32 v24, v17
	v_add_f32_e32 v10, v32, v10
	v_add_f32_e32 v12, v10, v11
	v_and_b32_e32 v11, 0xffff0000, v38
	v_and_b32_e32 v10, 0xffff0000, v34
	v_pk_mul_f32 v[10:11], v[24:25], v[10:11]
	v_cvt_pk_bf16_f32 v56, v28, v26
	v_cvt_pk_bf16_f32 v57, v18, v19
	v_cvt_pk_bf16_f32 v58, v14, v15
	s_nop 0
	v_add_f32_e32 v10, v33, v10
	v_add_f32_e32 v10, v10, v11
	v_cvt_pk_bf16_f32 v59, v12, v10
	global_load_dwordx4 v[194:197], v[0:1], off offset:224
	global_load_dwordx4 v[198:201], v[4:5], off offset:224
	global_load_dwordx4 v[202:205], v[2:3], off offset:224
	global_load_dwordx4 v[206:209], v[6:7], off offset:224
	ds_read_b128 v[26:29], v9 offset:10432
	ds_read_b128 v[30:33], v9 offset:10448
	s_waitcnt vmcnt(10)
	v_cndmask_b32_e32 v46, 0, v213, vcc
	v_cndmask_b32_e32 v47, 0, v212, vcc
	v_cndmask_b32_e32 v60, 0, v211, vcc
	v_cndmask_b32_e32 v61, 0, v210, vcc
	ds_read_b128 v[10:13], v9 offset:8384
	ds_read_b128 v[34:37], v9 offset:8400
	s_waitcnt vmcnt(10)
	v_cndmask_b32_e64 v62, 0, v217, s[0:1]
	v_cndmask_b32_e64 v63, 0, v216, s[0:1]
	v_cndmask_b32_e64 v64, 0, v215, s[0:1]
	v_cndmask_b32_e64 v65, 0, v214, s[0:1]
	ds_read_b128 v[14:17], v9 offset:8896
	ds_read_b128 v[38:41], v9 offset:8912
	v_lshlrev_b32_e32 v43, 16, v65
	v_lshlrev_b32_e32 v42, 16, v61
	s_waitcnt lgkmcnt(3)
	v_mov_b32_e32 v44, v10
	s_waitcnt lgkmcnt(1)
	v_mov_b32_e32 v45, v14
	v_pk_mul_f32 v[42:43], v[44:45], v[42:43]
	v_mov_b32_e32 v14, v11
	v_add_f32_e32 v10, v26, v42
	v_add_f32_e32 v44, v10, v43
	v_and_b32_e32 v43, 0xffff0000, v65
	v_and_b32_e32 v42, 0xffff0000, v61
	v_pk_mul_f32 v[10:11], v[14:15], v[42:43]
	v_mov_b32_e32 v14, v12
	v_add_f32_e32 v10, v27, v10
	v_add_f32_e32 v42, v10, v11
	v_lshlrev_b32_e32 v11, 16, v64
	v_lshlrev_b32_e32 v10, 16, v60
	v_mov_b32_e32 v15, v16
	v_pk_mul_f32 v[10:11], v[14:15], v[10:11]
	v_mov_b32_e32 v16, v13
	v_add_f32_e32 v10, v28, v10
	v_add_f32_e32 v43, v10, v11
	v_and_b32_e32 v11, 0xffff0000, v64
	v_and_b32_e32 v10, 0xffff0000, v60
	v_pk_mul_f32 v[10:11], v[16:17], v[10:11]
	v_mov_b32_e32 v12, v34
	v_add_f32_e32 v10, v29, v10
	v_add_f32_e32 v45, v10, v11
	v_lshlrev_b32_e32 v11, 16, v63
	v_lshlrev_b32_e32 v10, 16, v47
	s_waitcnt lgkmcnt(0)
	v_mov_b32_e32 v13, v38
	v_pk_mul_f32 v[10:11], v[12:13], v[10:11]
	v_mov_b32_e32 v38, v35
	v_add_f32_e32 v10, v30, v10
	v_add_f32_e32 v30, v10, v11
	v_and_b32_e32 v11, 0xffff0000, v63
	v_and_b32_e32 v10, 0xffff0000, v47
	v_pk_mul_f32 v[10:11], v[38:39], v[10:11]
	v_mov_b32_e32 v12, v36
	v_add_f32_e32 v10, v31, v10
	v_add_f32_e32 v31, v10, v11
	v_lshlrev_b32_e32 v11, 16, v62
	v_lshlrev_b32_e32 v10, 16, v46
	v_mov_b32_e32 v13, v40
	v_pk_mul_f32 v[10:11], v[12:13], v[10:11]
	v_mov_b32_e32 v40, v37
	v_add_f32_e32 v10, v32, v10
	v_add_f32_e32 v32, v10, v11
	v_and_b32_e32 v11, 0xffff0000, v62
	v_and_b32_e32 v10, 0xffff0000, v46
	v_pk_mul_f32 v[10:11], v[40:41], v[10:11]
	s_waitcnt vmcnt(10)
	v_cndmask_b32_e64 v34, 0, v221, s[6:7]
	v_add_f32_e32 v10, v33, v10
	v_add_f32_e32 v33, v10, v11
	v_cndmask_b32_e64 v35, 0, v220, s[6:7]
	v_cndmask_b32_e64 v36, 0, v219, s[6:7]
	v_cndmask_b32_e64 v37, 0, v218, s[6:7]
	ds_read_b128 v[10:13], v9 offset:9408
	ds_read_b128 v[14:17], v9 offset:9424
	s_waitcnt vmcnt(10)
	v_cndmask_b32_e64 v38, 0, v225, s[4:5]
	v_cndmask_b32_e64 v39, 0, v224, s[4:5]
	v_cndmask_b32_e64 v40, 0, v223, s[4:5]
	v_cndmask_b32_e64 v41, 0, v222, s[4:5]
	ds_read_b128 v[18:21], v9 offset:9920
	ds_read_b128 v[22:25], v9 offset:9936
	v_lshlrev_b32_e32 v27, 16, v41
	v_lshlrev_b32_e32 v26, 16, v37
	s_waitcnt lgkmcnt(3)
	v_mov_b32_e32 v28, v10
	s_waitcnt lgkmcnt(1)
	v_mov_b32_e32 v29, v18
	v_pk_mul_f32 v[26:27], v[28:29], v[26:27]
	v_mov_b32_e32 v18, v11
	v_add_f32_e32 v10, v44, v26
	v_add_f32_e32 v28, v10, v27
	v_and_b32_e32 v27, 0xffff0000, v41
	v_and_b32_e32 v26, 0xffff0000, v37
	v_pk_mul_f32 v[10:11], v[18:19], v[26:27]
	v_mov_b32_e32 v18, v12
	v_add_f32_e32 v10, v42, v10
	v_add_f32_e32 v26, v10, v11
	v_lshlrev_b32_e32 v11, 16, v40
	v_lshlrev_b32_e32 v10, 16, v36
	v_mov_b32_e32 v19, v20
	v_pk_mul_f32 v[10:11], v[18:19], v[10:11]
	v_mov_b32_e32 v20, v13
	v_add_f32_e32 v10, v43, v10
	v_add_f32_e32 v18, v10, v11
	v_and_b32_e32 v11, 0xffff0000, v40
	v_and_b32_e32 v10, 0xffff0000, v36
	v_pk_mul_f32 v[10:11], v[20:21], v[10:11]
	v_mov_b32_e32 v12, v14
	v_add_f32_e32 v10, v45, v10
	v_add_f32_e32 v19, v10, v11
	v_lshlrev_b32_e32 v11, 16, v39
	v_lshlrev_b32_e32 v10, 16, v35
	s_waitcnt lgkmcnt(0)
	v_mov_b32_e32 v13, v22
	v_pk_mul_f32 v[10:11], v[12:13], v[10:11]
	v_mov_b32_e32 v22, v15
	v_add_f32_e32 v10, v30, v10
	v_add_f32_e32 v14, v10, v11
	v_and_b32_e32 v11, 0xffff0000, v39
	v_and_b32_e32 v10, 0xffff0000, v35
	v_pk_mul_f32 v[10:11], v[22:23], v[10:11]
	v_mov_b32_e32 v12, v16
	v_add_f32_e32 v10, v31, v10
	v_add_f32_e32 v15, v10, v11
	v_lshlrev_b32_e32 v11, 16, v38
	v_lshlrev_b32_e32 v10, 16, v34
	v_mov_b32_e32 v13, v24
	v_pk_mul_f32 v[10:11], v[12:13], v[10:11]
	v_mov_b32_e32 v24, v17
	v_add_f32_e32 v10, v32, v10
	v_add_f32_e32 v12, v10, v11
	v_and_b32_e32 v11, 0xffff0000, v38
	v_and_b32_e32 v10, 0xffff0000, v34
	v_pk_mul_f32 v[10:11], v[24:25], v[10:11]
	v_cvt_pk_bf16_f32 v60, v28, v26
	v_cvt_pk_bf16_f32 v61, v18, v19
	v_cvt_pk_bf16_f32 v62, v14, v15
	s_nop 0
	v_add_f32_e32 v10, v33, v10
	v_add_f32_e32 v10, v10, v11
	v_cvt_pk_bf16_f32 v63, v12, v10
	ds_read_b128 v[26:29], v9 offset:10496
	ds_read_b128 v[30:33], v9 offset:10512
	s_waitcnt vmcnt(9)
	v_cndmask_b32_e32 v46, 0, v229, vcc
	v_cndmask_b32_e32 v47, 0, v228, vcc
	v_cndmask_b32_e32 v64, 0, v227, vcc
	v_cndmask_b32_e32 v65, 0, v226, vcc
	ds_read_b128 v[10:13], v9 offset:8448
	ds_read_b128 v[34:37], v9 offset:8464
	s_waitcnt vmcnt(9)
	v_cndmask_b32_e64 v66, 0, v233, s[0:1]
	v_cndmask_b32_e64 v67, 0, v232, s[0:1]
	v_cndmask_b32_e64 v68, 0, v231, s[0:1]
	v_cndmask_b32_e64 v69, 0, v230, s[0:1]
	ds_read_b128 v[14:17], v9 offset:8960
	ds_read_b128 v[38:41], v9 offset:8976
	v_lshlrev_b32_e32 v43, 16, v69
	v_lshlrev_b32_e32 v42, 16, v65
	s_waitcnt lgkmcnt(3)
	v_mov_b32_e32 v44, v10
	s_waitcnt lgkmcnt(1)
	v_mov_b32_e32 v45, v14
	v_pk_mul_f32 v[42:43], v[44:45], v[42:43]
	v_mov_b32_e32 v14, v11
	v_add_f32_e32 v10, v26, v42
	v_add_f32_e32 v44, v10, v43
	v_and_b32_e32 v43, 0xffff0000, v69
	v_and_b32_e32 v42, 0xffff0000, v65
	v_pk_mul_f32 v[10:11], v[14:15], v[42:43]
	v_mov_b32_e32 v14, v12
	v_add_f32_e32 v10, v27, v10
	v_add_f32_e32 v42, v10, v11
	v_lshlrev_b32_e32 v11, 16, v68
	v_lshlrev_b32_e32 v10, 16, v64
	v_mov_b32_e32 v15, v16
	v_pk_mul_f32 v[10:11], v[14:15], v[10:11]
	v_mov_b32_e32 v16, v13
	v_add_f32_e32 v10, v28, v10
	v_add_f32_e32 v43, v10, v11
	v_and_b32_e32 v11, 0xffff0000, v68
	v_and_b32_e32 v10, 0xffff0000, v64
	v_pk_mul_f32 v[10:11], v[16:17], v[10:11]
	v_mov_b32_e32 v12, v34
	v_add_f32_e32 v10, v29, v10
	v_add_f32_e32 v45, v10, v11
	v_lshlrev_b32_e32 v11, 16, v67
	v_lshlrev_b32_e32 v10, 16, v47
	s_waitcnt lgkmcnt(0)
	v_mov_b32_e32 v13, v38
	v_pk_mul_f32 v[10:11], v[12:13], v[10:11]
	v_mov_b32_e32 v38, v35
	v_add_f32_e32 v10, v30, v10
	v_add_f32_e32 v30, v10, v11
	v_and_b32_e32 v11, 0xffff0000, v67
	v_and_b32_e32 v10, 0xffff0000, v47
	v_pk_mul_f32 v[10:11], v[38:39], v[10:11]
	v_mov_b32_e32 v12, v36
	v_add_f32_e32 v10, v31, v10
	v_add_f32_e32 v31, v10, v11
	v_lshlrev_b32_e32 v11, 16, v66
	v_lshlrev_b32_e32 v10, 16, v46
	v_mov_b32_e32 v13, v40
	v_pk_mul_f32 v[10:11], v[12:13], v[10:11]
	v_mov_b32_e32 v40, v37
	v_add_f32_e32 v10, v32, v10
	v_add_f32_e32 v32, v10, v11
	v_and_b32_e32 v11, 0xffff0000, v66
	v_and_b32_e32 v10, 0xffff0000, v46
	v_pk_mul_f32 v[10:11], v[40:41], v[10:11]
	s_waitcnt vmcnt(9)
	v_cndmask_b32_e64 v34, 0, v237, s[6:7]
	v_add_f32_e32 v10, v33, v10
	v_add_f32_e32 v33, v10, v11
	v_cndmask_b32_e64 v35, 0, v236, s[6:7]
	v_cndmask_b32_e64 v36, 0, v235, s[6:7]
	v_cndmask_b32_e64 v37, 0, v234, s[6:7]
	ds_read_b128 v[10:13], v9 offset:9472
	ds_read_b128 v[14:17], v9 offset:9488
	s_waitcnt vmcnt(9)
	v_cndmask_b32_e64 v38, 0, v241, s[4:5]
	v_cndmask_b32_e64 v39, 0, v240, s[4:5]
	v_cndmask_b32_e64 v40, 0, v239, s[4:5]
	v_cndmask_b32_e64 v41, 0, v238, s[4:5]
	ds_read_b128 v[18:21], v9 offset:9984
	ds_read_b128 v[22:25], v9 offset:10000
	v_lshlrev_b32_e32 v27, 16, v41
	v_lshlrev_b32_e32 v26, 16, v37
	s_waitcnt lgkmcnt(3)
	v_mov_b32_e32 v28, v10
	s_waitcnt lgkmcnt(1)
	v_mov_b32_e32 v29, v18
	v_pk_mul_f32 v[26:27], v[28:29], v[26:27]
	v_mov_b32_e32 v18, v11
	v_add_f32_e32 v10, v44, v26
	v_add_f32_e32 v28, v10, v27
	v_and_b32_e32 v27, 0xffff0000, v41
	v_and_b32_e32 v26, 0xffff0000, v37
	v_pk_mul_f32 v[10:11], v[18:19], v[26:27]
	v_mov_b32_e32 v18, v12
	v_add_f32_e32 v10, v42, v10
	v_add_f32_e32 v26, v10, v11
	v_lshlrev_b32_e32 v11, 16, v40
	v_lshlrev_b32_e32 v10, 16, v36
	v_mov_b32_e32 v19, v20
	v_pk_mul_f32 v[10:11], v[18:19], v[10:11]
	v_mov_b32_e32 v20, v13
	v_add_f32_e32 v10, v43, v10
	v_add_f32_e32 v18, v10, v11
	v_and_b32_e32 v11, 0xffff0000, v40
	v_and_b32_e32 v10, 0xffff0000, v36
	v_pk_mul_f32 v[10:11], v[20:21], v[10:11]
	v_mov_b32_e32 v12, v14
	v_add_f32_e32 v10, v45, v10
	v_add_f32_e32 v19, v10, v11
	v_lshlrev_b32_e32 v11, 16, v39
	v_lshlrev_b32_e32 v10, 16, v35
	s_waitcnt lgkmcnt(0)
	v_mov_b32_e32 v13, v22
	v_pk_mul_f32 v[10:11], v[12:13], v[10:11]
	v_mov_b32_e32 v22, v15
	v_add_f32_e32 v10, v30, v10
	v_add_f32_e32 v14, v10, v11
	v_and_b32_e32 v11, 0xffff0000, v39
	v_and_b32_e32 v10, 0xffff0000, v35
	v_pk_mul_f32 v[10:11], v[22:23], v[10:11]
	v_mov_b32_e32 v12, v16
	v_add_f32_e32 v10, v31, v10
	v_add_f32_e32 v15, v10, v11
	v_lshlrev_b32_e32 v11, 16, v38
	v_lshlrev_b32_e32 v10, 16, v34
	v_mov_b32_e32 v13, v24
	v_pk_mul_f32 v[10:11], v[12:13], v[10:11]
	v_mov_b32_e32 v24, v17
	v_add_f32_e32 v10, v32, v10
	v_add_f32_e32 v12, v10, v11
	v_and_b32_e32 v11, 0xffff0000, v38
	v_and_b32_e32 v10, 0xffff0000, v34
	v_pk_mul_f32 v[10:11], v[24:25], v[10:11]
	v_cvt_pk_bf16_f32 v64, v28, v26
	v_cvt_pk_bf16_f32 v65, v18, v19
	v_cvt_pk_bf16_f32 v66, v14, v15
	s_nop 0
	v_add_f32_e32 v10, v33, v10
	v_add_f32_e32 v10, v10, v11
	v_cvt_pk_bf16_f32 v67, v12, v10
	ds_read_b128 v[26:29], v9 offset:10560
	ds_read_b128 v[30:33], v9 offset:10576
	s_waitcnt vmcnt(8)
	v_cndmask_b32_e32 v46, 0, v245, vcc
	v_cndmask_b32_e32 v47, 0, v244, vcc
	v_cndmask_b32_e32 v68, 0, v243, vcc
	v_cndmask_b32_e32 v69, 0, v242, vcc
	ds_read_b128 v[10:13], v9 offset:8512
	ds_read_b128 v[34:37], v9 offset:8528
	s_waitcnt vmcnt(8)
	v_cndmask_b32_e64 v70, 0, v249, s[0:1]
	v_cndmask_b32_e64 v71, 0, v248, s[0:1]
	v_cndmask_b32_e64 v72, 0, v247, s[0:1]
	v_cndmask_b32_e64 v73, 0, v246, s[0:1]
	ds_read_b128 v[14:17], v9 offset:9024
	ds_read_b128 v[38:41], v9 offset:9040
	v_lshlrev_b32_e32 v43, 16, v73
	v_lshlrev_b32_e32 v42, 16, v69
	s_waitcnt lgkmcnt(3)
	v_mov_b32_e32 v44, v10
	s_waitcnt lgkmcnt(1)
	v_mov_b32_e32 v45, v14
	v_pk_mul_f32 v[42:43], v[44:45], v[42:43]
	v_mov_b32_e32 v14, v11
	v_add_f32_e32 v10, v26, v42
	v_add_f32_e32 v44, v10, v43
	v_and_b32_e32 v43, 0xffff0000, v73
	v_and_b32_e32 v42, 0xffff0000, v69
	v_pk_mul_f32 v[10:11], v[14:15], v[42:43]
	v_mov_b32_e32 v14, v12
	v_add_f32_e32 v10, v27, v10
	v_add_f32_e32 v42, v10, v11
	v_lshlrev_b32_e32 v11, 16, v72
	v_lshlrev_b32_e32 v10, 16, v68
	v_mov_b32_e32 v15, v16
	v_pk_mul_f32 v[10:11], v[14:15], v[10:11]
	v_mov_b32_e32 v16, v13
	v_add_f32_e32 v10, v28, v10
	v_add_f32_e32 v43, v10, v11
	v_and_b32_e32 v11, 0xffff0000, v72
	v_and_b32_e32 v10, 0xffff0000, v68
	v_pk_mul_f32 v[10:11], v[16:17], v[10:11]
	v_mov_b32_e32 v12, v34
	v_add_f32_e32 v10, v29, v10
	v_add_f32_e32 v45, v10, v11
	v_lshlrev_b32_e32 v11, 16, v71
	v_lshlrev_b32_e32 v10, 16, v47
	s_waitcnt lgkmcnt(0)
	v_mov_b32_e32 v13, v38
	v_pk_mul_f32 v[10:11], v[12:13], v[10:11]
	v_mov_b32_e32 v38, v35
	v_add_f32_e32 v10, v30, v10
	v_add_f32_e32 v30, v10, v11
	v_and_b32_e32 v11, 0xffff0000, v71
	v_and_b32_e32 v10, 0xffff0000, v47
	v_pk_mul_f32 v[10:11], v[38:39], v[10:11]
	v_mov_b32_e32 v12, v36
	v_add_f32_e32 v10, v31, v10
	v_add_f32_e32 v31, v10, v11
	v_lshlrev_b32_e32 v11, 16, v70
	v_lshlrev_b32_e32 v10, 16, v46
	v_mov_b32_e32 v13, v40
	v_pk_mul_f32 v[10:11], v[12:13], v[10:11]
	v_mov_b32_e32 v40, v37
	v_add_f32_e32 v10, v32, v10
	v_add_f32_e32 v32, v10, v11
	v_and_b32_e32 v11, 0xffff0000, v70
	v_and_b32_e32 v10, 0xffff0000, v46
	v_pk_mul_f32 v[10:11], v[40:41], v[10:11]
	s_waitcnt vmcnt(8)
	v_cndmask_b32_e64 v34, 0, v255, s[6:7]
	v_add_f32_e32 v10, v33, v10
	v_add_f32_e32 v33, v10, v11
	v_cndmask_b32_e64 v35, 0, v254, s[6:7]
	v_cndmask_b32_e64 v36, 0, v253, s[6:7]
	v_cndmask_b32_e64 v37, 0, v252, s[6:7]
	ds_read_b128 v[10:13], v9 offset:9536
	ds_read_b128 v[14:17], v9 offset:9552
	s_waitcnt vmcnt(8)
	v_cndmask_b32_e64 v38, 0, v171, s[4:5]
	v_cndmask_b32_e64 v39, 0, v170, s[4:5]
	v_cndmask_b32_e64 v40, 0, v169, s[4:5]
	v_cndmask_b32_e64 v41, 0, v168, s[4:5]
	ds_read_b128 v[18:21], v9 offset:10048
	ds_read_b128 v[22:25], v9 offset:10064
	v_lshlrev_b32_e32 v27, 16, v41
	v_lshlrev_b32_e32 v26, 16, v37
	s_waitcnt lgkmcnt(3)
	v_mov_b32_e32 v28, v10
	s_waitcnt lgkmcnt(1)
	v_mov_b32_e32 v29, v18
	v_pk_mul_f32 v[26:27], v[28:29], v[26:27]
	v_mov_b32_e32 v18, v11
	v_add_f32_e32 v10, v44, v26
	v_add_f32_e32 v28, v10, v27
	v_and_b32_e32 v27, 0xffff0000, v41
	v_and_b32_e32 v26, 0xffff0000, v37
	v_pk_mul_f32 v[10:11], v[18:19], v[26:27]
	v_mov_b32_e32 v18, v12
	v_add_f32_e32 v10, v42, v10
	v_add_f32_e32 v26, v10, v11
	v_lshlrev_b32_e32 v11, 16, v40
	v_lshlrev_b32_e32 v10, 16, v36
	v_mov_b32_e32 v19, v20
	v_pk_mul_f32 v[10:11], v[18:19], v[10:11]
	v_mov_b32_e32 v20, v13
	v_add_f32_e32 v10, v43, v10
	v_add_f32_e32 v18, v10, v11
	v_and_b32_e32 v11, 0xffff0000, v40
	v_and_b32_e32 v10, 0xffff0000, v36
	v_pk_mul_f32 v[10:11], v[20:21], v[10:11]
	v_mov_b32_e32 v12, v14
	v_add_f32_e32 v10, v45, v10
	v_add_f32_e32 v19, v10, v11
	v_lshlrev_b32_e32 v11, 16, v39
	v_lshlrev_b32_e32 v10, 16, v35
	s_waitcnt lgkmcnt(0)
	v_mov_b32_e32 v13, v22
	v_pk_mul_f32 v[10:11], v[12:13], v[10:11]
	v_mov_b32_e32 v22, v15
	v_add_f32_e32 v10, v30, v10
	v_add_f32_e32 v14, v10, v11
	v_and_b32_e32 v11, 0xffff0000, v39
	v_and_b32_e32 v10, 0xffff0000, v35
	v_pk_mul_f32 v[10:11], v[22:23], v[10:11]
	v_mov_b32_e32 v12, v16
	v_add_f32_e32 v10, v31, v10
	v_add_f32_e32 v15, v10, v11
	v_lshlrev_b32_e32 v11, 16, v38
	v_lshlrev_b32_e32 v10, 16, v34
	v_mov_b32_e32 v13, v24
	v_pk_mul_f32 v[10:11], v[12:13], v[10:11]
	v_mov_b32_e32 v24, v17
	v_add_f32_e32 v10, v32, v10
	v_add_f32_e32 v12, v10, v11
	v_and_b32_e32 v11, 0xffff0000, v38
	v_and_b32_e32 v10, 0xffff0000, v34
	v_pk_mul_f32 v[10:11], v[24:25], v[10:11]
	v_cvt_pk_bf16_f32 v68, v28, v26
	v_cvt_pk_bf16_f32 v69, v18, v19
	v_cvt_pk_bf16_f32 v70, v14, v15
	s_nop 0
	v_add_f32_e32 v10, v33, v10
	v_add_f32_e32 v10, v10, v11
	v_cvt_pk_bf16_f32 v71, v12, v10
	ds_read_b128 v[26:29], v9 offset:10624
	ds_read_b128 v[30:33], v9 offset:10640
	s_waitcnt vmcnt(4)
	v_cndmask_b32_e32 v46, 0, v181, vcc
	v_cndmask_b32_e32 v47, 0, v180, vcc
	v_cndmask_b32_e32 v72, 0, v179, vcc
	v_cndmask_b32_e32 v73, 0, v178, vcc
	ds_read_b128 v[10:13], v9 offset:8576
	ds_read_b128 v[34:37], v9 offset:8592
	s_waitcnt vmcnt(4)
	v_cndmask_b32_e64 v74, 0, v185, s[0:1]
	v_cndmask_b32_e64 v75, 0, v184, s[0:1]
	v_cndmask_b32_e64 v76, 0, v183, s[0:1]
	v_cndmask_b32_e64 v77, 0, v182, s[0:1]
	ds_read_b128 v[14:17], v9 offset:9088
	ds_read_b128 v[38:41], v9 offset:9104
	v_lshlrev_b32_e32 v43, 16, v77
	v_lshlrev_b32_e32 v42, 16, v73
	s_waitcnt lgkmcnt(3)
	v_mov_b32_e32 v44, v10
	s_waitcnt lgkmcnt(1)
	v_mov_b32_e32 v45, v14
	v_pk_mul_f32 v[42:43], v[44:45], v[42:43]
	v_mov_b32_e32 v14, v11
	v_add_f32_e32 v10, v26, v42
	v_add_f32_e32 v44, v10, v43
	v_and_b32_e32 v43, 0xffff0000, v77
	v_and_b32_e32 v42, 0xffff0000, v73
	v_pk_mul_f32 v[10:11], v[14:15], v[42:43]
	v_mov_b32_e32 v14, v12
	v_add_f32_e32 v10, v27, v10
	v_add_f32_e32 v42, v10, v11
	v_lshlrev_b32_e32 v11, 16, v76
	v_lshlrev_b32_e32 v10, 16, v72
	v_mov_b32_e32 v15, v16
	v_pk_mul_f32 v[10:11], v[14:15], v[10:11]
	v_mov_b32_e32 v16, v13
	v_add_f32_e32 v10, v28, v10
	v_add_f32_e32 v43, v10, v11
	v_and_b32_e32 v11, 0xffff0000, v76
	v_and_b32_e32 v10, 0xffff0000, v72
	v_pk_mul_f32 v[10:11], v[16:17], v[10:11]
	v_mov_b32_e32 v12, v34
	v_add_f32_e32 v10, v29, v10
	v_add_f32_e32 v45, v10, v11
	v_lshlrev_b32_e32 v11, 16, v75
	v_lshlrev_b32_e32 v10, 16, v47
	s_waitcnt lgkmcnt(0)
	v_mov_b32_e32 v13, v38
	v_pk_mul_f32 v[10:11], v[12:13], v[10:11]
	v_mov_b32_e32 v38, v35
	v_add_f32_e32 v10, v30, v10
	v_add_f32_e32 v30, v10, v11
	v_and_b32_e32 v11, 0xffff0000, v75
	v_and_b32_e32 v10, 0xffff0000, v47
	v_pk_mul_f32 v[10:11], v[38:39], v[10:11]
	v_mov_b32_e32 v12, v36
	v_add_f32_e32 v10, v31, v10
	v_add_f32_e32 v31, v10, v11
	v_lshlrev_b32_e32 v11, 16, v74
	v_lshlrev_b32_e32 v10, 16, v46
	v_mov_b32_e32 v13, v40
	v_pk_mul_f32 v[10:11], v[12:13], v[10:11]
	v_mov_b32_e32 v40, v37
	v_add_f32_e32 v10, v32, v10
	v_add_f32_e32 v32, v10, v11
	v_and_b32_e32 v11, 0xffff0000, v74
	v_and_b32_e32 v10, 0xffff0000, v46
	v_pk_mul_f32 v[10:11], v[40:41], v[10:11]
	s_waitcnt vmcnt(4)
	v_cndmask_b32_e64 v34, 0, v189, s[6:7]
	v_add_f32_e32 v10, v33, v10
	v_add_f32_e32 v33, v10, v11
	v_cndmask_b32_e64 v35, 0, v188, s[6:7]
	v_cndmask_b32_e64 v36, 0, v187, s[6:7]
	v_cndmask_b32_e64 v37, 0, v186, s[6:7]
	ds_read_b128 v[10:13], v9 offset:9600
	ds_read_b128 v[14:17], v9 offset:9616
	s_waitcnt vmcnt(4)
	v_cndmask_b32_e64 v38, 0, v193, s[4:5]
	v_cndmask_b32_e64 v39, 0, v192, s[4:5]
	v_cndmask_b32_e64 v40, 0, v191, s[4:5]
	v_cndmask_b32_e64 v41, 0, v190, s[4:5]
	ds_read_b128 v[18:21], v9 offset:10112
	ds_read_b128 v[22:25], v9 offset:10128
	v_lshlrev_b32_e32 v27, 16, v41
	v_lshlrev_b32_e32 v26, 16, v37
	s_waitcnt lgkmcnt(3)
	v_mov_b32_e32 v28, v10
	s_waitcnt lgkmcnt(1)
	v_mov_b32_e32 v29, v18
	v_pk_mul_f32 v[26:27], v[28:29], v[26:27]
	v_mov_b32_e32 v18, v11
	v_add_f32_e32 v10, v44, v26
	v_add_f32_e32 v28, v10, v27
	v_and_b32_e32 v27, 0xffff0000, v41
	v_and_b32_e32 v26, 0xffff0000, v37
	v_pk_mul_f32 v[10:11], v[18:19], v[26:27]
	v_mov_b32_e32 v18, v12
	v_add_f32_e32 v10, v42, v10
	v_add_f32_e32 v26, v10, v11
	v_lshlrev_b32_e32 v11, 16, v40
	v_lshlrev_b32_e32 v10, 16, v36
	v_mov_b32_e32 v19, v20
	v_pk_mul_f32 v[10:11], v[18:19], v[10:11]
	v_mov_b32_e32 v20, v13
	v_add_f32_e32 v10, v43, v10
	v_add_f32_e32 v18, v10, v11
	v_and_b32_e32 v11, 0xffff0000, v40
	v_and_b32_e32 v10, 0xffff0000, v36
	v_pk_mul_f32 v[10:11], v[20:21], v[10:11]
	v_mov_b32_e32 v12, v14
	v_add_f32_e32 v10, v45, v10
	v_add_f32_e32 v19, v10, v11
	v_lshlrev_b32_e32 v11, 16, v39
	v_lshlrev_b32_e32 v10, 16, v35
	s_waitcnt lgkmcnt(0)
	v_mov_b32_e32 v13, v22
	v_pk_mul_f32 v[10:11], v[12:13], v[10:11]
	v_mov_b32_e32 v22, v15
	v_add_f32_e32 v10, v30, v10
	v_add_f32_e32 v14, v10, v11
	v_and_b32_e32 v11, 0xffff0000, v39
	v_and_b32_e32 v10, 0xffff0000, v35
	v_pk_mul_f32 v[10:11], v[22:23], v[10:11]
	v_mov_b32_e32 v12, v16
	v_add_f32_e32 v10, v31, v10
	v_add_f32_e32 v15, v10, v11
	v_lshlrev_b32_e32 v11, 16, v38
	v_lshlrev_b32_e32 v10, 16, v34
	v_mov_b32_e32 v13, v24
	v_pk_mul_f32 v[10:11], v[12:13], v[10:11]
	v_mov_b32_e32 v24, v17
	v_add_f32_e32 v10, v32, v10
	v_add_f32_e32 v12, v10, v11
	v_and_b32_e32 v11, 0xffff0000, v38
	v_and_b32_e32 v10, 0xffff0000, v34
	v_pk_mul_f32 v[10:11], v[24:25], v[10:11]
	v_cvt_pk_bf16_f32 v72, v28, v26
	v_cvt_pk_bf16_f32 v73, v18, v19
	v_cvt_pk_bf16_f32 v74, v14, v15
	v_lshlrev_b32_e32 v38, 3, v93
	v_add_f32_e32 v10, v33, v10
	v_add_f32_e32 v10, v10, v11
	v_cvt_pk_bf16_f32 v75, v12, v10
	s_nop 0
	s_nop 0
	ds_read_b128 v[18:21], v9 offset:10688
	ds_read_b128 v[22:25], v9 offset:10704
	v_or_b32_e32 v39, 16, v38
	s_waitcnt vmcnt(0)
	v_cndmask_b32_e32 v40, 0, v197, vcc
	v_cndmask_b32_e32 v41, 0, v196, vcc
	v_cndmask_b32_e32 v42, 0, v195, vcc
	v_cndmask_b32_e32 v43, 0, v194, vcc
	ds_read_b128 v[10:13], v9 offset:8640
	ds_read_b128 v[26:29], v9 offset:8656
	s_waitcnt vmcnt(0)
	v_cndmask_b32_e64 v44, 0, v201, s[0:1]
	v_cndmask_b32_e64 v45, 0, v200, s[0:1]
	v_cndmask_b32_e64 v46, 0, v199, s[0:1]
	v_cndmask_b32_e64 v47, 0, v198, s[0:1]
	ds_read_b128 v[14:17], v9 offset:9152
	ds_read_b128 v[30:33], v9 offset:9168
	v_lshlrev_b32_e32 v35, 16, v47
	v_lshlrev_b32_e32 v34, 16, v43
	s_waitcnt lgkmcnt(3)
	v_mov_b32_e32 v36, v10
	s_waitcnt lgkmcnt(1)
	v_mov_b32_e32 v37, v14
	v_pk_mul_f32 v[34:35], v[36:37], v[34:35]
	v_mov_b32_e32 v14, v11
	v_add_f32_e32 v10, v18, v34
	v_add_f32_e32 v36, v10, v35
	v_and_b32_e32 v35, 0xffff0000, v47
	v_and_b32_e32 v34, 0xffff0000, v43
	v_pk_mul_f32 v[10:11], v[14:15], v[34:35]
	v_mov_b32_e32 v14, v12
	v_add_f32_e32 v10, v19, v10
	v_add_f32_e32 v34, v10, v11
	v_lshlrev_b32_e32 v11, 16, v46
	v_lshlrev_b32_e32 v10, 16, v42
	v_mov_b32_e32 v15, v16
	v_pk_mul_f32 v[10:11], v[14:15], v[10:11]
	v_mov_b32_e32 v16, v13
	v_add_f32_e32 v10, v20, v10
	v_add_f32_e32 v35, v10, v11
	v_and_b32_e32 v11, 0xffff0000, v46
	v_and_b32_e32 v10, 0xffff0000, v42
	v_pk_mul_f32 v[10:11], v[16:17], v[10:11]
	v_mov_b32_e32 v12, v26
	v_add_f32_e32 v10, v21, v10
	v_add_f32_e32 v37, v10, v11
	v_lshlrev_b32_e32 v11, 16, v45
	v_lshlrev_b32_e32 v10, 16, v41
	s_waitcnt lgkmcnt(0)
	v_mov_b32_e32 v13, v30
	v_pk_mul_f32 v[10:11], v[12:13], v[10:11]
	v_mov_b32_e32 v30, v27
	v_add_f32_e32 v10, v22, v10
	v_add_f32_e32 v22, v10, v11
	v_and_b32_e32 v11, 0xffff0000, v45
	v_and_b32_e32 v10, 0xffff0000, v41
	v_pk_mul_f32 v[10:11], v[30:31], v[10:11]
	v_mov_b32_e32 v12, v28
	v_add_f32_e32 v10, v23, v10
	v_add_f32_e32 v23, v10, v11
	v_lshlrev_b32_e32 v11, 16, v44
	v_lshlrev_b32_e32 v10, 16, v40
	v_mov_b32_e32 v13, v32
	v_pk_mul_f32 v[10:11], v[12:13], v[10:11]
	v_mov_b32_e32 v32, v29
	v_add_f32_e32 v10, v24, v10
	v_add_f32_e32 v24, v10, v11
	v_and_b32_e32 v11, 0xffff0000, v44
	v_and_b32_e32 v10, 0xffff0000, v40
	v_pk_mul_f32 v[10:11], v[32:33], v[10:11]
	s_waitcnt vmcnt(0)
	v_cndmask_b32_e64 v26, 0, v205, s[6:7]
	v_add_f32_e32 v10, v25, v10
	v_add_f32_e32 v25, v10, v11
	v_cndmask_b32_e64 v27, 0, v204, s[6:7]
	v_cndmask_b32_e64 v28, 0, v203, s[6:7]
	v_cndmask_b32_e64 v29, 0, v202, s[6:7]
	ds_read_b128 v[0:3], v9 offset:9664
	ds_read_b128 v[10:13], v9 offset:9680
	s_waitcnt vmcnt(0)
	v_cndmask_b32_e64 v30, 0, v209, s[4:5]
	v_cndmask_b32_e64 v31, 0, v208, s[4:5]
	v_cndmask_b32_e64 v32, 0, v207, s[4:5]
	v_cndmask_b32_e64 v33, 0, v206, s[4:5]
	ds_read_b128 v[4:7], v9 offset:10176
	ds_read_b128 v[14:17], v9 offset:10192
	v_lshlrev_b32_e32 v19, 16, v33
	v_lshlrev_b32_e32 v18, 16, v29
	s_waitcnt lgkmcnt(3)
	v_mov_b32_e32 v20, v0
	s_waitcnt lgkmcnt(1)
	v_mov_b32_e32 v21, v4
	v_pk_mul_f32 v[18:19], v[20:21], v[18:19]
	v_mov_b32_e32 v4, v1
	v_add_f32_e32 v0, v36, v18
	v_add_f32_e32 v9, v0, v19
	v_and_b32_e32 v19, 0xffff0000, v33
	v_and_b32_e32 v18, 0xffff0000, v29
	v_pk_mul_f32 v[0:1], v[4:5], v[18:19]
	v_mov_b32_e32 v4, v2
	v_add_f32_e32 v0, v34, v0
	v_add_f32_e32 v18, v0, v1
	v_lshlrev_b32_e32 v1, 16, v32
	v_lshlrev_b32_e32 v0, 16, v28
	v_mov_b32_e32 v5, v6
	v_pk_mul_f32 v[0:1], v[4:5], v[0:1]
	v_mov_b32_e32 v6, v3
	v_add_f32_e32 v0, v35, v0
	v_add_f32_e32 v4, v0, v1
	v_and_b32_e32 v1, 0xffff0000, v32
	v_and_b32_e32 v0, 0xffff0000, v28
	v_pk_mul_f32 v[0:1], v[6:7], v[0:1]
	v_mov_b32_e32 v2, v10
	v_add_f32_e32 v0, v37, v0
	v_add_f32_e32 v5, v0, v1
	v_lshlrev_b32_e32 v1, 16, v31
	v_lshlrev_b32_e32 v0, 16, v27
	s_waitcnt lgkmcnt(0)
	v_mov_b32_e32 v3, v14
	v_pk_mul_f32 v[0:1], v[2:3], v[0:1]
	v_mov_b32_e32 v14, v11
	v_add_f32_e32 v0, v22, v0
	v_add_f32_e32 v6, v0, v1
	v_and_b32_e32 v1, 0xffff0000, v31
	v_and_b32_e32 v0, 0xffff0000, v27
	v_pk_mul_f32 v[0:1], v[14:15], v[0:1]
	v_mov_b32_e32 v2, v12
	v_add_f32_e32 v0, v23, v0
	v_add_f32_e32 v7, v0, v1
	v_lshlrev_b32_e32 v1, 16, v30
	v_lshlrev_b32_e32 v0, 16, v26
	v_mov_b32_e32 v3, v16
	v_pk_mul_f32 v[0:1], v[2:3], v[0:1]
	v_mov_b32_e32 v16, v13
	v_add_f32_e32 v0, v24, v0
	v_add_f32_e32 v2, v0, v1
	v_and_b32_e32 v1, 0xffff0000, v30
	v_and_b32_e32 v0, 0xffff0000, v26
	v_pk_mul_f32 v[0:1], v[16:17], v[0:1]
	v_cvt_pk_bf16_f32 v76, v9, v18
	v_cvt_pk_bf16_f32 v77, v4, v5
	v_cvt_pk_bf16_f32 v78, v6, v7
	v_cmp_eq_u32_e32 vcc, v38, v94
	v_add_f32_e32 v0, v25, v0
	v_add_f32_e32 v0, v0, v1
	v_cvt_pk_bf16_f32 v79, v2, v0
	v_or_b32_e32 v2, 1, v38
	v_cndmask_b32_e32 v0, 0, v134, vcc
	v_or_b32_e32 v1, 2, v38
	v_cmp_eq_u32_e32 vcc, v2, v94
	v_or_b32_e32 v4, 3, v38
	v_or_b32_e32 v3, 4, v38
	v_cndmask_b32_e32 v2, 0, v134, vcc
	v_cmp_eq_u32_e32 vcc, v1, v94
	v_or_b32_e32 v5, 6, v38
	v_or_b32_e32 v6, 5, v38
	v_cndmask_b32_e32 v1, 0, v134, vcc
	v_cmp_eq_u32_e32 vcc, v4, v94
	v_or_b32_e32 v7, 7, v38
	v_or_b32_e32 v11, 17, v38
	v_cndmask_b32_e32 v4, 0, v134, vcc
	v_cmp_eq_u32_e32 vcc, v3, v94
	v_or_b32_e32 v10, 18, v38
	v_or_b32_e32 v13, 19, v38
	v_cndmask_b32_e32 v3, 0, v134, vcc
	v_cmp_eq_u32_e32 vcc, v5, v94
	v_or_b32_e32 v12, 20, v38
	v_or_b32_e32 v14, 22, v38
	v_cndmask_b32_e32 v5, 0, v134, vcc
	v_cmp_eq_u32_e32 vcc, v6, v94
	v_or_b32_e32 v15, 21, v38
	v_or_b32_e32 v16, 23, v38
	v_cndmask_b32_e32 v6, 0, v134, vcc
	v_cmp_eq_u32_e32 vcc, v7, v94
	v_and_b32_e32 v18, 64, v132
	v_xor_b32_e32 v17, 32, v132
	v_cndmask_b32_e32 v7, 0, v134, vcc
	v_cmp_eq_u32_e32 vcc, v39, v94
	v_add_u32_e32 v18, 64, v18
	s_lshl_b32 s4, s62, 8
	v_cndmask_b32_e32 v9, 0, v134, vcc
	v_cmp_eq_u32_e32 vcc, v11, v94
	s_add_i32 s4, s4, 16
	v_cmp_eq_u32_e64 s[0:1], 0, v93
	v_cndmask_b32_e32 v11, 0, v134, vcc
	v_cmp_eq_u32_e32 vcc, v10, v94
	v_lshl_add_u32 v139, v94, 3, s4
	v_perm_b32 v82, v6, v3, s83
	v_cndmask_b32_e32 v10, 0, v134, vcc
	v_cmp_eq_u32_e32 vcc, v13, v94
	v_perm_b32 v81, v4, v1, s83
	v_perm_b32 v83, v7, v5, s83
	v_cndmask_b32_e32 v13, 0, v134, vcc
	v_cmp_eq_u32_e32 vcc, v12, v94
	v_perm_b32 v80, v2, v0, s83
	v_perm_b32 v85, v13, v10, s83
	v_cndmask_b32_e32 v12, 0, v134, vcc
	v_cmp_eq_u32_e32 vcc, v14, v94
	v_perm_b32 v84, v11, v9, s83
	s_nop 0
	v_cndmask_b32_e32 v14, 0, v134, vcc
	v_cmp_eq_u32_e32 vcc, v15, v94
	s_nop 1
	v_cndmask_b32_e32 v15, 0, v134, vcc
	v_cmp_eq_u32_e32 vcc, v16, v94
	v_perm_b32 v86, v15, v12, s83
	s_nop 0
	v_cndmask_b32_e32 v16, 0, v134, vcc
	v_cmp_lt_i32_e32 vcc, v17, v18
	v_perm_b32 v87, v16, v14, s83
	s_nop 0
	v_cndmask_b32_e32 v17, v132, v17, vcc
	v_lshlrev_b32_e32 v140, 2, v17
	v_lshlrev_b32_e32 v175, 2, v91
	global_load_dword v172, v175, s[42:43]
	global_load_dword v173, v175, s[36:37]
	global_load_dword v174, v175, s[40:41]
	s_setprio 1
	v_xad_u32 v148, v88, v8, v95
	ds_read_b128 v[0:3], v148 offset:16384
	ds_read_b128 v[4:7], v148 offset:49152
	s_waitcnt lgkmcnt(1)
	v_mfma_f32_32x32x16_bf16 v[32:47], v[48:51], v[0:3], 0
	v_or_b32_e32 v0, 32, v88
	v_xad_u32 v150, v0, v8, v95
	s_waitcnt lgkmcnt(0)
	v_mfma_f32_32x32x16_bf16 v[16:31], v[48:51], v[4:7], 0
	ds_read_b128 v[0:3], v150 offset:16384
	ds_read_b128 v[4:7], v150 offset:49152
	s_waitcnt lgkmcnt(1)
	v_mfma_f32_32x32x16_bf16 v[32:47], v[52:55], v[0:3], v[32:47]
	v_or_b32_e32 v0, 64, v88
	v_xad_u32 v145, v0, v8, v95
	s_waitcnt lgkmcnt(0)
	v_mfma_f32_32x32x16_bf16 v[16:31], v[52:55], v[4:7], v[16:31]
	ds_read_b128 v[0:3], v145 offset:16384
	ds_read_b128 v[4:7], v145 offset:49152
	s_waitcnt lgkmcnt(1)
	v_mfma_f32_32x32x16_bf16 v[32:47], v[56:59], v[0:3], v[32:47]
	v_or_b32_e32 v0, 0x60, v88
	v_xad_u32 v149, v0, v8, v95
	s_waitcnt lgkmcnt(0)
	v_mfma_f32_32x32x16_bf16 v[16:31], v[56:59], v[4:7], v[16:31]
	ds_read_b128 v[0:3], v149 offset:16384
	ds_read_b128 v[4:7], v149 offset:49152
	s_waitcnt lgkmcnt(1)
	v_mfma_f32_32x32x16_bf16 v[32:47], v[60:63], v[0:3], v[32:47]
	v_or_b32_e32 v0, 0x80, v88
	v_xad_u32 v144, v0, v8, v95
	s_waitcnt lgkmcnt(0)
	v_mfma_f32_32x32x16_bf16 v[16:31], v[60:63], v[4:7], v[16:31]
	ds_read_b128 v[0:3], v144 offset:16384
	ds_read_b128 v[4:7], v144 offset:49152
	s_waitcnt lgkmcnt(1)
	v_mfma_f32_32x32x16_bf16 v[32:47], v[64:67], v[0:3], v[32:47]
	v_or_b32_e32 v0, 0xa0, v88
	v_xad_u32 v147, v0, v8, v95
	s_waitcnt lgkmcnt(0)
	v_mfma_f32_32x32x16_bf16 v[16:31], v[64:67], v[4:7], v[16:31]
	ds_read_b128 v[0:3], v147 offset:16384
	ds_read_b128 v[4:7], v147 offset:49152
	s_waitcnt lgkmcnt(1)
	v_mfma_f32_32x32x16_bf16 v[32:47], v[68:71], v[0:3], v[32:47]
	v_or_b32_e32 v0, 0xc0, v88
	v_xad_u32 v143, v0, v8, v95
	s_waitcnt lgkmcnt(0)
	v_mfma_f32_32x32x16_bf16 v[16:31], v[68:71], v[4:7], v[16:31]
	ds_read_b128 v[0:3], v143 offset:16384
	ds_read_b128 v[4:7], v143 offset:49152
	s_waitcnt lgkmcnt(1)
	v_mfma_f32_32x32x16_bf16 v[32:47], v[72:75], v[0:3], v[32:47]
	v_or_b32_e32 v0, 0xe0, v88
	v_xad_u32 v146, v0, v8, v95
	s_waitcnt lgkmcnt(0)
	v_mfma_f32_32x32x16_bf16 v[16:31], v[72:75], v[4:7], v[16:31]
	ds_read_b128 v[0:3], v146 offset:16384
	ds_read_b128 v[4:7], v146 offset:49152
	s_waitcnt lgkmcnt(1)
	v_mfma_f32_32x32x16_bf16 v[32:47], v[76:79], v[0:3], v[32:47]
	s_waitcnt lgkmcnt(0)
	v_mfma_f32_32x32x16_bf16 v[16:31], v[76:79], v[4:7], v[16:31]
	v_mfma_f32_32x32x16_bf16 v[0:15], v[48:51], v[80:83], 0
	v_mfma_f32_32x32x16_bf16 v[0:15], v[52:55], v[84:87], v[0:15]
	s_setprio 0
	v_lshlrev_b32_e32 v88, 2, v91
	s_waitcnt vmcnt(0)
	v_mov_b32_e32 v91, v172
	v_mov_b32_e32 v97, v173
	v_mov_b32_e32 v96, v174
	v_mul_f32_e32 v91, 0xbfb8aa3b, v91
	v_exp_f32_e32 v106, v91
	v_add_f32_e32 v32, v32, v97
	v_add_f32_e32 v34, v34, v97
	v_add_f32_e32 v33, v33, v97
	v_add_f32_e32 v35, v35, v97
	v_mul_f32_e32 v32, 0xbfb8aa3b, v32
	v_mul_f32_e32 v34, 0xbfb8aa3b, v34
	v_add_f32_e32 v16, v16, v96
	v_add_f32_e32 v17, v17, v96
	v_mul_f32_e32 v33, 0xbfb8aa3b, v33
	v_mul_f32_e32 v35, 0xbfb8aa3b, v35
	v_exp_f32_e32 v32, v32
	v_exp_f32_e32 v34, v34
	v_mul_f32_e32 v16, 0xbfb8aa3b, v16
	v_mul_f32_e32 v17, 0xbfb8aa3b, v17
	v_exp_f32_e32 v33, v33
	v_exp_f32_e32 v107, v35
	v_add_f32_e32 v35, 1.0, v106
	v_exp_f32_e32 v91, v16
	v_exp_f32_e32 v98, v17
	v_frexp_mant_f32_e32 v100, v35
	v_cvt_f64_f32_e32 v[16:17], v35
	v_add_f32_e32 v99, -1.0, v35
	v_frexp_exp_i32_f64_e32 v16, v[16:17]
	v_cmp_gt_f32_e32 vcc, s84, v100
	v_add_f32_e32 v32, 1.0, v32
	v_add_f32_e32 v108, 1.0, v34
	v_sub_f32_e32 v34, v99, v35
	v_subbrev_co_u32_e32 v16, vcc, 0, v16, vcc
	v_add_f32_e32 v33, 1.0, v33
	v_sub_f32_e32 v99, v106, v99
	v_rcp_f32_e32 v109, v32
	v_add_f32_e32 v17, 1.0, v34
	v_sub_u32_e32 v32, 0, v16
	v_rcp_f32_e32 v111, v33
	v_add_f32_e32 v17, v99, v17
	v_ldexp_f32 v33, v35, v32
	v_add_f32_e32 v91, 1.0, v91
	v_ldexp_f32 v17, v17, v32
	v_add_f32_e32 v32, -1.0, v33
	v_add_f32_e32 v34, 1.0, v33
	v_rcp_f32_e32 v110, v91
	v_add_f32_e32 v35, 1.0, v32
	v_add_f32_e32 v91, -1.0, v34
	v_sub_f32_e32 v35, v33, v35
	v_sub_f32_e32 v33, v33, v91
	v_add_f32_e32 v35, v17, v35
	v_add_f32_e32 v17, v17, v33
	v_add_f32_e32 v91, v34, v17
	v_rcp_f32_e32 v100, v91
	v_add_f32_e32 v33, v32, v35
	v_sub_f32_e32 v34, v91, v34
	v_add_f32_e32 v98, 1.0, v98
	v_mul_f32_e32 v102, v33, v100
	v_sub_f32_e32 v17, v17, v34
	v_mul_f32_e32 v34, v91, v102
	v_rcp_f32_e32 v112, v98
	v_fma_f32 v98, v102, v91, -v34
	v_sub_f32_e32 v32, v33, v32
	v_fmac_f32_e32 v98, v102, v17
	v_sub_f32_e32 v101, v35, v32
	v_add_f32_e32 v32, v34, v98
	v_sub_f32_e32 v35, v33, v32
	v_mov_b32_e32 v99, v32
	v_pk_add_f32 v[32:33], v[32:33], v[34:35] neg_lo:[0,1] neg_hi:[0,1]
	v_cvt_f32_i32_e32 v16, v16
	v_pk_add_f32 v[32:33], v[32:33], v[98:99] neg_lo:[0,1] neg_hi:[0,1]
	v_cmp_neq_f32_e32 vcc, s86, v106
	v_add_f32_e32 v33, v101, v33
	v_add_f32_e32 v32, v32, v33
	v_add_f32_e32 v33, v35, v32
	v_mul_f32_e32 v99, v100, v33
	v_mul_f32_e32 v34, v91, v99
	v_sub_f32_e32 v35, v35, v33
	v_add_f32_e32 v103, v102, v99
	v_fma_f32 v98, v99, v91, -v34
	v_add_f32_e32 v101, v32, v35
	v_sub_f32_e32 v32, v103, v102
	v_fmac_f32_e32 v98, v99, v17
	v_sub_f32_e32 v17, v99, v32
	v_add_f32_e32 v32, v34, v98
	v_sub_f32_e32 v35, v33, v32
	v_mov_b32_e32 v99, v32
	v_pk_add_f32 v[32:33], v[32:33], v[34:35] neg_lo:[0,1] neg_hi:[0,1]
	v_add_f32_e32 v18, v18, v96
	v_pk_add_f32 v[32:33], v[32:33], v[98:99] neg_lo:[0,1] neg_hi:[0,1]
	v_mul_f32_e32 v18, 0xbfb8aa3b, v18
	v_add_f32_e32 v33, v101, v33
	v_add_f32_e32 v32, v32, v33
	v_add_f32_e32 v32, v35, v32
	v_mul_f32_e32 v32, v100, v32
	v_add_f32_e32 v17, v17, v32
	v_add_f32_e32 v32, v103, v17
	v_mul_f32_e32 v34, v32, v32
	v_sub_f32_e32 v35, v32, v103
	v_fmamk_f32 v91, v34, 0x3e9b6dac, v133
	v_sub_f32_e32 v35, v17, v35
	v_mul_f32_e32 v17, v32, v34
	v_fmaak_f32 v91, v34, v91, 0x3f2aaada
	v_ldexp_f32 v99, v35, 1
	v_pk_mul_f32 v[34:35], v[16:17], v[90:91]
	v_ldexp_f32 v33, v32, 1
	v_fma_f32 v32, v16, s85, -v34
	v_fmac_f32_e32 v32, 0xb102e308, v16
	v_pk_add_f32 v[16:17], v[34:35], v[32:33]
	v_mov_b32_e32 v98, v34
	v_sub_f32_e32 v91, v17, v33
	v_pk_add_f32 v[100:101], v[16:17], v[34:35] neg_lo:[0,1] neg_hi:[0,1]
	v_sub_f32_e32 v34, v35, v91
	v_add_f32_e32 v99, v99, v34
	v_pk_add_f32 v[34:35], v[16:17], v[98:99]
	v_mov_b32_e32 v33, v16
	v_mov_b32_e32 v101, v35
	v_pk_add_f32 v[104:105], v[32:33], v[100:101] neg_lo:[0,1] neg_hi:[0,1]
	v_pk_add_f32 v[32:33], v[32:33], v[100:101]
	v_mov_b32_e32 v103, v16
	v_pk_add_f32 v[100:101], v[32:33], v[16:17] op_sel:[1,0] op_sel_hi:[0,1] neg_lo:[0,1] neg_hi:[0,1]
	v_mov_b32_e32 v102, v99
	v_mov_b32_e32 v98, v35
	v_mov_b32_e32 v99, v33
	v_pk_mov_b32 v[16:17], v[16:17], v[100:101] op_sel:[1,0]
	v_pk_add_f32 v[34:35], v[34:35], v[100:101] op_sel_hi:[1,0] neg_lo:[0,1] neg_hi:[0,1]
	v_pk_add_f32 v[16:17], v[98:99], v[16:17] neg_lo:[0,1] neg_hi:[0,1]
	v_mov_b32_e32 v34, v104
	v_pk_add_f32 v[16:17], v[102:103], v[16:17] neg_lo:[0,1] neg_hi:[0,1]
	v_mov_b32_e32 v105, v33
	v_pk_add_f32 v[34:35], v[34:35], v[16:17]
	v_exp_f32_e32 v18, v18
	v_pk_add_f32 v[98:99], v[34:35], v[34:35] op_sel:[0,1] op_sel_hi:[1,0]
	v_add_f32_e32 v20, v20, v96
	v_pk_add_f32 v[32:33], v[32:33], v[98:99] op_sel:[1,0] op_sel_hi:[0,1]
	v_mov_b32_e32 v35, v32
	v_mov_b32_e32 v17, v98
	v_pk_add_f32 v[98:99], v[34:35], v[104:105] neg_lo:[0,1] neg_hi:[0,1]
	v_add_f32_e32 v18, 1.0, v18
	v_sub_f32_e32 v33, v34, v98
	v_pk_add_f32 v[16:17], v[16:17], v[98:99] neg_lo:[0,1] neg_hi:[0,1]
	v_sub_f32_e32 v33, v104, v33
	v_add_f32_e32 v16, v16, v33
	v_add_f32_e32 v16, v16, v17
	v_add_f32_e32 v16, v32, v16
	v_cndmask_b32_e32 v16, v135, v16, vcc
	v_cmp_ngt_f32_e32 vcc, -1.0, v106
	v_mul_f32_e32 v20, 0xbfb8aa3b, v20
	v_exp_f32_e32 v20, v20
	v_cndmask_b32_e32 v16, v136, v16, vcc
	v_cmp_neq_f32_e32 vcc, -1.0, v106
	v_add_f32_e32 v19, v19, v96
	v_mul_f32_e32 v19, 0xbfb8aa3b, v19
	v_cndmask_b32_e32 v16, v137, v16, vcc
	v_cmp_lt_f32_e64 vcc, |v106|, s87
	v_exp_f32_e32 v19, v19
	v_add_f32_e32 v21, v21, v96
	v_cndmask_b32_e32 v16, v16, v106, vcc
	v_mul_f32_e32 v33, 0xc1000000, v16
	v_mul_f32_e32 v16, v109, v33
	v_mul_f32_e32 v16, 0x3fb8aa3b, v16
	v_exp_f32_e32 v32, v16
	v_mul_f32_e32 v17, v111, v33
	v_mul_f32_e32 v17, 0x3fb8aa3b, v17
	v_exp_f32_e32 v34, v17
	v_rcp_f32_e32 v16, v108
	v_rcp_f32_e32 v17, v18
	v_fma_f32 v18, -v32, v32, 1.0
	v_sqrt_f32_e32 v18, v18
	v_mul_f32_e32 v16, v16, v33
	v_mul_f32_e32 v16, 0x3fb8aa3b, v16
	v_add_f32_e32 v19, 1.0, v19
	v_mul_f32_e32 v18, v110, v18
	v_mul_f32_e32 v18, v0, v18
	v_exp_f32_e32 v0, v16
	v_add_f32_e32 v16, 1.0, v107
	v_rcp_f32_e32 v16, v16
	v_rcp_f32_e32 v19, v19
	v_fma_f32 v91, -v0, v0, 1.0
	v_sqrt_f32_e32 v91, v91
	v_mul_f32_e32 v16, v16, v33
	v_mul_f32_e32 v16, 0x3fb8aa3b, v16
	v_exp_f32_e32 v98, v16
	v_add_f32_e32 v16, v36, v97
	v_mul_f32_e32 v16, 0xbfb8aa3b, v16
	v_exp_f32_e32 v16, v16
	v_mul_f32_e32 v91, v17, v91
	v_add_f32_e32 v17, 1.0, v20
	v_fma_f32 v36, -v98, v98, 1.0
	v_add_f32_e32 v16, 1.0, v16
	v_rcp_f32_e32 v16, v16
	v_sqrt_f32_e32 v36, v36
	v_rcp_f32_e32 v17, v17
	v_mul_f32_e32 v21, 0xbfb8aa3b, v21
	v_mul_f32_e32 v16, v16, v33
	v_mul_f32_e32 v16, 0x3fb8aa3b, v16
	v_exp_f32_e32 v20, v16
	v_add_f32_e32 v16, v37, v97
	v_mul_f32_e32 v16, 0xbfb8aa3b, v16
	v_exp_f32_e32 v16, v16
	v_mul_f32_e32 v36, v19, v36
	v_fma_f32 v19, -v20, v20, 1.0
	v_sqrt_f32_e32 v19, v19
	v_add_f32_e32 v16, 1.0, v16
	v_rcp_f32_e32 v16, v16
	v_exp_f32_e32 v21, v21
	v_mul_f32_e32 v17, v17, v19
	v_mul_f32_e32 v19, v4, v17
	v_mul_f32_e32 v16, v16, v33
	v_mul_f32_e32 v16, 0x3fb8aa3b, v16
	v_exp_f32_e32 v37, v16
	v_add_f32_e32 v16, v38, v97
	v_mul_f32_e32 v16, 0xbfb8aa3b, v16
	v_exp_f32_e32 v16, v16
	v_add_f32_e32 v4, 1.0, v21
	v_add_f32_e32 v21, v22, v96
	v_mul_f32_e32 v21, 0xbfb8aa3b, v21
	v_add_f32_e32 v16, 1.0, v16
	v_rcp_f32_e32 v16, v16
	v_fma_f32 v17, -v37, v37, 1.0
	v_exp_f32_e32 v21, v21
	v_rcp_f32_e32 v4, v4
	v_mul_f32_e32 v16, v16, v33
	v_mul_f32_e32 v16, 0x3fb8aa3b, v16
	v_sqrt_f32_e32 v17, v17
	v_exp_f32_e32 v38, v16
	v_add_f32_e32 v16, 1.0, v21
	v_add_f32_e32 v21, v39, v97
	v_mul_f32_e32 v4, v4, v17
	v_fma_f32 v17, -v38, v38, 1.0
	v_mul_f32_e32 v21, 0xbfb8aa3b, v21
	v_rcp_f32_e32 v16, v16
	v_sqrt_f32_e32 v17, v17
	v_exp_f32_e32 v21, v21
	v_add_f32_e32 v22, v23, v96
	v_mul_f32_e32 v22, 0xbfb8aa3b, v22
	v_mul_f32_e32 v23, v16, v17
	v_add_f32_e32 v16, 1.0, v21
	v_rcp_f32_e32 v16, v16
	v_add_f32_e32 v21, v40, v97
	v_mul_f32_e32 v21, 0xbfb8aa3b, v21
	v_exp_f32_e32 v21, v21
	v_mul_f32_e32 v16, v16, v33
	v_mul_f32_e32 v16, 0x3fb8aa3b, v16
	v_exp_f32_e32 v39, v16
	v_add_f32_e32 v16, 1.0, v21
	v_rcp_f32_e32 v16, v16
	v_exp_f32_e32 v22, v22
	v_add_f32_e32 v21, v24, v96
	v_mul_f32_e32 v21, 0xbfb8aa3b, v21
	v_mul_f32_e32 v16, v16, v33
	v_add_f32_e32 v17, 1.0, v22
	v_fma_f32 v22, -v39, v39, 1.0
	v_mul_f32_e32 v16, 0x3fb8aa3b, v16
	v_sqrt_f32_e32 v24, v22
	v_exp_f32_e32 v22, v16
	v_add_f32_e32 v16, v41, v97
	v_mul_f32_e32 v16, 0xbfb8aa3b, v16
	v_exp_f32_e32 v16, v16
	v_exp_f32_e32 v21, v21
	v_fma_f32 v40, -v22, v22, 1.0
	v_rcp_f32_e32 v17, v17
	v_add_f32_e32 v16, 1.0, v16
	v_rcp_f32_e32 v16, v16
	v_add_f32_e32 v21, 1.0, v21
	v_rcp_f32_e32 v21, v21
	v_sqrt_f32_e32 v40, v40
	v_mul_f32_e32 v16, v16, v33
	v_mul_f32_e32 v16, 0x3fb8aa3b, v16
	v_mul_f32_e32 v24, v17, v24
	v_mul_f32_e32 v17, v21, v40
	v_exp_f32_e32 v40, v16
	v_add_f32_e32 v16, v42, v97
	v_add_f32_e32 v25, v25, v96
	v_mul_f32_e32 v16, 0xbfb8aa3b, v16
	v_mul_f32_e32 v25, 0xbfb8aa3b, v25
	v_exp_f32_e32 v16, v16
	v_exp_f32_e32 v25, v25
	v_fma_f32 v35, -v34, v34, 1.0
	v_sqrt_f32_e32 v35, v35
	v_add_f32_e32 v16, 1.0, v16
	v_add_f32_e32 v21, 1.0, v25
	v_rcp_f32_e32 v16, v16
	v_rcp_f32_e32 v25, v21
	v_fma_f32 v21, -v40, v40, 1.0
	v_sqrt_f32_e32 v41, v21
	v_add_f32_e32 v21, v26, v96
	v_mul_f32_e32 v16, v16, v33
	v_mul_f32_e32 v21, 0xbfb8aa3b, v21
	v_mul_f32_e32 v16, 0x3fb8aa3b, v16
	v_exp_f32_e32 v26, v21
	v_mul_f32_e32 v21, v8, v17
	v_mul_f32_e32 v8, v25, v41
	v_exp_f32_e32 v41, v16
	v_add_f32_e32 v16, v43, v97
	v_mul_f32_e32 v16, 0xbfb8aa3b, v16
	v_exp_f32_e32 v16, v16
	v_add_f32_e32 v17, 1.0, v26
	v_fma_f32 v25, -v41, v41, 1.0
	v_add_f32_e32 v26, v27, v96
	v_add_f32_e32 v16, 1.0, v16
	v_rcp_f32_e32 v16, v16
	v_rcp_f32_e32 v17, v17
	v_sqrt_f32_e32 v25, v25
	v_mul_f32_e32 v26, 0xbfb8aa3b, v26
	v_mul_f32_e32 v16, v16, v33
	v_exp_f32_e32 v26, v26
	v_mul_f32_e32 v16, 0x3fb8aa3b, v16
	v_exp_f32_e32 v99, v16
	v_mul_f32_e32 v100, v17, v25
	v_add_f32_e32 v25, v44, v97
	v_add_f32_e32 v16, 1.0, v26
	v_mul_f32_e32 v25, 0xbfb8aa3b, v25
	v_add_f32_e32 v26, v28, v96
	v_fma_f32 v17, -v99, v99, 1.0
	v_exp_f32_e32 v25, v25
	v_mul_f32_e32 v26, 0xbfb8aa3b, v26
	v_rcp_f32_e32 v16, v16
	v_sqrt_f32_e32 v17, v17
	v_exp_f32_e32 v26, v26
	v_add_f32_e32 v25, 1.0, v25
	v_rcp_f32_e32 v25, v25
	v_mul_f32_e32 v101, v16, v17
	v_add_f32_e32 v16, 1.0, v26
	v_add_f32_e32 v26, v29, v96
	v_mul_f32_e32 v26, 0xbfb8aa3b, v26
	v_exp_f32_e32 v26, v26
	v_rcp_f32_e32 v17, v16
	v_mul_f32_e32 v16, v25, v33
	v_add_f32_e32 v25, v45, v97
	v_mul_f32_e32 v25, 0xbfb8aa3b, v25
	v_exp_f32_e32 v25, v25
	v_add_f32_e32 v26, 1.0, v26
	v_rcp_f32_e32 v42, v26
	v_add_f32_e32 v26, v46, v97
	v_mul_f32_e32 v26, 0xbfb8aa3b, v26
	v_exp_f32_e32 v26, v26
	v_add_f32_e32 v25, 1.0, v25
	v_rcp_f32_e32 v25, v25
	v_add_f32_e32 v27, v30, v96
	v_mul_f32_e32 v27, 0xbfb8aa3b, v27
	v_exp_f32_e32 v27, v27
	v_add_f32_e32 v26, 1.0, v26
	v_rcp_f32_e32 v26, v26
	v_mul_f32_e32 v25, v25, v33
	v_mul_f32_e32 v25, 0x3fb8aa3b, v25
	v_exp_f32_e32 v43, v25
	v_add_f32_e32 v25, 1.0, v27
	v_rcp_f32_e32 v44, v25
	v_mul_f32_e32 v25, v26, v33
	v_add_f32_e32 v26, v47, v97
	v_mul_f32_e32 v26, 0xbfb8aa3b, v26
	v_exp_f32_e32 v26, v26
	v_add_f32_e32 v27, v31, v96
	v_mul_f32_e32 v27, 0xbfb8aa3b, v27
	v_exp_f32_e32 v27, v27
	v_add_f32_e32 v26, 1.0, v26
	v_mul_f32_e32 v16, 0x3fb8aa3b, v16
	v_rcp_f32_e32 v26, v26
	v_exp_f32_e32 v16, v16
	v_mul_f32_e32 v25, 0x3fb8aa3b, v25
	v_fmac_f32_e32 v18, 0, v32
	v_mul_f32_e32 v35, v112, v35
	v_exp_f32_e32 v45, v25
	v_add_f32_e32 v25, 1.0, v27
	v_mul_f32_e32 v31, v34, v18
	v_rcp_f32_e32 v46, v25
	v_mul_f32_e32 v25, v26, v33
	v_fmac_f32_e32 v31, v1, v35
	v_mul_f32_e32 v33, v32, v34
	v_mul_f32_e32 v30, v0, v31
	v_mul_f32_e32 v34, v0, v33
	v_fma_f32 v0, -v16, v16, 1.0
	v_sqrt_f32_e32 v1, v0
	v_mul_f32_e32 v25, 0x3fb8aa3b, v25
	v_fmac_f32_e32 v30, v2, v91
	v_fmac_f32_e32 v21, 0, v22
	v_fma_f32 v2, -v43, v43, 1.0
	v_exp_f32_e32 v47, v25
	v_mul_f32_e32 v25, v40, v21
	v_mov_b32_e32 v0, v89
	v_sqrt_f32_e32 v2, v2
	v_fmac_f32_e32 v25, v9, v8
	v_pk_mul_f32 v[8:9], v[16:17], v[0:1]
	v_mul_f32_e32 v29, v98, v30
	v_fmac_f32_e32 v19, 0, v20
	v_fmac_f32_e32 v8, v12, v9
	v_fmac_f32_e32 v29, v3, v36
	v_mul_f32_e32 v28, v37, v19
	v_mov_b32_e32 v3, v8
	v_fmac_f32_e32 v28, v5, v4
	v_pk_mul_f32 v[4:5], v[42:43], v[2:3]
	v_fma_f32 v0, -v45, v45, 1.0
	v_fmac_f32_e32 v5, v13, v4
	v_sqrt_f32_e32 v4, v0
	v_mul_f32_e32 v27, v38, v28
	v_fmac_f32_e32 v27, v6, v23
	v_mul_f32_e32 v26, v39, v27
	v_fmac_f32_e32 v26, v7, v24
	v_pk_mul_f32 v[6:7], v[44:45], v[4:5]
	v_fma_f32 v0, -v47, v47, 1.0
	v_fmac_f32_e32 v7, v14, v6
	v_sqrt_f32_e32 v6, v0
	ds_bpermute_b32 v0, v140, v29
	v_mul_f32_e32 v24, v41, v25
	v_mul_f32_e32 v35, v98, v34
	v_mul_f32_e32 v36, v20, v37
	v_fmac_f32_e32 v24, v10, v100
	v_mul_f32_e32 v37, v38, v36
	v_mul_f32_e32 v23, v99, v24
	ds_bpermute_b32 v13, v140, v35
	v_mul_f32_e32 v38, v39, v37
	v_fmac_f32_e32 v23, v11, v101
	v_pk_mul_f32 v[10:11], v[46:47], v[6:7]
	s_waitcnt lgkmcnt(1)
	v_cndmask_b32_e64 v14, v29, v0, s[0:1]
	v_fmac_f32_e32 v11, v15, v10
	v_cndmask_b32_e64 v10, v0, v29, s[0:1]
	ds_bpermute_b32 v0, v140, v38
	ds_bpermute_b32 v3, v140, v26
	v_mul_f32_e32 v39, v22, v40
	v_mul_f32_e32 v40, v41, v39
	s_waitcnt lgkmcnt(2)
	v_cndmask_b32_e64 v1, v13, v35, s[0:1]
	v_mul_f32_e32 v12, v99, v40
	v_mul_f32_e32 v9, v16, v43
	v_cndmask_b32_e64 v2, v35, v13, s[0:1]
	v_fmac_f32_e32 v10, 0, v1
	v_mul_f32_e32 v4, v45, v9
	v_mul_f32_e32 v15, v35, v13
	v_fmac_f32_e32 v14, v2, v10
	s_waitcnt lgkmcnt(1)
	v_cndmask_b32_e64 v1, v0, v38, s[0:1]
	s_waitcnt lgkmcnt(0)
	v_cndmask_b32_e64 v17, v3, v26, s[0:1]
	v_cndmask_b32_e64 v41, v26, v3, s[0:1]
	ds_bpermute_b32 v2, v140, v12
	ds_bpermute_b32 v3, v140, v23
	v_mul_f32_e32 v6, v47, v4
	v_cndmask_b32_e64 v0, v38, v0, s[0:1]
	v_mul_f32_e32 v42, v15, v1
	v_fmac_f32_e32 v17, v1, v14
	v_mul_f32_e32 v43, v0, v42
	v_fmac_f32_e32 v41, v0, v17
	ds_bpermute_b32 v1, v140, v6
	ds_bpermute_b32 v0, v140, v11
	s_waitcnt lgkmcnt(3)
	v_cndmask_b32_e64 v47, v2, v12, s[0:1]
	s_waitcnt lgkmcnt(2)
	v_cndmask_b32_e64 v44, v3, v23, s[0:1]
	v_cndmask_b32_e64 v2, v12, v2, s[0:1]
	v_cndmask_b32_e64 v45, v23, v3, s[0:1]
	v_mul_f32_e32 v46, v47, v43
	v_fmac_f32_e32 v44, v47, v41
	v_mul_f32_e32 v47, v2, v46
	v_fmac_f32_e32 v45, v2, v44
	s_waitcnt lgkmcnt(1)
	v_cndmask_b32_e64 v2, v1, v6, s[0:1]
	s_waitcnt lgkmcnt(0)
	v_cndmask_b32_e64 v91, v0, v11, s[0:1]
	v_mul_f32_e32 v96, v2, v47
	v_fmac_f32_e32 v91, v2, v45
	s_and_saveexec_b64 s[4:5], s[0:1]
	v_mul_f32_e32 v3, v91, v1
	v_mul_f32_e32 v2, v96, v1
	v_add_f32_e32 v3, v3, v0
	ds_write_b64 v139, v[2:3]
	s_or_b64 exec, exec, s[4:5]
	s_cmp_gt_i32 s62, 0
	s_cselect_b64 s[12:13], -1, 0
	s_cmp_lt_i32 s62, 1
	v_mul_i32_i24_e32 v141, 0xffffff08, v94
	s_waitcnt lgkmcnt(0)
	s_barrier
	s_cbranch_scc1 .LBB0_327
	s_cmp_lt_u32 s62, 8
	s_cbranch_scc1 .LBB0_328
	v_add_u32_e32 v95, v95, v141
	s_and_b32 s4, s62, 0x7ffffff8
	v_mov_b32_e32 v0, 1.0
	v_mov_b32_e32 v3, 0
	s_mov_b32 s5, 0

.LBB0_331:
	v_lshl_add_u64 v[126:127], s[36:37], 0, v[88:89]
	v_lshl_add_u64 v[128:129], s[40:41], 0, v[88:89]
	v_lshl_add_u64 v[130:131], s[42:43], 0, v[88:89]
	v_cndmask_b32_e64 v1, v13, 1.0, s[0:1]
	v_cndmask_b32_e64 v2, v10, 0, s[0:1]
	v_cndmask_b32_e64 v10, v42, v15, s[0:1]
	v_cndmask_b32_e64 v13, v17, v14, s[0:1]
	v_cndmask_b32_e64 v14, v46, v43, s[0:1]
	v_cndmask_b32_e64 v15, v44, v41, s[0:1]
	s_ashr_i32 s9, s8, 31
	v_lshlrev_b32_e32 v88, 2, v94
	v_cndmask_b32_e64 v17, v96, v47, s[0:1]
	v_cndmask_b32_e64 v41, v91, v45, s[0:1]
	v_fmac_f32_e32 v18, v32, v2
	v_mul_f32_e32 v32, v1, v32
	v_fmac_f32_e32 v31, v33, v2
	v_mul_f32_e32 v33, v1, v33
	v_fmac_f32_e32 v30, v34, v2
	v_mul_f32_e32 v34, v1, v34
	v_fmac_f32_e32 v29, v35, v2
	v_mul_f32_e32 v1, v1, v35
	v_fmac_f32_e32 v19, v20, v13
	v_mul_f32_e32 v2, v20, v10
	v_fmac_f32_e32 v28, v36, v13
	v_mul_f32_e32 v20, v36, v10
	v_fmac_f32_e32 v27, v37, v13
	v_mul_f32_e32 v35, v37, v10
	v_fmac_f32_e32 v26, v38, v13
	v_mul_f32_e32 v10, v38, v10
	v_fmac_f32_e32 v23, v12, v15
	v_mul_f32_e32 v38, v12, v14
	v_lshl_add_u64 v[12:13], s[22:23], 0, v[88:89]
	s_lshl_b64 s[4:5], s[8:9], 12
	v_fmac_f32_e32 v24, v40, v15
	v_mul_f32_e32 v37, v40, v14
	v_fmac_f32_e32 v7, v4, v41
	v_mul_f32_e32 v40, v4, v17
	v_lshl_add_u64 v[94:95], v[12:13], 0, s[4:5]
	v_lshlrev_b32_e32 v12, 14, v93
	v_mul_f32_e32 v4, v32, v0
	v_mov_b32_e32 v13, v89
	v_fmac_f32_e32 v18, v32, v3
	v_cvt_pk_bf16_f32 v4, v18, v4
	v_lshl_add_u64 v[96:97], v[94:95], 0, v[12:13]
	global_load_dword v172, v[130:131], off offset:128
	global_load_dword v173, v[126:127], off offset:128
	global_load_dword v174, v[128:129], off offset:128
	global_store_dword v[96:97], v4, off nt
	v_mul_f32_e32 v4, v33, v0
	v_or_b32_e32 v88, 0x1000, v12
	v_fmac_f32_e32 v21, v22, v15
	v_mul_f32_e32 v22, v22, v14
	v_fmac_f32_e32 v25, v39, v15
	v_mul_f32_e32 v36, v39, v14
	v_fmac_f32_e32 v31, v33, v3
	v_cvt_pk_bf16_f32 v4, v31, v4
	v_lshl_add_u64 v[14:15], v[94:95], 0, v[88:89]
	v_or_b32_e32 v98, 0x2000, v12
	v_mov_b32_e32 v99, v89
	global_store_dword v[14:15], v4, off nt
	v_mul_f32_e32 v4, v34, v0
	v_lshl_add_u64 v[14:15], v[94:95], 0, v[98:99]
	v_fmac_f32_e32 v29, v1, v3
	v_mul_f32_e32 v1, v1, v0
	v_or_b32_e32 v100, 0x3000, v12
	v_mov_b32_e32 v101, v89
	v_fmac_f32_e32 v30, v34, v3
	v_cvt_pk_bf16_f32 v4, v30, v4
	global_store_dword v[14:15], v4, off nt
	v_cvt_pk_bf16_f32 v1, v29, v1
	v_lshl_add_u64 v[14:15], v[94:95], 0, v[100:101]
	global_store_dword v[14:15], v1, off nt
	v_mul_f32_e32 v1, v2, v0
	v_or_b32_e32 v102, 0x8000, v12
	v_mov_b32_e32 v103, v89
	v_fmac_f32_e32 v19, v2, v3
	v_cvt_pk_bf16_f32 v1, v19, v1
	v_lshl_add_u64 v[14:15], v[94:95], 0, v[102:103]
	global_store_dword v[14:15], v1, off nt
	v_mul_f32_e32 v1, v20, v0
	v_or_b32_e32 v104, 0x9000, v12
	v_mov_b32_e32 v105, v89
	v_fmac_f32_e32 v28, v20, v3
	v_cvt_pk_bf16_f32 v1, v28, v1
	v_lshl_add_u64 v[14:15], v[94:95], 0, v[104:105]
	global_store_dword v[14:15], v1, off nt
	v_mul_f32_e32 v1, v35, v0
	v_or_b32_e32 v106, 0xa000, v12
	v_mov_b32_e32 v107, v89
	v_fmac_f32_e32 v27, v35, v3
	v_cvt_pk_bf16_f32 v1, v27, v1
	v_lshl_add_u64 v[14:15], v[94:95], 0, v[106:107]
	global_store_dword v[14:15], v1, off nt
	v_mul_f32_e32 v1, v10, v0
	v_or_b32_e32 v108, 0xb000, v12
	v_mov_b32_e32 v109, v89
	v_fmac_f32_e32 v26, v10, v3
	v_cvt_pk_bf16_f32 v1, v26, v1
	v_lshl_add_u64 v[14:15], v[94:95], 0, v[108:109]
	global_store_dword v[14:15], v1, off nt
	v_mul_f32_e32 v1, v22, v0
	v_or_b32_e32 v110, 0x10000, v12
	v_mov_b32_e32 v111, v89
	v_fmac_f32_e32 v21, v22, v3
	v_cvt_pk_bf16_f32 v1, v21, v1
	v_lshl_add_u64 v[14:15], v[94:95], 0, v[110:111]
	global_store_dword v[14:15], v1, off nt
	v_mul_f32_e32 v1, v36, v0
	v_or_b32_e32 v112, 0x11000, v12
	v_mov_b32_e32 v113, v89
	v_fmac_f32_e32 v25, v36, v3
	v_cvt_pk_bf16_f32 v1, v25, v1
	v_lshl_add_u64 v[14:15], v[94:95], 0, v[112:113]
	global_store_dword v[14:15], v1, off nt
	v_mul_f32_e32 v1, v37, v0
	v_or_b32_e32 v114, 0x12000, v12
	v_mov_b32_e32 v115, v89
	v_fmac_f32_e32 v24, v37, v3
	v_cvt_pk_bf16_f32 v1, v24, v1
	v_lshl_add_u64 v[14:15], v[94:95], 0, v[114:115]
	global_store_dword v[14:15], v1, off nt
	v_mul_f32_e32 v1, v38, v0
	v_or_b32_e32 v116, 0x13000, v12
	v_mov_b32_e32 v117, v89
	v_fmac_f32_e32 v8, v16, v41
	v_mul_f32_e32 v16, v16, v17
	v_fmac_f32_e32 v23, v38, v3
	v_cvt_pk_bf16_f32 v1, v23, v1
	v_lshl_add_u64 v[14:15], v[94:95], 0, v[116:117]
	global_store_dword v[14:15], v1, off nt
	v_fmac_f32_e32 v8, v16, v3
	v_mul_f32_e32 v1, v16, v0
	v_or_b32_e32 v118, 0x18000, v12
	v_mov_b32_e32 v119, v89
	v_fmac_f32_e32 v5, v9, v41
	v_mul_f32_e32 v39, v9, v17
	v_cvt_pk_bf16_f32 v1, v8, v1
	v_lshl_add_u64 v[8:9], v[94:95], 0, v[118:119]
	global_store_dword v[8:9], v1, off nt
	v_fmac_f32_e32 v5, v39, v3
	v_mul_f32_e32 v1, v39, v0
	v_or_b32_e32 v120, 0x19000, v12
	v_mov_b32_e32 v121, v89
	v_cvt_pk_bf16_f32 v1, v5, v1
	v_lshl_add_u64 v[4:5], v[94:95], 0, v[120:121]
	v_fmac_f32_e32 v11, v6, v41
	v_mul_f32_e32 v6, v6, v17
	s_lshl_b32 s6, s63, 11
	global_store_dword v[4:5], v1, off nt
	v_mul_f32_e32 v1, v40, v0
	v_or_b32_e32 v122, 0x1a000, v12
	v_mov_b32_e32 v123, v89
	s_or_b32 s6, s6, s70
	v_fmac_f32_e32 v7, v40, v3
	v_cvt_pk_bf16_f32 v1, v7, v1
	v_lshl_add_u64 v[4:5], v[94:95], 0, v[122:123]
	v_mul_f32_e32 v0, v6, v0
	v_or_b32_e32 v124, 0x1b000, v12
	v_mov_b32_e32 v125, v89
	v_lshl_add_u32 v142, v92, 3, 16
	v_cmp_gt_i32_e64 s[4:5], 32, v92
	v_add_u32_e32 v92, s6, v92
	global_store_dword v[4:5], v1, off nt
	v_fmac_f32_e32 v11, v6, v3
	v_cvt_pk_bf16_f32 v2, v11, v0
	v_lshl_add_u64 v[0:1], v[94:95], 0, v[124:125]
	global_store_dword v[0:1], v2, off nt
	s_and_saveexec_b64 s[6:7], s[4:5]
	s_cbranch_execz .LBB0_333
	ds_read2_b64 v[0:3], v142 offset1:32
	ds_read2_b64 v[4:7], v142 offset0:64 offset1:96
	ds_read2_b64 v[8:11], v142 offset0:128 offset1:160
	ds_read2_b64 v[12:15], v142 offset0:192 offset1:224
	v_ashrrev_i32_e32 v93, 31, v92
	s_waitcnt lgkmcnt(3)
	v_fma_f32 v16, 0, v0, v1
	v_pk_mul_f32 v[0:1], v[0:1], v[2:3]
	v_fma_f32 v2, v2, v16, v3
	s_waitcnt lgkmcnt(2)
	v_fma_f32 v2, v4, v2, v5
	v_fma_f32 v2, v6, v2, v7
	s_waitcnt lgkmcnt(1)
	v_fma_f32 v3, v8, v2, v9
	v_mov_b32_e32 v2, v0
	v_mov_b32_e32 v16, v4
	v_mov_b32_e32 v17, v10
	v_pk_mul_f32 v[0:1], v[0:1], v[4:5]
	v_pk_fma_f32 v[2:3], v[2:3], v[16:17], v[10:11]
	v_pk_mul_f32 v[0:1], v[0:1], v[6:7]
	s_waitcnt lgkmcnt(0)
	v_mov_b32_e32 v9, v12
	v_mov_b32_e32 v1, v3
	v_pk_mul_f32 v[2:3], v[0:1], v[8:9]
	v_pk_fma_f32 v[0:1], v[0:1], v[8:9], v[12:13]
	v_pk_mul_f32 v[2:3], v[2:3], v[10:11]
	v_mov_b32_e32 v4, v12
	v_mov_b32_e32 v0, v2
	v_mov_b32_e32 v5, v14
	v_pk_mul_f32 v[2:3], v[2:3], v[12:13]
	v_pk_fma_f32 v[0:1], v[0:1], v[4:5], v[14:15]
	v_pk_mul_f32 v[2:3], v[2:3], v[14:15]
	s_nop 0
	v_mov_b32_e32 v3, v1
	v_lshl_add_u64 v[0:1], v[92:93], 3, s[24:25]
	global_store_dwordx2 v[0:1], v[2:3], off
.LBB0_333:
	s_or_b64 exec, exec, s[6:7]
	s_setprio 1
	ds_read_b128 v[0:3], v148 offset:24576
	ds_read_b128 v[4:7], v148 offset:57344
	s_waitcnt lgkmcnt(1)
	v_mfma_f32_32x32x16_bf16 v[32:47], v[48:51], v[0:3], 0
	s_waitcnt lgkmcnt(0)
	v_mfma_f32_32x32x16_bf16 v[16:31], v[48:51], v[4:7], 0
	ds_read_b128 v[0:3], v150 offset:24576
	ds_read_b128 v[4:7], v150 offset:57344
	s_waitcnt lgkmcnt(1)
	v_mfma_f32_32x32x16_bf16 v[32:47], v[52:55], v[0:3], v[32:47]
	s_waitcnt lgkmcnt(0)
	v_mfma_f32_32x32x16_bf16 v[16:31], v[52:55], v[4:7], v[16:31]
	ds_read_b128 v[0:3], v145 offset:24576
	ds_read_b128 v[4:7], v145 offset:57344
	s_waitcnt lgkmcnt(1)
	v_mfma_f32_32x32x16_bf16 v[32:47], v[56:59], v[0:3], v[32:47]
	s_waitcnt lgkmcnt(0)
	v_mfma_f32_32x32x16_bf16 v[16:31], v[56:59], v[4:7], v[16:31]
	ds_read_b128 v[0:3], v149 offset:24576
	ds_read_b128 v[4:7], v149 offset:57344
	s_waitcnt lgkmcnt(1)
	v_mfma_f32_32x32x16_bf16 v[32:47], v[60:63], v[0:3], v[32:47]
	s_waitcnt lgkmcnt(0)
	v_mfma_f32_32x32x16_bf16 v[16:31], v[60:63], v[4:7], v[16:31]
	ds_read_b128 v[0:3], v144 offset:24576
	ds_read_b128 v[4:7], v144 offset:57344
	s_waitcnt lgkmcnt(1)
	v_mfma_f32_32x32x16_bf16 v[32:47], v[64:67], v[0:3], v[32:47]
	s_waitcnt lgkmcnt(0)
	v_mfma_f32_32x32x16_bf16 v[16:31], v[64:67], v[4:7], v[16:31]
	ds_read_b128 v[0:3], v147 offset:24576
	ds_read_b128 v[4:7], v147 offset:57344
	s_waitcnt lgkmcnt(1)
	v_mfma_f32_32x32x16_bf16 v[32:47], v[68:71], v[0:3], v[32:47]
	s_waitcnt lgkmcnt(0)
	v_mfma_f32_32x32x16_bf16 v[16:31], v[68:71], v[4:7], v[16:31]
	ds_read_b128 v[0:3], v143 offset:24576
	ds_read_b128 v[4:7], v143 offset:57344
	s_waitcnt lgkmcnt(1)
	v_mfma_f32_32x32x16_bf16 v[32:47], v[72:75], v[0:3], v[32:47]
	s_waitcnt lgkmcnt(0)
	v_mfma_f32_32x32x16_bf16 v[16:31], v[72:75], v[4:7], v[16:31]
	ds_read_b128 v[0:3], v146 offset:24576
	ds_read_b128 v[4:7], v146 offset:57344
	s_waitcnt lgkmcnt(1)
	v_mfma_f32_32x32x16_bf16 v[32:47], v[76:79], v[0:3], v[32:47]
	s_waitcnt lgkmcnt(0)
	v_mfma_f32_32x32x16_bf16 v[16:31], v[76:79], v[4:7], v[16:31]
	v_mfma_f32_32x32x16_bf16 v[0:15], v[56:59], v[80:83], 0
	v_mfma_f32_32x32x16_bf16 v[0:15], v[60:63], v[84:87], v[0:15]
	s_setprio 0
	s_waitcnt vmcnt(16)
	v_mov_b32_e32 v91, v172
	v_mov_b32_e32 v151, v173
	v_mov_b32_e32 v93, v174
	v_mul_f32_e32 v91, 0xbfb8aa3b, v91
	v_exp_f32_e32 v160, v91
	v_add_f32_e32 v32, v32, v151
	v_add_f32_e32 v34, v34, v151
	v_add_f32_e32 v33, v33, v151
	v_add_f32_e32 v35, v35, v151
	v_mul_f32_e32 v32, 0xbfb8aa3b, v32
	v_mul_f32_e32 v34, 0xbfb8aa3b, v34
	v_add_f32_e32 v16, v16, v93
	v_add_f32_e32 v17, v17, v93
	v_mul_f32_e32 v33, 0xbfb8aa3b, v33
	v_mul_f32_e32 v35, 0xbfb8aa3b, v35
	v_exp_f32_e32 v32, v32
	v_exp_f32_e32 v34, v34
	v_mul_f32_e32 v16, 0xbfb8aa3b, v16
	v_mul_f32_e32 v17, 0xbfb8aa3b, v17
	v_exp_f32_e32 v33, v33
	v_exp_f32_e32 v161, v35
	v_add_f32_e32 v35, 1.0, v160
	v_exp_f32_e32 v91, v16
	v_exp_f32_e32 v152, v17
	v_frexp_mant_f32_e32 v154, v35
	v_cvt_f64_f32_e32 v[16:17], v35
	v_add_f32_e32 v153, -1.0, v35
	v_frexp_exp_i32_f64_e32 v16, v[16:17]
	v_cmp_gt_f32_e32 vcc, s84, v154
	v_add_f32_e32 v32, 1.0, v32
	v_add_f32_e32 v162, 1.0, v34
	v_sub_f32_e32 v34, v153, v35
	v_subbrev_co_u32_e32 v16, vcc, 0, v16, vcc
	v_add_f32_e32 v33, 1.0, v33
	v_sub_f32_e32 v153, v160, v153
	v_rcp_f32_e32 v163, v32
	v_add_f32_e32 v17, 1.0, v34
	v_sub_u32_e32 v32, 0, v16
	v_rcp_f32_e32 v165, v33
	v_add_f32_e32 v17, v153, v17
	v_ldexp_f32 v33, v35, v32
	v_add_f32_e32 v91, 1.0, v91
	v_ldexp_f32 v17, v17, v32
	v_add_f32_e32 v32, -1.0, v33
	v_add_f32_e32 v34, 1.0, v33
	v_rcp_f32_e32 v164, v91
	v_add_f32_e32 v35, 1.0, v32
	v_add_f32_e32 v91, -1.0, v34
	v_sub_f32_e32 v35, v33, v35
	v_sub_f32_e32 v33, v33, v91
	v_add_f32_e32 v35, v17, v35
	v_add_f32_e32 v17, v17, v33
	v_add_f32_e32 v91, v34, v17
	v_rcp_f32_e32 v154, v91
	v_add_f32_e32 v33, v32, v35
	v_sub_f32_e32 v34, v91, v34
	v_add_f32_e32 v152, 1.0, v152
	v_mul_f32_e32 v156, v33, v154
	v_sub_f32_e32 v17, v17, v34
	v_mul_f32_e32 v34, v91, v156
	v_rcp_f32_e32 v166, v152
	v_fma_f32 v152, v156, v91, -v34
	v_sub_f32_e32 v32, v33, v32
	v_fmac_f32_e32 v152, v156, v17
	v_sub_f32_e32 v155, v35, v32
	v_add_f32_e32 v32, v34, v152
	v_sub_f32_e32 v35, v33, v32
	v_mov_b32_e32 v153, v32
	v_pk_add_f32 v[32:33], v[32:33], v[34:35] neg_lo:[0,1] neg_hi:[0,1]
	v_cvt_f32_i32_e32 v16, v16
	v_pk_add_f32 v[32:33], v[32:33], v[152:153] neg_lo:[0,1] neg_hi:[0,1]
	v_cmp_neq_f32_e32 vcc, s86, v160
	v_add_f32_e32 v33, v155, v33
	v_add_f32_e32 v32, v32, v33
	v_add_f32_e32 v33, v35, v32
	v_mul_f32_e32 v153, v154, v33
	v_mul_f32_e32 v34, v91, v153
	v_sub_f32_e32 v35, v35, v33
	v_add_f32_e32 v157, v156, v153
	v_fma_f32 v152, v153, v91, -v34
	v_add_f32_e32 v155, v32, v35
	v_sub_f32_e32 v32, v157, v156
	v_fmac_f32_e32 v152, v153, v17
	v_sub_f32_e32 v17, v153, v32
	v_add_f32_e32 v32, v34, v152
	v_sub_f32_e32 v35, v33, v32
	v_mov_b32_e32 v153, v32
	v_pk_add_f32 v[32:33], v[32:33], v[34:35] neg_lo:[0,1] neg_hi:[0,1]
	v_add_f32_e32 v18, v18, v93
	v_pk_add_f32 v[32:33], v[32:33], v[152:153] neg_lo:[0,1] neg_hi:[0,1]
	v_mul_f32_e32 v18, 0xbfb8aa3b, v18
	v_add_f32_e32 v33, v155, v33
	v_add_f32_e32 v32, v32, v33
	v_add_f32_e32 v32, v35, v32
	v_mul_f32_e32 v32, v154, v32
	v_add_f32_e32 v17, v17, v32
	v_add_f32_e32 v32, v157, v17
	v_mul_f32_e32 v34, v32, v32
	v_sub_f32_e32 v35, v32, v157
	v_fmamk_f32 v91, v34, 0x3e9b6dac, v133
	v_sub_f32_e32 v35, v17, v35
	v_mul_f32_e32 v17, v32, v34
	v_fmaak_f32 v91, v34, v91, 0x3f2aaada
	v_ldexp_f32 v153, v35, 1
	v_pk_mul_f32 v[34:35], v[16:17], v[90:91]
	v_ldexp_f32 v33, v32, 1
	v_fma_f32 v32, v16, s85, -v34
	v_fmac_f32_e32 v32, 0xb102e308, v16
	v_pk_add_f32 v[16:17], v[34:35], v[32:33]
	v_mov_b32_e32 v152, v34
	v_sub_f32_e32 v91, v17, v33
	v_pk_add_f32 v[154:155], v[16:17], v[34:35] neg_lo:[0,1] neg_hi:[0,1]
	v_sub_f32_e32 v34, v35, v91
	v_add_f32_e32 v153, v153, v34
	v_pk_add_f32 v[34:35], v[16:17], v[152:153]
	v_mov_b32_e32 v33, v16
	v_mov_b32_e32 v155, v35
	v_pk_add_f32 v[158:159], v[32:33], v[154:155] neg_lo:[0,1] neg_hi:[0,1]
	v_pk_add_f32 v[32:33], v[32:33], v[154:155]
	v_mov_b32_e32 v157, v16
	v_pk_add_f32 v[154:155], v[32:33], v[16:17] op_sel:[1,0] op_sel_hi:[0,1] neg_lo:[0,1] neg_hi:[0,1]
	v_mov_b32_e32 v156, v153
	v_mov_b32_e32 v152, v35
	v_mov_b32_e32 v153, v33
	v_pk_mov_b32 v[16:17], v[16:17], v[154:155] op_sel:[1,0]
	v_pk_add_f32 v[34:35], v[34:35], v[154:155] op_sel_hi:[1,0] neg_lo:[0,1] neg_hi:[0,1]
	v_pk_add_f32 v[16:17], v[152:153], v[16:17] neg_lo:[0,1] neg_hi:[0,1]
	v_mov_b32_e32 v34, v158
	v_pk_add_f32 v[16:17], v[156:157], v[16:17] neg_lo:[0,1] neg_hi:[0,1]
	v_mov_b32_e32 v159, v33
	v_pk_add_f32 v[34:35], v[34:35], v[16:17]
	v_exp_f32_e32 v18, v18
	v_pk_add_f32 v[152:153], v[34:35], v[34:35] op_sel:[0,1] op_sel_hi:[1,0]
	v_add_f32_e32 v20, v20, v93
	v_pk_add_f32 v[32:33], v[32:33], v[152:153] op_sel:[1,0] op_sel_hi:[0,1]
	v_mov_b32_e32 v35, v32
	v_mov_b32_e32 v17, v152
	v_pk_add_f32 v[152:153], v[34:35], v[158:159] neg_lo:[0,1] neg_hi:[0,1]
	v_add_f32_e32 v18, 1.0, v18
	v_sub_f32_e32 v33, v34, v152
	v_pk_add_f32 v[16:17], v[16:17], v[152:153] neg_lo:[0,1] neg_hi:[0,1]
	v_sub_f32_e32 v33, v158, v33
	v_add_f32_e32 v16, v16, v33
	v_add_f32_e32 v16, v16, v17
	v_add_f32_e32 v16, v32, v16
	v_cndmask_b32_e32 v16, v135, v16, vcc
	v_cmp_ngt_f32_e32 vcc, -1.0, v160
	v_mul_f32_e32 v20, 0xbfb8aa3b, v20
	v_exp_f32_e32 v20, v20
	v_cndmask_b32_e32 v16, v136, v16, vcc
	v_cmp_neq_f32_e32 vcc, -1.0, v160
	v_add_f32_e32 v19, v19, v93
	v_mul_f32_e32 v19, 0xbfb8aa3b, v19
	v_cndmask_b32_e32 v16, v137, v16, vcc
	v_cmp_lt_f32_e64 vcc, |v160|, s87
	v_exp_f32_e32 v19, v19
	v_add_f32_e32 v21, v21, v93
	v_cndmask_b32_e32 v16, v16, v160, vcc
	v_mul_f32_e32 v33, 0xc1000000, v16
	v_mul_f32_e32 v16, v163, v33
	v_mul_f32_e32 v16, 0x3fb8aa3b, v16
	v_exp_f32_e32 v32, v16
	v_mul_f32_e32 v17, v165, v33
	v_mul_f32_e32 v17, 0x3fb8aa3b, v17
	v_exp_f32_e32 v34, v17
	v_rcp_f32_e32 v16, v162
	v_rcp_f32_e32 v17, v18
	v_fma_f32 v18, -v32, v32, 1.0
	v_sqrt_f32_e32 v18, v18
	v_mul_f32_e32 v16, v16, v33
	v_mul_f32_e32 v16, 0x3fb8aa3b, v16
	v_add_f32_e32 v19, 1.0, v19
	v_mul_f32_e32 v18, v164, v18
	v_mul_f32_e32 v18, v0, v18
	v_exp_f32_e32 v0, v16
	v_add_f32_e32 v16, 1.0, v161
	v_rcp_f32_e32 v16, v16
	v_rcp_f32_e32 v19, v19
	v_fma_f32 v91, -v0, v0, 1.0
	v_sqrt_f32_e32 v91, v91
	v_mul_f32_e32 v16, v16, v33
	v_mul_f32_e32 v16, 0x3fb8aa3b, v16
	v_exp_f32_e32 v152, v16
	v_add_f32_e32 v16, v36, v151
	v_mul_f32_e32 v16, 0xbfb8aa3b, v16
	v_exp_f32_e32 v16, v16
	v_mul_f32_e32 v91, v17, v91
	v_add_f32_e32 v17, 1.0, v20
	v_fma_f32 v36, -v152, v152, 1.0
	v_add_f32_e32 v16, 1.0, v16
	v_rcp_f32_e32 v16, v16
	v_sqrt_f32_e32 v36, v36
	v_rcp_f32_e32 v17, v17
	v_mul_f32_e32 v21, 0xbfb8aa3b, v21
	v_mul_f32_e32 v16, v16, v33
	v_mul_f32_e32 v16, 0x3fb8aa3b, v16
	v_exp_f32_e32 v20, v16
	v_add_f32_e32 v16, v37, v151
	v_mul_f32_e32 v16, 0xbfb8aa3b, v16
	v_exp_f32_e32 v16, v16
	v_mul_f32_e32 v36, v19, v36
	v_fma_f32 v19, -v20, v20, 1.0
	v_sqrt_f32_e32 v19, v19
	v_add_f32_e32 v16, 1.0, v16
	v_rcp_f32_e32 v16, v16
	v_exp_f32_e32 v21, v21
	v_mul_f32_e32 v17, v17, v19
	v_mul_f32_e32 v19, v4, v17
	v_mul_f32_e32 v16, v16, v33
	v_mul_f32_e32 v16, 0x3fb8aa3b, v16
	v_exp_f32_e32 v37, v16
	v_add_f32_e32 v16, v38, v151
	v_mul_f32_e32 v16, 0xbfb8aa3b, v16
	v_exp_f32_e32 v16, v16
	v_add_f32_e32 v4, 1.0, v21
	v_add_f32_e32 v21, v22, v93
	v_mul_f32_e32 v21, 0xbfb8aa3b, v21
	v_add_f32_e32 v16, 1.0, v16
	v_rcp_f32_e32 v16, v16
	v_fma_f32 v17, -v37, v37, 1.0
	v_exp_f32_e32 v21, v21
	v_rcp_f32_e32 v4, v4
	v_mul_f32_e32 v16, v16, v33
	v_mul_f32_e32 v16, 0x3fb8aa3b, v16
	v_sqrt_f32_e32 v17, v17
	v_exp_f32_e32 v38, v16
	v_add_f32_e32 v16, 1.0, v21
	v_add_f32_e32 v21, v39, v151
	v_mul_f32_e32 v4, v4, v17
	v_fma_f32 v17, -v38, v38, 1.0
	v_mul_f32_e32 v21, 0xbfb8aa3b, v21
	v_rcp_f32_e32 v16, v16
	v_sqrt_f32_e32 v17, v17
	v_exp_f32_e32 v21, v21
	v_add_f32_e32 v22, v23, v93
	v_mul_f32_e32 v22, 0xbfb8aa3b, v22
	v_mul_f32_e32 v23, v16, v17
	v_add_f32_e32 v16, 1.0, v21
	v_rcp_f32_e32 v16, v16
	v_add_f32_e32 v21, v40, v151
	v_mul_f32_e32 v21, 0xbfb8aa3b, v21
	v_exp_f32_e32 v21, v21
	v_mul_f32_e32 v16, v16, v33
	v_mul_f32_e32 v16, 0x3fb8aa3b, v16
	v_exp_f32_e32 v39, v16
	v_add_f32_e32 v16, 1.0, v21
	v_rcp_f32_e32 v16, v16
	v_exp_f32_e32 v22, v22
	v_add_f32_e32 v21, v24, v93
	v_mul_f32_e32 v21, 0xbfb8aa3b, v21
	v_mul_f32_e32 v16, v16, v33
	v_add_f32_e32 v17, 1.0, v22
	v_fma_f32 v22, -v39, v39, 1.0
	v_mul_f32_e32 v16, 0x3fb8aa3b, v16
	v_sqrt_f32_e32 v24, v22
	v_exp_f32_e32 v22, v16
	v_add_f32_e32 v16, v41, v151
	v_mul_f32_e32 v16, 0xbfb8aa3b, v16
	v_exp_f32_e32 v16, v16
	v_exp_f32_e32 v21, v21
	v_fma_f32 v40, -v22, v22, 1.0
	v_rcp_f32_e32 v17, v17
	v_add_f32_e32 v16, 1.0, v16
	v_rcp_f32_e32 v16, v16
	v_add_f32_e32 v21, 1.0, v21
	v_rcp_f32_e32 v21, v21
	v_sqrt_f32_e32 v40, v40
	v_mul_f32_e32 v16, v16, v33
	v_mul_f32_e32 v16, 0x3fb8aa3b, v16
	v_mul_f32_e32 v24, v17, v24
	v_mul_f32_e32 v17, v21, v40
	v_exp_f32_e32 v40, v16
	v_add_f32_e32 v16, v42, v151
	v_add_f32_e32 v25, v25, v93
	v_mul_f32_e32 v16, 0xbfb8aa3b, v16
	v_mul_f32_e32 v25, 0xbfb8aa3b, v25
	v_exp_f32_e32 v16, v16
	v_exp_f32_e32 v25, v25
	v_fma_f32 v35, -v34, v34, 1.0
	v_sqrt_f32_e32 v35, v35
	v_add_f32_e32 v16, 1.0, v16
	v_add_f32_e32 v21, 1.0, v25
	v_rcp_f32_e32 v16, v16
	v_rcp_f32_e32 v25, v21
	v_fma_f32 v21, -v40, v40, 1.0
	v_sqrt_f32_e32 v41, v21
	v_add_f32_e32 v21, v26, v93
	v_mul_f32_e32 v16, v16, v33
	v_mul_f32_e32 v21, 0xbfb8aa3b, v21
	v_mul_f32_e32 v16, 0x3fb8aa3b, v16
	v_exp_f32_e32 v26, v21
	v_mul_f32_e32 v21, v8, v17
	v_mul_f32_e32 v8, v25, v41
	v_exp_f32_e32 v41, v16
	v_add_f32_e32 v16, v43, v151
	v_mul_f32_e32 v16, 0xbfb8aa3b, v16
	v_exp_f32_e32 v16, v16
	v_add_f32_e32 v17, 1.0, v26
	v_fma_f32 v25, -v41, v41, 1.0
	v_add_f32_e32 v26, v27, v93
	v_add_f32_e32 v16, 1.0, v16
	v_rcp_f32_e32 v16, v16
	v_rcp_f32_e32 v17, v17
	v_sqrt_f32_e32 v25, v25
	v_mul_f32_e32 v26, 0xbfb8aa3b, v26
	v_mul_f32_e32 v16, v16, v33
	v_exp_f32_e32 v26, v26
	v_mul_f32_e32 v16, 0x3fb8aa3b, v16
	v_exp_f32_e32 v153, v16
	v_mul_f32_e32 v154, v17, v25
	v_add_f32_e32 v25, v44, v151
	v_add_f32_e32 v16, 1.0, v26
	v_mul_f32_e32 v25, 0xbfb8aa3b, v25
	v_add_f32_e32 v26, v28, v93
	v_fma_f32 v17, -v153, v153, 1.0
	v_exp_f32_e32 v25, v25
	v_mul_f32_e32 v26, 0xbfb8aa3b, v26
	v_rcp_f32_e32 v16, v16
	v_sqrt_f32_e32 v17, v17
	v_exp_f32_e32 v26, v26
	v_add_f32_e32 v25, 1.0, v25
	v_rcp_f32_e32 v25, v25
	v_mul_f32_e32 v155, v16, v17
	v_add_f32_e32 v16, 1.0, v26
	v_add_f32_e32 v26, v29, v93
	v_mul_f32_e32 v26, 0xbfb8aa3b, v26
	v_exp_f32_e32 v26, v26
	v_rcp_f32_e32 v17, v16
	v_mul_f32_e32 v16, v25, v33
	v_add_f32_e32 v25, v45, v151
	v_mul_f32_e32 v25, 0xbfb8aa3b, v25
	v_exp_f32_e32 v25, v25
	v_add_f32_e32 v26, 1.0, v26
	v_rcp_f32_e32 v42, v26
	v_add_f32_e32 v26, v46, v151
	v_mul_f32_e32 v26, 0xbfb8aa3b, v26
	v_exp_f32_e32 v26, v26
	v_add_f32_e32 v25, 1.0, v25
	v_rcp_f32_e32 v25, v25
	v_add_f32_e32 v27, v30, v93
	v_mul_f32_e32 v27, 0xbfb8aa3b, v27
	v_exp_f32_e32 v27, v27
	v_add_f32_e32 v26, 1.0, v26
	v_rcp_f32_e32 v26, v26
	v_mul_f32_e32 v25, v25, v33
	v_mul_f32_e32 v25, 0x3fb8aa3b, v25
	v_exp_f32_e32 v43, v25
	v_add_f32_e32 v25, 1.0, v27
	v_rcp_f32_e32 v44, v25
	v_mul_f32_e32 v25, v26, v33
	v_add_f32_e32 v26, v47, v151
	v_mul_f32_e32 v26, 0xbfb8aa3b, v26
	v_exp_f32_e32 v26, v26
	v_add_f32_e32 v27, v31, v93
	v_mul_f32_e32 v27, 0xbfb8aa3b, v27
	v_exp_f32_e32 v27, v27
	v_add_f32_e32 v26, 1.0, v26
	v_mul_f32_e32 v16, 0x3fb8aa3b, v16
	v_rcp_f32_e32 v26, v26
	v_exp_f32_e32 v16, v16
	v_mul_f32_e32 v25, 0x3fb8aa3b, v25
	v_fmac_f32_e32 v18, 0, v32
	v_mul_f32_e32 v35, v166, v35
	v_exp_f32_e32 v45, v25
	v_add_f32_e32 v25, 1.0, v27
	v_mul_f32_e32 v31, v34, v18
	v_rcp_f32_e32 v46, v25
	v_mul_f32_e32 v25, v26, v33
	v_fmac_f32_e32 v31, v1, v35
	v_mul_f32_e32 v33, v32, v34
	v_fmac_f32_e32 v19, 0, v20
	v_mul_f32_e32 v30, v0, v31
	v_mul_f32_e32 v34, v0, v33
	v_mul_f32_e32 v28, v37, v19
	v_fma_f32 v0, -v16, v16, 1.0
	v_fmac_f32_e32 v28, v5, v4
	v_sqrt_f32_e32 v1, v0
	v_mul_f32_e32 v27, v38, v28
	v_fmac_f32_e32 v30, v2, v91
	v_fmac_f32_e32 v27, v6, v23
	v_fma_f32 v2, -v43, v43, 1.0
	v_mul_f32_e32 v26, v39, v27
	v_mov_b32_e32 v0, v89
	v_sqrt_f32_e32 v2, v2
	v_fmac_f32_e32 v26, v7, v24
	v_pk_mul_f32 v[6:7], v[16:17], v[0:1]
	v_mul_f32_e32 v29, v152, v30
	v_fmac_f32_e32 v6, v12, v7
	v_fmac_f32_e32 v29, v3, v36
	v_mov_b32_e32 v3, v6
	v_mul_f32_e32 v25, 0x3fb8aa3b, v25
	v_pk_mul_f32 v[4:5], v[42:43], v[2:3]
	v_fma_f32 v0, -v45, v45, 1.0
	v_exp_f32_e32 v47, v25
	v_fmac_f32_e32 v5, v13, v4
	v_sqrt_f32_e32 v4, v0
	v_fmac_f32_e32 v21, 0, v22
	v_mul_f32_e32 v25, v40, v21
	v_fmac_f32_e32 v25, v9, v8
	v_pk_mul_f32 v[8:9], v[44:45], v[4:5]
	v_fma_f32 v0, -v47, v47, 1.0
	v_fmac_f32_e32 v9, v14, v8
	v_sqrt_f32_e32 v8, v0
	ds_bpermute_b32 v0, v140, v29
	v_mul_f32_e32 v24, v41, v25
	v_mul_f32_e32 v35, v152, v34
	v_mul_f32_e32 v36, v20, v37
	v_fmac_f32_e32 v24, v10, v154
	v_mul_f32_e32 v37, v38, v36
	v_mul_f32_e32 v23, v153, v24
	ds_bpermute_b32 v13, v140, v35
	v_mul_f32_e32 v38, v39, v37
	v_fmac_f32_e32 v23, v11, v155
	v_pk_mul_f32 v[10:11], v[46:47], v[8:9]
	s_waitcnt lgkmcnt(1)
	v_cndmask_b32_e64 v14, v29, v0, s[0:1]
	v_fmac_f32_e32 v11, v15, v10
	v_cndmask_b32_e64 v10, v0, v29, s[0:1]
	ds_bpermute_b32 v0, v140, v38
	ds_bpermute_b32 v3, v140, v26
	v_mul_f32_e32 v39, v22, v40
	v_mul_f32_e32 v40, v41, v39
	s_waitcnt lgkmcnt(2)
	v_cndmask_b32_e64 v1, v13, v35, s[0:1]
	v_mul_f32_e32 v12, v153, v40
	v_mul_f32_e32 v7, v16, v43
	v_cndmask_b32_e64 v2, v35, v13, s[0:1]
	v_fmac_f32_e32 v10, 0, v1
	v_mul_f32_e32 v4, v45, v7
	v_mul_f32_e32 v15, v35, v13
	v_fmac_f32_e32 v14, v2, v10
	s_waitcnt lgkmcnt(1)
	v_cndmask_b32_e64 v1, v0, v38, s[0:1]
	s_waitcnt lgkmcnt(0)
	v_cndmask_b32_e64 v17, v3, v26, s[0:1]
	v_cndmask_b32_e64 v41, v26, v3, s[0:1]
	ds_bpermute_b32 v2, v140, v12
	ds_bpermute_b32 v3, v140, v23
	v_mul_f32_e32 v8, v47, v4
	v_cndmask_b32_e64 v0, v38, v0, s[0:1]
	v_mul_f32_e32 v42, v15, v1
	v_fmac_f32_e32 v17, v1, v14
	v_mul_f32_e32 v43, v0, v42
	v_fmac_f32_e32 v41, v0, v17
	ds_bpermute_b32 v1, v140, v8
	ds_bpermute_b32 v0, v140, v11
	s_waitcnt lgkmcnt(3)
	v_cndmask_b32_e64 v47, v2, v12, s[0:1]
	s_waitcnt lgkmcnt(2)
	v_cndmask_b32_e64 v44, v3, v23, s[0:1]
	v_cndmask_b32_e64 v2, v12, v2, s[0:1]
	v_cndmask_b32_e64 v45, v23, v3, s[0:1]
	v_mul_f32_e32 v46, v47, v43
	v_fmac_f32_e32 v44, v47, v41
	v_mul_f32_e32 v47, v2, v46
	v_fmac_f32_e32 v45, v2, v44
	s_waitcnt lgkmcnt(1)
	v_cndmask_b32_e64 v2, v1, v8, s[0:1]
	s_waitcnt lgkmcnt(0)
	v_cndmask_b32_e64 v91, v0, v11, s[0:1]
	v_mul_f32_e32 v93, v2, v47
	v_fmac_f32_e32 v91, v2, v45
	s_and_saveexec_b64 s[6:7], s[0:1]
	v_mul_f32_e32 v3, v91, v1
	v_mul_f32_e32 v2, v93, v1
	v_add_f32_e32 v3, v3, v0
	ds_write_b64 v139, v[2:3] offset:2048
	s_or_b64 exec, exec, s[6:7]
	v_cndmask_b32_e64 v0, 0, 1, s[12:13]
	v_cmp_ne_u32_e64 s[6:7], 1, v0
	s_andn2_b64 vcc, exec, s[12:13]
	s_waitcnt lgkmcnt(0)
	s_barrier
	s_cbranch_vccnz .LBB0_340
	s_cmp_lt_u32 s62, 8
	s_cbranch_scc1 .LBB0_341
	s_add_i32 s9, 16, 0x800
	s_and_b32 s8, s62, 0x7ffffff8
	v_add3_u32 v151, v141, v138, s9
	v_mov_b32_e32 v0, 1.0
	v_mov_b32_e32 v3, 0
	s_mov_b32 s9, 0

.LBB0_344:
	v_cndmask_b32_e64 v1, v13, 1.0, s[0:1]
	v_cndmask_b32_e64 v2, v10, 0, s[0:1]
	v_cndmask_b32_e64 v10, v42, v15, s[0:1]
	v_cndmask_b32_e64 v13, v17, v14, s[0:1]
	v_cndmask_b32_e64 v14, v46, v43, s[0:1]
	v_cndmask_b32_e64 v15, v44, v41, s[0:1]
	v_cndmask_b32_e64 v17, v93, v47, s[0:1]
	v_cndmask_b32_e64 v41, v91, v45, s[0:1]
	v_fmac_f32_e32 v18, v32, v2
	v_mul_f32_e32 v32, v1, v32
	v_fmac_f32_e32 v31, v33, v2
	v_mul_f32_e32 v33, v1, v33
	v_fmac_f32_e32 v30, v34, v2
	v_mul_f32_e32 v34, v1, v34
	v_fmac_f32_e32 v29, v35, v2
	v_mul_f32_e32 v1, v1, v35
	v_fmac_f32_e32 v27, v37, v13
	v_mul_f32_e32 v35, v37, v10
	v_fmac_f32_e32 v24, v40, v15
	v_mul_f32_e32 v37, v40, v14
	v_fmac_f32_e32 v9, v4, v41
	v_mul_f32_e32 v40, v4, v17
	v_mul_f32_e32 v4, v32, v0
	v_fmac_f32_e32 v18, v32, v3
	v_cvt_pk_bf16_f32 v4, v18, v4
	v_fmac_f32_e32 v19, v20, v13
	v_mul_f32_e32 v2, v20, v10
	v_fmac_f32_e32 v28, v36, v13
	v_mul_f32_e32 v20, v36, v10
	v_fmac_f32_e32 v26, v38, v13
	v_mul_f32_e32 v10, v38, v10
	v_fmac_f32_e32 v23, v12, v15
	v_mul_f32_e32 v38, v12, v14
	v_lshl_add_u64 v[12:13], v[94:95], 0, s[38:39]
	global_load_dword v172, v[130:131], off offset:256
	global_load_dword v173, v[126:127], off offset:256
	global_load_dword v174, v[128:129], off offset:256
	global_store_dword v[96:97], v4, off offset:128 nt
	v_mul_f32_e32 v4, v33, v0
	v_fmac_f32_e32 v21, v22, v15
	v_mul_f32_e32 v22, v22, v14
	v_fmac_f32_e32 v25, v39, v15
	v_mul_f32_e32 v36, v39, v14
	v_fmac_f32_e32 v31, v33, v3
	v_cvt_pk_bf16_f32 v4, v31, v4
	v_lshl_add_u64 v[14:15], v[12:13], 0, v[88:89]
	global_store_dword v[14:15], v4, off nt
	v_mul_f32_e32 v4, v34, v0
	v_lshl_add_u64 v[14:15], v[12:13], 0, v[98:99]
	v_fmac_f32_e32 v29, v1, v3
	v_mul_f32_e32 v1, v1, v0
	v_fmac_f32_e32 v30, v34, v3
	v_cvt_pk_bf16_f32 v4, v30, v4
	global_store_dword v[14:15], v4, off nt
	v_cvt_pk_bf16_f32 v1, v29, v1
	v_lshl_add_u64 v[14:15], v[12:13], 0, v[100:101]
	global_store_dword v[14:15], v1, off nt
	v_mul_f32_e32 v1, v2, v0
	v_fmac_f32_e32 v19, v2, v3
	v_cvt_pk_bf16_f32 v1, v19, v1
	v_lshl_add_u64 v[14:15], v[12:13], 0, v[102:103]
	global_store_dword v[14:15], v1, off nt
	v_mul_f32_e32 v1, v20, v0
	v_fmac_f32_e32 v28, v20, v3
	v_cvt_pk_bf16_f32 v1, v28, v1
	v_lshl_add_u64 v[14:15], v[12:13], 0, v[104:105]
	global_store_dword v[14:15], v1, off nt
	v_mul_f32_e32 v1, v35, v0
	v_fmac_f32_e32 v27, v35, v3
	v_cvt_pk_bf16_f32 v1, v27, v1
	v_lshl_add_u64 v[14:15], v[12:13], 0, v[106:107]
	global_store_dword v[14:15], v1, off nt
	v_mul_f32_e32 v1, v10, v0
	v_fmac_f32_e32 v26, v10, v3
	v_cvt_pk_bf16_f32 v1, v26, v1
	v_lshl_add_u64 v[14:15], v[12:13], 0, v[108:109]
	global_store_dword v[14:15], v1, off nt
	v_mul_f32_e32 v1, v22, v0
	v_fmac_f32_e32 v21, v22, v3
	v_cvt_pk_bf16_f32 v1, v21, v1
	v_lshl_add_u64 v[14:15], v[12:13], 0, v[110:111]
	global_store_dword v[14:15], v1, off nt
	v_mul_f32_e32 v1, v36, v0
	v_fmac_f32_e32 v25, v36, v3
	v_cvt_pk_bf16_f32 v1, v25, v1
	v_lshl_add_u64 v[14:15], v[12:13], 0, v[112:113]
	global_store_dword v[14:15], v1, off nt
	v_mul_f32_e32 v1, v37, v0
	v_fmac_f32_e32 v24, v37, v3
	v_cvt_pk_bf16_f32 v1, v24, v1
	v_lshl_add_u64 v[14:15], v[12:13], 0, v[114:115]
	global_store_dword v[14:15], v1, off nt
	v_mul_f32_e32 v1, v38, v0
	v_fmac_f32_e32 v6, v16, v41
	v_mul_f32_e32 v16, v16, v17
	v_fmac_f32_e32 v23, v38, v3
	v_cvt_pk_bf16_f32 v1, v23, v1
	v_lshl_add_u64 v[14:15], v[12:13], 0, v[116:117]
	global_store_dword v[14:15], v1, off nt
	v_fmac_f32_e32 v6, v16, v3
	v_mul_f32_e32 v1, v16, v0
	v_fmac_f32_e32 v5, v7, v41
	v_mul_f32_e32 v39, v7, v17
	v_cvt_pk_bf16_f32 v1, v6, v1
	v_lshl_add_u64 v[6:7], v[12:13], 0, v[118:119]
	global_store_dword v[6:7], v1, off nt
	v_fmac_f32_e32 v5, v39, v3
	v_mul_f32_e32 v1, v39, v0
	v_cvt_pk_bf16_f32 v1, v5, v1
	v_lshl_add_u64 v[4:5], v[12:13], 0, v[120:121]
	v_fmac_f32_e32 v11, v8, v41
	v_mul_f32_e32 v8, v8, v17
	global_store_dword v[4:5], v1, off nt
	v_mul_f32_e32 v1, v40, v0
	v_fmac_f32_e32 v9, v40, v3
	v_cvt_pk_bf16_f32 v1, v9, v1
	v_lshl_add_u64 v[4:5], v[12:13], 0, v[122:123]
	v_mul_f32_e32 v0, v8, v0
	global_store_dword v[4:5], v1, off nt
	v_fmac_f32_e32 v11, v8, v3
	v_cvt_pk_bf16_f32 v2, v11, v0
	v_lshl_add_u64 v[0:1], v[12:13], 0, v[124:125]
	global_store_dword v[0:1], v2, off nt
	s_and_saveexec_b64 s[8:9], s[4:5]
	s_cbranch_execz .LBB0_346
	v_add_u32_e32 v12, 0x800, v142
	ds_read2_b64 v[0:3], v12 offset1:32
	ds_read2_b64 v[4:7], v12 offset0:64 offset1:96
	ds_read2_b64 v[8:11], v12 offset0:128 offset1:160
	ds_read2_b64 v[12:15], v12 offset0:192 offset1:224
	s_waitcnt lgkmcnt(3)
	v_fma_f32 v16, 0, v0, v1
	v_pk_mul_f32 v[0:1], v[0:1], v[2:3]
	v_fma_f32 v2, v2, v16, v3
	s_waitcnt lgkmcnt(2)
	v_fma_f32 v2, v4, v2, v5
	v_fma_f32 v2, v6, v2, v7
	s_waitcnt lgkmcnt(1)
	v_fma_f32 v3, v8, v2, v9
	v_mov_b32_e32 v2, v0
	v_mov_b32_e32 v16, v4
	v_mov_b32_e32 v17, v10
	v_pk_mul_f32 v[0:1], v[0:1], v[4:5]
	v_pk_fma_f32 v[2:3], v[2:3], v[16:17], v[10:11]
	v_pk_mul_f32 v[0:1], v[0:1], v[6:7]
	s_waitcnt lgkmcnt(0)
	v_mov_b32_e32 v9, v12
	v_mov_b32_e32 v1, v3
	v_pk_mul_f32 v[2:3], v[0:1], v[8:9]
	v_pk_fma_f32 v[0:1], v[0:1], v[8:9], v[12:13]
	v_pk_mul_f32 v[2:3], v[2:3], v[10:11]
	v_mov_b32_e32 v4, v12
	v_mov_b32_e32 v0, v2
	v_mov_b32_e32 v5, v14
	v_pk_mul_f32 v[2:3], v[2:3], v[12:13]
	v_pk_fma_f32 v[0:1], v[0:1], v[4:5], v[14:15]
	v_pk_mul_f32 v[2:3], v[2:3], v[14:15]
	v_add_u32_e32 v0, 32, v92
	v_mov_b32_e32 v3, v1
	v_ashrrev_i32_e32 v1, 31, v0
	v_lshl_add_u64 v[0:1], v[0:1], 3, s[24:25]
	global_store_dwordx2 v[0:1], v[2:3], off
.LBB0_346:
	s_or_b64 exec, exec, s[8:9]
	s_setprio 1
	ds_read_b128 v[0:3], v148 offset:32768
	ds_read_b128 v[4:7], v150 offset:32768
	v_add_u32_e32 v8, 0x8000, v150
	s_waitcnt lgkmcnt(1)
	v_mfma_f32_32x32x16_bf16 v[16:31], v[48:51], v[0:3], 0
	v_add_u32_e32 v0, 0x8000, v148
	ds_read_b128 v[0:3], v0 offset:32768
	ds_read_b128 v[8:11], v8 offset:32768
	s_waitcnt lgkmcnt(1)
	v_mfma_f32_32x32x16_bf16 v[32:47], v[48:51], v[0:3], 0
	v_mfma_f32_32x32x16_bf16 v[16:31], v[52:55], v[4:7], v[16:31]
	ds_read_b128 v[0:3], v145 offset:32768
	ds_read_b128 v[4:7], v149 offset:32768
	s_waitcnt lgkmcnt(2)
	v_mfma_f32_32x32x16_bf16 v[32:47], v[52:55], v[8:11], v[32:47]
	v_add_u32_e32 v8, 0x8000, v149
	ds_read_b128 v[8:11], v8 offset:32768
	s_waitcnt lgkmcnt(2)
	v_mfma_f32_32x32x16_bf16 v[16:31], v[56:59], v[0:3], v[16:31]
	v_add_u32_e32 v0, 0x8000, v145
	ds_read_b128 v[0:3], v0 offset:32768
	s_waitcnt lgkmcnt(0)
	v_mfma_f32_32x32x16_bf16 v[32:47], v[56:59], v[0:3], v[32:47]
	v_mfma_f32_32x32x16_bf16 v[16:31], v[60:63], v[4:7], v[16:31]
	ds_read_b128 v[0:3], v144 offset:32768
	ds_read_b128 v[4:7], v147 offset:32768
	v_mfma_f32_32x32x16_bf16 v[32:47], v[60:63], v[8:11], v[32:47]
	v_add_u32_e32 v8, 0x8000, v147
	ds_read_b128 v[8:11], v8 offset:32768
	s_waitcnt lgkmcnt(2)
	v_mfma_f32_32x32x16_bf16 v[16:31], v[64:67], v[0:3], v[16:31]
	v_add_u32_e32 v0, 0x8000, v144
	ds_read_b128 v[0:3], v0 offset:32768
	s_waitcnt lgkmcnt(0)
	v_mfma_f32_32x32x16_bf16 v[32:47], v[64:67], v[0:3], v[32:47]
	v_mfma_f32_32x32x16_bf16 v[16:31], v[68:71], v[4:7], v[16:31]
	ds_read_b128 v[0:3], v143 offset:32768
	ds_read_b128 v[4:7], v146 offset:32768
	v_mfma_f32_32x32x16_bf16 v[32:47], v[68:71], v[8:11], v[32:47]
	v_add_u32_e32 v8, 0x8000, v146
	ds_read_b128 v[8:11], v8 offset:32768
	s_waitcnt lgkmcnt(2)
	v_mfma_f32_32x32x16_bf16 v[16:31], v[72:75], v[0:3], v[16:31]
	v_add_u32_e32 v0, 0x8000, v143
	ds_read_b128 v[0:3], v0 offset:32768
	s_waitcnt lgkmcnt(0)
	v_mfma_f32_32x32x16_bf16 v[32:47], v[72:75], v[0:3], v[32:47]
	v_mfma_f32_32x32x16_bf16 v[16:31], v[76:79], v[4:7], v[16:31]
	v_mfma_f32_32x32x16_bf16 v[32:47], v[76:79], v[8:11], v[32:47]
	v_mfma_f32_32x32x16_bf16 v[0:15], v[64:67], v[80:83], 0
	v_mfma_f32_32x32x16_bf16 v[0:15], v[68:71], v[84:87], v[0:15]
	s_setprio 0
	s_waitcnt vmcnt(16)
	v_mov_b32_e32 v91, v172
	v_mov_b32_e32 v151, v173
	v_mov_b32_e32 v93, v174
	v_mul_f32_e32 v91, 0xbfb8aa3b, v91
	v_exp_f32_e32 v160, v91
	s_nop 0
	v_add_f32_e32 v18, v18, v151
	v_add_f32_e32 v19, v19, v151
	v_mul_f32_e32 v18, 0xbfb8aa3b, v18
	v_add_f32_e32 v16, v16, v151
	v_add_f32_e32 v32, v32, v93
	v_add_f32_e32 v17, v17, v151
	v_mul_f32_e32 v19, 0xbfb8aa3b, v19
	v_exp_f32_e32 v18, v18
	v_add_f32_e32 v33, v33, v93
	v_mul_f32_e32 v16, 0xbfb8aa3b, v16
	v_mul_f32_e32 v32, 0xbfb8aa3b, v32
	v_mul_f32_e32 v17, 0xbfb8aa3b, v17
	v_exp_f32_e32 v161, v19
	v_add_f32_e32 v19, 1.0, v160
	v_mul_f32_e32 v33, 0xbfb8aa3b, v33
	v_exp_f32_e32 v91, v16
	v_exp_f32_e32 v32, v32
	v_exp_f32_e32 v152, v17
	v_frexp_mant_f32_e32 v154, v19
	v_cvt_f64_f32_e32 v[16:17], v19
	v_exp_f32_e32 v33, v33
	v_add_f32_e32 v153, -1.0, v19
	v_frexp_exp_i32_f64_e32 v16, v[16:17]
	v_cmp_gt_f32_e32 vcc, s84, v154
	v_add_f32_e32 v162, 1.0, v18
	v_sub_f32_e32 v18, v153, v19
	v_subbrev_co_u32_e32 v16, vcc, 0, v16, vcc
	v_sub_f32_e32 v153, v160, v153
	v_add_f32_e32 v17, 1.0, v18
	v_sub_u32_e32 v18, 0, v16
	v_add_f32_e32 v32, 1.0, v32
	v_add_f32_e32 v17, v153, v17
	v_ldexp_f32 v19, v19, v18
	v_add_f32_e32 v91, 1.0, v91
	v_add_f32_e32 v33, 1.0, v33
	v_rcp_f32_e32 v164, v32
	v_ldexp_f32 v17, v17, v18
	v_add_f32_e32 v18, -1.0, v19
	v_add_f32_e32 v32, 1.0, v19
	v_rcp_f32_e32 v163, v91
	v_rcp_f32_e32 v166, v33
	v_add_f32_e32 v33, 1.0, v18
	v_add_f32_e32 v91, -1.0, v32
	v_sub_f32_e32 v33, v19, v33
	v_sub_f32_e32 v19, v19, v91
	v_add_f32_e32 v33, v17, v33
	v_add_f32_e32 v17, v17, v19
	v_add_f32_e32 v91, v32, v17
	v_rcp_f32_e32 v154, v91
	v_add_f32_e32 v19, v18, v33
	v_sub_f32_e32 v32, v91, v32
	v_add_f32_e32 v152, 1.0, v152
	v_mul_f32_e32 v156, v19, v154
	v_sub_f32_e32 v17, v17, v32
	v_mul_f32_e32 v32, v91, v156
	v_rcp_f32_e32 v165, v152
	v_fma_f32 v152, v156, v91, -v32
	v_sub_f32_e32 v18, v19, v18
	v_fmac_f32_e32 v152, v156, v17
	v_sub_f32_e32 v155, v33, v18
	v_add_f32_e32 v18, v32, v152
	v_sub_f32_e32 v33, v19, v18
	v_mov_b32_e32 v153, v18
	v_pk_add_f32 v[18:19], v[18:19], v[32:33] neg_lo:[0,1] neg_hi:[0,1]
	v_cvt_f32_i32_e32 v16, v16
	v_pk_add_f32 v[18:19], v[18:19], v[152:153] neg_lo:[0,1] neg_hi:[0,1]
	v_cmp_neq_f32_e32 vcc, s86, v160
	v_add_f32_e32 v19, v155, v19
	v_add_f32_e32 v18, v18, v19
	v_add_f32_e32 v19, v33, v18
	v_mul_f32_e32 v153, v154, v19
	v_mul_f32_e32 v32, v91, v153
	v_sub_f32_e32 v33, v33, v19
	v_add_f32_e32 v157, v156, v153
	v_fma_f32 v152, v153, v91, -v32
	v_add_f32_e32 v155, v18, v33
	v_sub_f32_e32 v18, v157, v156
	v_fmac_f32_e32 v152, v153, v17
	v_sub_f32_e32 v17, v153, v18
	v_add_f32_e32 v18, v32, v152
	v_sub_f32_e32 v33, v19, v18
	v_mov_b32_e32 v153, v18
	v_pk_add_f32 v[18:19], v[18:19], v[32:33] neg_lo:[0,1] neg_hi:[0,1]
	v_add_f32_e32 v34, v34, v93
	v_pk_add_f32 v[18:19], v[18:19], v[152:153] neg_lo:[0,1] neg_hi:[0,1]
	v_mul_f32_e32 v34, 0xbfb8aa3b, v34
	v_add_f32_e32 v19, v155, v19
	v_add_f32_e32 v18, v18, v19
	v_add_f32_e32 v18, v33, v18
	v_mul_f32_e32 v18, v154, v18
	v_add_f32_e32 v17, v17, v18
	v_add_f32_e32 v18, v157, v17
	v_mul_f32_e32 v32, v18, v18
	v_sub_f32_e32 v33, v18, v157
	v_fmamk_f32 v91, v32, 0x3e9b6dac, v133
	v_sub_f32_e32 v33, v17, v33
	v_mul_f32_e32 v17, v18, v32
	v_fmaak_f32 v91, v32, v91, 0x3f2aaada
	v_ldexp_f32 v153, v33, 1
	v_pk_mul_f32 v[32:33], v[16:17], v[90:91]
	v_ldexp_f32 v19, v18, 1
	v_fma_f32 v18, v16, s85, -v32
	v_fmac_f32_e32 v18, 0xb102e308, v16
	v_pk_add_f32 v[16:17], v[32:33], v[18:19]
	v_mov_b32_e32 v152, v32
	v_sub_f32_e32 v91, v17, v19
	v_pk_add_f32 v[154:155], v[16:17], v[32:33] neg_lo:[0,1] neg_hi:[0,1]
	v_sub_f32_e32 v32, v33, v91
	v_add_f32_e32 v153, v153, v32
	v_pk_add_f32 v[32:33], v[16:17], v[152:153]
	v_mov_b32_e32 v19, v16
	v_mov_b32_e32 v155, v33
	v_pk_add_f32 v[158:159], v[18:19], v[154:155] neg_lo:[0,1] neg_hi:[0,1]
	v_pk_add_f32 v[18:19], v[18:19], v[154:155]
	v_mov_b32_e32 v157, v16
	v_pk_add_f32 v[154:155], v[18:19], v[16:17] op_sel:[1,0] op_sel_hi:[0,1] neg_lo:[0,1] neg_hi:[0,1]
	v_mov_b32_e32 v156, v153
	v_mov_b32_e32 v152, v33
	v_mov_b32_e32 v153, v19
	v_pk_mov_b32 v[16:17], v[16:17], v[154:155] op_sel:[1,0]
	v_pk_add_f32 v[32:33], v[32:33], v[154:155] op_sel_hi:[1,0] neg_lo:[0,1] neg_hi:[0,1]
	v_pk_add_f32 v[16:17], v[152:153], v[16:17] neg_lo:[0,1] neg_hi:[0,1]
	v_mov_b32_e32 v32, v158
	v_pk_add_f32 v[16:17], v[156:157], v[16:17] neg_lo:[0,1] neg_hi:[0,1]
	v_mov_b32_e32 v159, v19
	v_pk_add_f32 v[32:33], v[32:33], v[16:17]
	v_exp_f32_e32 v34, v34
	v_pk_add_f32 v[152:153], v[32:33], v[32:33] op_sel:[0,1] op_sel_hi:[1,0]
	v_add_f32_e32 v36, v36, v93
	v_pk_add_f32 v[18:19], v[18:19], v[152:153] op_sel:[1,0] op_sel_hi:[0,1]
	v_mov_b32_e32 v33, v18
	v_mov_b32_e32 v17, v152
	v_pk_add_f32 v[152:153], v[32:33], v[158:159] neg_lo:[0,1] neg_hi:[0,1]
	v_add_f32_e32 v34, 1.0, v34
	v_sub_f32_e32 v19, v32, v152
	v_pk_add_f32 v[16:17], v[16:17], v[152:153] neg_lo:[0,1] neg_hi:[0,1]
	v_sub_f32_e32 v19, v158, v19
	v_add_f32_e32 v16, v16, v19
	v_add_f32_e32 v16, v16, v17
	v_add_f32_e32 v16, v18, v16
	v_cndmask_b32_e32 v16, v135, v16, vcc
	v_cmp_ngt_f32_e32 vcc, -1.0, v160
	v_mul_f32_e32 v36, 0xbfb8aa3b, v36
	v_exp_f32_e32 v36, v36
	v_cndmask_b32_e32 v16, v136, v16, vcc
	v_cmp_neq_f32_e32 vcc, -1.0, v160
	s_nop 1
	v_cndmask_b32_e32 v16, v137, v16, vcc
	v_cmp_lt_f32_e64 vcc, |v160|, s87
	s_nop 1
	v_cndmask_b32_e32 v16, v16, v160, vcc
	v_mul_f32_e32 v33, 0xc1000000, v16
	v_mul_f32_e32 v16, v163, v33
	v_mul_f32_e32 v16, 0x3fb8aa3b, v16
	v_exp_f32_e32 v32, v16
	v_rcp_f32_e32 v16, v162
	v_mul_f32_e32 v17, v165, v33
	v_mul_f32_e32 v17, 0x3fb8aa3b, v17
	v_fma_f32 v18, -v32, v32, 1.0
	v_sqrt_f32_e32 v18, v18
	v_mul_f32_e32 v16, v16, v33
	v_mul_f32_e32 v16, 0x3fb8aa3b, v16
	v_exp_f32_e32 v91, v17
	v_mul_f32_e32 v18, v164, v18
	v_mul_f32_e32 v18, v0, v18
	v_exp_f32_e32 v0, v16
	v_add_f32_e32 v16, 1.0, v161
	v_rcp_f32_e32 v16, v16
	v_fma_f32 v19, -v91, v91, 1.0
	v_sqrt_f32_e32 v19, v19
	v_rcp_f32_e32 v17, v34
	v_mul_f32_e32 v16, v16, v33
	v_mul_f32_e32 v16, 0x3fb8aa3b, v16
	v_exp_f32_e32 v152, v16
	v_add_f32_e32 v16, v20, v151
	v_mul_f32_e32 v16, 0xbfb8aa3b, v16
	v_mul_f32_e32 v34, v166, v19
	v_add_f32_e32 v19, v35, v93
	v_exp_f32_e32 v16, v16
	v_mul_f32_e32 v19, 0xbfb8aa3b, v19
	v_exp_f32_e32 v19, v19
	v_fma_f32 v20, -v152, v152, 1.0
	v_add_f32_e32 v16, 1.0, v16
	v_rcp_f32_e32 v16, v16
	v_add_f32_e32 v19, 1.0, v19
	v_rcp_f32_e32 v19, v19
	v_sqrt_f32_e32 v20, v20
	v_mul_f32_e32 v16, v16, v33
	v_mul_f32_e32 v16, 0x3fb8aa3b, v16
	v_fma_f32 v35, -v0, v0, 1.0
	v_mul_f32_e32 v153, v19, v20
	v_exp_f32_e32 v20, v16
	v_add_f32_e32 v16, v21, v151
	v_mul_f32_e32 v16, 0xbfb8aa3b, v16
	v_exp_f32_e32 v16, v16
	v_sqrt_f32_e32 v35, v35
	v_fma_f32 v19, -v20, v20, 1.0
	v_add_f32_e32 v21, v37, v93
	v_add_f32_e32 v16, 1.0, v16
	v_rcp_f32_e32 v16, v16
	v_mul_f32_e32 v35, v17, v35
	v_add_f32_e32 v17, 1.0, v36
	v_rcp_f32_e32 v17, v17
	v_mul_f32_e32 v16, v16, v33
	v_mul_f32_e32 v16, 0x3fb8aa3b, v16
	v_exp_f32_e32 v36, v16
	v_add_f32_e32 v16, v22, v151
	v_mul_f32_e32 v16, 0xbfb8aa3b, v16
	v_exp_f32_e32 v16, v16
	v_sqrt_f32_e32 v19, v19
	v_mul_f32_e32 v21, 0xbfb8aa3b, v21
	v_exp_f32_e32 v21, v21
	v_add_f32_e32 v16, 1.0, v16
	v_rcp_f32_e32 v16, v16
	v_mul_f32_e32 v17, v17, v19
	v_mul_f32_e32 v19, v4, v17
	v_add_f32_e32 v4, 1.0, v21
	v_add_f32_e32 v21, v38, v93
	v_mul_f32_e32 v21, 0xbfb8aa3b, v21
	v_mul_f32_e32 v16, v16, v33
	v_fma_f32 v17, -v36, v36, 1.0
	v_exp_f32_e32 v21, v21
	v_mul_f32_e32 v16, 0x3fb8aa3b, v16
	v_rcp_f32_e32 v4, v4
	v_sqrt_f32_e32 v17, v17
	v_exp_f32_e32 v37, v16
	v_add_f32_e32 v16, 1.0, v21
	v_add_f32_e32 v21, v23, v151
	v_mul_f32_e32 v4, v4, v17
	v_fma_f32 v17, -v37, v37, 1.0
	v_mul_f32_e32 v21, 0xbfb8aa3b, v21
	v_rcp_f32_e32 v16, v16
	v_sqrt_f32_e32 v17, v17
	v_exp_f32_e32 v21, v21
	v_add_f32_e32 v22, v39, v93
	v_mul_f32_e32 v22, 0xbfb8aa3b, v22
	v_mul_f32_e32 v23, v16, v17
	v_add_f32_e32 v16, 1.0, v21
	v_rcp_f32_e32 v16, v16
	v_add_f32_e32 v21, v24, v151
	v_mul_f32_e32 v21, 0xbfb8aa3b, v21
	v_exp_f32_e32 v21, v21
	v_mul_f32_e32 v16, v16, v33
	v_mul_f32_e32 v16, 0x3fb8aa3b, v16
	v_exp_f32_e32 v24, v16
	v_add_f32_e32 v16, 1.0, v21
	v_rcp_f32_e32 v16, v16
	v_exp_f32_e32 v22, v22
	v_add_f32_e32 v21, v40, v93
	v_mul_f32_e32 v21, 0xbfb8aa3b, v21
	v_mul_f32_e32 v16, v16, v33
	v_add_f32_e32 v17, 1.0, v22
	v_fma_f32 v22, -v24, v24, 1.0
	v_mul_f32_e32 v16, 0x3fb8aa3b, v16
	v_sqrt_f32_e32 v38, v22
	v_exp_f32_e32 v22, v16
	v_add_f32_e32 v16, v25, v151
	v_mul_f32_e32 v16, 0xbfb8aa3b, v16
	v_exp_f32_e32 v16, v16
	v_exp_f32_e32 v21, v21
	v_add_f32_e32 v39, v41, v93
	v_fma_f32 v25, -v22, v22, 1.0
	v_add_f32_e32 v16, 1.0, v16
	v_rcp_f32_e32 v16, v16
	v_add_f32_e32 v21, 1.0, v21
	v_mul_f32_e32 v39, 0xbfb8aa3b, v39
	v_rcp_f32_e32 v17, v17
	v_rcp_f32_e32 v21, v21
	v_sqrt_f32_e32 v25, v25
	v_exp_f32_e32 v39, v39
	v_mul_f32_e32 v16, v16, v33
	v_mul_f32_e32 v16, 0x3fb8aa3b, v16
	v_mul_f32_e32 v38, v17, v38
	v_mul_f32_e32 v17, v21, v25
	v_add_f32_e32 v21, 1.0, v39
	v_exp_f32_e32 v39, v16
	v_add_f32_e32 v16, v26, v151
	v_mul_f32_e32 v16, 0xbfb8aa3b, v16
	v_exp_f32_e32 v16, v16
	v_rcp_f32_e32 v25, v21
	v_fma_f32 v21, -v39, v39, 1.0
	v_sqrt_f32_e32 v26, v21
	v_add_f32_e32 v16, 1.0, v16
	v_add_f32_e32 v21, v42, v93
	v_rcp_f32_e32 v16, v16
	v_mul_f32_e32 v21, 0xbfb8aa3b, v21
	v_exp_f32_e32 v40, v21
	v_mul_f32_e32 v21, v8, v17
	v_mul_f32_e32 v16, v16, v33
	v_mul_f32_e32 v16, 0x3fb8aa3b, v16
	v_add_f32_e32 v17, 1.0, v40
	v_exp_f32_e32 v40, v16
	v_add_f32_e32 v16, v27, v151
	v_mul_f32_e32 v16, 0xbfb8aa3b, v16
	v_exp_f32_e32 v16, v16
	v_mul_f32_e32 v8, v25, v26
	v_fma_f32 v25, -v40, v40, 1.0
	v_add_f32_e32 v26, v43, v93
	v_add_f32_e32 v16, 1.0, v16
	v_rcp_f32_e32 v16, v16
	v_rcp_f32_e32 v17, v17
	v_sqrt_f32_e32 v25, v25
	v_mul_f32_e32 v26, 0xbfb8aa3b, v26
	v_mul_f32_e32 v16, v16, v33
	v_exp_f32_e32 v26, v26
	v_mul_f32_e32 v16, 0x3fb8aa3b, v16
	v_exp_f32_e32 v41, v16
	v_mul_f32_e32 v154, v17, v25
	v_add_f32_e32 v25, v28, v151
	v_add_f32_e32 v16, 1.0, v26
	v_mul_f32_e32 v25, 0xbfb8aa3b, v25
	v_add_f32_e32 v26, v44, v93
	v_fma_f32 v17, -v41, v41, 1.0
	v_exp_f32_e32 v25, v25
	v_mul_f32_e32 v26, 0xbfb8aa3b, v26
	v_rcp_f32_e32 v16, v16
	v_sqrt_f32_e32 v17, v17
	v_exp_f32_e32 v26, v26
	v_add_f32_e32 v25, 1.0, v25
	v_rcp_f32_e32 v25, v25
	v_mul_f32_e32 v155, v16, v17
	v_add_f32_e32 v16, 1.0, v26
	v_add_f32_e32 v26, v45, v93
	v_mul_f32_e32 v26, 0xbfb8aa3b, v26
	v_exp_f32_e32 v26, v26
	v_rcp_f32_e32 v17, v16
	v_mul_f32_e32 v16, v25, v33
	v_add_f32_e32 v25, v29, v151
	v_mul_f32_e32 v25, 0xbfb8aa3b, v25
	v_exp_f32_e32 v25, v25
	v_add_f32_e32 v26, 1.0, v26
	v_rcp_f32_e32 v42, v26
	v_add_f32_e32 v26, v30, v151
	v_mul_f32_e32 v26, 0xbfb8aa3b, v26
	v_exp_f32_e32 v26, v26
	v_add_f32_e32 v25, 1.0, v25
	v_rcp_f32_e32 v25, v25
	v_add_f32_e32 v27, v46, v93
	v_mul_f32_e32 v27, 0xbfb8aa3b, v27
	v_exp_f32_e32 v27, v27
	v_add_f32_e32 v26, 1.0, v26
	v_rcp_f32_e32 v26, v26
	v_mul_f32_e32 v25, v25, v33
	v_mul_f32_e32 v25, 0x3fb8aa3b, v25
	v_exp_f32_e32 v43, v25
	v_add_f32_e32 v25, 1.0, v27
	v_rcp_f32_e32 v44, v25
	v_mul_f32_e32 v25, v26, v33
	v_add_f32_e32 v26, v31, v151
	v_mul_f32_e32 v26, 0xbfb8aa3b, v26
	v_exp_f32_e32 v26, v26
	v_add_f32_e32 v27, v47, v93
	v_mul_f32_e32 v27, 0xbfb8aa3b, v27
	v_exp_f32_e32 v27, v27
	v_add_f32_e32 v26, 1.0, v26
	v_mul_f32_e32 v16, 0x3fb8aa3b, v16
	v_rcp_f32_e32 v26, v26
	v_exp_f32_e32 v16, v16
	v_mul_f32_e32 v25, 0x3fb8aa3b, v25
	v_fmac_f32_e32 v18, 0, v32
	v_exp_f32_e32 v45, v25
	v_add_f32_e32 v25, 1.0, v27
	v_mul_f32_e32 v31, v91, v18
	v_rcp_f32_e32 v46, v25
	v_mul_f32_e32 v25, v26, v33
	v_fmac_f32_e32 v31, v1, v34
	v_mul_f32_e32 v33, v32, v91
	v_fmac_f32_e32 v19, 0, v20
	v_mul_f32_e32 v30, v0, v31
	v_mul_f32_e32 v34, v0, v33
	v_mul_f32_e32 v28, v36, v19
	v_fma_f32 v0, -v16, v16, 1.0
	v_fmac_f32_e32 v28, v5, v4
	v_sqrt_f32_e32 v1, v0
	v_mul_f32_e32 v27, v37, v28
	v_fmac_f32_e32 v30, v2, v35
	v_fmac_f32_e32 v27, v6, v23
	v_fma_f32 v2, -v43, v43, 1.0
	v_mul_f32_e32 v26, v24, v27
	v_mov_b32_e32 v0, v89
	v_sqrt_f32_e32 v2, v2
	v_fmac_f32_e32 v26, v7, v38
	v_pk_mul_f32 v[6:7], v[16:17], v[0:1]
	v_mul_f32_e32 v29, v152, v30
	v_fmac_f32_e32 v6, v12, v7
	v_fmac_f32_e32 v29, v3, v153
	v_mov_b32_e32 v3, v6
	v_mul_f32_e32 v25, 0x3fb8aa3b, v25
	v_pk_mul_f32 v[4:5], v[42:43], v[2:3]
	v_fma_f32 v0, -v45, v45, 1.0
	v_exp_f32_e32 v47, v25
	v_fmac_f32_e32 v5, v13, v4
	v_sqrt_f32_e32 v4, v0
	v_fmac_f32_e32 v21, 0, v22
	v_mul_f32_e32 v25, v39, v21
	v_mul_f32_e32 v36, v20, v36
	v_fmac_f32_e32 v25, v9, v8
	v_pk_mul_f32 v[8:9], v[44:45], v[4:5]
	v_fma_f32 v0, -v47, v47, 1.0
	v_mul_f32_e32 v37, v37, v36
	v_fmac_f32_e32 v9, v14, v8
	v_sqrt_f32_e32 v8, v0
	ds_bpermute_b32 v0, v140, v29
	v_mul_f32_e32 v38, v24, v37
	v_mul_f32_e32 v24, v40, v25
	v_mul_f32_e32 v35, v152, v34
	v_fmac_f32_e32 v24, v10, v154
	v_mul_f32_e32 v23, v41, v24
	ds_bpermute_b32 v13, v140, v35
	v_fmac_f32_e32 v23, v11, v155
	v_pk_mul_f32 v[10:11], v[46:47], v[8:9]
	s_waitcnt lgkmcnt(1)
	v_cndmask_b32_e64 v14, v29, v0, s[0:1]
	v_fmac_f32_e32 v11, v15, v10
	v_cndmask_b32_e64 v10, v0, v29, s[0:1]
	ds_bpermute_b32 v0, v140, v38
	ds_bpermute_b32 v3, v140, v26
	v_mul_f32_e32 v39, v22, v39
	v_mul_f32_e32 v40, v40, v39
	s_waitcnt lgkmcnt(2)
	v_cndmask_b32_e64 v1, v13, v35, s[0:1]
	v_mul_f32_e32 v12, v41, v40
	v_mul_f32_e32 v7, v16, v43
	v_cndmask_b32_e64 v2, v35, v13, s[0:1]
	v_fmac_f32_e32 v10, 0, v1
	v_mul_f32_e32 v4, v45, v7
	v_mul_f32_e32 v15, v35, v13
	v_fmac_f32_e32 v14, v2, v10
	s_waitcnt lgkmcnt(1)
	v_cndmask_b32_e64 v1, v0, v38, s[0:1]
	s_waitcnt lgkmcnt(0)
	v_cndmask_b32_e64 v17, v3, v26, s[0:1]
	v_cndmask_b32_e64 v41, v26, v3, s[0:1]
	ds_bpermute_b32 v2, v140, v12
	ds_bpermute_b32 v3, v140, v23
	v_mul_f32_e32 v8, v47, v4
	v_cndmask_b32_e64 v0, v38, v0, s[0:1]
	v_mul_f32_e32 v42, v15, v1
	v_fmac_f32_e32 v17, v1, v14
	v_mul_f32_e32 v43, v0, v42
	v_fmac_f32_e32 v41, v0, v17
	ds_bpermute_b32 v1, v140, v8
	ds_bpermute_b32 v0, v140, v11
	s_waitcnt lgkmcnt(3)
	v_cndmask_b32_e64 v47, v2, v12, s[0:1]
	s_waitcnt lgkmcnt(2)
	v_cndmask_b32_e64 v44, v3, v23, s[0:1]
	v_cndmask_b32_e64 v2, v12, v2, s[0:1]
	v_cndmask_b32_e64 v45, v23, v3, s[0:1]
	v_mul_f32_e32 v46, v47, v43
	v_fmac_f32_e32 v44, v47, v41
	v_mul_f32_e32 v47, v2, v46
	v_fmac_f32_e32 v45, v2, v44
	s_waitcnt lgkmcnt(1)
	v_cndmask_b32_e64 v2, v1, v8, s[0:1]
	s_waitcnt lgkmcnt(0)
	v_cndmask_b32_e64 v91, v0, v11, s[0:1]
	v_mul_f32_e32 v93, v2, v47
	v_fmac_f32_e32 v91, v2, v45
	s_and_saveexec_b64 s[8:9], s[0:1]
	v_mul_f32_e32 v3, v91, v1
	v_mul_f32_e32 v2, v93, v1
	v_add_f32_e32 v3, v3, v0
	ds_write_b64 v139, v[2:3] offset:4096
	s_or_b64 exec, exec, s[8:9]
	s_and_b64 vcc, exec, s[6:7]
	s_waitcnt lgkmcnt(0)
	s_barrier
	s_cbranch_vccnz .LBB0_353
	s_cmp_lt_u32 s62, 8
	s_cbranch_scc1 .LBB0_354
	s_add_i32 s9, 16, 0x1000
	s_and_b32 s8, s62, 0x7ffffff8
	v_add3_u32 v151, v141, v138, s9
	v_mov_b32_e32 v0, 1.0
	v_mov_b32_e32 v3, 0
	s_mov_b32 s9, 0

.LBB0_357:
	v_cndmask_b32_e64 v1, v13, 1.0, s[0:1]
	v_cndmask_b32_e64 v2, v10, 0, s[0:1]
	v_cndmask_b32_e64 v10, v42, v15, s[0:1]
	v_cndmask_b32_e64 v13, v17, v14, s[0:1]
	v_cndmask_b32_e64 v14, v46, v43, s[0:1]
	v_cndmask_b32_e64 v15, v44, v41, s[0:1]
	v_cndmask_b32_e64 v17, v93, v47, s[0:1]
	v_cndmask_b32_e64 v41, v91, v45, s[0:1]
	v_fmac_f32_e32 v18, v32, v2
	v_mul_f32_e32 v32, v1, v32
	v_fmac_f32_e32 v31, v33, v2
	v_mul_f32_e32 v33, v1, v33
	v_fmac_f32_e32 v30, v34, v2
	v_mul_f32_e32 v34, v1, v34
	v_fmac_f32_e32 v29, v35, v2
	v_mul_f32_e32 v1, v1, v35
	v_fmac_f32_e32 v27, v37, v13
	v_mul_f32_e32 v35, v37, v10
	v_fmac_f32_e32 v24, v40, v15
	v_mul_f32_e32 v37, v40, v14
	v_fmac_f32_e32 v9, v4, v41
	v_mul_f32_e32 v40, v4, v17
	v_mul_f32_e32 v4, v32, v0
	v_fmac_f32_e32 v18, v32, v3
	v_cvt_pk_bf16_f32 v4, v18, v4
	v_fmac_f32_e32 v19, v20, v13
	v_mul_f32_e32 v2, v20, v10
	v_fmac_f32_e32 v28, v36, v13
	v_mul_f32_e32 v20, v36, v10
	v_fmac_f32_e32 v26, v38, v13
	v_mul_f32_e32 v10, v38, v10
	v_fmac_f32_e32 v23, v12, v15
	v_mul_f32_e32 v38, v12, v14
	v_lshl_add_u64 v[12:13], v[94:95], 0, s[48:49]
	global_load_dword v172, v[130:131], off offset:384
	global_load_dword v173, v[126:127], off offset:384
	global_load_dword v174, v[128:129], off offset:384
	global_store_dword v[96:97], v4, off offset:256 nt
	v_mul_f32_e32 v4, v33, v0
	v_fmac_f32_e32 v21, v22, v15
	v_mul_f32_e32 v22, v22, v14
	v_fmac_f32_e32 v25, v39, v15
	v_mul_f32_e32 v36, v39, v14
	v_fmac_f32_e32 v31, v33, v3
	v_cvt_pk_bf16_f32 v4, v31, v4
	v_lshl_add_u64 v[14:15], v[12:13], 0, v[88:89]
	global_store_dword v[14:15], v4, off nt
	v_mul_f32_e32 v4, v34, v0
	v_lshl_add_u64 v[14:15], v[12:13], 0, v[98:99]
	v_fmac_f32_e32 v29, v1, v3
	v_mul_f32_e32 v1, v1, v0
	v_fmac_f32_e32 v30, v34, v3
	v_cvt_pk_bf16_f32 v4, v30, v4
	global_store_dword v[14:15], v4, off nt
	v_cvt_pk_bf16_f32 v1, v29, v1
	v_lshl_add_u64 v[14:15], v[12:13], 0, v[100:101]
	global_store_dword v[14:15], v1, off nt
	v_mul_f32_e32 v1, v2, v0
	v_fmac_f32_e32 v19, v2, v3
	v_cvt_pk_bf16_f32 v1, v19, v1
	v_lshl_add_u64 v[14:15], v[12:13], 0, v[102:103]
	global_store_dword v[14:15], v1, off nt
	v_mul_f32_e32 v1, v20, v0
	v_fmac_f32_e32 v28, v20, v3
	v_cvt_pk_bf16_f32 v1, v28, v1
	v_lshl_add_u64 v[14:15], v[12:13], 0, v[104:105]
	global_store_dword v[14:15], v1, off nt
	v_mul_f32_e32 v1, v35, v0
	v_fmac_f32_e32 v27, v35, v3
	v_cvt_pk_bf16_f32 v1, v27, v1
	v_lshl_add_u64 v[14:15], v[12:13], 0, v[106:107]
	global_store_dword v[14:15], v1, off nt
	v_mul_f32_e32 v1, v10, v0
	v_fmac_f32_e32 v26, v10, v3
	v_cvt_pk_bf16_f32 v1, v26, v1
	v_lshl_add_u64 v[14:15], v[12:13], 0, v[108:109]
	global_store_dword v[14:15], v1, off nt
	v_mul_f32_e32 v1, v22, v0
	v_fmac_f32_e32 v21, v22, v3
	v_cvt_pk_bf16_f32 v1, v21, v1
	v_lshl_add_u64 v[14:15], v[12:13], 0, v[110:111]
	global_store_dword v[14:15], v1, off nt
	v_mul_f32_e32 v1, v36, v0
	v_fmac_f32_e32 v25, v36, v3
	v_cvt_pk_bf16_f32 v1, v25, v1
	v_lshl_add_u64 v[14:15], v[12:13], 0, v[112:113]
	global_store_dword v[14:15], v1, off nt
	v_mul_f32_e32 v1, v37, v0
	v_fmac_f32_e32 v24, v37, v3
	v_cvt_pk_bf16_f32 v1, v24, v1
	v_lshl_add_u64 v[14:15], v[12:13], 0, v[114:115]
	global_store_dword v[14:15], v1, off nt
	v_mul_f32_e32 v1, v38, v0
	v_fmac_f32_e32 v6, v16, v41
	v_mul_f32_e32 v16, v16, v17
	v_fmac_f32_e32 v23, v38, v3
	v_cvt_pk_bf16_f32 v1, v23, v1
	v_lshl_add_u64 v[14:15], v[12:13], 0, v[116:117]
	global_store_dword v[14:15], v1, off nt
	v_fmac_f32_e32 v6, v16, v3
	v_mul_f32_e32 v1, v16, v0
	v_fmac_f32_e32 v5, v7, v41
	v_mul_f32_e32 v39, v7, v17
	v_cvt_pk_bf16_f32 v1, v6, v1
	v_lshl_add_u64 v[6:7], v[12:13], 0, v[118:119]
	global_store_dword v[6:7], v1, off nt
	v_fmac_f32_e32 v5, v39, v3
	v_mul_f32_e32 v1, v39, v0
	v_cvt_pk_bf16_f32 v1, v5, v1
	v_lshl_add_u64 v[4:5], v[12:13], 0, v[120:121]
	v_fmac_f32_e32 v11, v8, v41
	v_mul_f32_e32 v8, v8, v17
	global_store_dword v[4:5], v1, off nt
	v_mul_f32_e32 v1, v40, v0
	v_fmac_f32_e32 v9, v40, v3
	v_cvt_pk_bf16_f32 v1, v9, v1
	v_lshl_add_u64 v[4:5], v[12:13], 0, v[122:123]
	v_mul_f32_e32 v0, v8, v0
	global_store_dword v[4:5], v1, off nt
	v_fmac_f32_e32 v11, v8, v3
	v_cvt_pk_bf16_f32 v2, v11, v0
	v_lshl_add_u64 v[0:1], v[12:13], 0, v[124:125]
	global_store_dword v[0:1], v2, off nt
	s_and_saveexec_b64 s[8:9], s[4:5]
	s_cbranch_execz .LBB0_359
	v_add_u32_e32 v12, 0x1000, v142
	ds_read2_b64 v[0:3], v12 offset1:32
	ds_read2_b64 v[4:7], v12 offset0:64 offset1:96
	ds_read2_b64 v[8:11], v12 offset0:128 offset1:160
	ds_read2_b64 v[12:15], v12 offset0:192 offset1:224
	s_waitcnt lgkmcnt(3)
	v_fma_f32 v16, 0, v0, v1
	v_pk_mul_f32 v[0:1], v[0:1], v[2:3]
	v_fma_f32 v2, v2, v16, v3
	s_waitcnt lgkmcnt(2)
	v_fma_f32 v2, v4, v2, v5
	v_fma_f32 v2, v6, v2, v7
	s_waitcnt lgkmcnt(1)
	v_fma_f32 v3, v8, v2, v9
	v_mov_b32_e32 v2, v0
	v_mov_b32_e32 v16, v4
	v_mov_b32_e32 v17, v10
	v_pk_mul_f32 v[0:1], v[0:1], v[4:5]
	v_pk_fma_f32 v[2:3], v[2:3], v[16:17], v[10:11]
	v_pk_mul_f32 v[0:1], v[0:1], v[6:7]
	s_waitcnt lgkmcnt(0)
	v_mov_b32_e32 v9, v12
	v_mov_b32_e32 v1, v3
	v_pk_mul_f32 v[2:3], v[0:1], v[8:9]
	v_pk_fma_f32 v[0:1], v[0:1], v[8:9], v[12:13]
	v_pk_mul_f32 v[2:3], v[2:3], v[10:11]
	v_mov_b32_e32 v4, v12
	v_mov_b32_e32 v0, v2
	v_mov_b32_e32 v5, v14
	v_pk_mul_f32 v[2:3], v[2:3], v[12:13]
	v_pk_fma_f32 v[0:1], v[0:1], v[4:5], v[14:15]
	v_pk_mul_f32 v[2:3], v[2:3], v[14:15]
	v_add_u32_e32 v0, 64, v92
	v_mov_b32_e32 v3, v1
	v_ashrrev_i32_e32 v1, 31, v0
	v_lshl_add_u64 v[0:1], v[0:1], 3, s[24:25]
	global_store_dwordx2 v[0:1], v[2:3], off
.LBB0_359:
	s_or_b64 exec, exec, s[8:9]
	s_setprio 1
	ds_read_b128 v[0:3], v148 offset:40960
	ds_read_b128 v[4:7], v150 offset:40960
	v_add_u32_e32 v8, 0xa000, v150
	s_waitcnt lgkmcnt(1)
	v_mfma_f32_32x32x16_bf16 v[16:31], v[48:51], v[0:3], 0
	v_add_u32_e32 v0, 0xa000, v148
	ds_read_b128 v[0:3], v0 offset:32768
	ds_read_b128 v[8:11], v8 offset:32768
	s_waitcnt lgkmcnt(1)
	v_mfma_f32_32x32x16_bf16 v[32:47], v[48:51], v[0:3], 0
	v_mfma_f32_32x32x16_bf16 v[16:31], v[52:55], v[4:7], v[16:31]
	ds_read_b128 v[0:3], v145 offset:40960
	ds_read_b128 v[4:7], v149 offset:40960
	s_waitcnt lgkmcnt(2)
	v_mfma_f32_32x32x16_bf16 v[32:47], v[52:55], v[8:11], v[32:47]
	v_add_u32_e32 v8, 0xa000, v149
	ds_read_b128 v[8:11], v8 offset:32768
	s_waitcnt lgkmcnt(2)
	v_mfma_f32_32x32x16_bf16 v[16:31], v[56:59], v[0:3], v[16:31]
	v_add_u32_e32 v0, 0xa000, v145
	ds_read_b128 v[0:3], v0 offset:32768
	s_waitcnt lgkmcnt(0)
	v_mfma_f32_32x32x16_bf16 v[32:47], v[56:59], v[0:3], v[32:47]
	v_mfma_f32_32x32x16_bf16 v[16:31], v[60:63], v[4:7], v[16:31]
	ds_read_b128 v[0:3], v144 offset:40960
	ds_read_b128 v[4:7], v147 offset:40960
	v_mfma_f32_32x32x16_bf16 v[32:47], v[60:63], v[8:11], v[32:47]
	v_add_u32_e32 v8, 0xa000, v147
	ds_read_b128 v[8:11], v8 offset:32768
	s_waitcnt lgkmcnt(2)
	v_mfma_f32_32x32x16_bf16 v[16:31], v[64:67], v[0:3], v[16:31]
	v_add_u32_e32 v0, 0xa000, v144
	ds_read_b128 v[0:3], v0 offset:32768
	s_waitcnt lgkmcnt(0)
	v_mfma_f32_32x32x16_bf16 v[32:47], v[64:67], v[0:3], v[32:47]
	v_mfma_f32_32x32x16_bf16 v[16:31], v[68:71], v[4:7], v[16:31]
	ds_read_b128 v[0:3], v143 offset:40960
	ds_read_b128 v[4:7], v146 offset:40960
	v_mfma_f32_32x32x16_bf16 v[32:47], v[68:71], v[8:11], v[32:47]
	v_add_u32_e32 v8, 0xa000, v146
	ds_read_b128 v[8:11], v8 offset:32768
	s_waitcnt lgkmcnt(2)
	v_mfma_f32_32x32x16_bf16 v[16:31], v[72:75], v[0:3], v[16:31]
	v_add_u32_e32 v0, 0xa000, v143
	ds_read_b128 v[0:3], v0 offset:32768
	s_waitcnt lgkmcnt(0)
	v_mfma_f32_32x32x16_bf16 v[32:47], v[72:75], v[0:3], v[32:47]
	v_mfma_f32_32x32x16_bf16 v[16:31], v[76:79], v[4:7], v[16:31]
	v_mfma_f32_32x32x16_bf16 v[32:47], v[76:79], v[8:11], v[32:47]
	v_mfma_f32_32x32x16_bf16 v[0:15], v[72:75], v[80:83], 0
	v_mfma_f32_32x32x16_bf16 v[0:15], v[76:79], v[84:87], v[0:15]
	s_setprio 0
	s_waitcnt vmcnt(16)
	v_mov_b32_e32 v50, v172
	v_mov_b32_e32 v49, v173
	v_mov_b32_e32 v48, v174
	v_mul_f32_e32 v50, 0xbfb8aa3b, v50
	v_exp_f32_e32 v58, v50
	s_nop 0
	v_add_f32_e32 v18, v18, v49
	v_add_f32_e32 v19, v19, v49
	v_mul_f32_e32 v18, 0xbfb8aa3b, v18
	v_add_f32_e32 v16, v16, v49
	v_add_f32_e32 v32, v32, v48
	v_add_f32_e32 v17, v17, v49
	v_mul_f32_e32 v19, 0xbfb8aa3b, v19
	v_exp_f32_e32 v18, v18
	v_add_f32_e32 v33, v33, v48
	v_mul_f32_e32 v16, 0xbfb8aa3b, v16
	v_mul_f32_e32 v32, 0xbfb8aa3b, v32
	v_mul_f32_e32 v17, 0xbfb8aa3b, v17
	v_exp_f32_e32 v59, v19
	v_add_f32_e32 v19, 1.0, v58
	v_mul_f32_e32 v33, 0xbfb8aa3b, v33
	v_exp_f32_e32 v50, v16
	v_exp_f32_e32 v32, v32
	v_exp_f32_e32 v51, v17
	v_frexp_mant_f32_e32 v53, v19
	v_cvt_f64_f32_e32 v[16:17], v19
	v_exp_f32_e32 v33, v33
	v_add_f32_e32 v52, -1.0, v19
	v_frexp_exp_i32_f64_e32 v16, v[16:17]
	v_cmp_gt_f32_e32 vcc, s84, v53
	v_add_f32_e32 v60, 1.0, v18
	v_sub_f32_e32 v18, v52, v19
	v_subbrev_co_u32_e32 v16, vcc, 0, v16, vcc
	v_sub_f32_e32 v52, v58, v52
	v_add_f32_e32 v17, 1.0, v18
	v_sub_u32_e32 v18, 0, v16
	v_add_f32_e32 v32, 1.0, v32
	v_add_f32_e32 v17, v52, v17
	v_ldexp_f32 v19, v19, v18
	v_add_f32_e32 v50, 1.0, v50
	v_add_f32_e32 v33, 1.0, v33
	v_rcp_f32_e32 v62, v32
	v_ldexp_f32 v17, v17, v18
	v_add_f32_e32 v18, -1.0, v19
	v_add_f32_e32 v32, 1.0, v19
	v_rcp_f32_e32 v61, v50
	v_rcp_f32_e32 v64, v33
	v_add_f32_e32 v33, 1.0, v18
	v_add_f32_e32 v50, -1.0, v32
	v_sub_f32_e32 v33, v19, v33
	v_sub_f32_e32 v19, v19, v50
	v_add_f32_e32 v33, v17, v33
	v_add_f32_e32 v17, v17, v19
	v_add_f32_e32 v52, v32, v17
	v_rcp_f32_e32 v53, v52
	v_add_f32_e32 v19, v18, v33
	v_sub_f32_e32 v32, v52, v32
	v_sub_f32_e32 v17, v17, v32
	v_mul_f32_e32 v55, v19, v53
	v_mul_f32_e32 v32, v52, v55
	v_fma_f32 v50, v55, v52, -v32
	v_sub_f32_e32 v18, v19, v18
	v_fmac_f32_e32 v50, v55, v17
	v_sub_f32_e32 v54, v33, v18
	v_add_f32_e32 v18, v32, v50
	v_add_f32_e32 v51, 1.0, v51
	v_sub_f32_e32 v33, v19, v18
	v_rcp_f32_e32 v63, v51
	v_mov_b32_e32 v51, v18
	v_pk_add_f32 v[18:19], v[18:19], v[32:33] neg_lo:[0,1] neg_hi:[0,1]
	v_cvt_f32_i32_e32 v16, v16
	v_pk_add_f32 v[18:19], v[18:19], v[50:51] neg_lo:[0,1] neg_hi:[0,1]
	v_cmp_neq_f32_e32 vcc, s86, v58
	v_add_f32_e32 v19, v54, v19
	v_add_f32_e32 v18, v18, v19
	v_add_f32_e32 v19, v33, v18
	v_mul_f32_e32 v51, v53, v19
	v_mul_f32_e32 v32, v52, v51
	v_sub_f32_e32 v33, v33, v19
	v_add_f32_e32 v56, v55, v51
	v_fma_f32 v50, v51, v52, -v32
	v_add_f32_e32 v54, v18, v33
	v_sub_f32_e32 v18, v56, v55
	v_fmac_f32_e32 v50, v51, v17
	v_sub_f32_e32 v17, v51, v18
	v_add_f32_e32 v18, v32, v50
	v_sub_f32_e32 v33, v19, v18
	v_mov_b32_e32 v51, v18
	v_pk_add_f32 v[18:19], v[18:19], v[32:33] neg_lo:[0,1] neg_hi:[0,1]
	v_add_f32_e32 v34, v34, v48
	v_pk_add_f32 v[18:19], v[18:19], v[50:51] neg_lo:[0,1] neg_hi:[0,1]
	v_mul_f32_e32 v34, 0xbfb8aa3b, v34
	v_add_f32_e32 v19, v54, v19
	v_add_f32_e32 v18, v18, v19
	v_add_f32_e32 v18, v33, v18
	v_mul_f32_e32 v18, v53, v18
	v_add_f32_e32 v17, v17, v18
	v_add_f32_e32 v18, v56, v17
	v_mul_f32_e32 v32, v18, v18
	v_sub_f32_e32 v33, v18, v56
	v_fmamk_f32 v50, v32, 0x3e9b6dac, v133
	v_sub_f32_e32 v33, v17, v33
	v_mul_f32_e32 v17, v18, v32
	v_fmaak_f32 v91, v32, v50, 0x3f2aaada
	v_ldexp_f32 v51, v33, 1
	v_pk_mul_f32 v[32:33], v[16:17], v[90:91]
	v_ldexp_f32 v19, v18, 1
	v_fma_f32 v18, v16, s85, -v32
	v_fmac_f32_e32 v18, 0xb102e308, v16
	v_pk_add_f32 v[16:17], v[32:33], v[18:19]
	v_mov_b32_e32 v50, v32
	v_sub_f32_e32 v54, v17, v19
	v_pk_add_f32 v[52:53], v[16:17], v[32:33] neg_lo:[0,1] neg_hi:[0,1]
	v_sub_f32_e32 v32, v33, v54
	v_add_f32_e32 v51, v51, v32
	v_pk_add_f32 v[32:33], v[16:17], v[50:51]
	v_mov_b32_e32 v19, v16
	v_mov_b32_e32 v53, v33
	v_pk_add_f32 v[56:57], v[18:19], v[52:53] neg_lo:[0,1] neg_hi:[0,1]
	v_pk_add_f32 v[18:19], v[18:19], v[52:53]
	v_mov_b32_e32 v55, v16
	v_pk_add_f32 v[52:53], v[18:19], v[16:17] op_sel:[1,0] op_sel_hi:[0,1] neg_lo:[0,1] neg_hi:[0,1]
	v_mov_b32_e32 v54, v51
	v_mov_b32_e32 v50, v33
	v_mov_b32_e32 v51, v19
	v_pk_mov_b32 v[16:17], v[16:17], v[52:53] op_sel:[1,0]
	v_pk_add_f32 v[32:33], v[32:33], v[52:53] op_sel_hi:[1,0] neg_lo:[0,1] neg_hi:[0,1]
	v_pk_add_f32 v[16:17], v[50:51], v[16:17] neg_lo:[0,1] neg_hi:[0,1]
	v_mov_b32_e32 v32, v56
	v_pk_add_f32 v[16:17], v[54:55], v[16:17] neg_lo:[0,1] neg_hi:[0,1]
	v_mov_b32_e32 v57, v19
	v_pk_add_f32 v[32:33], v[32:33], v[16:17]
	v_exp_f32_e32 v34, v34
	v_pk_add_f32 v[50:51], v[32:33], v[32:33] op_sel:[0,1] op_sel_hi:[1,0]
	v_add_f32_e32 v36, v36, v48
	v_pk_add_f32 v[18:19], v[18:19], v[50:51] op_sel:[1,0] op_sel_hi:[0,1]
	v_mov_b32_e32 v33, v18
	v_mov_b32_e32 v17, v50
	v_pk_add_f32 v[50:51], v[32:33], v[56:57] neg_lo:[0,1] neg_hi:[0,1]
	v_add_f32_e32 v34, 1.0, v34
	v_sub_f32_e32 v19, v32, v50
	v_pk_add_f32 v[16:17], v[16:17], v[50:51] neg_lo:[0,1] neg_hi:[0,1]
	v_sub_f32_e32 v19, v56, v19
	v_add_f32_e32 v16, v16, v19
	v_add_f32_e32 v16, v16, v17
	v_add_f32_e32 v16, v18, v16
	v_cndmask_b32_e32 v16, v135, v16, vcc
	v_cmp_ngt_f32_e32 vcc, -1.0, v58
	v_mul_f32_e32 v36, 0xbfb8aa3b, v36
	v_exp_f32_e32 v36, v36
	v_cndmask_b32_e32 v16, v136, v16, vcc
	v_cmp_neq_f32_e32 vcc, -1.0, v58
	s_nop 1
	v_cndmask_b32_e32 v16, v137, v16, vcc
	v_cmp_lt_f32_e64 vcc, |v58|, s87
	s_nop 1
	v_cndmask_b32_e32 v16, v16, v58, vcc
	v_mul_f32_e32 v33, 0xc1000000, v16
	v_mul_f32_e32 v16, v61, v33
	v_mul_f32_e32 v16, 0x3fb8aa3b, v16
	v_exp_f32_e32 v32, v16
	v_rcp_f32_e32 v16, v60
	v_mul_f32_e32 v17, v63, v33
	v_mul_f32_e32 v17, 0x3fb8aa3b, v17
	v_fma_f32 v18, -v32, v32, 1.0
	v_sqrt_f32_e32 v18, v18
	v_mul_f32_e32 v16, v16, v33
	v_mul_f32_e32 v16, 0x3fb8aa3b, v16
	v_exp_f32_e32 v50, v17
	v_mul_f32_e32 v18, v62, v18
	v_mul_f32_e32 v18, v0, v18
	v_exp_f32_e32 v0, v16
	v_add_f32_e32 v16, 1.0, v59
	v_rcp_f32_e32 v16, v16
	v_fma_f32 v19, -v50, v50, 1.0
	v_sqrt_f32_e32 v19, v19
	v_rcp_f32_e32 v17, v34
	v_mul_f32_e32 v16, v16, v33
	v_mul_f32_e32 v16, 0x3fb8aa3b, v16
	v_exp_f32_e32 v51, v16
	v_add_f32_e32 v16, v20, v49
	v_mul_f32_e32 v16, 0xbfb8aa3b, v16
	v_mul_f32_e32 v34, v64, v19
	v_add_f32_e32 v19, v35, v48
	v_exp_f32_e32 v16, v16
	v_mul_f32_e32 v19, 0xbfb8aa3b, v19
	v_exp_f32_e32 v19, v19
	v_fma_f32 v20, -v51, v51, 1.0
	v_add_f32_e32 v16, 1.0, v16
	v_rcp_f32_e32 v16, v16
	v_add_f32_e32 v19, 1.0, v19
	v_rcp_f32_e32 v19, v19
	v_sqrt_f32_e32 v20, v20
	v_mul_f32_e32 v16, v16, v33
	v_mul_f32_e32 v16, 0x3fb8aa3b, v16
	v_fma_f32 v35, -v0, v0, 1.0
	v_mul_f32_e32 v52, v19, v20
	v_exp_f32_e32 v20, v16
	v_add_f32_e32 v16, v21, v49
	v_mul_f32_e32 v16, 0xbfb8aa3b, v16
	v_exp_f32_e32 v16, v16
	v_sqrt_f32_e32 v35, v35
	v_fma_f32 v19, -v20, v20, 1.0
	v_add_f32_e32 v21, v37, v48
	v_add_f32_e32 v16, 1.0, v16
	v_rcp_f32_e32 v16, v16
	v_mul_f32_e32 v35, v17, v35
	v_add_f32_e32 v17, 1.0, v36
	v_rcp_f32_e32 v17, v17
	v_mul_f32_e32 v16, v16, v33
	v_mul_f32_e32 v16, 0x3fb8aa3b, v16
	v_exp_f32_e32 v36, v16
	v_add_f32_e32 v16, v22, v49
	v_mul_f32_e32 v16, 0xbfb8aa3b, v16
	v_exp_f32_e32 v16, v16
	v_sqrt_f32_e32 v19, v19
	v_mul_f32_e32 v21, 0xbfb8aa3b, v21
	v_exp_f32_e32 v21, v21
	v_add_f32_e32 v16, 1.0, v16
	v_rcp_f32_e32 v16, v16
	v_mul_f32_e32 v17, v17, v19
	v_mul_f32_e32 v19, v4, v17
	v_add_f32_e32 v4, 1.0, v21
	v_add_f32_e32 v21, v38, v48
	v_mul_f32_e32 v21, 0xbfb8aa3b, v21
	v_mul_f32_e32 v16, v16, v33
	v_fma_f32 v17, -v36, v36, 1.0
	v_exp_f32_e32 v21, v21
	v_mul_f32_e32 v16, 0x3fb8aa3b, v16
	v_rcp_f32_e32 v4, v4
	v_sqrt_f32_e32 v17, v17
	v_exp_f32_e32 v37, v16
	v_add_f32_e32 v16, 1.0, v21
	v_add_f32_e32 v21, v23, v49
	v_mul_f32_e32 v4, v4, v17
	v_fma_f32 v17, -v37, v37, 1.0
	v_mul_f32_e32 v21, 0xbfb8aa3b, v21
	v_rcp_f32_e32 v16, v16
	v_sqrt_f32_e32 v17, v17
	v_exp_f32_e32 v21, v21
	v_add_f32_e32 v22, v39, v48
	v_mul_f32_e32 v22, 0xbfb8aa3b, v22
	v_mul_f32_e32 v23, v16, v17
	v_add_f32_e32 v16, 1.0, v21
	v_rcp_f32_e32 v16, v16
	v_add_f32_e32 v21, v24, v49
	v_mul_f32_e32 v21, 0xbfb8aa3b, v21
	v_exp_f32_e32 v21, v21
	v_mul_f32_e32 v16, v16, v33
	v_mul_f32_e32 v16, 0x3fb8aa3b, v16
	v_exp_f32_e32 v24, v16
	v_add_f32_e32 v16, 1.0, v21
	v_rcp_f32_e32 v16, v16
	v_exp_f32_e32 v22, v22
	v_add_f32_e32 v21, v40, v48
	v_mul_f32_e32 v21, 0xbfb8aa3b, v21
	v_mul_f32_e32 v16, v16, v33
	v_add_f32_e32 v17, 1.0, v22
	v_fma_f32 v22, -v24, v24, 1.0
	v_mul_f32_e32 v16, 0x3fb8aa3b, v16
	v_sqrt_f32_e32 v38, v22
	v_exp_f32_e32 v22, v16
	v_add_f32_e32 v16, v25, v49
	v_mul_f32_e32 v16, 0xbfb8aa3b, v16
	v_exp_f32_e32 v16, v16
	v_exp_f32_e32 v21, v21
	v_add_f32_e32 v39, v41, v48
	v_fma_f32 v25, -v22, v22, 1.0
	v_add_f32_e32 v16, 1.0, v16
	v_rcp_f32_e32 v16, v16
	v_add_f32_e32 v21, 1.0, v21
	v_mul_f32_e32 v39, 0xbfb8aa3b, v39
	v_rcp_f32_e32 v17, v17
	v_rcp_f32_e32 v21, v21
	v_sqrt_f32_e32 v25, v25
	v_exp_f32_e32 v39, v39
	v_mul_f32_e32 v16, v16, v33
	v_mul_f32_e32 v16, 0x3fb8aa3b, v16
	v_mul_f32_e32 v38, v17, v38
	v_mul_f32_e32 v17, v21, v25
	v_add_f32_e32 v21, 1.0, v39
	v_exp_f32_e32 v39, v16
	v_add_f32_e32 v16, v26, v49
	v_mul_f32_e32 v16, 0xbfb8aa3b, v16
	v_exp_f32_e32 v16, v16
	v_rcp_f32_e32 v25, v21
	v_fma_f32 v21, -v39, v39, 1.0
	v_sqrt_f32_e32 v26, v21
	v_add_f32_e32 v16, 1.0, v16
	v_add_f32_e32 v21, v42, v48
	v_rcp_f32_e32 v16, v16
	v_mul_f32_e32 v21, 0xbfb8aa3b, v21
	v_exp_f32_e32 v40, v21
	v_mul_f32_e32 v21, v8, v17
	v_mul_f32_e32 v16, v16, v33
	v_mul_f32_e32 v16, 0x3fb8aa3b, v16
	v_add_f32_e32 v17, 1.0, v40
	v_exp_f32_e32 v40, v16
	v_add_f32_e32 v16, v27, v49
	v_mul_f32_e32 v16, 0xbfb8aa3b, v16
	v_exp_f32_e32 v16, v16
	v_mul_f32_e32 v8, v25, v26
	v_fma_f32 v25, -v40, v40, 1.0
	v_add_f32_e32 v26, v43, v48
	v_add_f32_e32 v16, 1.0, v16
	v_rcp_f32_e32 v16, v16
	v_rcp_f32_e32 v17, v17
	v_sqrt_f32_e32 v25, v25
	v_mul_f32_e32 v26, 0xbfb8aa3b, v26
	v_mul_f32_e32 v16, v16, v33
	v_exp_f32_e32 v26, v26
	v_mul_f32_e32 v16, 0x3fb8aa3b, v16
	v_exp_f32_e32 v41, v16
	v_mul_f32_e32 v53, v17, v25
	v_add_f32_e32 v25, v28, v49
	v_add_f32_e32 v16, 1.0, v26
	v_mul_f32_e32 v25, 0xbfb8aa3b, v25
	v_add_f32_e32 v26, v44, v48
	v_fma_f32 v17, -v41, v41, 1.0
	v_exp_f32_e32 v25, v25
	v_mul_f32_e32 v26, 0xbfb8aa3b, v26
	v_rcp_f32_e32 v16, v16
	v_sqrt_f32_e32 v17, v17
	v_exp_f32_e32 v26, v26
	v_add_f32_e32 v25, 1.0, v25
	v_rcp_f32_e32 v25, v25
	v_mul_f32_e32 v54, v16, v17
	v_add_f32_e32 v16, 1.0, v26
	v_add_f32_e32 v26, v45, v48
	v_mul_f32_e32 v26, 0xbfb8aa3b, v26
	v_exp_f32_e32 v26, v26
	v_rcp_f32_e32 v17, v16
	v_mul_f32_e32 v16, v25, v33
	v_add_f32_e32 v25, v29, v49
	v_mul_f32_e32 v25, 0xbfb8aa3b, v25
	v_exp_f32_e32 v25, v25
	v_add_f32_e32 v26, 1.0, v26
	v_rcp_f32_e32 v42, v26
	v_add_f32_e32 v26, v30, v49
	v_mul_f32_e32 v26, 0xbfb8aa3b, v26
	v_exp_f32_e32 v26, v26
	v_add_f32_e32 v25, 1.0, v25
	v_rcp_f32_e32 v25, v25
	v_add_f32_e32 v27, v46, v48
	v_mul_f32_e32 v27, 0xbfb8aa3b, v27
	v_exp_f32_e32 v27, v27
	v_add_f32_e32 v26, 1.0, v26
	v_rcp_f32_e32 v26, v26
	v_mul_f32_e32 v25, v25, v33
	v_mul_f32_e32 v25, 0x3fb8aa3b, v25
	v_exp_f32_e32 v43, v25
	v_add_f32_e32 v25, 1.0, v27
	v_rcp_f32_e32 v44, v25
	v_mul_f32_e32 v25, v26, v33
	v_add_f32_e32 v26, v31, v49
	v_mul_f32_e32 v26, 0xbfb8aa3b, v26
	v_exp_f32_e32 v26, v26
	v_add_f32_e32 v27, v47, v48
	v_mul_f32_e32 v27, 0xbfb8aa3b, v27
	v_exp_f32_e32 v27, v27
	v_add_f32_e32 v26, 1.0, v26
	v_mul_f32_e32 v16, 0x3fb8aa3b, v16
	v_rcp_f32_e32 v26, v26
	v_exp_f32_e32 v16, v16
	v_mul_f32_e32 v25, 0x3fb8aa3b, v25
	v_fmac_f32_e32 v18, 0, v32
	v_exp_f32_e32 v45, v25
	v_add_f32_e32 v25, 1.0, v27
	v_mul_f32_e32 v31, v50, v18
	v_rcp_f32_e32 v46, v25
	v_mul_f32_e32 v25, v26, v33
	v_fmac_f32_e32 v31, v1, v34
	v_mul_f32_e32 v33, v32, v50
	v_fmac_f32_e32 v19, 0, v20
	v_mul_f32_e32 v30, v0, v31
	v_mul_f32_e32 v34, v0, v33
	v_mul_f32_e32 v28, v36, v19
	v_fma_f32 v0, -v16, v16, 1.0
	v_fmac_f32_e32 v28, v5, v4
	v_sqrt_f32_e32 v1, v0
	v_mul_f32_e32 v27, v37, v28
	v_fmac_f32_e32 v30, v2, v35
	v_fmac_f32_e32 v27, v6, v23
	v_fma_f32 v2, -v43, v43, 1.0
	v_mul_f32_e32 v26, v24, v27
	v_mov_b32_e32 v0, v89
	v_sqrt_f32_e32 v2, v2
	v_fmac_f32_e32 v26, v7, v38
	v_pk_mul_f32 v[6:7], v[16:17], v[0:1]
	v_mul_f32_e32 v29, v51, v30
	v_fmac_f32_e32 v6, v12, v7
	v_fmac_f32_e32 v29, v3, v52
	v_mov_b32_e32 v3, v6
	v_mul_f32_e32 v25, 0x3fb8aa3b, v25
	v_pk_mul_f32 v[4:5], v[42:43], v[2:3]
	v_fma_f32 v0, -v45, v45, 1.0
	v_exp_f32_e32 v47, v25
	v_fmac_f32_e32 v5, v13, v4
	v_sqrt_f32_e32 v4, v0
	v_fmac_f32_e32 v21, 0, v22
	v_mul_f32_e32 v25, v39, v21
	v_mul_f32_e32 v36, v20, v36
	v_fmac_f32_e32 v25, v9, v8
	v_pk_mul_f32 v[8:9], v[44:45], v[4:5]
	v_fma_f32 v0, -v47, v47, 1.0
	v_mul_f32_e32 v37, v37, v36
	v_fmac_f32_e32 v9, v14, v8
	v_sqrt_f32_e32 v8, v0
	ds_bpermute_b32 v0, v140, v29
	v_mul_f32_e32 v38, v24, v37
	v_mul_f32_e32 v24, v40, v25
	v_mul_f32_e32 v35, v51, v34
	v_fmac_f32_e32 v24, v10, v53
	v_mul_f32_e32 v23, v41, v24
	ds_bpermute_b32 v13, v140, v35
	v_fmac_f32_e32 v23, v11, v54
	v_pk_mul_f32 v[10:11], v[46:47], v[8:9]
	s_waitcnt lgkmcnt(1)
	v_cndmask_b32_e64 v14, v29, v0, s[0:1]
	v_fmac_f32_e32 v11, v15, v10
	v_cndmask_b32_e64 v10, v0, v29, s[0:1]
	ds_bpermute_b32 v0, v140, v38
	ds_bpermute_b32 v3, v140, v26
	v_mul_f32_e32 v39, v22, v39
	v_mul_f32_e32 v40, v40, v39
	s_waitcnt lgkmcnt(2)
	v_cndmask_b32_e64 v1, v13, v35, s[0:1]
	v_mul_f32_e32 v12, v41, v40
	v_mul_f32_e32 v7, v16, v43
	v_cndmask_b32_e64 v2, v35, v13, s[0:1]
	v_fmac_f32_e32 v10, 0, v1
	v_mul_f32_e32 v4, v45, v7
	v_mul_f32_e32 v15, v35, v13
	v_fmac_f32_e32 v14, v2, v10
	s_waitcnt lgkmcnt(1)
	v_cndmask_b32_e64 v1, v0, v38, s[0:1]
	s_waitcnt lgkmcnt(0)
	v_cndmask_b32_e64 v17, v3, v26, s[0:1]
	v_cndmask_b32_e64 v41, v26, v3, s[0:1]
	ds_bpermute_b32 v2, v140, v12
	ds_bpermute_b32 v3, v140, v23
	v_mul_f32_e32 v8, v47, v4
	v_cndmask_b32_e64 v0, v38, v0, s[0:1]
	v_mul_f32_e32 v42, v15, v1
	v_fmac_f32_e32 v17, v1, v14
	v_mul_f32_e32 v43, v0, v42
	v_fmac_f32_e32 v41, v0, v17
	ds_bpermute_b32 v1, v140, v8
	ds_bpermute_b32 v0, v140, v11
	s_waitcnt lgkmcnt(3)
	v_cndmask_b32_e64 v47, v2, v12, s[0:1]
	s_waitcnt lgkmcnt(2)
	v_cndmask_b32_e64 v44, v3, v23, s[0:1]
	v_cndmask_b32_e64 v2, v12, v2, s[0:1]
	v_cndmask_b32_e64 v45, v23, v3, s[0:1]
	v_mul_f32_e32 v46, v47, v43
	v_fmac_f32_e32 v44, v47, v41
	v_mul_f32_e32 v47, v2, v46
	v_fmac_f32_e32 v45, v2, v44
	s_waitcnt lgkmcnt(1)
	v_cndmask_b32_e64 v2, v1, v8, s[0:1]
	s_waitcnt lgkmcnt(0)
	v_cndmask_b32_e64 v48, v0, v11, s[0:1]
	v_mul_f32_e32 v49, v2, v47
	v_fmac_f32_e32 v48, v2, v45
	s_and_saveexec_b64 s[8:9], s[0:1]
	v_mul_f32_e32 v3, v48, v1
	v_mul_f32_e32 v2, v49, v1
	v_add_f32_e32 v3, v3, v0
	ds_write_b64 v139, v[2:3] offset:6144
	s_or_b64 exec, exec, s[8:9]
	s_and_b64 vcc, exec, s[6:7]
	s_waitcnt lgkmcnt(0)
	s_barrier
	s_cbranch_vccnz .LBB0_366
	s_cmp_lt_u32 s62, 8
	s_cbranch_scc1 .LBB0_367
	s_and_b32 s6, s62, 0x7ffffff8
	v_add3_u32 v50, v141, v138, s88
	v_mov_b32_e32 v0, 1.0
	v_mov_b32_e32 v3, 0
	s_mov_b32 s7, 0
